# v39 plus phase-1 scalar block precomputed in previous MFMA block (10 loops) plus s_setprio 1 as m0 spacer
# speedup vs baseline: 1.0029x; 1.0029x over previous
; #define PG8_STAGE(bufoff, gbase, voff) do { _Pragma("unroll") for (int _i = 0; _i < 2; ++_i) \
;         __builtin_amdgcn_global_load_lds((const unsigned*)((const char*)(gbase) + (voff)[_i]), (LAS unsigned*)(lds + (bufoff) + ldsw + _i * 8192), 16, 0, 0); } while (0)
; #define PG8_LDA(dst, b, h) do { _Pragma("unroll") for (int m = 0; m < 4; ++m) _Pragma("unroll") for (int k = 0; k < 2; ++k) dst[m][k] = *(const LAS bf16x8*)(lds + PG8_SA(b, h) + aoff + m * 2048 + k * 1024); } while (0)
; #define PG8_LDB(dst, b, h) do { _Pragma("unroll") for (int n = 0; n < 2; ++n) _Pragma("unroll") for (int k = 0; k < 2; ++k) dst[n][k] = *(const LAS bf16x8*)(lds + PG8_SB(b, h) + boff + n * 2048 + k * 1024); } while (0)
; #define PG8_MMA(ai, bj, At, Bt) do { __builtin_amdgcn_s_setprio(1); _Pragma("unroll") for (int m = 0; m < 4; ++m) _Pragma("unroll") for (int n = 0; n < 2; ++n) _Pragma("unroll") for (int k = 0; k < 2; ++k) \
;         acc[ai][bj][m][n] = __builtin_amdgcn_mfma_f32_16x16x32_bf16(Bt[n][k], At[m][k], acc[ai][bj][m][n], 0, 0, 0); __builtin_amdgcn_s_setprio(0); } while (0)
; #define PG8_WAIT_V(n) asm volatile("s_waitcnt vmcnt(" #n ")" ::: "memory")
; #define PG8_WAIT_L(n) asm volatile("s_waitcnt lgkmcnt(" #n ")" ::: "memory")
; template <class Map, class Epi>
; DI void gemm_phase(LAS unsigned char* lds, const Map& MP, const Epi& E, const int nM, const int nN, const int K, const int lda, const int ldb) {
;     ...
;         for (int t = 0; t < nt; t += 2) {
;             const bool last = (t == nt - 2);
;             const char* a1 = cA + (size_t)(t + 1) * kstep;
;             const char* a2 = last ? nA : cA + (size_t)(t + 2) * kstep; const char* b2 = last ? nB : cB + (size_t)(t + 2) * kstep;
;             const char* a3 = a2 + kstep; const char* b3 = b2 + kstep;
;             PG8_LDB(B0, 0, 0); PG8_SCHED; PG8_LDA(At, 0, 0); PG8_STAGE(PG8_SA(1, 1), a1 + hstepA, voffA);
;             PG8_WAIT_L(8); PG8_BAR; PG8_WAIT_L(0); PG8_MMA(0, 0, At, B0); PG8_BAR; PG8_SCHED;
;             PG8_LDB(B1, 0, 1); PG8_STAGE(PG8_SB(0, 0), b2, voffB);
;             PG8_BAR; PG8_WAIT_L(0); PG8_MMA(0, 1, At, B1); PG8_BAR;
;             PG8_LDA(At, 0, 1); PG8_STAGE(PG8_SA(0, 0), a2, voffA);
;             PG8_BAR; PG8_WAIT_L(0); PG8_MMA(1, 0, At, B0); PG8_BAR; PG8_SCHED;
;             PG8_STAGE(PG8_SB(0, 1), b2 + hstepB, voffB);
;             PG8_WAIT_V(6); PG8_BAR; PG8_MMA(1, 1, At, B1); PG8_BAR;
.LBB1_229:
	s_add_i32 m0, s2, 0xc000
	ds_read_b128 v[160:163], v168
	ds_read_b128 v[170:173], v168 offset:1024
	ds_read_b128 v[174:177], v168 offset:2048
	ds_read_b128 v[178:181], v168 offset:3072
	ds_read_b128 v[182:185], v168 offset:4096
	ds_read_b128 v[186:189], v168 offset:5120
	ds_read_b128 v[190:193], v168 offset:6144
	ds_read_b128 v[198:201], v168 offset:7168
	global_load_lds_dwordx4 v154, s[24:25]
	s_add_i32 m0, s2, 0xe000
	s_setprio 1
	global_load_lds_dwordx4 v152, s[24:25]
	s_waitcnt lgkmcnt(8)
	s_barrier
	s_waitcnt lgkmcnt(7)
	v_mfma_f32_16x16x32_bf16 v[140:143], v[72:75], v[160:163], v[140:143]
	v_mfma_f32_16x16x32_bf16 v[136:139], v[80:83], v[160:163], v[136:139]
	s_waitcnt lgkmcnt(5)
	v_mfma_f32_16x16x32_bf16 v[124:127], v[72:75], v[174:177], v[124:127]
	v_mfma_f32_16x16x32_bf16 v[120:123], v[80:83], v[174:177], v[120:123]
	s_waitcnt lgkmcnt(3)
	v_mfma_f32_16x16x32_bf16 v[108:111], v[72:75], v[182:185], v[108:111]
	v_mfma_f32_16x16x32_bf16 v[104:107], v[80:83], v[182:185], v[104:107]
	s_waitcnt lgkmcnt(1)
	v_mfma_f32_16x16x32_bf16 v[92:95], v[72:75], v[190:193], v[92:95]
	v_mfma_f32_16x16x32_bf16 v[88:91], v[80:83], v[190:193], v[88:91]
	v_mfma_f32_16x16x32_bf16 v[140:143], v[76:79], v[170:173], v[140:143]
	s_add_i32 s58, s48, s34
	v_mfma_f32_16x16x32_bf16 v[136:139], v[84:87], v[170:173], v[136:139]
	v_lshl_add_u64 v[194:195], s[26:27], 0, v[148:149]
	v_mfma_f32_16x16x32_bf16 v[124:127], v[76:79], v[178:181], v[124:127]
	v_lshl_add_u64 v[218:219], s[26:27], 0, v[144:145]
	v_mfma_f32_16x16x32_bf16 v[120:123], v[84:87], v[178:181], v[120:123]
	v_mfma_f32_16x16x32_bf16 v[108:111], v[76:79], v[186:189], v[108:111]
	v_mfma_f32_16x16x32_bf16 v[104:107], v[84:87], v[186:189], v[104:107]
	s_waitcnt lgkmcnt(0)
	v_mfma_f32_16x16x32_bf16 v[92:95], v[76:79], v[198:201], v[92:95]
	v_mfma_f32_16x16x32_bf16 v[88:91], v[84:87], v[198:201], v[88:91]
	s_barrier
	s_setprio 0
	s_mov_b32 m0, s58
	ds_read_b128 v[202:205], v169
	ds_read_b128 v[206:209], v169 offset:1024
	ds_read_b128 v[210:213], v169 offset:2048
	ds_read_b128 v[214:217], v169 offset:3072
	global_load_lds_dwordx4 v[194:195], off
	s_add_i32 m0, s58, 0x2000
	s_setprio 1
	global_load_lds_dwordx4 v[218:219], off
	s_barrier
	s_waitcnt lgkmcnt(3)
	v_mfma_f32_16x16x32_bf16 v[132:135], v[202:205], v[160:163], v[132:135]
	s_waitcnt lgkmcnt(1)
	v_mfma_f32_16x16x32_bf16 v[128:131], v[210:213], v[160:163], v[128:131]
	v_mfma_f32_16x16x32_bf16 v[116:119], v[202:205], v[174:177], v[116:119]
	v_mfma_f32_16x16x32_bf16 v[112:115], v[210:213], v[174:177], v[112:115]
	v_mfma_f32_16x16x32_bf16 v[100:103], v[202:205], v[182:185], v[100:103]
	v_mfma_f32_16x16x32_bf16 v[96:99], v[210:213], v[182:185], v[96:99]
	v_mfma_f32_16x16x32_bf16 v[68:71], v[202:205], v[190:193], v[68:71]
	v_mfma_f32_16x16x32_bf16 v[64:67], v[210:213], v[190:193], v[64:67]
	v_mfma_f32_16x16x32_bf16 v[132:135], v[206:209], v[170:173], v[132:135]
	v_lshl_add_u64 v[222:223], s[28:29], 0, v[146:147]
	s_mov_b32 m0, s2
	s_waitcnt lgkmcnt(0)
	v_mfma_f32_16x16x32_bf16 v[128:131], v[214:217], v[170:173], v[128:131]
	v_lshl_add_u64 v[220:221], s[28:29], 0, v[150:151]
	v_mfma_f32_16x16x32_bf16 v[116:119], v[206:209], v[178:181], v[116:119]
	v_mfma_f32_16x16x32_bf16 v[112:115], v[214:217], v[178:181], v[112:115]
	v_mfma_f32_16x16x32_bf16 v[100:103], v[206:209], v[186:189], v[100:103]
	v_mfma_f32_16x16x32_bf16 v[96:99], v[214:217], v[186:189], v[96:99]
	v_mfma_f32_16x16x32_bf16 v[68:71], v[206:209], v[198:201], v[68:71]
	v_mfma_f32_16x16x32_bf16 v[64:67], v[214:217], v[198:201], v[64:67]
	s_barrier
	s_setprio 0
	ds_read_b128 v[160:163], v168 offset:16384
	ds_read_b128 v[170:173], v168 offset:17408
	ds_read_b128 v[174:177], v168 offset:18432
	ds_read_b128 v[178:181], v168 offset:19456
	ds_read_b128 v[182:185], v168 offset:20480
	ds_read_b128 v[186:189], v168 offset:21504
	ds_read_b128 v[190:193], v168 offset:22528
	ds_read_b128 v[198:201], v168 offset:23552
	global_load_lds_dwordx4 v[220:221], off
	s_mov_b32 m0, s4
	s_setprio 1
	global_load_lds_dwordx4 v[222:223], off
	s_waitcnt vmcnt(10)
	s_barrier
	s_waitcnt lgkmcnt(7)
	v_mfma_f32_16x16x32_bf16 v[60:63], v[72:75], v[160:163], v[60:63]
	v_mfma_f32_16x16x32_bf16 v[56:59], v[80:83], v[160:163], v[56:59]
	s_waitcnt lgkmcnt(5)
	v_mfma_f32_16x16x32_bf16 v[44:47], v[72:75], v[174:177], v[44:47]
	v_mfma_f32_16x16x32_bf16 v[40:43], v[80:83], v[174:177], v[40:43]
	s_waitcnt lgkmcnt(3)
	v_mfma_f32_16x16x32_bf16 v[28:31], v[72:75], v[182:185], v[28:31]
	v_mfma_f32_16x16x32_bf16 v[24:27], v[80:83], v[182:185], v[24:27]
	s_waitcnt lgkmcnt(1)
	v_mfma_f32_16x16x32_bf16 v[12:15], v[72:75], v[190:193], v[12:15]
	v_mfma_f32_16x16x32_bf16 v[8:11], v[80:83], v[190:193], v[8:11]
	v_mfma_f32_16x16x32_bf16 v[60:63], v[76:79], v[170:173], v[60:63]
	s_add_u32 s58, s26, 0x20000
	s_addc_u32 s59, s27, 0
	v_mfma_f32_16x16x32_bf16 v[56:59], v[84:87], v[170:173], v[56:59]
	s_add_i32 s60, s49, s34
	v_mfma_f32_16x16x32_bf16 v[44:47], v[76:79], v[178:181], v[44:47]
	v_mfma_f32_16x16x32_bf16 v[40:43], v[84:87], v[178:181], v[40:43]
	v_mfma_f32_16x16x32_bf16 v[28:31], v[76:79], v[186:189], v[28:31]
	v_mfma_f32_16x16x32_bf16 v[24:27], v[84:87], v[186:189], v[24:27]
	s_waitcnt lgkmcnt(0)
	v_mfma_f32_16x16x32_bf16 v[12:15], v[76:79], v[198:201], v[12:15]
	v_mfma_f32_16x16x32_bf16 v[8:11], v[84:87], v[198:201], v[8:11]
	s_barrier
	s_setprio 0
	s_mov_b32 m0, s60
	s_nop 0
	global_load_lds_dwordx4 v148, s[58:59]
	s_add_i32 m0, s60, 0x2000
	s_setprio 1
	global_load_lds_dwordx4 v144, s[58:59]
	s_waitcnt vmcnt(6)
	s_barrier
; #define PG8_STAGE(bufoff, gbase, voff) do { _Pragma("unroll") for (int _i = 0; _i < 2; ++_i) \
;         __builtin_amdgcn_global_load_lds((const unsigned*)((const char*)(gbase) + (voff)[_i]), (LAS unsigned*)(lds + (bufoff) + ldsw + _i * 8192), 16, 0, 0); } while (0)
; #define PG8_LDA(dst, b, h) do { _Pragma("unroll") for (int m = 0; m < 4; ++m) _Pragma("unroll") for (int k = 0; k < 2; ++k) dst[m][k] = *(const LAS bf16x8*)(lds + PG8_SA(b, h) + aoff + m * 2048 + k * 1024); } while (0)
; #define PG8_LDB(dst, b, h) do { _Pragma("unroll") for (int n = 0; n < 2; ++n) _Pragma("unroll") for (int k = 0; k < 2; ++k) dst[n][k] = *(const LAS bf16x8*)(lds + PG8_SB(b, h) + boff + n * 2048 + k * 1024); } while (0)
; #define PG8_MMA(ai, bj, At, Bt) do { __builtin_amdgcn_s_setprio(1); _Pragma("unroll") for (int m = 0; m < 4; ++m) _Pragma("unroll") for (int n = 0; n < 2; ++n) _Pragma("unroll") for (int k = 0; k < 2; ++k) \
;         acc[ai][bj][m][n] = __builtin_amdgcn_mfma_f32_16x16x32_bf16(Bt[n][k], At[m][k], acc[ai][bj][m][n], 0, 0, 0); __builtin_amdgcn_s_setprio(0); } while (0)
; #define PG8_WAIT_V(n) asm volatile("s_waitcnt vmcnt(" #n ")" ::: "memory")
; #define PG8_WAIT_L(n) asm volatile("s_waitcnt lgkmcnt(" #n ")" ::: "memory")
; #define PG8_BAR __builtin_amdgcn_s_barrier()
; #define PG8_SCHED __builtin_amdgcn_sched_barrier(0)
; template <class Map, class Epi>
; DI void gemm_phase(LAS unsigned char* lds, const Map& MP, const Epi& E, const int nM, const int nN, const int K, const int lda, const int ldb) {
;     ...
;             PG8_BAR; PG8_WAIT_L(0); PG8_MMA(1, 0, At, B0); PG8_BAR; PG8_SCHED;
;             PG8_STAGE(PG8_SB(0, 1), b2 + hstepB, voffB);
;             PG8_WAIT_V(6); PG8_BAR; PG8_MMA(1, 1, At, B1); PG8_BAR;
;             PG8_LDB(B0, 1, 0); PG8_SCHED; PG8_LDA(At, 1, 0); PG8_STAGE(PG8_SA(0, 1), a2 + hstepA, voffA);
;             PG8_WAIT_L(8); PG8_BAR; PG8_WAIT_L(0); PG8_MMA(0, 0, At, B0); PG8_BAR; PG8_SCHED;
;             PG8_LDB(B1, 1, 1); PG8_STAGE(PG8_SB(1, 0), b3, voffB);
;             PG8_BAR; PG8_WAIT_L(0); PG8_MMA(0, 1, At, B1); PG8_BAR;
	v_mfma_f32_16x16x32_bf16 v[52:55], v[202:205], v[160:163], v[52:55]
	v_mfma_f32_16x16x32_bf16 v[48:51], v[210:213], v[160:163], v[48:51]
	s_add_i32 s58, 0, 0x18000
	v_add_u32_e32 v84, s58, v166
	ds_read_b128 v[72:75], v84
	v_mfma_f32_16x16x32_bf16 v[36:39], v[202:205], v[174:177], v[36:39]
	v_mfma_f32_16x16x32_bf16 v[32:35], v[210:213], v[174:177], v[32:35]
	ds_read_b128 v[76:79], v84 offset:1024
	v_mfma_f32_16x16x32_bf16 v[20:23], v[202:205], v[182:185], v[20:23]
	v_mfma_f32_16x16x32_bf16 v[16:19], v[210:213], v[182:185], v[16:19]
	ds_read_b128 v[80:83], v84 offset:2048
	v_mfma_f32_16x16x32_bf16 v[4:7], v[202:205], v[190:193], v[4:7]
	v_mfma_f32_16x16x32_bf16 v[0:3], v[210:213], v[190:193], v[0:3]
	ds_read_b128 v[84:87], v84 offset:3072
	v_mfma_f32_16x16x32_bf16 v[52:55], v[206:209], v[170:173], v[52:55]
	s_add_u32 s28, s28, 0x80000
	s_addc_u32 s29, s29, 0
	v_mfma_f32_16x16x32_bf16 v[48:51], v[214:217], v[170:173], v[48:51]
	v_mfma_f32_16x16x32_bf16 v[36:39], v[206:209], v[178:181], v[36:39]
	v_mfma_f32_16x16x32_bf16 v[32:35], v[214:217], v[178:181], v[32:35]
	v_mfma_f32_16x16x32_bf16 v[20:23], v[206:209], v[186:189], v[20:23]
	v_mfma_f32_16x16x32_bf16 v[16:19], v[214:217], v[186:189], v[16:19]
	v_mfma_f32_16x16x32_bf16 v[4:7], v[206:209], v[198:201], v[4:7]
	v_mfma_f32_16x16x32_bf16 v[0:3], v[214:217], v[198:201], v[0:3]
	s_barrier
	s_setprio 0
	s_mov_b32 m0, s5
	ds_read_b128 v[160:163], v168 offset:32768
	ds_read_b128 v[170:173], v168 offset:33792
	ds_read_b128 v[174:177], v168 offset:34816
	ds_read_b128 v[178:181], v168 offset:35840
	ds_read_b128 v[182:185], v168 offset:36864
	ds_read_b128 v[186:189], v168 offset:37888
	ds_read_b128 v[190:193], v168 offset:38912
	ds_read_b128 v[198:201], v168 offset:39936
	global_load_lds_dwordx4 v150, s[28:29]
	s_mov_b32 m0, s23
	s_setprio 1
	global_load_lds_dwordx4 v146, s[28:29]
	s_waitcnt lgkmcnt(8)
	s_barrier
	s_waitcnt lgkmcnt(7)
	v_mfma_f32_16x16x32_bf16 v[140:143], v[72:75], v[160:163], v[140:143]
	v_mfma_f32_16x16x32_bf16 v[136:139], v[80:83], v[160:163], v[136:139]
	s_waitcnt lgkmcnt(5)
	v_mfma_f32_16x16x32_bf16 v[124:127], v[72:75], v[174:177], v[124:127]
	v_mfma_f32_16x16x32_bf16 v[120:123], v[80:83], v[174:177], v[120:123]
	s_waitcnt lgkmcnt(3)
	v_mfma_f32_16x16x32_bf16 v[108:111], v[72:75], v[182:185], v[108:111]
	v_mfma_f32_16x16x32_bf16 v[104:107], v[80:83], v[182:185], v[104:107]
	s_waitcnt lgkmcnt(1)
	v_mfma_f32_16x16x32_bf16 v[92:95], v[72:75], v[190:193], v[92:95]
	v_mfma_f32_16x16x32_bf16 v[88:91], v[80:83], v[190:193], v[88:91]
	v_mfma_f32_16x16x32_bf16 v[140:143], v[76:79], v[170:173], v[140:143]
	s_add_i32 s28, 0, 0x1c000
	v_mfma_f32_16x16x32_bf16 v[136:139], v[84:87], v[170:173], v[136:139]
	s_add_i32 s29, s58, s34
	v_mfma_f32_16x16x32_bf16 v[124:127], v[76:79], v[178:181], v[124:127]
	v_add_u32_e32 v196, s28, v166
	v_mfma_f32_16x16x32_bf16 v[120:123], v[84:87], v[178:181], v[120:123]
	v_lshl_add_u64 v[194:195], v[194:195], 0, s[12:13]
	v_mfma_f32_16x16x32_bf16 v[108:111], v[76:79], v[186:189], v[108:111]
	v_mfma_f32_16x16x32_bf16 v[104:107], v[84:87], v[186:189], v[104:107]
	s_waitcnt lgkmcnt(0)
	v_mfma_f32_16x16x32_bf16 v[92:95], v[76:79], v[198:201], v[92:95]
	v_mfma_f32_16x16x32_bf16 v[88:91], v[84:87], v[198:201], v[88:91]
	s_barrier
	s_setprio 0
	s_mov_b32 m0, s29
	ds_read_b128 v[202:205], v196
	ds_read_b128 v[206:209], v196 offset:1024
	ds_read_b128 v[210:213], v196 offset:2048
	ds_read_b128 v[214:217], v196 offset:3072
	global_load_lds_dwordx4 v[194:195], off
	v_lshl_add_u64 v[194:195], v[218:219], 0, s[12:13]
	s_add_i32 m0, s29, 0x2000
	s_setprio 1
	global_load_lds_dwordx4 v[194:195], off
	s_barrier
	s_waitcnt lgkmcnt(3)
	v_mfma_f32_16x16x32_bf16 v[132:135], v[202:205], v[160:163], v[132:135]
	s_waitcnt lgkmcnt(1)
	v_mfma_f32_16x16x32_bf16 v[128:131], v[210:213], v[160:163], v[128:131]
	v_mfma_f32_16x16x32_bf16 v[116:119], v[202:205], v[174:177], v[116:119]
	v_mfma_f32_16x16x32_bf16 v[112:115], v[210:213], v[174:177], v[112:115]
	v_mfma_f32_16x16x32_bf16 v[100:103], v[202:205], v[182:185], v[100:103]
	v_mfma_f32_16x16x32_bf16 v[96:99], v[210:213], v[182:185], v[96:99]
	v_mfma_f32_16x16x32_bf16 v[68:71], v[202:205], v[190:193], v[68:71]
	v_mfma_f32_16x16x32_bf16 v[64:67], v[210:213], v[190:193], v[64:67]
	v_mfma_f32_16x16x32_bf16 v[132:135], v[206:209], v[170:173], v[132:135]
	s_mov_b32 m0, s39
	s_waitcnt lgkmcnt(0)
	v_mfma_f32_16x16x32_bf16 v[128:131], v[214:217], v[170:173], v[128:131]
	v_lshl_add_u64 v[194:195], v[220:221], 0, s[12:13]
	v_mfma_f32_16x16x32_bf16 v[116:119], v[206:209], v[178:181], v[116:119]
	v_mfma_f32_16x16x32_bf16 v[112:115], v[214:217], v[178:181], v[112:115]
	v_mfma_f32_16x16x32_bf16 v[100:103], v[206:209], v[186:189], v[100:103]
	v_mfma_f32_16x16x32_bf16 v[96:99], v[214:217], v[186:189], v[96:99]
	v_mfma_f32_16x16x32_bf16 v[68:71], v[206:209], v[198:201], v[68:71]
	v_mfma_f32_16x16x32_bf16 v[64:67], v[214:217], v[198:201], v[64:67]
	s_barrier
; #define PG8_WAIT_V(n) asm volatile("s_waitcnt vmcnt(" #n ")" ::: "memory")
; #define PG8_WAIT_L(n) asm volatile("s_waitcnt lgkmcnt(" #n ")" ::: "memory")
; #define PG8_BAR __builtin_amdgcn_s_barrier()
;     DI void operator()(const f32x4 (&acc)[2][2][4][2], const Unit& u, int wr, int wc, int fr, int fq) const {
;         const int row0 = u.pm * BM + wr * 64 + fr, col0 = u.pn * BM + wc * 32 + 8 * fq;
;         f32x4 sc[2][2];
; #pragma unroll
;         for (int bj = 0; bj < 2; ++bj)
; #pragma unroll
;             for (int n = 0; n < 2; ++n) sc[bj][n] = scale ? *(const f32x4*)(scale + col0 + bj * HALF + 4 * n) : (f32x4){1.f, 1.f, 1.f, 1.f};
; template <class Map, class Epi>
; DI void gemm_phase(LAS unsigned char* lds, const Map& MP, const Epi& E, const int nM, const int nN, const int K, const int lda, const int ldb) {
;     ...
;             const bool last = (t == nt - 2);
;             const char* a1 = cA + (size_t)(t + 1) * kstep;
;             const char* a2 = last ? nA : cA + (size_t)(t + 2) * kstep; const char* b2 = last ? nB : cB + (size_t)(t + 2) * kstep;
;             const char* a3 = a2 + kstep; const char* b3 = b2 + kstep;
;             PG8_LDB(B0, 0, 0); PG8_SCHED; PG8_LDA(At, 0, 0); PG8_STAGE(PG8_SA(1, 1), a1 + hstepA, voffA);
;             PG8_WAIT_L(8); PG8_BAR; PG8_WAIT_L(0); PG8_MMA(0, 0, At, B0); PG8_BAR; PG8_SCHED;
;             PG8_LDB(B1, 0, 1); PG8_STAGE(PG8_SB(0, 0), b2, voffB);
;             PG8_BAR; PG8_WAIT_L(0); PG8_MMA(0, 1, At, B1); PG8_BAR;
;             PG8_LDA(At, 0, 1); PG8_STAGE(PG8_SA(0, 0), a2, voffA);
;             PG8_BAR; PG8_WAIT_L(0); PG8_MMA(1, 0, At, B0); PG8_BAR; PG8_SCHED;
;             PG8_STAGE(PG8_SB(0, 1), b2 + hstepB, voffB);
;             PG8_WAIT_V(6); PG8_BAR; PG8_MMA(1, 1, At, B1); PG8_BAR;
;             PG8_LDB(B0, 1, 0); PG8_SCHED; PG8_LDA(At, 1, 0); PG8_STAGE(PG8_SA(0, 1), a2 + hstepA, voffA);
;             PG8_WAIT_L(8); PG8_BAR; PG8_WAIT_L(0); PG8_MMA(0, 0, At, B0); PG8_BAR; PG8_SCHED;
;             PG8_LDB(B1, 1, 1); PG8_STAGE(PG8_SB(1, 0), b3, voffB);
;             PG8_BAR; PG8_WAIT_L(0); PG8_MMA(0, 1, At, B1); PG8_BAR;
;             PG8_LDA(At, 1, 1); PG8_STAGE(PG8_SA(1, 0), a3, voffA);
;             PG8_BAR; PG8_WAIT_L(0); PG8_MMA(1, 0, At, B0); PG8_BAR; PG8_SCHED;
;             PG8_STAGE(PG8_SB(1, 1), b3 + hstepB, voffB);
;             PG8_WAIT_V(6); PG8_BAR; PG8_MMA(1, 1, At, B1); PG8_BAR;
	s_setprio 0
	ds_read_b128 v[160:163], v168 offset:49152
	ds_read_b128 v[170:173], v168 offset:50176
	ds_read_b128 v[174:177], v168 offset:51200
	ds_read_b128 v[178:181], v168 offset:52224
	ds_read_b128 v[182:185], v168 offset:53248
	ds_read_b128 v[186:189], v168 offset:54272
	ds_read_b128 v[190:193], v168 offset:55296
	ds_read_b128 v[198:201], v168 offset:56320
	global_load_lds_dwordx4 v[194:195], off
	v_lshl_add_u64 v[194:195], v[222:223], 0, s[12:13]
	s_mov_b32 m0, s46
	s_setprio 1
	global_load_lds_dwordx4 v[194:195], off
	s_waitcnt vmcnt(10)
	s_barrier
	s_waitcnt lgkmcnt(7)
	v_mfma_f32_16x16x32_bf16 v[60:63], v[72:75], v[160:163], v[60:63]
	v_mfma_f32_16x16x32_bf16 v[56:59], v[80:83], v[160:163], v[56:59]
	s_waitcnt lgkmcnt(5)
	v_mfma_f32_16x16x32_bf16 v[44:47], v[72:75], v[174:177], v[44:47]
	v_mfma_f32_16x16x32_bf16 v[40:43], v[80:83], v[174:177], v[40:43]
	s_waitcnt lgkmcnt(3)
	v_mfma_f32_16x16x32_bf16 v[28:31], v[72:75], v[182:185], v[28:31]
	v_mfma_f32_16x16x32_bf16 v[24:27], v[80:83], v[182:185], v[24:27]
	s_waitcnt lgkmcnt(1)
	v_mfma_f32_16x16x32_bf16 v[12:15], v[72:75], v[190:193], v[12:15]
	v_mfma_f32_16x16x32_bf16 v[8:11], v[80:83], v[190:193], v[8:11]
	v_mfma_f32_16x16x32_bf16 v[60:63], v[76:79], v[170:173], v[60:63]
	s_add_u32 s26, s26, 0x20080
	s_addc_u32 s27, s27, 0
	v_mfma_f32_16x16x32_bf16 v[56:59], v[84:87], v[170:173], v[56:59]
	s_add_i32 s28, s28, s34
	v_mfma_f32_16x16x32_bf16 v[44:47], v[76:79], v[178:181], v[44:47]
	v_mfma_f32_16x16x32_bf16 v[40:43], v[84:87], v[178:181], v[40:43]
	v_mfma_f32_16x16x32_bf16 v[28:31], v[76:79], v[186:189], v[28:31]
	v_mfma_f32_16x16x32_bf16 v[24:27], v[84:87], v[186:189], v[24:27]
	s_waitcnt lgkmcnt(0)
	v_mfma_f32_16x16x32_bf16 v[12:15], v[76:79], v[198:201], v[12:15]
	v_mfma_f32_16x16x32_bf16 v[8:11], v[84:87], v[198:201], v[8:11]
	s_barrier
	s_setprio 0
	s_mov_b32 m0, s28
	s_nop 0
	global_load_lds_dwordx4 v148, s[26:27]
	s_add_i32 m0, s28, 0x2000
	s_setprio 1
	global_load_lds_dwordx4 v144, s[26:27]
	s_waitcnt vmcnt(6)
	s_barrier
	v_mfma_f32_16x16x32_bf16 v[52:55], v[202:205], v[160:163], v[52:55]
	v_mfma_f32_16x16x32_bf16 v[48:51], v[210:213], v[160:163], v[48:51]
	ds_read_b128 v[72:75], v167
	v_mfma_f32_16x16x32_bf16 v[36:39], v[202:205], v[174:177], v[36:39]
	v_mfma_f32_16x16x32_bf16 v[32:35], v[210:213], v[174:177], v[32:35]
	ds_read_b128 v[76:79], v167 offset:1024
	v_mfma_f32_16x16x32_bf16 v[20:23], v[202:205], v[182:185], v[20:23]
	v_mfma_f32_16x16x32_bf16 v[16:19], v[210:213], v[182:185], v[16:19]
	ds_read_b128 v[80:83], v167 offset:2048
	v_mfma_f32_16x16x32_bf16 v[4:7], v[202:205], v[190:193], v[4:7]
	v_mfma_f32_16x16x32_bf16 v[0:3], v[210:213], v[190:193], v[0:3]
	ds_read_b128 v[84:87], v167 offset:3072
	v_mfma_f32_16x16x32_bf16 v[52:55], v[206:209], v[170:173], v[52:55]
	s_add_i32 s57, s57, 2
	v_mfma_f32_16x16x32_bf16 v[48:51], v[214:217], v[170:173], v[48:51]
	s_add_u32 s55, s55, 0x100
	s_addc_u32 s56, s56, 0
	v_mfma_f32_16x16x32_bf16 v[36:39], v[206:209], v[178:181], v[36:39]
	s_add_u32 s24, s24, 0x100
	s_addc_u32 s25, s25, 0
	v_mfma_f32_16x16x32_bf16 v[32:35], v[214:217], v[178:181], v[32:35]
	s_add_u32 s26, s24, 0xfff80080
	s_addc_u32 s27, s25, -1
	s_cmp_eq_u32 s57, 4
	s_cselect_b32 s29, s17, s27
	s_cselect_b32 s28, s43, s26
	s_cselect_b32 s27, s53, s56
	s_cselect_b32 s26, s54, s55
	s_cmp_gt_u32 s57, 5
	v_mfma_f32_16x16x32_bf16 v[20:23], v[206:209], v[186:189], v[20:23]
	v_mfma_f32_16x16x32_bf16 v[16:19], v[214:217], v[186:189], v[16:19]
	v_mfma_f32_16x16x32_bf16 v[4:7], v[206:209], v[198:201], v[4:7]
	v_mfma_f32_16x16x32_bf16 v[0:3], v[214:217], v[198:201], v[0:3]
	s_barrier
	s_setprio 0
	s_cbranch_scc0 .LBB1_229
	s_waitcnt lgkmcnt(0)
	s_lshl_b32 s17, s42, 8
	v_mov_b32_e32 v170, v164
	v_mov_b32_e32 v72, v165
	s_or_b32 s17, s17, s38
	v_mov_b32_e32 v80, 1.0
	v_lshl_add_u32 v160, v72, 3, s17
	v_ashrrev_i32_e32 v161, 31, v160
	v_cndmask_b32_e64 v72, 0, 1, s[14:15]
	v_lshl_add_u64 v[162:163], v[160:161], 2, s[8:9]
	v_cmp_ne_u32_e64 s[42:43], 1, v72
	s_andn2_b64 vcc, exec, s[14:15]
	v_mov_b32_e32 v84, 1.0
	v_mov_b32_e32 v85, 1.0
	v_mov_b32_e32 v86, 1.0
	v_mov_b32_e32 v87, 1.0
	s_cbranch_vccnz .LBB1_232
	global_load_dwordx4 v[84:87], v[162:163], off

; #define PG8_STAGE(bufoff, gbase, voff) do { _Pragma("unroll") for (int _i = 0; _i < 2; ++_i) \
;         __builtin_amdgcn_global_load_lds((const unsigned*)((const char*)(gbase) + (voff)[_i]), (LAS unsigned*)(lds + (bufoff) + ldsw + _i * 8192), 16, 0, 0); } while (0)
; #define PG8_LDA(dst, b, h) do { _Pragma("unroll") for (int m = 0; m < 4; ++m) _Pragma("unroll") for (int k = 0; k < 2; ++k) dst[m][k] = *(const LAS bf16x8*)(lds + PG8_SA(b, h) + aoff + m * 2048 + k * 1024); } while (0)
; #define PG8_LDB(dst, b, h) do { _Pragma("unroll") for (int n = 0; n < 2; ++n) _Pragma("unroll") for (int k = 0; k < 2; ++k) dst[n][k] = *(const LAS bf16x8*)(lds + PG8_SB(b, h) + boff + n * 2048 + k * 1024); } while (0)
; #define PG8_MMA(ai, bj, At, Bt) do { __builtin_amdgcn_s_setprio(1); _Pragma("unroll") for (int m = 0; m < 4; ++m) _Pragma("unroll") for (int n = 0; n < 2; ++n) _Pragma("unroll") for (int k = 0; k < 2; ++k) \
;         acc[ai][bj][m][n] = __builtin_amdgcn_mfma_f32_16x16x32_bf16(Bt[n][k], At[m][k], acc[ai][bj][m][n], 0, 0, 0); __builtin_amdgcn_s_setprio(0); } while (0)
; #define PG8_WAIT_V(n) asm volatile("s_waitcnt vmcnt(" #n ")" ::: "memory")
; #define PG8_WAIT_L(n) asm volatile("s_waitcnt lgkmcnt(" #n ")" ::: "memory")
; template <class Map, class Epi>
; DI void gemm_phase(LAS unsigned char* lds, const Map& MP, const Epi& E, const int nM, const int nN, const int K, const int lda, const int ldb) {
;     ...
;         for (int t = 0; t < nt; t += 2) {
;             const bool last = (t == nt - 2);
;             const char* a1 = cA + (size_t)(t + 1) * kstep;
;             const char* a2 = last ? nA : cA + (size_t)(t + 2) * kstep; const char* b2 = last ? nB : cB + (size_t)(t + 2) * kstep;
;             const char* a3 = a2 + kstep; const char* b3 = b2 + kstep;
;             PG8_LDB(B0, 0, 0); PG8_SCHED; PG8_LDA(At, 0, 0); PG8_STAGE(PG8_SA(1, 1), a1 + hstepA, voffA);
;             PG8_WAIT_L(8); PG8_BAR; PG8_WAIT_L(0); PG8_MMA(0, 0, At, B0); PG8_BAR; PG8_SCHED;
;             PG8_LDB(B1, 0, 1); PG8_STAGE(PG8_SB(0, 0), b2, voffB);
;             PG8_BAR; PG8_WAIT_L(0); PG8_MMA(0, 1, At, B1); PG8_BAR;
;             PG8_LDA(At, 0, 1); PG8_STAGE(PG8_SA(0, 0), a2, voffA);
;             PG8_BAR; PG8_WAIT_L(0); PG8_MMA(1, 0, At, B0); PG8_BAR; PG8_SCHED;
;             PG8_STAGE(PG8_SB(0, 1), b2 + hstepB, voffB);
;             PG8_WAIT_V(6); PG8_BAR; PG8_MMA(1, 1, At, B1); PG8_BAR;
.LBB1_693:
	s_add_i32 m0, s31, 0xc000
	ds_read_b128 v[166:169], v148
	ds_read_b128 v[170:173], v148 offset:1024
	ds_read_b128 v[174:177], v148 offset:2048
	ds_read_b128 v[178:181], v148 offset:3072
	ds_read_b128 v[182:185], v148 offset:4096
	ds_read_b128 v[186:189], v148 offset:5120
	ds_read_b128 v[190:193], v148 offset:6144
	ds_read_b128 v[198:201], v148 offset:7168
	global_load_lds_dwordx4 v138, s[20:21]
	s_add_i32 m0, s31, 0xe000
	s_setprio 1
	global_load_lds_dwordx4 v136, s[20:21]
	s_waitcnt lgkmcnt(8)
	s_barrier
	s_waitcnt lgkmcnt(7)
	v_mfma_f32_16x16x32_bf16 v[124:127], v[150:153], v[166:169], v[124:127]
	v_mfma_f32_16x16x32_bf16 v[120:123], v[158:161], v[166:169], v[120:123]
	s_waitcnt lgkmcnt(5)
	v_mfma_f32_16x16x32_bf16 v[116:119], v[150:153], v[174:177], v[116:119]
	v_mfma_f32_16x16x32_bf16 v[112:115], v[158:161], v[174:177], v[112:115]
	s_waitcnt lgkmcnt(3)
	v_mfma_f32_16x16x32_bf16 v[100:103], v[150:153], v[182:185], v[100:103]
	v_mfma_f32_16x16x32_bf16 v[96:99], v[158:161], v[182:185], v[96:99]
	s_waitcnt lgkmcnt(1)
	v_mfma_f32_16x16x32_bf16 v[84:87], v[150:153], v[190:193], v[84:87]
	v_mfma_f32_16x16x32_bf16 v[80:83], v[158:161], v[190:193], v[80:83]
	v_mfma_f32_16x16x32_bf16 v[124:127], v[154:157], v[170:173], v[124:127]
	s_add_i32 s3, s44, s29
	v_mfma_f32_16x16x32_bf16 v[120:123], v[162:165], v[170:173], v[120:123]
	v_lshl_add_u64 v[194:195], s[22:23], 0, v[132:133]
	v_mfma_f32_16x16x32_bf16 v[116:119], v[154:157], v[178:181], v[116:119]
	v_lshl_add_u64 v[218:219], s[22:23], 0, v[128:129]
	v_mfma_f32_16x16x32_bf16 v[112:115], v[162:165], v[178:181], v[112:115]
	v_mfma_f32_16x16x32_bf16 v[100:103], v[154:157], v[186:189], v[100:103]
	v_mfma_f32_16x16x32_bf16 v[96:99], v[162:165], v[186:189], v[96:99]
	s_waitcnt lgkmcnt(0)
	v_mfma_f32_16x16x32_bf16 v[84:87], v[154:157], v[198:201], v[84:87]
	v_mfma_f32_16x16x32_bf16 v[80:83], v[162:165], v[198:201], v[80:83]
	s_barrier
	s_setprio 0
	s_mov_b32 m0, s3
	ds_read_b128 v[202:205], v149
	ds_read_b128 v[206:209], v149 offset:1024
	ds_read_b128 v[210:213], v149 offset:2048
	ds_read_b128 v[214:217], v149 offset:3072
	global_load_lds_dwordx4 v[194:195], off
	s_add_i32 m0, s3, 0x2000
	s_setprio 1
	global_load_lds_dwordx4 v[218:219], off
	s_barrier
	s_waitcnt lgkmcnt(3)
	v_mfma_f32_16x16x32_bf16 v[108:111], v[202:205], v[166:169], v[108:111]
	s_waitcnt lgkmcnt(1)
	v_mfma_f32_16x16x32_bf16 v[104:107], v[210:213], v[166:169], v[104:107]
	v_mfma_f32_16x16x32_bf16 v[92:95], v[202:205], v[174:177], v[92:95]
	v_mfma_f32_16x16x32_bf16 v[88:91], v[210:213], v[174:177], v[88:91]
	v_mfma_f32_16x16x32_bf16 v[76:79], v[202:205], v[182:185], v[76:79]
	v_mfma_f32_16x16x32_bf16 v[72:75], v[210:213], v[182:185], v[72:75]
	v_mfma_f32_16x16x32_bf16 v[68:71], v[202:205], v[190:193], v[68:71]
	v_mfma_f32_16x16x32_bf16 v[64:67], v[210:213], v[190:193], v[64:67]
	v_mfma_f32_16x16x32_bf16 v[108:111], v[206:209], v[170:173], v[108:111]
	v_lshl_add_u64 v[222:223], s[24:25], 0, v[130:131]
	s_mov_b32 m0, s31
	s_waitcnt lgkmcnt(0)
	v_mfma_f32_16x16x32_bf16 v[104:107], v[214:217], v[170:173], v[104:107]
	v_lshl_add_u64 v[220:221], s[24:25], 0, v[134:135]
	v_mfma_f32_16x16x32_bf16 v[92:95], v[206:209], v[178:181], v[92:95]
	v_mfma_f32_16x16x32_bf16 v[88:91], v[214:217], v[178:181], v[88:91]
	v_mfma_f32_16x16x32_bf16 v[76:79], v[206:209], v[186:189], v[76:79]
	v_mfma_f32_16x16x32_bf16 v[72:75], v[214:217], v[186:189], v[72:75]
	v_mfma_f32_16x16x32_bf16 v[68:71], v[206:209], v[198:201], v[68:71]
	v_mfma_f32_16x16x32_bf16 v[64:67], v[214:217], v[198:201], v[64:67]
	s_barrier
	s_setprio 0
	ds_read_b128 v[166:169], v148 offset:16384
	ds_read_b128 v[170:173], v148 offset:17408
	ds_read_b128 v[174:177], v148 offset:18432
	ds_read_b128 v[178:181], v148 offset:19456
	ds_read_b128 v[182:185], v148 offset:20480
	ds_read_b128 v[186:189], v148 offset:21504
	ds_read_b128 v[190:193], v148 offset:22528
	ds_read_b128 v[198:201], v148 offset:23552
	global_load_lds_dwordx4 v[220:221], off
	s_mov_b32 m0, s11
	s_setprio 1
	global_load_lds_dwordx4 v[222:223], off
	s_waitcnt vmcnt(10)
	s_barrier
	s_waitcnt lgkmcnt(7)
	v_mfma_f32_16x16x32_bf16 v[60:63], v[150:153], v[166:169], v[60:63]
	v_mfma_f32_16x16x32_bf16 v[56:59], v[158:161], v[166:169], v[56:59]
	s_waitcnt lgkmcnt(5)
	v_mfma_f32_16x16x32_bf16 v[52:55], v[150:153], v[174:177], v[52:55]
	v_mfma_f32_16x16x32_bf16 v[48:51], v[158:161], v[174:177], v[48:51]
	s_waitcnt lgkmcnt(3)
	v_mfma_f32_16x16x32_bf16 v[36:39], v[150:153], v[182:185], v[36:39]
	v_mfma_f32_16x16x32_bf16 v[32:35], v[158:161], v[182:185], v[32:35]
	s_waitcnt lgkmcnt(1)
	v_mfma_f32_16x16x32_bf16 v[20:23], v[150:153], v[190:193], v[20:23]
	v_mfma_f32_16x16x32_bf16 v[16:19], v[158:161], v[190:193], v[16:19]
	v_mfma_f32_16x16x32_bf16 v[60:63], v[154:157], v[170:173], v[60:63]
	s_add_u32 s56, s22, 0x80000
	s_addc_u32 s57, s23, 0
	v_mfma_f32_16x16x32_bf16 v[56:59], v[162:165], v[170:173], v[56:59]
	s_add_i32 s3, s45, s29
	v_mfma_f32_16x16x32_bf16 v[52:55], v[154:157], v[178:181], v[52:55]
	v_mfma_f32_16x16x32_bf16 v[48:51], v[162:165], v[178:181], v[48:51]
	v_mfma_f32_16x16x32_bf16 v[36:39], v[154:157], v[186:189], v[36:39]
	v_mfma_f32_16x16x32_bf16 v[32:35], v[162:165], v[186:189], v[32:35]
	s_waitcnt lgkmcnt(0)
	v_mfma_f32_16x16x32_bf16 v[20:23], v[154:157], v[198:201], v[20:23]
	v_mfma_f32_16x16x32_bf16 v[16:19], v[162:165], v[198:201], v[16:19]
	s_barrier
	s_setprio 0
	s_mov_b32 m0, s3
	s_nop 0
	global_load_lds_dwordx4 v132, s[56:57]
	s_add_i32 m0, s3, 0x2000
	s_setprio 1
	global_load_lds_dwordx4 v128, s[56:57]
	s_waitcnt vmcnt(6)
	s_barrier
; #define PG8_STAGE(bufoff, gbase, voff) do { _Pragma("unroll") for (int _i = 0; _i < 2; ++_i) \
;         __builtin_amdgcn_global_load_lds((const unsigned*)((const char*)(gbase) + (voff)[_i]), (LAS unsigned*)(lds + (bufoff) + ldsw + _i * 8192), 16, 0, 0); } while (0)
; #define PG8_LDA(dst, b, h) do { _Pragma("unroll") for (int m = 0; m < 4; ++m) _Pragma("unroll") for (int k = 0; k < 2; ++k) dst[m][k] = *(const LAS bf16x8*)(lds + PG8_SA(b, h) + aoff + m * 2048 + k * 1024); } while (0)
; #define PG8_LDB(dst, b, h) do { _Pragma("unroll") for (int n = 0; n < 2; ++n) _Pragma("unroll") for (int k = 0; k < 2; ++k) dst[n][k] = *(const LAS bf16x8*)(lds + PG8_SB(b, h) + boff + n * 2048 + k * 1024); } while (0)
; #define PG8_MMA(ai, bj, At, Bt) do { __builtin_amdgcn_s_setprio(1); _Pragma("unroll") for (int m = 0; m < 4; ++m) _Pragma("unroll") for (int n = 0; n < 2; ++n) _Pragma("unroll") for (int k = 0; k < 2; ++k) \
;         acc[ai][bj][m][n] = __builtin_amdgcn_mfma_f32_16x16x32_bf16(Bt[n][k], At[m][k], acc[ai][bj][m][n], 0, 0, 0); __builtin_amdgcn_s_setprio(0); } while (0)
; #define PG8_WAIT_V(n) asm volatile("s_waitcnt vmcnt(" #n ")" ::: "memory")
; #define PG8_WAIT_L(n) asm volatile("s_waitcnt lgkmcnt(" #n ")" ::: "memory")
; #define PG8_BAR __builtin_amdgcn_s_barrier()
; #define PG8_SCHED __builtin_amdgcn_sched_barrier(0)
; template <class Map, class Epi>
; DI void gemm_phase(LAS unsigned char* lds, const Map& MP, const Epi& E, const int nM, const int nN, const int K, const int lda, const int ldb) {
;     ...
;             PG8_BAR; PG8_WAIT_L(0); PG8_MMA(1, 0, At, B0); PG8_BAR; PG8_SCHED;
;             PG8_STAGE(PG8_SB(0, 1), b2 + hstepB, voffB);
;             PG8_WAIT_V(6); PG8_BAR; PG8_MMA(1, 1, At, B1); PG8_BAR;
;             PG8_LDB(B0, 1, 0); PG8_SCHED; PG8_LDA(At, 1, 0); PG8_STAGE(PG8_SA(0, 1), a2 + hstepA, voffA);
;             PG8_WAIT_L(8); PG8_BAR; PG8_WAIT_L(0); PG8_MMA(0, 0, At, B0); PG8_BAR; PG8_SCHED;
;             PG8_LDB(B1, 1, 1); PG8_STAGE(PG8_SB(1, 0), b3, voffB);
;             PG8_BAR; PG8_WAIT_L(0); PG8_MMA(0, 1, At, B1); PG8_BAR;
;             PG8_LDA(At, 1, 1); PG8_STAGE(PG8_SA(1, 0), a3, voffA);
;             PG8_BAR; PG8_WAIT_L(0); PG8_MMA(1, 0, At, B0); PG8_BAR; PG8_SCHED;
	v_mfma_f32_16x16x32_bf16 v[44:47], v[202:205], v[166:169], v[44:47]
	v_mfma_f32_16x16x32_bf16 v[40:43], v[210:213], v[166:169], v[40:43]
	s_add_i32 s3, 0, 0x18000
	v_add_u32_e32 v162, s3, v146
	ds_read_b128 v[150:153], v162
	v_mfma_f32_16x16x32_bf16 v[28:31], v[202:205], v[174:177], v[28:31]
	v_mfma_f32_16x16x32_bf16 v[24:27], v[210:213], v[174:177], v[24:27]
	ds_read_b128 v[154:157], v162 offset:1024
	v_mfma_f32_16x16x32_bf16 v[12:15], v[202:205], v[182:185], v[12:15]
	v_mfma_f32_16x16x32_bf16 v[8:11], v[210:213], v[182:185], v[8:11]
	ds_read_b128 v[158:161], v162 offset:2048
	v_mfma_f32_16x16x32_bf16 v[4:7], v[202:205], v[190:193], v[4:7]
	v_mfma_f32_16x16x32_bf16 v[0:3], v[210:213], v[190:193], v[0:3]
	ds_read_b128 v[162:165], v162 offset:3072
	v_mfma_f32_16x16x32_bf16 v[44:47], v[206:209], v[170:173], v[44:47]
	s_add_u32 s24, s24, 0x80000
	s_addc_u32 s25, s25, 0
	v_mfma_f32_16x16x32_bf16 v[40:43], v[214:217], v[170:173], v[40:43]
	v_mfma_f32_16x16x32_bf16 v[28:31], v[206:209], v[178:181], v[28:31]
	v_mfma_f32_16x16x32_bf16 v[24:27], v[214:217], v[178:181], v[24:27]
	v_mfma_f32_16x16x32_bf16 v[12:15], v[206:209], v[186:189], v[12:15]
	v_mfma_f32_16x16x32_bf16 v[8:11], v[214:217], v[186:189], v[8:11]
	v_mfma_f32_16x16x32_bf16 v[4:7], v[206:209], v[198:201], v[4:7]
	v_mfma_f32_16x16x32_bf16 v[0:3], v[214:217], v[198:201], v[0:3]
	s_barrier
	s_setprio 0
	s_mov_b32 m0, s34
	ds_read_b128 v[166:169], v148 offset:32768
	ds_read_b128 v[170:173], v148 offset:33792
	ds_read_b128 v[174:177], v148 offset:34816
	ds_read_b128 v[178:181], v148 offset:35840
	ds_read_b128 v[182:185], v148 offset:36864
	ds_read_b128 v[186:189], v148 offset:37888
	ds_read_b128 v[190:193], v148 offset:38912
	ds_read_b128 v[198:201], v148 offset:39936
	global_load_lds_dwordx4 v134, s[24:25]
	s_mov_b32 m0, s35
	s_setprio 1
	global_load_lds_dwordx4 v130, s[24:25]
	s_waitcnt lgkmcnt(8)
	s_barrier
	s_waitcnt lgkmcnt(7)
	v_mfma_f32_16x16x32_bf16 v[124:127], v[150:153], v[166:169], v[124:127]
	v_mfma_f32_16x16x32_bf16 v[120:123], v[158:161], v[166:169], v[120:123]
	s_waitcnt lgkmcnt(5)
	v_mfma_f32_16x16x32_bf16 v[116:119], v[150:153], v[174:177], v[116:119]
	v_mfma_f32_16x16x32_bf16 v[112:115], v[158:161], v[174:177], v[112:115]
	s_waitcnt lgkmcnt(3)
	v_mfma_f32_16x16x32_bf16 v[100:103], v[150:153], v[182:185], v[100:103]
	v_mfma_f32_16x16x32_bf16 v[96:99], v[158:161], v[182:185], v[96:99]
	s_waitcnt lgkmcnt(1)
	v_mfma_f32_16x16x32_bf16 v[84:87], v[150:153], v[190:193], v[84:87]
	v_mfma_f32_16x16x32_bf16 v[80:83], v[158:161], v[190:193], v[80:83]
	v_mfma_f32_16x16x32_bf16 v[124:127], v[154:157], v[170:173], v[124:127]
	s_add_i32 s24, 0, 0x1c000
	v_mfma_f32_16x16x32_bf16 v[120:123], v[162:165], v[170:173], v[120:123]
	s_add_i32 s3, s3, s29
	v_mfma_f32_16x16x32_bf16 v[116:119], v[154:157], v[178:181], v[116:119]
	v_add_u32_e32 v196, s24, v146
	v_mfma_f32_16x16x32_bf16 v[112:115], v[162:165], v[178:181], v[112:115]
	v_lshl_add_u64 v[194:195], v[194:195], 0, s[8:9]
	v_mfma_f32_16x16x32_bf16 v[100:103], v[154:157], v[186:189], v[100:103]
	v_mfma_f32_16x16x32_bf16 v[96:99], v[162:165], v[186:189], v[96:99]
	s_waitcnt lgkmcnt(0)
	v_mfma_f32_16x16x32_bf16 v[84:87], v[154:157], v[198:201], v[84:87]
	v_mfma_f32_16x16x32_bf16 v[80:83], v[162:165], v[198:201], v[80:83]
	s_barrier
	s_setprio 0
	s_mov_b32 m0, s3
	ds_read_b128 v[202:205], v196
	ds_read_b128 v[206:209], v196 offset:1024
	ds_read_b128 v[210:213], v196 offset:2048
	ds_read_b128 v[214:217], v196 offset:3072
	global_load_lds_dwordx4 v[194:195], off
	v_lshl_add_u64 v[194:195], v[218:219], 0, s[8:9]
	s_add_i32 m0, s3, 0x2000
	s_setprio 1
	global_load_lds_dwordx4 v[194:195], off
	s_barrier
	s_waitcnt lgkmcnt(3)
	v_mfma_f32_16x16x32_bf16 v[108:111], v[202:205], v[166:169], v[108:111]
	s_waitcnt lgkmcnt(1)
	v_mfma_f32_16x16x32_bf16 v[104:107], v[210:213], v[166:169], v[104:107]
	v_mfma_f32_16x16x32_bf16 v[92:95], v[202:205], v[174:177], v[92:95]
	v_mfma_f32_16x16x32_bf16 v[88:91], v[210:213], v[174:177], v[88:91]
	v_mfma_f32_16x16x32_bf16 v[76:79], v[202:205], v[182:185], v[76:79]
	v_mfma_f32_16x16x32_bf16 v[72:75], v[210:213], v[182:185], v[72:75]
	v_mfma_f32_16x16x32_bf16 v[68:71], v[202:205], v[190:193], v[68:71]
	v_mfma_f32_16x16x32_bf16 v[64:67], v[210:213], v[190:193], v[64:67]
	v_mfma_f32_16x16x32_bf16 v[108:111], v[206:209], v[170:173], v[108:111]
	s_mov_b32 m0, s39
	s_waitcnt lgkmcnt(0)
	v_mfma_f32_16x16x32_bf16 v[104:107], v[214:217], v[170:173], v[104:107]
	v_lshl_add_u64 v[194:195], v[220:221], 0, s[8:9]
	v_mfma_f32_16x16x32_bf16 v[92:95], v[206:209], v[178:181], v[92:95]
	v_mfma_f32_16x16x32_bf16 v[88:91], v[214:217], v[178:181], v[88:91]
	v_mfma_f32_16x16x32_bf16 v[76:79], v[206:209], v[186:189], v[76:79]
	v_mfma_f32_16x16x32_bf16 v[72:75], v[214:217], v[186:189], v[72:75]
	v_mfma_f32_16x16x32_bf16 v[68:71], v[206:209], v[198:201], v[68:71]
	v_mfma_f32_16x16x32_bf16 v[64:67], v[214:217], v[198:201], v[64:67]
	s_barrier
	s_setprio 0
	ds_read_b128 v[166:169], v148 offset:49152
	ds_read_b128 v[170:173], v148 offset:50176
	ds_read_b128 v[174:177], v148 offset:51200
	ds_read_b128 v[178:181], v148 offset:52224
	ds_read_b128 v[182:185], v148 offset:53248
	ds_read_b128 v[186:189], v148 offset:54272
	ds_read_b128 v[190:193], v148 offset:55296
	ds_read_b128 v[198:201], v148 offset:56320
	global_load_lds_dwordx4 v[194:195], off
	v_lshl_add_u64 v[194:195], v[222:223], 0, s[8:9]
	s_mov_b32 m0, s42
	s_setprio 1
	global_load_lds_dwordx4 v[194:195], off
	s_waitcnt vmcnt(10)
	s_barrier
; #define PG8_STAGE(bufoff, gbase, voff) do { _Pragma("unroll") for (int _i = 0; _i < 2; ++_i) \
;         __builtin_amdgcn_global_load_lds((const unsigned*)((const char*)(gbase) + (voff)[_i]), (LAS unsigned*)(lds + (bufoff) + ldsw + _i * 8192), 16, 0, 0); } while (0)
; #define PG8_LDA(dst, b, h) do { _Pragma("unroll") for (int m = 0; m < 4; ++m) _Pragma("unroll") for (int k = 0; k < 2; ++k) dst[m][k] = *(const LAS bf16x8*)(lds + PG8_SA(b, h) + aoff + m * 2048 + k * 1024); } while (0)
; #define PG8_WAIT_V(n) asm volatile("s_waitcnt vmcnt(" #n ")" ::: "memory")
; #define PG8_WAIT_L(n) asm volatile("s_waitcnt lgkmcnt(" #n ")" ::: "memory")
; template <class Map, class Epi>
; DI void gemm_phase(LAS unsigned char* lds, const Map& MP, const Epi& E, const int nM, const int nN, const int K, const int lda, const int ldb) {
;     ...
;             const bool last = (t == nt - 2);
;             const char* a1 = cA + (size_t)(t + 1) * kstep;
;             const char* a2 = last ? nA : cA + (size_t)(t + 2) * kstep; const char* b2 = last ? nB : cB + (size_t)(t + 2) * kstep;
;             const char* a3 = a2 + kstep; const char* b3 = b2 + kstep;
;             PG8_LDB(B0, 0, 0); PG8_SCHED; PG8_LDA(At, 0, 0); PG8_STAGE(PG8_SA(1, 1), a1 + hstepA, voffA);
;             PG8_WAIT_L(8); PG8_BAR; PG8_WAIT_L(0); PG8_MMA(0, 0, At, B0); PG8_BAR; PG8_SCHED;
;             PG8_LDB(B1, 0, 1); PG8_STAGE(PG8_SB(0, 0), b2, voffB);
;             PG8_BAR; PG8_WAIT_L(0); PG8_MMA(0, 1, At, B1); PG8_BAR;
;             PG8_LDA(At, 0, 1); PG8_STAGE(PG8_SA(0, 0), a2, voffA);
;             PG8_BAR; PG8_WAIT_L(0); PG8_MMA(1, 0, At, B0); PG8_BAR; PG8_SCHED;
;             PG8_STAGE(PG8_SB(0, 1), b2 + hstepB, voffB);
;             PG8_WAIT_V(6); PG8_BAR; PG8_MMA(1, 1, At, B1); PG8_BAR;
;             PG8_LDB(B0, 1, 0); PG8_SCHED; PG8_LDA(At, 1, 0); PG8_STAGE(PG8_SA(0, 1), a2 + hstepA, voffA);
;             PG8_WAIT_L(8); PG8_BAR; PG8_WAIT_L(0); PG8_MMA(0, 0, At, B0); PG8_BAR; PG8_SCHED;
;             PG8_LDB(B1, 1, 1); PG8_STAGE(PG8_SB(1, 0), b3, voffB);
;             PG8_BAR; PG8_WAIT_L(0); PG8_MMA(0, 1, At, B1); PG8_BAR;
;             PG8_LDA(At, 1, 1); PG8_STAGE(PG8_SA(1, 0), a3, voffA);
;             PG8_BAR; PG8_WAIT_L(0); PG8_MMA(1, 0, At, B0); PG8_BAR; PG8_SCHED;
;             PG8_STAGE(PG8_SB(1, 1), b3 + hstepB, voffB);
;             PG8_WAIT_V(6); PG8_BAR; PG8_MMA(1, 1, At, B1); PG8_BAR;
	s_waitcnt lgkmcnt(7)
	v_mfma_f32_16x16x32_bf16 v[60:63], v[150:153], v[166:169], v[60:63]
	v_mfma_f32_16x16x32_bf16 v[56:59], v[158:161], v[166:169], v[56:59]
	s_waitcnt lgkmcnt(5)
	v_mfma_f32_16x16x32_bf16 v[52:55], v[150:153], v[174:177], v[52:55]
	v_mfma_f32_16x16x32_bf16 v[48:51], v[158:161], v[174:177], v[48:51]
	s_waitcnt lgkmcnt(3)
	v_mfma_f32_16x16x32_bf16 v[36:39], v[150:153], v[182:185], v[36:39]
	v_mfma_f32_16x16x32_bf16 v[32:35], v[158:161], v[182:185], v[32:35]
	s_waitcnt lgkmcnt(1)
	v_mfma_f32_16x16x32_bf16 v[20:23], v[150:153], v[190:193], v[20:23]
	v_mfma_f32_16x16x32_bf16 v[16:19], v[158:161], v[190:193], v[16:19]
	v_mfma_f32_16x16x32_bf16 v[60:63], v[154:157], v[170:173], v[60:63]
	s_add_u32 s22, s22, 0x80080
	s_addc_u32 s23, s23, 0
	v_mfma_f32_16x16x32_bf16 v[56:59], v[162:165], v[170:173], v[56:59]
	s_add_i32 s3, s24, s29
	v_mfma_f32_16x16x32_bf16 v[52:55], v[154:157], v[178:181], v[52:55]
	v_mfma_f32_16x16x32_bf16 v[48:51], v[162:165], v[178:181], v[48:51]
	v_mfma_f32_16x16x32_bf16 v[36:39], v[154:157], v[186:189], v[36:39]
	v_mfma_f32_16x16x32_bf16 v[32:35], v[162:165], v[186:189], v[32:35]
	s_waitcnt lgkmcnt(0)
	v_mfma_f32_16x16x32_bf16 v[20:23], v[154:157], v[198:201], v[20:23]
	v_mfma_f32_16x16x32_bf16 v[16:19], v[162:165], v[198:201], v[16:19]
	s_barrier
	s_setprio 0
	s_mov_b32 m0, s3
	s_nop 0
	global_load_lds_dwordx4 v132, s[22:23]
	s_add_i32 m0, s3, 0x2000
	s_setprio 1
	global_load_lds_dwordx4 v128, s[22:23]
	s_waitcnt vmcnt(6)
	s_barrier
	v_mfma_f32_16x16x32_bf16 v[44:47], v[202:205], v[166:169], v[44:47]
	v_mfma_f32_16x16x32_bf16 v[40:43], v[210:213], v[166:169], v[40:43]
	ds_read_b128 v[150:153], v147
	v_mfma_f32_16x16x32_bf16 v[28:31], v[202:205], v[174:177], v[28:31]
	v_mfma_f32_16x16x32_bf16 v[24:27], v[210:213], v[174:177], v[24:27]
	ds_read_b128 v[154:157], v147 offset:1024
	v_mfma_f32_16x16x32_bf16 v[12:15], v[202:205], v[182:185], v[12:15]
	v_mfma_f32_16x16x32_bf16 v[8:11], v[210:213], v[182:185], v[8:11]
	ds_read_b128 v[158:161], v147 offset:2048
	v_mfma_f32_16x16x32_bf16 v[4:7], v[202:205], v[190:193], v[4:7]
	v_mfma_f32_16x16x32_bf16 v[0:3], v[210:213], v[190:193], v[0:3]
	ds_read_b128 v[162:165], v147 offset:3072
	v_mfma_f32_16x16x32_bf16 v[44:47], v[206:209], v[170:173], v[44:47]
	s_add_i32 s54, s54, 2
	v_mfma_f32_16x16x32_bf16 v[40:43], v[214:217], v[170:173], v[40:43]
	s_add_u32 s52, s52, 0x100
	s_addc_u32 s53, s53, 0
	v_mfma_f32_16x16x32_bf16 v[28:31], v[206:209], v[178:181], v[28:31]
	s_add_u32 s20, s20, 0x100
	s_addc_u32 s21, s21, 0
	v_mfma_f32_16x16x32_bf16 v[24:27], v[214:217], v[178:181], v[24:27]
	s_add_u32 s3, s20, 0xfff80080
	s_addc_u32 s22, s21, -1
	s_cmp_eq_u32 s54, 28
	s_cselect_b32 s25, s15, s22
	s_cselect_b32 s24, s48, s3
	s_cselect_b32 s23, s13, s53
	s_cselect_b32 s22, s49, s52
	s_cmp_gt_u32 s54, 29
	v_mfma_f32_16x16x32_bf16 v[12:15], v[206:209], v[186:189], v[12:15]
	v_mfma_f32_16x16x32_bf16 v[8:11], v[214:217], v[186:189], v[8:11]
	v_mfma_f32_16x16x32_bf16 v[4:7], v[206:209], v[198:201], v[4:7]
	v_mfma_f32_16x16x32_bf16 v[0:3], v[214:217], v[198:201], v[0:3]
	s_barrier
	s_setprio 0
	s_cbranch_scc0 .LBB1_693
; DI unsigned pack2(float a, float b) { f32x2 v = {a, b}; hwbf16x2 r = __builtin_convertvector(v, hwbf16x2); return __builtin_bit_cast(unsigned, r); }
;     DI const char* a(const Unit& u) const { return (const char*)(A + (size_t)u.pm * BM * lda); }
;     DI const char* a(const Unit& u) const { return (const char*)(A + (size_t)u.pm * BM * 2048 + (u.pn >> 1) * 512); }
;     DI const char* a(const Unit& u) const { return (const char*)((u.pn < 12 ? A1 : A2) + (size_t)u.pm * BM * 512); }
; #define PG8_WAIT_V(n) asm volatile("s_waitcnt vmcnt(" #n ")" ::: "memory")
; #define PG8_BAR __builtin_amdgcn_s_barrier()
;     DI void operator()(const f32x4 (&acc)[2][2][4][2], const Unit& u, int wr, int wc, int fr, int fq) const {
;         bf16_t* O = O1; int ldc = ldc1, pn = u.pn; if (pn >= split) { O = O2; ldc = ldc2; pn -= split; }
;         const int row0 = u.pm * BM + wr * 64 + fr, col0 = pn * BM + wc * 32 + 8 * fq;
; #pragma unroll
;         for (int ai = 0; ai < 2; ++ai)
; #pragma unroll
;             for (int m = 0; m < 4; ++m) { bf16_t* rowp = O + (size_t)(row0 + ai * HALF + m * 16) * ldc + col0;
; #pragma unroll
;                 for (int bj = 0; bj < 2; ++bj) { const f32x4 v0 = acc[ai][bj][m][0], v1 = acc[ai][bj][m][1];
;                     u32x4 o; o[0] = pack2(v0[0], v0[1]); o[1] = pack2(v0[2], v0[3]); o[2] = pack2(v1[0], v1[1]); o[3] = pack2(v1[2], v1[3]);
;                     *(u32x4*)(rowp + bj * HALF) = o; } }
; template <class Map, class Epi>
; DI void gemm_phase(LAS unsigned char* lds, const Map& MP, const Epi& E, const int nM, const int nN, const int K, const int lda, const int ldb) {
;     ...
;         if (!has_next) break;
; #pragma unroll
;         for (int a = 0; a < 2; ++a)
; #pragma unroll
;             for (int b = 0; b < 2; ++b)
; #pragma unroll
;                 for (int m = 0; m < 4; ++m)
; #pragma unroll
;                     for (int n = 0; n < 2; ++n) acc[a][b][m][n] = (f32x4){0.f, 0.f, 0.f, 0.f};
;         cur = nxt; cA = nA; cB = nB; ++ui;
;     }
;     PG8_WAIT_V(0);
;     if (wr == 0) PG8_BAR;
;     PG8_BAR;
	s_waitcnt lgkmcnt(0)
	s_lshl_b32 s3, s10, 8
	v_mov_b32_e32 v150, v144
	v_mov_b32_e32 v151, v145
	s_add_i32 s3, s3, s37
	v_cvt_pk_bf16_f32 v68, v68, v69
	v_add_u32_e32 v154, s3, v150
	s_lshl_b32 s3, s47, 8
	s_or_b32 s3, s3, s38
	v_lshl_add_u32 v150, v151, 3, s3
	v_ashrrev_i32_e32 v151, 31, v150
	v_lshl_add_u64 v[150:151], v[150:151], 1, s[6:7]
	v_cvt_pk_bf16_f32 v69, v70, v71
	v_cvt_pk_bf16_f32 v70, v64, v65
	v_add_u32_e32 v64, 0x80, v154
	v_mad_i64_i32 v[152:153], s[20:21], v154, s46, v[150:151]
	v_cvt_pk_bf16_f32 v108, v108, v109
	v_cvt_pk_bf16_f32 v109, v110, v111
	v_cvt_pk_bf16_f32 v110, v104, v105
	v_cvt_pk_bf16_f32 v111, v106, v107
	v_add_u32_e32 v104, 16, v154
	v_mad_i64_i32 v[64:65], s[20:21], v64, s46, v[150:151]
	v_cvt_pk_bf16_f32 v44, v44, v45
	v_cvt_pk_bf16_f32 v45, v46, v47
	v_cvt_pk_bf16_f32 v46, v40, v41
	v_cvt_pk_bf16_f32 v47, v42, v43
	v_add_u32_e32 v40, 0x90, v154
	global_store_dwordx4 v[152:153], v[108:111], off offset:256
	v_cvt_pk_bf16_f32 v92, v92, v93
	v_cvt_pk_bf16_f32 v93, v94, v95
	v_mad_i64_i32 v[108:109], s[20:21], v104, s46, v[150:151]
	v_cvt_pk_bf16_f32 v94, v88, v89
	v_cvt_pk_bf16_f32 v95, v90, v91
	v_add_u32_e32 v88, 32, v154
	global_store_dwordx4 v[64:65], v[44:47], off offset:256
	v_cvt_pk_bf16_f32 v28, v28, v29
	v_cvt_pk_bf16_f32 v29, v30, v31
	v_mad_i64_i32 v[44:45], s[20:21], v40, s46, v[150:151]
	v_cvt_pk_bf16_f32 v30, v24, v25
	v_cvt_pk_bf16_f32 v31, v26, v27
	v_add_u32_e32 v24, 0xa0, v154
	global_store_dwordx4 v[108:109], v[92:95], off offset:256
	v_cvt_pk_bf16_f32 v76, v76, v77
	v_cvt_pk_bf16_f32 v77, v78, v79
	v_mad_i64_i32 v[92:93], s[20:21], v88, s46, v[150:151]
	v_cvt_pk_bf16_f32 v78, v72, v73
	v_cvt_pk_bf16_f32 v79, v74, v75
	v_add_u32_e32 v72, 48, v154
	global_store_dwordx4 v[44:45], v[28:31], off offset:256
	v_cvt_pk_bf16_f32 v12, v12, v13
	v_cvt_pk_bf16_f32 v13, v14, v15
	v_mad_i64_i32 v[28:29], s[20:21], v24, s46, v[150:151]
	v_cvt_pk_bf16_f32 v14, v8, v9
	v_cvt_pk_bf16_f32 v15, v10, v11
	v_add_u32_e32 v8, 0xb0, v154
	global_store_dwordx4 v[92:93], v[76:79], off offset:256
	global_store_dwordx4 v[28:29], v[12:15], off offset:256
	v_cvt_pk_bf16_f32 v124, v124, v125
	v_mad_i64_i32 v[76:77], s[20:21], v72, s46, v[150:151]
	v_mad_i64_i32 v[12:13], s[20:21], v8, s46, v[150:151]
	v_cvt_pk_bf16_f32 v125, v126, v127
	v_cvt_pk_bf16_f32 v126, v120, v121
	v_cvt_pk_bf16_f32 v127, v122, v123
	v_cvt_pk_bf16_f32 v104, v116, v117
	v_cvt_pk_bf16_f32 v105, v118, v119
	v_cvt_pk_bf16_f32 v106, v112, v113
	v_cvt_pk_bf16_f32 v107, v114, v115
	v_cvt_pk_bf16_f32 v88, v100, v101
	v_cvt_pk_bf16_f32 v89, v102, v103
	v_cvt_pk_bf16_f32 v90, v96, v97
	v_cvt_pk_bf16_f32 v91, v98, v99
	v_cvt_pk_bf16_f32 v72, v84, v85
	v_cvt_pk_bf16_f32 v73, v86, v87
	v_cvt_pk_bf16_f32 v74, v80, v81
	v_cvt_pk_bf16_f32 v75, v82, v83
	v_cvt_pk_bf16_f32 v71, v66, v67
	v_cvt_pk_bf16_f32 v60, v60, v61
	v_cvt_pk_bf16_f32 v61, v62, v63
	v_cvt_pk_bf16_f32 v62, v56, v57
	v_cvt_pk_bf16_f32 v63, v58, v59
	v_cvt_pk_bf16_f32 v40, v52, v53
	v_cvt_pk_bf16_f32 v41, v54, v55
	v_cvt_pk_bf16_f32 v42, v48, v49
	v_cvt_pk_bf16_f32 v43, v50, v51
	v_cvt_pk_bf16_f32 v24, v36, v37
	v_cvt_pk_bf16_f32 v25, v38, v39
	v_cvt_pk_bf16_f32 v26, v32, v33
	v_cvt_pk_bf16_f32 v27, v34, v35
	v_cvt_pk_bf16_f32 v8, v20, v21
	v_cvt_pk_bf16_f32 v9, v22, v23
	v_cvt_pk_bf16_f32 v10, v16, v17
	v_cvt_pk_bf16_f32 v11, v18, v19
	v_cvt_pk_bf16_f32 v4, v4, v5
	v_cvt_pk_bf16_f32 v5, v6, v7
	v_cvt_pk_bf16_f32 v6, v0, v1
	v_cvt_pk_bf16_f32 v7, v2, v3
	s_and_b64 vcc, exec, s[40:41]
	s_mov_b32 s47, s12
	s_mov_b32 s10, s14
	s_mov_b64 s[20:21], s[18:19]
	s_mov_b64 s[22:23], s[16:17]
	global_store_dwordx4 v[152:153], v[124:127], off
	global_store_dwordx4 v[108:109], v[104:107], off
	global_store_dwordx4 v[92:93], v[88:91], off
	global_store_dwordx4 v[76:77], v[72:75], off
	global_store_dwordx4 v[76:77], v[68:71], off offset:256
	global_store_dwordx4 v[64:65], v[60:63], off
	global_store_dwordx4 v[44:45], v[40:43], off
	global_store_dwordx4 v[28:29], v[24:27], off
	global_store_dwordx4 v[12:13], v[8:11], off
	global_store_dwordx4 v[12:13], v[4:7], off offset:256
	s_cbranch_vccz .LBB1_690
	s_waitcnt vmcnt(0)
	s_cmpk_gt_u32 s4, 0xff
	s_cbranch_scc1 .LBB1_697
	s_barrier

; #define PG8_STAGE(bufoff, gbase, voff) do { _Pragma("unroll") for (int _i = 0; _i < 2; ++_i) \
;         __builtin_amdgcn_global_load_lds((const unsigned*)((const char*)(gbase) + (voff)[_i]), (LAS unsigned*)(lds + (bufoff) + ldsw + _i * 8192), 16, 0, 0); } while (0)
; #define PG8_LDA(dst, b, h) do { _Pragma("unroll") for (int m = 0; m < 4; ++m) _Pragma("unroll") for (int k = 0; k < 2; ++k) dst[m][k] = *(const LAS bf16x8*)(lds + PG8_SA(b, h) + aoff + m * 2048 + k * 1024); } while (0)
; #define PG8_LDB(dst, b, h) do { _Pragma("unroll") for (int n = 0; n < 2; ++n) _Pragma("unroll") for (int k = 0; k < 2; ++k) dst[n][k] = *(const LAS bf16x8*)(lds + PG8_SB(b, h) + boff + n * 2048 + k * 1024); } while (0)
; #define PG8_MMA(ai, bj, At, Bt) do { __builtin_amdgcn_s_setprio(1); _Pragma("unroll") for (int m = 0; m < 4; ++m) _Pragma("unroll") for (int n = 0; n < 2; ++n) _Pragma("unroll") for (int k = 0; k < 2; ++k) \
;         acc[ai][bj][m][n] = __builtin_amdgcn_mfma_f32_16x16x32_bf16(Bt[n][k], At[m][k], acc[ai][bj][m][n], 0, 0, 0); __builtin_amdgcn_s_setprio(0); } while (0)
; #define PG8_WAIT_V(n) asm volatile("s_waitcnt vmcnt(" #n ")" ::: "memory")
; #define PG8_WAIT_L(n) asm volatile("s_waitcnt lgkmcnt(" #n ")" ::: "memory")
; template <class Map, class Epi>
; DI void gemm_phase(LAS unsigned char* lds, const Map& MP, const Epi& E, const int nM, const int nN, const int K, const int lda, const int ldb) {
;     ...
;         for (int t = 0; t < nt; t += 2) {
;             const bool last = (t == nt - 2);
;             const char* a1 = cA + (size_t)(t + 1) * kstep;
;             const char* a2 = last ? nA : cA + (size_t)(t + 2) * kstep; const char* b2 = last ? nB : cB + (size_t)(t + 2) * kstep;
;             const char* a3 = a2 + kstep; const char* b3 = b2 + kstep;
;             PG8_LDB(B0, 0, 0); PG8_SCHED; PG8_LDA(At, 0, 0); PG8_STAGE(PG8_SA(1, 1), a1 + hstepA, voffA);
;             PG8_WAIT_L(8); PG8_BAR; PG8_WAIT_L(0); PG8_MMA(0, 0, At, B0); PG8_BAR; PG8_SCHED;
;             PG8_LDB(B1, 0, 1); PG8_STAGE(PG8_SB(0, 0), b2, voffB);
;             PG8_BAR; PG8_WAIT_L(0); PG8_MMA(0, 1, At, B1); PG8_BAR;
;             PG8_LDA(At, 0, 1); PG8_STAGE(PG8_SA(0, 0), a2, voffA);
;             PG8_BAR; PG8_WAIT_L(0); PG8_MMA(1, 0, At, B0); PG8_BAR; PG8_SCHED;
;             PG8_STAGE(PG8_SB(0, 1), b2 + hstepB, voffB);
;             PG8_WAIT_V(6); PG8_BAR; PG8_MMA(1, 1, At, B1); PG8_BAR;
.LBB1_925:
	s_add_i32 m0, s24, 0xc000
	ds_read_b128 v[168:171], v150
	ds_read_b128 v[172:175], v150 offset:1024
	ds_read_b128 v[176:179], v150 offset:2048
	ds_read_b128 v[180:183], v150 offset:3072
	ds_read_b128 v[184:187], v150 offset:4096
	ds_read_b128 v[188:191], v150 offset:5120
	ds_read_b128 v[192:195], v150 offset:6144
	ds_read_b128 v[198:201], v150 offset:7168
	global_load_lds_dwordx4 v138, s[10:11]
	s_add_i32 m0, s24, 0xe000
	s_setprio 1
	global_load_lds_dwordx4 v136, s[10:11]
	s_waitcnt lgkmcnt(8)
	s_barrier
	s_waitcnt lgkmcnt(7)
	v_mfma_f32_16x16x32_bf16 v[124:127], v[152:155], v[168:171], v[124:127]
	v_mfma_f32_16x16x32_bf16 v[120:123], v[160:163], v[168:171], v[120:123]
	s_waitcnt lgkmcnt(5)
	v_mfma_f32_16x16x32_bf16 v[108:111], v[152:155], v[176:179], v[108:111]
	v_mfma_f32_16x16x32_bf16 v[104:107], v[160:163], v[176:179], v[104:107]
	s_waitcnt lgkmcnt(3)
	v_mfma_f32_16x16x32_bf16 v[92:95], v[152:155], v[184:187], v[92:95]
	v_mfma_f32_16x16x32_bf16 v[88:91], v[160:163], v[184:187], v[88:91]
	s_waitcnt lgkmcnt(1)
	v_mfma_f32_16x16x32_bf16 v[76:79], v[152:155], v[192:195], v[76:79]
	v_mfma_f32_16x16x32_bf16 v[72:75], v[160:163], v[192:195], v[72:75]
	v_mfma_f32_16x16x32_bf16 v[124:127], v[156:159], v[172:175], v[124:127]
	s_add_i32 s3, s35, s22
	v_mfma_f32_16x16x32_bf16 v[120:123], v[164:167], v[172:175], v[120:123]
	v_lshl_add_u64 v[144:145], s[12:13], 0, v[132:133]
	v_mfma_f32_16x16x32_bf16 v[108:111], v[156:159], v[180:183], v[108:111]
	v_lshl_add_u64 v[218:219], s[12:13], 0, v[128:129]
	v_mfma_f32_16x16x32_bf16 v[104:107], v[164:167], v[180:183], v[104:107]
	v_mfma_f32_16x16x32_bf16 v[92:95], v[156:159], v[188:191], v[92:95]
	v_mfma_f32_16x16x32_bf16 v[88:91], v[164:167], v[188:191], v[88:91]
	s_waitcnt lgkmcnt(0)
	v_mfma_f32_16x16x32_bf16 v[76:79], v[156:159], v[198:201], v[76:79]
	v_mfma_f32_16x16x32_bf16 v[72:75], v[164:167], v[198:201], v[72:75]
	s_barrier
	s_setprio 0
	s_mov_b32 m0, s3
	ds_read_b128 v[202:205], v151
	ds_read_b128 v[206:209], v151 offset:1024
	ds_read_b128 v[210:213], v151 offset:2048
	ds_read_b128 v[214:217], v151 offset:3072
	global_load_lds_dwordx4 v[144:145], off
	s_add_i32 m0, s3, 0x2000
	s_setprio 1
	global_load_lds_dwordx4 v[218:219], off
	s_barrier
	s_waitcnt lgkmcnt(3)
	v_mfma_f32_16x16x32_bf16 v[116:119], v[202:205], v[168:171], v[116:119]
	s_waitcnt lgkmcnt(1)
	v_mfma_f32_16x16x32_bf16 v[112:115], v[210:213], v[168:171], v[112:115]
	v_mfma_f32_16x16x32_bf16 v[100:103], v[202:205], v[176:179], v[100:103]
	v_mfma_f32_16x16x32_bf16 v[96:99], v[210:213], v[176:179], v[96:99]
	v_mfma_f32_16x16x32_bf16 v[84:87], v[202:205], v[184:187], v[84:87]
	v_mfma_f32_16x16x32_bf16 v[80:83], v[210:213], v[184:187], v[80:83]
	v_mfma_f32_16x16x32_bf16 v[68:71], v[202:205], v[192:195], v[68:71]
	v_mfma_f32_16x16x32_bf16 v[64:67], v[210:213], v[192:195], v[64:67]
	v_mfma_f32_16x16x32_bf16 v[116:119], v[206:209], v[172:175], v[116:119]
	v_lshl_add_u64 v[222:223], s[14:15], 0, v[130:131]
	s_mov_b32 m0, s24
	s_waitcnt lgkmcnt(0)
	v_mfma_f32_16x16x32_bf16 v[112:115], v[214:217], v[172:175], v[112:115]
	v_lshl_add_u64 v[220:221], s[14:15], 0, v[134:135]
	v_mfma_f32_16x16x32_bf16 v[100:103], v[206:209], v[180:183], v[100:103]
	v_mfma_f32_16x16x32_bf16 v[96:99], v[214:217], v[180:183], v[96:99]
	v_mfma_f32_16x16x32_bf16 v[84:87], v[206:209], v[188:191], v[84:87]
	v_mfma_f32_16x16x32_bf16 v[80:83], v[214:217], v[188:191], v[80:83]
	v_mfma_f32_16x16x32_bf16 v[68:71], v[206:209], v[198:201], v[68:71]
	v_mfma_f32_16x16x32_bf16 v[64:67], v[214:217], v[198:201], v[64:67]
	s_barrier
	s_setprio 0
	ds_read_b128 v[168:171], v150 offset:16384
	ds_read_b128 v[172:175], v150 offset:17408
	ds_read_b128 v[176:179], v150 offset:18432
	ds_read_b128 v[180:183], v150 offset:19456
	ds_read_b128 v[184:187], v150 offset:20480
	ds_read_b128 v[188:191], v150 offset:21504
	ds_read_b128 v[192:195], v150 offset:22528
	ds_read_b128 v[198:201], v150 offset:23552
	global_load_lds_dwordx4 v[220:221], off
	s_mov_b32 m0, s9
	s_setprio 1
	global_load_lds_dwordx4 v[222:223], off
	s_waitcnt vmcnt(10)
	s_barrier
	s_waitcnt lgkmcnt(7)
	v_mfma_f32_16x16x32_bf16 v[60:63], v[152:155], v[168:171], v[60:63]
	v_mfma_f32_16x16x32_bf16 v[56:59], v[160:163], v[168:171], v[56:59]
	s_waitcnt lgkmcnt(5)
	v_mfma_f32_16x16x32_bf16 v[44:47], v[152:155], v[176:179], v[44:47]
	v_mfma_f32_16x16x32_bf16 v[40:43], v[160:163], v[176:179], v[40:43]
	s_waitcnt lgkmcnt(3)
	v_mfma_f32_16x16x32_bf16 v[28:31], v[152:155], v[184:187], v[28:31]
	v_mfma_f32_16x16x32_bf16 v[24:27], v[160:163], v[184:187], v[24:27]
	s_waitcnt lgkmcnt(1)
	v_mfma_f32_16x16x32_bf16 v[12:15], v[152:155], v[192:195], v[12:15]
	v_mfma_f32_16x16x32_bf16 v[8:11], v[160:163], v[192:195], v[8:11]
	v_mfma_f32_16x16x32_bf16 v[60:63], v[156:159], v[172:175], v[60:63]
	s_add_u32 s56, s12, 0x80000
	s_addc_u32 s57, s13, 0
	v_mfma_f32_16x16x32_bf16 v[56:59], v[164:167], v[172:175], v[56:59]
	s_add_i32 s3, s36, s22
	v_mfma_f32_16x16x32_bf16 v[44:47], v[156:159], v[180:183], v[44:47]
	v_mfma_f32_16x16x32_bf16 v[40:43], v[164:167], v[180:183], v[40:43]
	v_mfma_f32_16x16x32_bf16 v[28:31], v[156:159], v[188:191], v[28:31]
	v_mfma_f32_16x16x32_bf16 v[24:27], v[164:167], v[188:191], v[24:27]
	s_waitcnt lgkmcnt(0)
	v_mfma_f32_16x16x32_bf16 v[12:15], v[156:159], v[198:201], v[12:15]
	v_mfma_f32_16x16x32_bf16 v[8:11], v[164:167], v[198:201], v[8:11]
	s_barrier
	s_setprio 0
	s_mov_b32 m0, s3
	s_nop 0
	global_load_lds_dwordx4 v132, s[56:57]
	s_add_i32 m0, s3, 0x2000
	s_setprio 1
	global_load_lds_dwordx4 v128, s[56:57]
	s_waitcnt vmcnt(6)
	s_barrier
; #define PG8_STAGE(bufoff, gbase, voff) do { _Pragma("unroll") for (int _i = 0; _i < 2; ++_i) \
;         __builtin_amdgcn_global_load_lds((const unsigned*)((const char*)(gbase) + (voff)[_i]), (LAS unsigned*)(lds + (bufoff) + ldsw + _i * 8192), 16, 0, 0); } while (0)
; #define PG8_LDA(dst, b, h) do { _Pragma("unroll") for (int m = 0; m < 4; ++m) _Pragma("unroll") for (int k = 0; k < 2; ++k) dst[m][k] = *(const LAS bf16x8*)(lds + PG8_SA(b, h) + aoff + m * 2048 + k * 1024); } while (0)
; #define PG8_LDB(dst, b, h) do { _Pragma("unroll") for (int n = 0; n < 2; ++n) _Pragma("unroll") for (int k = 0; k < 2; ++k) dst[n][k] = *(const LAS bf16x8*)(lds + PG8_SB(b, h) + boff + n * 2048 + k * 1024); } while (0)
; #define PG8_MMA(ai, bj, At, Bt) do { __builtin_amdgcn_s_setprio(1); _Pragma("unroll") for (int m = 0; m < 4; ++m) _Pragma("unroll") for (int n = 0; n < 2; ++n) _Pragma("unroll") for (int k = 0; k < 2; ++k) \
;         acc[ai][bj][m][n] = __builtin_amdgcn_mfma_f32_16x16x32_bf16(Bt[n][k], At[m][k], acc[ai][bj][m][n], 0, 0, 0); __builtin_amdgcn_s_setprio(0); } while (0)
; #define PG8_WAIT_V(n) asm volatile("s_waitcnt vmcnt(" #n ")" ::: "memory")
; #define PG8_WAIT_L(n) asm volatile("s_waitcnt lgkmcnt(" #n ")" ::: "memory")
; #define PG8_BAR __builtin_amdgcn_s_barrier()
; #define PG8_SCHED __builtin_amdgcn_sched_barrier(0)
; template <class Map, class Epi>
; DI void gemm_phase(LAS unsigned char* lds, const Map& MP, const Epi& E, const int nM, const int nN, const int K, const int lda, const int ldb) {
;     ...
;             PG8_WAIT_V(6); PG8_BAR; PG8_MMA(1, 1, At, B1); PG8_BAR;
;             PG8_LDB(B0, 1, 0); PG8_SCHED; PG8_LDA(At, 1, 0); PG8_STAGE(PG8_SA(0, 1), a2 + hstepA, voffA);
;             PG8_WAIT_L(8); PG8_BAR; PG8_WAIT_L(0); PG8_MMA(0, 0, At, B0); PG8_BAR; PG8_SCHED;
;             PG8_LDB(B1, 1, 1); PG8_STAGE(PG8_SB(1, 0), b3, voffB);
;             PG8_BAR; PG8_WAIT_L(0); PG8_MMA(0, 1, At, B1); PG8_BAR;
;             PG8_LDA(At, 1, 1); PG8_STAGE(PG8_SA(1, 0), a3, voffA);
;             PG8_BAR; PG8_WAIT_L(0); PG8_MMA(1, 0, At, B0); PG8_BAR; PG8_SCHED;
	v_mfma_f32_16x16x32_bf16 v[52:55], v[202:205], v[168:171], v[52:55]
	v_mfma_f32_16x16x32_bf16 v[48:51], v[210:213], v[168:171], v[48:51]
	s_add_i32 s3, 0, 0x18000
	v_add_u32_e32 v164, s3, v148
	ds_read_b128 v[152:155], v164
	v_mfma_f32_16x16x32_bf16 v[36:39], v[202:205], v[176:179], v[36:39]
	v_mfma_f32_16x16x32_bf16 v[32:35], v[210:213], v[176:179], v[32:35]
	ds_read_b128 v[156:159], v164 offset:1024
	v_mfma_f32_16x16x32_bf16 v[20:23], v[202:205], v[184:187], v[20:23]
	v_mfma_f32_16x16x32_bf16 v[16:19], v[210:213], v[184:187], v[16:19]
	ds_read_b128 v[160:163], v164 offset:2048
	v_mfma_f32_16x16x32_bf16 v[4:7], v[202:205], v[192:195], v[4:7]
	v_mfma_f32_16x16x32_bf16 v[0:3], v[210:213], v[192:195], v[0:3]
	ds_read_b128 v[164:167], v164 offset:3072
	v_mfma_f32_16x16x32_bf16 v[52:55], v[206:209], v[172:175], v[52:55]
	s_add_u32 s14, s14, 0x80000
	s_addc_u32 s15, s15, 0
	v_mfma_f32_16x16x32_bf16 v[48:51], v[214:217], v[172:175], v[48:51]
	v_mfma_f32_16x16x32_bf16 v[36:39], v[206:209], v[180:183], v[36:39]
	v_mfma_f32_16x16x32_bf16 v[32:35], v[214:217], v[180:183], v[32:35]
	v_mfma_f32_16x16x32_bf16 v[20:23], v[206:209], v[188:191], v[20:23]
	v_mfma_f32_16x16x32_bf16 v[16:19], v[214:217], v[188:191], v[16:19]
	v_mfma_f32_16x16x32_bf16 v[4:7], v[206:209], v[198:201], v[4:7]
	v_mfma_f32_16x16x32_bf16 v[0:3], v[214:217], v[198:201], v[0:3]
	s_barrier
	s_setprio 0
	s_mov_b32 m0, s25
	ds_read_b128 v[168:171], v150 offset:32768
	ds_read_b128 v[172:175], v150 offset:33792
	ds_read_b128 v[176:179], v150 offset:34816
	ds_read_b128 v[180:183], v150 offset:35840
	ds_read_b128 v[184:187], v150 offset:36864
	ds_read_b128 v[188:191], v150 offset:37888
	ds_read_b128 v[192:195], v150 offset:38912
	ds_read_b128 v[198:201], v150 offset:39936
	global_load_lds_dwordx4 v134, s[14:15]
	s_mov_b32 m0, s26
	s_setprio 1
	global_load_lds_dwordx4 v130, s[14:15]
	s_waitcnt lgkmcnt(8)
	s_barrier
	s_waitcnt lgkmcnt(7)
	v_mfma_f32_16x16x32_bf16 v[124:127], v[152:155], v[168:171], v[124:127]
	v_mfma_f32_16x16x32_bf16 v[120:123], v[160:163], v[168:171], v[120:123]
	s_waitcnt lgkmcnt(5)
	v_mfma_f32_16x16x32_bf16 v[108:111], v[152:155], v[176:179], v[108:111]
	v_mfma_f32_16x16x32_bf16 v[104:107], v[160:163], v[176:179], v[104:107]
	s_waitcnt lgkmcnt(3)
	v_mfma_f32_16x16x32_bf16 v[92:95], v[152:155], v[184:187], v[92:95]
	v_mfma_f32_16x16x32_bf16 v[88:91], v[160:163], v[184:187], v[88:91]
	s_waitcnt lgkmcnt(1)
	v_mfma_f32_16x16x32_bf16 v[76:79], v[152:155], v[192:195], v[76:79]
	v_mfma_f32_16x16x32_bf16 v[72:75], v[160:163], v[192:195], v[72:75]
	v_mfma_f32_16x16x32_bf16 v[124:127], v[156:159], v[172:175], v[124:127]
	s_add_i32 s14, 0, 0x1c000
	v_mfma_f32_16x16x32_bf16 v[120:123], v[164:167], v[172:175], v[120:123]
	s_add_i32 s3, s3, s22
	v_mfma_f32_16x16x32_bf16 v[108:111], v[156:159], v[180:183], v[108:111]
	v_add_u32_e32 v196, s14, v148
	v_mfma_f32_16x16x32_bf16 v[104:107], v[164:167], v[180:183], v[104:107]
	v_lshl_add_u64 v[144:145], v[144:145], 0, s[44:45]
	v_mfma_f32_16x16x32_bf16 v[92:95], v[156:159], v[188:191], v[92:95]
	v_mfma_f32_16x16x32_bf16 v[88:91], v[164:167], v[188:191], v[88:91]
	s_waitcnt lgkmcnt(0)
	v_mfma_f32_16x16x32_bf16 v[76:79], v[156:159], v[198:201], v[76:79]
	v_mfma_f32_16x16x32_bf16 v[72:75], v[164:167], v[198:201], v[72:75]
	s_barrier
	s_setprio 0
	s_mov_b32 m0, s3
	ds_read_b128 v[202:205], v196
	ds_read_b128 v[206:209], v196 offset:1024
	ds_read_b128 v[210:213], v196 offset:2048
	ds_read_b128 v[214:217], v196 offset:3072
	global_load_lds_dwordx4 v[144:145], off
	v_lshl_add_u64 v[144:145], v[218:219], 0, s[44:45]
	s_add_i32 m0, s3, 0x2000
	s_setprio 1
	global_load_lds_dwordx4 v[144:145], off
	s_barrier
	s_waitcnt lgkmcnt(3)
	v_mfma_f32_16x16x32_bf16 v[116:119], v[202:205], v[168:171], v[116:119]
	s_waitcnt lgkmcnt(1)
	v_mfma_f32_16x16x32_bf16 v[112:115], v[210:213], v[168:171], v[112:115]
	v_mfma_f32_16x16x32_bf16 v[100:103], v[202:205], v[176:179], v[100:103]
	v_mfma_f32_16x16x32_bf16 v[96:99], v[210:213], v[176:179], v[96:99]
	v_mfma_f32_16x16x32_bf16 v[84:87], v[202:205], v[184:187], v[84:87]
	v_mfma_f32_16x16x32_bf16 v[80:83], v[210:213], v[184:187], v[80:83]
	v_mfma_f32_16x16x32_bf16 v[68:71], v[202:205], v[192:195], v[68:71]
	v_mfma_f32_16x16x32_bf16 v[64:67], v[210:213], v[192:195], v[64:67]
	v_mfma_f32_16x16x32_bf16 v[116:119], v[206:209], v[172:175], v[116:119]
	s_mov_b32 m0, s30
	s_waitcnt lgkmcnt(0)
	v_mfma_f32_16x16x32_bf16 v[112:115], v[214:217], v[172:175], v[112:115]
	v_lshl_add_u64 v[144:145], v[220:221], 0, s[44:45]
	v_mfma_f32_16x16x32_bf16 v[100:103], v[206:209], v[180:183], v[100:103]
	v_mfma_f32_16x16x32_bf16 v[96:99], v[214:217], v[180:183], v[96:99]
	v_mfma_f32_16x16x32_bf16 v[84:87], v[206:209], v[188:191], v[84:87]
	v_mfma_f32_16x16x32_bf16 v[80:83], v[214:217], v[188:191], v[80:83]
	v_mfma_f32_16x16x32_bf16 v[68:71], v[206:209], v[198:201], v[68:71]
	v_mfma_f32_16x16x32_bf16 v[64:67], v[214:217], v[198:201], v[64:67]
	s_barrier
	s_setprio 0
	ds_read_b128 v[168:171], v150 offset:49152
	ds_read_b128 v[172:175], v150 offset:50176
	ds_read_b128 v[176:179], v150 offset:51200
	ds_read_b128 v[180:183], v150 offset:52224
	ds_read_b128 v[184:187], v150 offset:53248
	ds_read_b128 v[188:191], v150 offset:54272
	ds_read_b128 v[192:195], v150 offset:55296
	ds_read_b128 v[198:201], v150 offset:56320
	global_load_lds_dwordx4 v[144:145], off
	v_lshl_add_u64 v[144:145], v[222:223], 0, s[44:45]
	s_mov_b32 m0, s31
	s_setprio 1
	global_load_lds_dwordx4 v[144:145], off
	s_waitcnt vmcnt(10)
	s_barrier
;     DI void operator()(const f32x4 (&acc)[2][2][4][2], const Unit& u, int wr, int wc, int fr, int fq) const {
;     ...
;         for (int ai = 0; ai < 2; ++ai)
; #pragma unroll
;             for (int m = 0; m < 4; ++m) { const size_t ro = (size_t)(row0 + ai * HALF + m * 16) * D + col0;
; #pragma unroll
;                 for (int bj = 0; bj < 2; ++bj) {
;                     f32x4 x0, x1;
;                     if constexpr (IB) { const u32x4 w = *(const u32x4*)((const bf16_t*)Xin + ro + bj * HALF);
;                         x0 = (f32x4){bflo(w[0]), bfhi(w[0]), bflo(w[1]), bfhi(w[1])}; x1 = (f32x4){bflo(w[2]), bfhi(w[2]), bflo(w[3]), bfhi(w[3])}; }
; template <class Map, class Epi>
; DI void gemm_phase(LAS unsigned char* lds, const Map& MP, const Epi& E, const int nM, const int nN, const int K, const int lda, const int ldb) {
;     ...
;             const bool last = (t == nt - 2);
;             const char* a1 = cA + (size_t)(t + 1) * kstep;
;             const char* a2 = last ? nA : cA + (size_t)(t + 2) * kstep; const char* b2 = last ? nB : cB + (size_t)(t + 2) * kstep;
;             const char* a3 = a2 + kstep; const char* b3 = b2 + kstep;
;             PG8_LDB(B0, 0, 0); PG8_SCHED; PG8_LDA(At, 0, 0); PG8_STAGE(PG8_SA(1, 1), a1 + hstepA, voffA);
;             PG8_WAIT_L(8); PG8_BAR; PG8_WAIT_L(0); PG8_MMA(0, 0, At, B0); PG8_BAR; PG8_SCHED;
;             PG8_LDB(B1, 0, 1); PG8_STAGE(PG8_SB(0, 0), b2, voffB);
;             PG8_BAR; PG8_WAIT_L(0); PG8_MMA(0, 1, At, B1); PG8_BAR;
;             PG8_LDA(At, 0, 1); PG8_STAGE(PG8_SA(0, 0), a2, voffA);
;             PG8_BAR; PG8_WAIT_L(0); PG8_MMA(1, 0, At, B0); PG8_BAR; PG8_SCHED;
;             PG8_STAGE(PG8_SB(0, 1), b2 + hstepB, voffB);
;             PG8_WAIT_V(6); PG8_BAR; PG8_MMA(1, 1, At, B1); PG8_BAR;
;             PG8_LDB(B0, 1, 0); PG8_SCHED; PG8_LDA(At, 1, 0); PG8_STAGE(PG8_SA(0, 1), a2 + hstepA, voffA);
;             PG8_WAIT_L(8); PG8_BAR; PG8_WAIT_L(0); PG8_MMA(0, 0, At, B0); PG8_BAR; PG8_SCHED;
;             PG8_LDB(B1, 1, 1); PG8_STAGE(PG8_SB(1, 0), b3, voffB);
;             PG8_BAR; PG8_WAIT_L(0); PG8_MMA(0, 1, At, B1); PG8_BAR;
;             PG8_LDA(At, 1, 1); PG8_STAGE(PG8_SA(1, 0), a3, voffA);
;             PG8_BAR; PG8_WAIT_L(0); PG8_MMA(1, 0, At, B0); PG8_BAR; PG8_SCHED;
;             PG8_STAGE(PG8_SB(1, 1), b3 + hstepB, voffB);
;             PG8_WAIT_V(6); PG8_BAR; PG8_MMA(1, 1, At, B1); PG8_BAR;
	s_waitcnt lgkmcnt(7)
	v_mfma_f32_16x16x32_bf16 v[60:63], v[152:155], v[168:171], v[60:63]
	v_mfma_f32_16x16x32_bf16 v[56:59], v[160:163], v[168:171], v[56:59]
	s_waitcnt lgkmcnt(5)
	v_mfma_f32_16x16x32_bf16 v[44:47], v[152:155], v[176:179], v[44:47]
	v_mfma_f32_16x16x32_bf16 v[40:43], v[160:163], v[176:179], v[40:43]
	s_waitcnt lgkmcnt(3)
	v_mfma_f32_16x16x32_bf16 v[28:31], v[152:155], v[184:187], v[28:31]
	v_mfma_f32_16x16x32_bf16 v[24:27], v[160:163], v[184:187], v[24:27]
	s_waitcnt lgkmcnt(1)
	v_mfma_f32_16x16x32_bf16 v[12:15], v[152:155], v[192:195], v[12:15]
	v_mfma_f32_16x16x32_bf16 v[8:11], v[160:163], v[192:195], v[8:11]
	v_mfma_f32_16x16x32_bf16 v[60:63], v[156:159], v[172:175], v[60:63]
	s_add_u32 s12, s12, 0x80080
	s_addc_u32 s13, s13, 0
	v_mfma_f32_16x16x32_bf16 v[56:59], v[164:167], v[172:175], v[56:59]
	s_add_i32 s3, s14, s22
	v_mfma_f32_16x16x32_bf16 v[44:47], v[156:159], v[180:183], v[44:47]
	v_mfma_f32_16x16x32_bf16 v[40:43], v[164:167], v[180:183], v[40:43]
	v_mfma_f32_16x16x32_bf16 v[28:31], v[156:159], v[188:191], v[28:31]
	v_mfma_f32_16x16x32_bf16 v[24:27], v[164:167], v[188:191], v[24:27]
	s_waitcnt lgkmcnt(0)
	v_mfma_f32_16x16x32_bf16 v[12:15], v[156:159], v[198:201], v[12:15]
	v_mfma_f32_16x16x32_bf16 v[8:11], v[164:167], v[198:201], v[8:11]
	s_barrier
	s_setprio 0
	s_mov_b32 m0, s3
	s_nop 0
	global_load_lds_dwordx4 v132, s[12:13]
	s_add_i32 m0, s3, 0x2000
	s_setprio 1
	global_load_lds_dwordx4 v128, s[12:13]
	s_waitcnt vmcnt(6)
	s_barrier
	v_mfma_f32_16x16x32_bf16 v[52:55], v[202:205], v[168:171], v[52:55]
	v_mfma_f32_16x16x32_bf16 v[48:51], v[210:213], v[168:171], v[48:51]
	ds_read_b128 v[152:155], v149
	v_mfma_f32_16x16x32_bf16 v[36:39], v[202:205], v[176:179], v[36:39]
	v_mfma_f32_16x16x32_bf16 v[32:35], v[210:213], v[176:179], v[32:35]
	ds_read_b128 v[156:159], v149 offset:1024
	v_mfma_f32_16x16x32_bf16 v[20:23], v[202:205], v[184:187], v[20:23]
	v_mfma_f32_16x16x32_bf16 v[16:19], v[210:213], v[184:187], v[16:19]
	ds_read_b128 v[160:163], v149 offset:2048
	v_mfma_f32_16x16x32_bf16 v[4:7], v[202:205], v[192:195], v[4:7]
	v_mfma_f32_16x16x32_bf16 v[0:3], v[210:213], v[192:195], v[0:3]
	ds_read_b128 v[164:167], v149 offset:3072
	v_mfma_f32_16x16x32_bf16 v[52:55], v[206:209], v[172:175], v[52:55]
	s_add_i32 s48, s48, 2
	v_mfma_f32_16x16x32_bf16 v[48:51], v[214:217], v[172:175], v[48:51]
	s_add_u32 s39, s39, 0x100
	s_addc_u32 s47, s47, 0
	v_mfma_f32_16x16x32_bf16 v[36:39], v[206:209], v[180:183], v[36:39]
	s_add_u32 s10, s10, 0x100
	s_addc_u32 s11, s11, 0
	v_mfma_f32_16x16x32_bf16 v[32:35], v[214:217], v[180:183], v[32:35]
	s_add_u32 s3, s10, 0xfff80080
	s_addc_u32 s12, s11, -1
	s_cmp_eq_u32 s48, 28
	s_cselect_b32 s15, s4, s12
	s_cselect_b32 s14, s5, s3
	s_cselect_b32 s13, s37, s47
	s_cselect_b32 s12, s38, s39
	s_cmp_gt_u32 s48, 29
	v_mfma_f32_16x16x32_bf16 v[20:23], v[206:209], v[188:191], v[20:23]
	v_mfma_f32_16x16x32_bf16 v[16:19], v[214:217], v[188:191], v[16:19]
	v_mfma_f32_16x16x32_bf16 v[4:7], v[206:209], v[198:201], v[4:7]
	v_mfma_f32_16x16x32_bf16 v[0:3], v[214:217], v[198:201], v[0:3]
	s_barrier
	s_setprio 0
	s_cbranch_scc0 .LBB1_925
	s_waitcnt lgkmcnt(0)
	v_mov_b32_e32 v152, v147
	v_mov_b32_e32 v144, v146
	s_lshl_b32 s2, s2, 8
	s_or_b32 s2, s2, s29
	v_lshl_add_u32 v144, v144, 3, s2
	s_lshl_b32 s2, s8, 8
	s_add_i32 s2, s2, s28
	v_add_u32_e32 v152, s2, v152
	v_ashrrev_i32_e32 v153, 31, v152
	v_lshlrev_b64 v[152:153], 12, v[152:153]
	v_ashrrev_i32_e32 v145, 31, v144
	v_lshl_add_u64 v[152:153], s[42:43], 0, v[152:153]
	v_lshl_add_u64 v[144:145], v[144:145], 1, v[152:153]
	global_load_dwordx4 v[160:163], v[144:145], off
	global_load_dwordx4 v[164:167], v[144:145], off offset:256
	s_mov_b64 s[98:99], 0x10000
	v_lshl_add_u64 v[154:155], v[144:145], 0, s[98:99]
	global_load_dwordx4 v[168:171], v[154:155], off
	global_load_dwordx4 v[172:175], v[154:155], off offset:256
	s_mov_b64 s[98:99], 0x20000
	v_lshl_add_u64 v[154:155], v[144:145], 0, s[98:99]
	global_load_dwordx4 v[176:179], v[154:155], off
	global_load_dwordx4 v[180:183], v[154:155], off offset:256
	s_mov_b64 s[98:99], 0x30000
	v_lshl_add_u64 v[154:155], v[144:145], 0, s[98:99]
	global_load_dwordx4 v[184:187], v[154:155], off
	global_load_dwordx4 v[188:191], v[154:155], off offset:256
	s_mov_b64 s[98:99], 0x80000
	v_lshl_add_u64 v[154:155], v[144:145], 0, s[98:99]
	global_load_dwordx4 v[192:195], v[154:155], off
	global_load_dwordx4 v[198:201], v[154:155], off offset:256
	s_mov_b64 s[98:99], 0x90000
	v_lshl_add_u64 v[154:155], v[144:145], 0, s[98:99]
	global_load_dwordx4 v[202:205], v[154:155], off
	global_load_dwordx4 v[206:209], v[154:155], off offset:256
	s_mov_b64 s[98:99], 0xa0000
	v_lshl_add_u64 v[154:155], v[144:145], 0, s[98:99]
	global_load_dwordx4 v[210:213], v[154:155], off
	global_load_dwordx4 v[214:217], v[154:155], off offset:256
	s_mov_b64 s[98:99], 0xb0000
	v_lshl_add_u64 v[154:155], v[144:145], 0, s[98:99]
	global_load_dwordx4 v[248:251], v[154:155], off
	global_load_dwordx4 v[252:255], v[154:155], off offset:256
	s_waitcnt vmcnt(15)
	s_nop 1
	v_mov_b32_e32 v152, v160
	v_mov_b32_e32 v153, v161
	v_mov_b32_e32 v154, v162
	v_mov_b32_e32 v155, v163
	s_mov_b64 s[2:3], 0x10000
	s_mov_b32 s8, s52
	s_mov_b64 s[10:11], s[6:7]
	s_mov_b64 s[12:13], s[54:55]
	s_waitcnt lgkmcnt(0)
	v_lshlrev_b32_e32 v156, 16, v152
	v_and_b32_e32 v157, 0xffff0000, v152
	v_lshlrev_b32_e32 v152, 16, v153
	v_and_b32_e32 v153, 0xffff0000, v153
	v_lshlrev_b32_e32 v158, 16, v154
	v_and_b32_e32 v159, 0xffff0000, v154
	v_lshlrev_b32_e32 v154, 16, v155
	v_and_b32_e32 v155, 0xffff0000, v155
	v_pk_add_f32 v[126:127], v[126:127], v[152:153]
	v_pk_add_f32 v[124:125], v[124:125], v[156:157]
	v_pk_add_f32 v[152:153], v[122:123], v[154:155]
	v_pk_add_f32 v[122:123], v[120:121], v[158:159]
	v_cvt_pk_bf16_f32 v120, v124, v125
	v_cvt_pk_bf16_f32 v121, v126, v127
	v_cvt_pk_bf16_f32 v122, v122, v123
	v_cvt_pk_bf16_f32 v123, v152, v153
	global_store_dwordx4 v[144:145], v[120:123], off
	s_waitcnt vmcnt(15)
; DI unsigned pack2(float a, float b) { f32x2 v = {a, b}; hwbf16x2 r = __builtin_convertvector(v, hwbf16x2); return __builtin_bit_cast(unsigned, r); }
; DI float bflo(unsigned w) { return __uint_as_float(w << 16); }
; DI float bfhi(unsigned w) { return __uint_as_float(w & 0xffff0000u); }
;     DI void operator()(const f32x4 (&acc)[2][2][4][2], const Unit& u, int wr, int wc, int fr, int fq) const {
;     ...
;         for (int ai = 0; ai < 2; ++ai)
; #pragma unroll
;             for (int m = 0; m < 4; ++m) { const size_t ro = (size_t)(row0 + ai * HALF + m * 16) * D + col0;
; #pragma unroll
;                 for (int bj = 0; bj < 2; ++bj) {
;                     f32x4 x0, x1;
;                     if constexpr (IB) { const u32x4 w = *(const u32x4*)((const bf16_t*)Xin + ro + bj * HALF);
;                         x0 = (f32x4){bflo(w[0]), bfhi(w[0]), bflo(w[1]), bfhi(w[1])}; x1 = (f32x4){bflo(w[2]), bfhi(w[2]), bflo(w[3]), bfhi(w[3])}; }
;                     else { x0 = *(const f32x4*)((const float*)Xin + ro + bj * HALF); x1 = *(const f32x4*)((const float*)Xin + ro + bj * HALF + 4); }
;                     x0 += acc[ai][bj][m][0] * sc[bj][0]; x1 += acc[ai][bj][m][1] * sc[bj][1];
;                     if constexpr (OB) { u32x4 o; o[0] = pack2(x0[0], x0[1]); o[1] = pack2(x0[2], x0[3]); o[2] = pack2(x1[0], x1[1]); o[3] = pack2(x1[2], x1[3]);
;                         *(u32x4*)((bf16_t*)Xout + ro + bj * HALF) = o; }
;                     else { *(f32x4*)((float*)Xout + ro + bj * HALF) = x0; *(f32x4*)((float*)Xout + ro + bj * HALF + 4) = x1; } } }
	s_nop 1
	v_mov_b32_e32 v120, v164
	v_mov_b32_e32 v121, v165
	v_mov_b32_e32 v122, v166
	v_mov_b32_e32 v123, v167
	s_waitcnt lgkmcnt(0)
	v_lshlrev_b32_e32 v124, 16, v120
	v_and_b32_e32 v125, 0xffff0000, v120
	v_lshlrev_b32_e32 v120, 16, v121
	v_and_b32_e32 v121, 0xffff0000, v121
	v_lshlrev_b32_e32 v126, 16, v122
	v_and_b32_e32 v127, 0xffff0000, v122
	v_lshlrev_b32_e32 v122, 16, v123
	v_and_b32_e32 v123, 0xffff0000, v123
	v_pk_add_f32 v[116:117], v[116:117], v[124:125]
	v_pk_add_f32 v[118:119], v[118:119], v[120:121]
	v_pk_add_f32 v[120:121], v[114:115], v[122:123]
	v_pk_add_f32 v[114:115], v[112:113], v[126:127]
	v_cvt_pk_bf16_f32 v112, v116, v117
	v_lshl_add_u64 v[116:117], v[144:145], 0, s[2:3]
	s_mov_b32 s2, 0x10000
	v_cvt_pk_bf16_f32 v113, v118, v119
	v_add_co_u32_e32 v118, vcc, s2, v144
	v_cvt_pk_bf16_f32 v114, v114, v115
	v_cvt_pk_bf16_f32 v115, v120, v121
	v_addc_co_u32_e32 v119, vcc, 0, v145, vcc
	global_store_dwordx4 v[144:145], v[112:115], off offset:256
	s_waitcnt vmcnt(15)
	s_nop 1
	v_mov_b32_e32 v112, v168
	v_mov_b32_e32 v113, v169
	v_mov_b32_e32 v114, v170
	v_mov_b32_e32 v115, v171
	s_mov_b64 s[2:3], 0x20000
	s_waitcnt lgkmcnt(0)
	v_lshlrev_b32_e32 v120, 16, v112
	v_and_b32_e32 v121, 0xffff0000, v112
	v_lshlrev_b32_e32 v112, 16, v113
	v_and_b32_e32 v113, 0xffff0000, v113
	v_lshlrev_b32_e32 v122, 16, v114
	v_and_b32_e32 v123, 0xffff0000, v114
	v_lshlrev_b32_e32 v114, 16, v115
	v_and_b32_e32 v115, 0xffff0000, v115
	v_pk_add_f32 v[110:111], v[110:111], v[112:113]
	v_pk_add_f32 v[108:109], v[108:109], v[120:121]
	v_pk_add_f32 v[112:113], v[106:107], v[114:115]
	v_pk_add_f32 v[106:107], v[104:105], v[122:123]
	v_cvt_pk_bf16_f32 v104, v108, v109
	v_cvt_pk_bf16_f32 v105, v110, v111
	v_cvt_pk_bf16_f32 v106, v106, v107
	v_cvt_pk_bf16_f32 v107, v112, v113
	global_store_dwordx4 v[118:119], v[104:107], off
	s_waitcnt vmcnt(15)
	s_nop 1
	v_mov_b32_e32 v104, v172
	v_mov_b32_e32 v105, v173
	v_mov_b32_e32 v106, v174
	v_mov_b32_e32 v107, v175
	s_waitcnt lgkmcnt(0)
	v_lshlrev_b32_e32 v108, 16, v104
	v_and_b32_e32 v109, 0xffff0000, v104
	v_lshlrev_b32_e32 v104, 16, v105
	v_and_b32_e32 v105, 0xffff0000, v105
	v_lshlrev_b32_e32 v110, 16, v106
	v_and_b32_e32 v111, 0xffff0000, v106
	v_lshlrev_b32_e32 v106, 16, v107
	v_and_b32_e32 v107, 0xffff0000, v107
	v_pk_add_f32 v[100:101], v[100:101], v[108:109]
	v_pk_add_f32 v[102:103], v[102:103], v[104:105]
	v_pk_add_f32 v[104:105], v[98:99], v[106:107]
	v_pk_add_f32 v[98:99], v[96:97], v[110:111]
	v_cvt_pk_bf16_f32 v96, v100, v101
	v_lshl_add_u64 v[100:101], v[144:145], 0, s[2:3]
	s_mov_b32 s2, 0x20000
	v_cvt_pk_bf16_f32 v97, v102, v103
	v_add_co_u32_e32 v102, vcc, s2, v144
	v_cvt_pk_bf16_f32 v98, v98, v99
	v_cvt_pk_bf16_f32 v99, v104, v105
	v_addc_co_u32_e32 v103, vcc, 0, v145, vcc
	global_store_dwordx4 v[116:117], v[96:99], off offset:256
	s_waitcnt vmcnt(15)
	s_nop 1
	v_mov_b32_e32 v96, v176
	v_mov_b32_e32 v97, v177
	v_mov_b32_e32 v98, v178
	v_mov_b32_e32 v99, v179
	s_mov_b64 s[2:3], 0x30000
	s_waitcnt lgkmcnt(0)
	v_lshlrev_b32_e32 v104, 16, v96
	v_and_b32_e32 v105, 0xffff0000, v96
	v_lshlrev_b32_e32 v96, 16, v97
	v_and_b32_e32 v97, 0xffff0000, v97
	v_lshlrev_b32_e32 v106, 16, v98
	v_and_b32_e32 v107, 0xffff0000, v98
	v_lshlrev_b32_e32 v98, 16, v99
	v_and_b32_e32 v99, 0xffff0000, v99
	v_pk_add_f32 v[94:95], v[94:95], v[96:97]
	v_pk_add_f32 v[92:93], v[92:93], v[104:105]
	v_pk_add_f32 v[96:97], v[90:91], v[98:99]
	v_pk_add_f32 v[90:91], v[88:89], v[106:107]
	v_cvt_pk_bf16_f32 v88, v92, v93
	v_cvt_pk_bf16_f32 v89, v94, v95
	v_cvt_pk_bf16_f32 v90, v90, v91
	v_cvt_pk_bf16_f32 v91, v96, v97
	global_store_dwordx4 v[102:103], v[88:91], off
	s_waitcnt vmcnt(15)
	s_nop 1
	v_mov_b32_e32 v88, v180
	v_mov_b32_e32 v89, v181
	v_mov_b32_e32 v90, v182
	v_mov_b32_e32 v91, v183
	s_waitcnt lgkmcnt(0)
	v_lshlrev_b32_e32 v92, 16, v88
	v_and_b32_e32 v93, 0xffff0000, v88
	v_lshlrev_b32_e32 v88, 16, v89
	v_and_b32_e32 v89, 0xffff0000, v89
	v_lshlrev_b32_e32 v94, 16, v90
	v_and_b32_e32 v95, 0xffff0000, v90
	v_lshlrev_b32_e32 v90, 16, v91
	v_and_b32_e32 v91, 0xffff0000, v91
	v_pk_add_f32 v[86:87], v[86:87], v[88:89]
	v_pk_add_f32 v[84:85], v[84:85], v[92:93]
	v_pk_add_f32 v[88:89], v[82:83], v[90:91]
	v_pk_add_f32 v[82:83], v[80:81], v[94:95]
	v_cvt_pk_bf16_f32 v80, v84, v85
	v_cvt_pk_bf16_f32 v81, v86, v87
	v_cvt_pk_bf16_f32 v82, v82, v83
	v_cvt_pk_bf16_f32 v83, v88, v89
	global_store_dwordx4 v[100:101], v[80:83], off offset:256
	s_nop 1
	v_lshl_add_u64 v[80:81], v[144:145], 0, s[2:3]
	s_mov_b32 s2, 0x30000
	v_add_co_u32_e32 v86, vcc, s2, v144
	s_mov_b64 s[2:3], 0x80000
	s_nop 0
	v_addc_co_u32_e32 v87, vcc, 0, v145, vcc
	s_waitcnt vmcnt(15)
	s_nop 1
	v_mov_b32_e32 v82, v184
	v_mov_b32_e32 v83, v185
	v_mov_b32_e32 v84, v186
	v_mov_b32_e32 v85, v187
	s_waitcnt lgkmcnt(0)
	v_lshlrev_b32_e32 v88, 16, v82
	v_and_b32_e32 v89, 0xffff0000, v82
	v_lshlrev_b32_e32 v82, 16, v83
	v_and_b32_e32 v83, 0xffff0000, v83
	v_lshlrev_b32_e32 v90, 16, v84
	v_and_b32_e32 v91, 0xffff0000, v84
	v_lshlrev_b32_e32 v84, 16, v85
	v_and_b32_e32 v85, 0xffff0000, v85
	v_pk_add_f32 v[78:79], v[78:79], v[82:83]
	v_pk_add_f32 v[76:77], v[76:77], v[88:89]
	v_pk_add_f32 v[82:83], v[74:75], v[84:85]
	v_pk_add_f32 v[74:75], v[72:73], v[90:91]
	v_cvt_pk_bf16_f32 v72, v76, v77
	v_cvt_pk_bf16_f32 v73, v78, v79
	v_cvt_pk_bf16_f32 v74, v74, v75
	v_cvt_pk_bf16_f32 v75, v82, v83
	global_store_dwordx4 v[86:87], v[72:75], off
	s_waitcnt vmcnt(15)
	s_nop 1
	v_mov_b32_e32 v72, v188
	v_mov_b32_e32 v73, v189
	v_mov_b32_e32 v74, v190
	v_mov_b32_e32 v75, v191
	s_waitcnt lgkmcnt(0)
; DI unsigned pack2(float a, float b) { f32x2 v = {a, b}; hwbf16x2 r = __builtin_convertvector(v, hwbf16x2); return __builtin_bit_cast(unsigned, r); }
; DI float bflo(unsigned w) { return __uint_as_float(w << 16); }
; DI float bfhi(unsigned w) { return __uint_as_float(w & 0xffff0000u); }
;     DI void operator()(const f32x4 (&acc)[2][2][4][2], const Unit& u, int wr, int wc, int fr, int fq) const {
;     ...
;         for (int ai = 0; ai < 2; ++ai)
; #pragma unroll
;             for (int m = 0; m < 4; ++m) { const size_t ro = (size_t)(row0 + ai * HALF + m * 16) * D + col0;
; #pragma unroll
;                 for (int bj = 0; bj < 2; ++bj) {
;                     f32x4 x0, x1;
;                     if constexpr (IB) { const u32x4 w = *(const u32x4*)((const bf16_t*)Xin + ro + bj * HALF);
;                         x0 = (f32x4){bflo(w[0]), bfhi(w[0]), bflo(w[1]), bfhi(w[1])}; x1 = (f32x4){bflo(w[2]), bfhi(w[2]), bflo(w[3]), bfhi(w[3])}; }
;                     else { x0 = *(const f32x4*)((const float*)Xin + ro + bj * HALF); x1 = *(const f32x4*)((const float*)Xin + ro + bj * HALF + 4); }
;                     x0 += acc[ai][bj][m][0] * sc[bj][0]; x1 += acc[ai][bj][m][1] * sc[bj][1];
;                     if constexpr (OB) { u32x4 o; o[0] = pack2(x0[0], x0[1]); o[1] = pack2(x0[2], x0[3]); o[2] = pack2(x1[0], x1[1]); o[3] = pack2(x1[2], x1[3]);
;                         *(u32x4*)((bf16_t*)Xout + ro + bj * HALF) = o; }
;                     else { *(f32x4*)((float*)Xout + ro + bj * HALF) = x0; *(f32x4*)((float*)Xout + ro + bj * HALF + 4) = x1; } } }
	v_lshlrev_b32_e32 v76, 16, v72
	v_and_b32_e32 v77, 0xffff0000, v72
	v_lshlrev_b32_e32 v72, 16, v73
	v_and_b32_e32 v73, 0xffff0000, v73
	v_lshlrev_b32_e32 v78, 16, v74
	v_and_b32_e32 v79, 0xffff0000, v74
	v_lshlrev_b32_e32 v74, 16, v75
	v_and_b32_e32 v75, 0xffff0000, v75
	v_pk_add_f32 v[70:71], v[70:71], v[72:73]
	v_pk_add_f32 v[68:69], v[68:69], v[76:77]
	v_pk_add_f32 v[72:73], v[66:67], v[74:75]
	v_pk_add_f32 v[66:67], v[64:65], v[78:79]
	v_cvt_pk_bf16_f32 v64, v68, v69
	v_cvt_pk_bf16_f32 v65, v70, v71
	v_cvt_pk_bf16_f32 v66, v66, v67
	v_cvt_pk_bf16_f32 v67, v72, v73
	global_store_dwordx4 v[80:81], v[64:67], off offset:256
	s_nop 1
	v_lshl_add_u64 v[64:65], v[144:145], 0, s[2:3]
	s_mov_b32 s2, 0x80000
	v_add_co_u32_e32 v70, vcc, s2, v144
	s_mov_b64 s[2:3], 0x90000
	s_nop 0
	v_addc_co_u32_e32 v71, vcc, 0, v145, vcc
	s_waitcnt vmcnt(15)
	s_nop 1
	v_mov_b32_e32 v66, v192
	v_mov_b32_e32 v67, v193
	v_mov_b32_e32 v68, v194
	v_mov_b32_e32 v69, v195
	s_waitcnt lgkmcnt(0)
	v_lshlrev_b32_e32 v72, 16, v66
	v_and_b32_e32 v73, 0xffff0000, v66
	v_lshlrev_b32_e32 v66, 16, v67
	v_and_b32_e32 v67, 0xffff0000, v67
	v_lshlrev_b32_e32 v74, 16, v68
	v_and_b32_e32 v75, 0xffff0000, v68
	v_lshlrev_b32_e32 v68, 16, v69
	v_and_b32_e32 v69, 0xffff0000, v69
	v_pk_add_f32 v[62:63], v[62:63], v[66:67]
	v_pk_add_f32 v[60:61], v[60:61], v[72:73]
	v_pk_add_f32 v[66:67], v[58:59], v[68:69]
	v_pk_add_f32 v[58:59], v[56:57], v[74:75]
	v_cvt_pk_bf16_f32 v56, v60, v61
	v_cvt_pk_bf16_f32 v57, v62, v63
	v_cvt_pk_bf16_f32 v58, v58, v59
	v_cvt_pk_bf16_f32 v59, v66, v67
	global_store_dwordx4 v[70:71], v[56:59], off
	s_waitcnt vmcnt(15)
	s_nop 1
	v_mov_b32_e32 v56, v198
	v_mov_b32_e32 v57, v199
	v_mov_b32_e32 v58, v200
	v_mov_b32_e32 v59, v201
	s_waitcnt lgkmcnt(0)
	v_lshlrev_b32_e32 v60, 16, v56
	v_and_b32_e32 v61, 0xffff0000, v56
	v_lshlrev_b32_e32 v56, 16, v57
	v_and_b32_e32 v57, 0xffff0000, v57
	v_lshlrev_b32_e32 v62, 16, v58
	v_and_b32_e32 v63, 0xffff0000, v58
	v_lshlrev_b32_e32 v58, 16, v59
	v_and_b32_e32 v59, 0xffff0000, v59
	v_pk_add_f32 v[54:55], v[54:55], v[56:57]
	v_pk_add_f32 v[52:53], v[52:53], v[60:61]
	v_pk_add_f32 v[56:57], v[50:51], v[58:59]
	v_pk_add_f32 v[50:51], v[48:49], v[62:63]
	v_cvt_pk_bf16_f32 v48, v52, v53
	v_cvt_pk_bf16_f32 v49, v54, v55
	v_cvt_pk_bf16_f32 v50, v50, v51
	v_cvt_pk_bf16_f32 v51, v56, v57
	global_store_dwordx4 v[64:65], v[48:51], off offset:256
	s_nop 1
	v_lshl_add_u64 v[48:49], v[144:145], 0, s[2:3]
	s_mov_b32 s2, 0x90000
	v_add_co_u32_e32 v54, vcc, s2, v144
	s_mov_b64 s[2:3], 0xa0000
	s_nop 0
	v_addc_co_u32_e32 v55, vcc, 0, v145, vcc
	s_waitcnt vmcnt(15)
	s_nop 1
	v_mov_b32_e32 v50, v202
	v_mov_b32_e32 v51, v203
	v_mov_b32_e32 v52, v204
	v_mov_b32_e32 v53, v205
	s_waitcnt lgkmcnt(0)
	v_lshlrev_b32_e32 v56, 16, v50
	v_and_b32_e32 v57, 0xffff0000, v50
	v_lshlrev_b32_e32 v50, 16, v51
	v_and_b32_e32 v51, 0xffff0000, v51
	v_lshlrev_b32_e32 v58, 16, v52
	v_and_b32_e32 v59, 0xffff0000, v52
	v_lshlrev_b32_e32 v52, 16, v53
	v_and_b32_e32 v53, 0xffff0000, v53
	v_pk_add_f32 v[46:47], v[46:47], v[50:51]
	v_pk_add_f32 v[44:45], v[44:45], v[56:57]
	v_pk_add_f32 v[50:51], v[42:43], v[52:53]
	v_pk_add_f32 v[42:43], v[40:41], v[58:59]
	v_cvt_pk_bf16_f32 v40, v44, v45
	v_cvt_pk_bf16_f32 v41, v46, v47
	v_cvt_pk_bf16_f32 v42, v42, v43
	v_cvt_pk_bf16_f32 v43, v50, v51
	global_store_dwordx4 v[54:55], v[40:43], off
	s_waitcnt vmcnt(15)
	s_nop 1
	v_mov_b32_e32 v40, v206
	v_mov_b32_e32 v41, v207
	v_mov_b32_e32 v42, v208
	v_mov_b32_e32 v43, v209
	s_waitcnt lgkmcnt(0)
; DI unsigned pack2(float a, float b) { f32x2 v = {a, b}; hwbf16x2 r = __builtin_convertvector(v, hwbf16x2); return __builtin_bit_cast(unsigned, r); }
; DI float bflo(unsigned w) { return __uint_as_float(w << 16); }
; DI float bfhi(unsigned w) { return __uint_as_float(w & 0xffff0000u); }
;     DI const char* a(const Unit& u) const { return (const char*)(A + (size_t)u.pm * BM * lda); }
;     DI const char* a(const Unit& u) const { return (const char*)(A + (size_t)u.pm * BM * 2048 + (u.pn >> 1) * 512); }
;     DI void operator()(const f32x4 (&acc)[2][2][4][2], const Unit& u, int wr, int wc, int fr, int fq) const {
;     ...
;         for (int ai = 0; ai < 2; ++ai)
; #pragma unroll
;             for (int m = 0; m < 4; ++m) { const size_t ro = (size_t)(row0 + ai * HALF + m * 16) * D + col0;
; #pragma unroll
;                 for (int bj = 0; bj < 2; ++bj) {
;                     f32x4 x0, x1;
;                     if constexpr (IB) { const u32x4 w = *(const u32x4*)((const bf16_t*)Xin + ro + bj * HALF);
;                         x0 = (f32x4){bflo(w[0]), bfhi(w[0]), bflo(w[1]), bfhi(w[1])}; x1 = (f32x4){bflo(w[2]), bfhi(w[2]), bflo(w[3]), bfhi(w[3])}; }
;                     else { x0 = *(const f32x4*)((const float*)Xin + ro + bj * HALF); x1 = *(const f32x4*)((const float*)Xin + ro + bj * HALF + 4); }
;                     x0 += acc[ai][bj][m][0] * sc[bj][0]; x1 += acc[ai][bj][m][1] * sc[bj][1];
;                     if constexpr (OB) { u32x4 o; o[0] = pack2(x0[0], x0[1]); o[1] = pack2(x0[2], x0[3]); o[2] = pack2(x1[0], x1[1]); o[3] = pack2(x1[2], x1[3]);
;                         *(u32x4*)((bf16_t*)Xout + ro + bj * HALF) = o; }
;                     else { *(f32x4*)((float*)Xout + ro + bj * HALF) = x0; *(f32x4*)((float*)Xout + ro + bj * HALF + 4) = x1; } } }
; template <class Map, class Epi>
; DI void gemm_phase(LAS unsigned char* lds, const Map& MP, const Epi& E, const int nM, const int nN, const int K, const int lda, const int ldb) {
;     ...
;         if (!has_next) break;
; #pragma unroll
;         for (int a = 0; a < 2; ++a)
; #pragma unroll
;             for (int b = 0; b < 2; ++b)
; #pragma unroll
;                 for (int m = 0; m < 4; ++m)
; #pragma unroll
;                     for (int n = 0; n < 2; ++n) acc[a][b][m][n] = (f32x4){0.f, 0.f, 0.f, 0.f};
;         cur = nxt; cA = nA; cB = nB; ++ui;
;     }
;     PG8_WAIT_V(0);
;     if (wr == 0) PG8_BAR;
;     PG8_BAR;
	v_lshlrev_b32_e32 v44, 16, v40
	v_and_b32_e32 v45, 0xffff0000, v40
	v_lshlrev_b32_e32 v40, 16, v41
	v_and_b32_e32 v41, 0xffff0000, v41
	v_lshlrev_b32_e32 v46, 16, v42
	v_and_b32_e32 v47, 0xffff0000, v42
	v_lshlrev_b32_e32 v42, 16, v43
	v_and_b32_e32 v43, 0xffff0000, v43
	v_pk_add_f32 v[38:39], v[38:39], v[40:41]
	v_pk_add_f32 v[36:37], v[36:37], v[44:45]
	v_pk_add_f32 v[40:41], v[34:35], v[42:43]
	v_pk_add_f32 v[34:35], v[32:33], v[46:47]
	v_cvt_pk_bf16_f32 v32, v36, v37
	v_cvt_pk_bf16_f32 v33, v38, v39
	v_cvt_pk_bf16_f32 v34, v34, v35
	v_cvt_pk_bf16_f32 v35, v40, v41
	global_store_dwordx4 v[48:49], v[32:35], off offset:256
	s_nop 1
	v_lshl_add_u64 v[32:33], v[144:145], 0, s[2:3]
	s_mov_b32 s2, 0xa0000
	v_add_co_u32_e32 v38, vcc, s2, v144
	s_mov_b64 s[2:3], 0xb0000
	s_nop 0
	v_addc_co_u32_e32 v39, vcc, 0, v145, vcc
	s_waitcnt vmcnt(15)
	s_nop 1
	v_mov_b32_e32 v34, v210
	v_mov_b32_e32 v35, v211
	v_mov_b32_e32 v36, v212
	v_mov_b32_e32 v37, v213
	s_waitcnt lgkmcnt(0)
	v_lshlrev_b32_e32 v40, 16, v34
	v_and_b32_e32 v41, 0xffff0000, v34
	v_lshlrev_b32_e32 v34, 16, v35
	v_and_b32_e32 v35, 0xffff0000, v35
	v_lshlrev_b32_e32 v42, 16, v36
	v_and_b32_e32 v43, 0xffff0000, v36
	v_lshlrev_b32_e32 v36, 16, v37
	v_and_b32_e32 v37, 0xffff0000, v37
	v_pk_add_f32 v[30:31], v[30:31], v[34:35]
	v_pk_add_f32 v[28:29], v[28:29], v[40:41]
	v_pk_add_f32 v[34:35], v[26:27], v[36:37]
	v_pk_add_f32 v[26:27], v[24:25], v[42:43]
	v_cvt_pk_bf16_f32 v24, v28, v29
	v_cvt_pk_bf16_f32 v25, v30, v31
	v_cvt_pk_bf16_f32 v26, v26, v27
	v_cvt_pk_bf16_f32 v27, v34, v35
	global_store_dwordx4 v[38:39], v[24:27], off
	s_waitcnt vmcnt(15)
	s_nop 1
	v_mov_b32_e32 v24, v214
	v_mov_b32_e32 v25, v215
	v_mov_b32_e32 v26, v216
	v_mov_b32_e32 v27, v217
	s_waitcnt lgkmcnt(0)
	v_lshlrev_b32_e32 v28, 16, v24
	v_and_b32_e32 v29, 0xffff0000, v24
	v_lshlrev_b32_e32 v24, 16, v25
	v_and_b32_e32 v25, 0xffff0000, v25
	v_lshlrev_b32_e32 v30, 16, v26
	v_and_b32_e32 v31, 0xffff0000, v26
	v_lshlrev_b32_e32 v26, 16, v27
	v_and_b32_e32 v27, 0xffff0000, v27
	v_pk_add_f32 v[22:23], v[22:23], v[24:25]
	v_pk_add_f32 v[20:21], v[20:21], v[28:29]
	v_pk_add_f32 v[24:25], v[18:19], v[26:27]
	v_pk_add_f32 v[18:19], v[16:17], v[30:31]
	v_cvt_pk_bf16_f32 v16, v20, v21
	v_cvt_pk_bf16_f32 v17, v22, v23
	v_cvt_pk_bf16_f32 v18, v18, v19
	v_cvt_pk_bf16_f32 v19, v24, v25
	global_store_dwordx4 v[32:33], v[16:19], off offset:256
	s_nop 1
	v_lshl_add_u64 v[16:17], v[144:145], 0, s[2:3]
	s_mov_b32 s2, 0xb0000
	v_add_co_u32_e32 v22, vcc, s2, v144
	s_mov_b32 s2, s46
	s_nop 0
	v_addc_co_u32_e32 v23, vcc, 0, v145, vcc
	s_waitcnt vmcnt(15)
	s_nop 1
	v_mov_b32_e32 v18, v248
	v_mov_b32_e32 v19, v249
	v_mov_b32_e32 v20, v250
	v_mov_b32_e32 v21, v251
	s_and_b64 vcc, exec, s[40:41]
	s_waitcnt lgkmcnt(0)
	v_lshlrev_b32_e32 v24, 16, v18
	v_and_b32_e32 v25, 0xffff0000, v18
	v_lshlrev_b32_e32 v18, 16, v19
	v_and_b32_e32 v19, 0xffff0000, v19
	v_lshlrev_b32_e32 v26, 16, v20
	v_and_b32_e32 v27, 0xffff0000, v20
	v_lshlrev_b32_e32 v20, 16, v21
	v_and_b32_e32 v21, 0xffff0000, v21
	v_pk_add_f32 v[14:15], v[14:15], v[18:19]
	v_pk_add_f32 v[12:13], v[12:13], v[24:25]
	v_pk_add_f32 v[18:19], v[10:11], v[20:21]
	v_pk_add_f32 v[10:11], v[8:9], v[26:27]
	v_cvt_pk_bf16_f32 v8, v12, v13
	v_cvt_pk_bf16_f32 v9, v14, v15
	v_cvt_pk_bf16_f32 v10, v10, v11
	v_cvt_pk_bf16_f32 v11, v18, v19
	global_store_dwordx4 v[22:23], v[8:11], off
	s_waitcnt vmcnt(15)
	s_nop 1
	v_mov_b32_e32 v8, v252
	v_mov_b32_e32 v9, v253
	v_mov_b32_e32 v10, v254
	v_mov_b32_e32 v11, v255
	s_waitcnt lgkmcnt(0)
	v_lshlrev_b32_e32 v12, 16, v8
	v_and_b32_e32 v13, 0xffff0000, v8
	v_lshlrev_b32_e32 v8, 16, v9
	v_and_b32_e32 v9, 0xffff0000, v9
	v_lshlrev_b32_e32 v14, 16, v10
	v_and_b32_e32 v15, 0xffff0000, v10
	v_lshlrev_b32_e32 v10, 16, v11
	v_and_b32_e32 v11, 0xffff0000, v11
	v_pk_add_f32 v[6:7], v[6:7], v[8:9]
	v_pk_add_f32 v[4:5], v[4:5], v[12:13]
	v_pk_add_f32 v[8:9], v[2:3], v[10:11]
	v_pk_add_f32 v[2:3], v[0:1], v[14:15]
	v_cvt_pk_bf16_f32 v0, v4, v5
	v_cvt_pk_bf16_f32 v1, v6, v7
	v_cvt_pk_bf16_f32 v2, v2, v3
	v_cvt_pk_bf16_f32 v3, v8, v9
	global_store_dwordx4 v[16:17], v[0:3], off offset:256
	s_cbranch_vccz .LBB1_922
	s_waitcnt vmcnt(0)
	s_cmpk_gt_u32 s17, 0xff
	s_cbranch_scc1 .LBB1_929
	s_barrier

; #define PG8_STAGE(bufoff, gbase, voff) do { _Pragma("unroll") for (int _i = 0; _i < 2; ++_i) \
;         __builtin_amdgcn_global_load_lds((const unsigned*)((const char*)(gbase) + (voff)[_i]), (LAS unsigned*)(lds + (bufoff) + ldsw + _i * 8192), 16, 0, 0); } while (0)
; #define PG8_LDA(dst, b, h) do { _Pragma("unroll") for (int m = 0; m < 4; ++m) _Pragma("unroll") for (int k = 0; k < 2; ++k) dst[m][k] = *(const LAS bf16x8*)(lds + PG8_SA(b, h) + aoff + m * 2048 + k * 1024); } while (0)
; #define PG8_LDB(dst, b, h) do { _Pragma("unroll") for (int n = 0; n < 2; ++n) _Pragma("unroll") for (int k = 0; k < 2; ++k) dst[n][k] = *(const LAS bf16x8*)(lds + PG8_SB(b, h) + boff + n * 2048 + k * 1024); } while (0)
; #define PG8_MMA(ai, bj, At, Bt) do { __builtin_amdgcn_s_setprio(1); _Pragma("unroll") for (int m = 0; m < 4; ++m) _Pragma("unroll") for (int n = 0; n < 2; ++n) _Pragma("unroll") for (int k = 0; k < 2; ++k) \
;         acc[ai][bj][m][n] = __builtin_amdgcn_mfma_f32_16x16x32_bf16(Bt[n][k], At[m][k], acc[ai][bj][m][n], 0, 0, 0); __builtin_amdgcn_s_setprio(0); } while (0)
; #define PG8_WAIT_V(n) asm volatile("s_waitcnt vmcnt(" #n ")" ::: "memory")
; #define PG8_WAIT_L(n) asm volatile("s_waitcnt lgkmcnt(" #n ")" ::: "memory")
; template <class Map, class Epi>
; DI void gemm_phase(LAS unsigned char* lds, const Map& MP, const Epi& E, const int nM, const int nN, const int K, const int lda, const int ldb) {
;     ...
;         for (int t = 0; t < nt; t += 2) {
;             const bool last = (t == nt - 2);
;             const char* a1 = cA + (size_t)(t + 1) * kstep;
;             const char* a2 = last ? nA : cA + (size_t)(t + 2) * kstep; const char* b2 = last ? nB : cB + (size_t)(t + 2) * kstep;
;             const char* a3 = a2 + kstep; const char* b3 = b2 + kstep;
;             PG8_LDB(B0, 0, 0); PG8_SCHED; PG8_LDA(At, 0, 0); PG8_STAGE(PG8_SA(1, 1), a1 + hstepA, voffA);
;             PG8_WAIT_L(8); PG8_BAR; PG8_WAIT_L(0); PG8_MMA(0, 0, At, B0); PG8_BAR; PG8_SCHED;
;             PG8_LDB(B1, 0, 1); PG8_STAGE(PG8_SB(0, 0), b2, voffB);
;             PG8_BAR; PG8_WAIT_L(0); PG8_MMA(0, 1, At, B1); PG8_BAR;
;             PG8_LDA(At, 0, 1); PG8_STAGE(PG8_SA(0, 0), a2, voffA);
;             PG8_BAR; PG8_WAIT_L(0); PG8_MMA(1, 0, At, B0); PG8_BAR; PG8_SCHED;
;             PG8_STAGE(PG8_SB(0, 1), b2 + hstepB, voffB);
;             PG8_WAIT_V(6); PG8_BAR; PG8_MMA(1, 1, At, B1); PG8_BAR;
.LBB1_1069:
	s_add_i32 m0, s38, 0xc000
	ds_read_b128 v[96:99], v190
	ds_read_b128 v[100:103], v190 offset:1024
	ds_read_b128 v[108:111], v190 offset:2048
	ds_read_b128 v[112:115], v190 offset:3072
	ds_read_b128 v[160:163], v190 offset:4096
	ds_read_b128 v[164:167], v190 offset:5120
	ds_read_b128 v[198:201], v190 offset:6144
	ds_read_b128 v[202:205], v190 offset:7168
	global_load_lds_dwordx4 v178, s[42:43]
	s_add_i32 m0, s38, 0xe000
	s_setprio 1
	global_load_lds_dwordx4 v176, s[42:43]
	s_waitcnt lgkmcnt(8)
	s_barrier
	s_waitcnt lgkmcnt(7)
	v_mfma_f32_16x16x32_bf16 v[148:151], v[80:83], v[96:99], v[148:151]
	v_mfma_f32_16x16x32_bf16 v[144:147], v[88:91], v[96:99], v[144:147]
	s_waitcnt lgkmcnt(5)
	v_mfma_f32_16x16x32_bf16 v[136:139], v[80:83], v[108:111], v[136:139]
	v_mfma_f32_16x16x32_bf16 v[128:131], v[88:91], v[108:111], v[128:131]
	s_waitcnt lgkmcnt(3)
	v_mfma_f32_16x16x32_bf16 v[120:123], v[80:83], v[160:163], v[120:123]
	v_mfma_f32_16x16x32_bf16 v[104:107], v[88:91], v[160:163], v[104:107]
	s_waitcnt lgkmcnt(1)
	v_mfma_f32_16x16x32_bf16 v[76:79], v[80:83], v[198:201], v[76:79]
	v_mfma_f32_16x16x32_bf16 v[72:75], v[88:91], v[198:201], v[72:75]
	v_mfma_f32_16x16x32_bf16 v[148:151], v[84:87], v[100:103], v[148:151]
	s_add_i32 s68, s31, s66
	v_mfma_f32_16x16x32_bf16 v[144:147], v[92:95], v[100:103], v[144:147]
	v_lshl_add_u64 v[184:185], s[24:25], 0, v[172:173]
	v_mfma_f32_16x16x32_bf16 v[136:139], v[84:87], v[112:115], v[136:139]
	v_lshl_add_u64 v[194:195], s[24:25], 0, v[168:169]
	v_mfma_f32_16x16x32_bf16 v[128:131], v[92:95], v[112:115], v[128:131]
	v_mfma_f32_16x16x32_bf16 v[120:123], v[84:87], v[164:167], v[120:123]
	v_mfma_f32_16x16x32_bf16 v[104:107], v[92:95], v[164:167], v[104:107]
	s_waitcnt lgkmcnt(0)
	v_mfma_f32_16x16x32_bf16 v[76:79], v[84:87], v[202:205], v[76:79]
	v_mfma_f32_16x16x32_bf16 v[72:75], v[92:95], v[202:205], v[72:75]
	s_barrier
	s_setprio 0
	s_mov_b32 m0, s68
	ds_read_b128 v[206:209], v191
	ds_read_b128 v[210:213], v191 offset:1024
	ds_read_b128 v[214:217], v191 offset:2048
	ds_read_b128 v[218:221], v191 offset:3072
	global_load_lds_dwordx4 v[184:185], off
	s_add_i32 m0, s68, 0x2000
	s_setprio 1
	global_load_lds_dwordx4 v[194:195], off
	s_barrier
	s_waitcnt lgkmcnt(3)
	v_mfma_f32_16x16x32_bf16 v[156:159], v[206:209], v[96:99], v[156:159]
	s_waitcnt lgkmcnt(1)
	v_mfma_f32_16x16x32_bf16 v[96:99], v[214:217], v[96:99], v[152:155]
	v_mfma_f32_16x16x32_bf16 v[156:159], v[210:213], v[100:103], v[156:159]
	s_waitcnt lgkmcnt(0)
	v_mfma_f32_16x16x32_bf16 v[96:99], v[218:221], v[100:103], v[96:99]
	v_mfma_f32_16x16x32_bf16 v[100:103], v[206:209], v[108:111], v[140:143]
	v_mfma_f32_16x16x32_bf16 v[108:111], v[214:217], v[108:111], v[132:135]
	v_mfma_f32_16x16x32_bf16 v[116:119], v[214:217], v[160:163], v[116:119]
	v_mfma_f32_16x16x32_bf16 v[68:71], v[206:209], v[198:201], v[68:71]
	v_mfma_f32_16x16x32_bf16 v[64:67], v[214:217], v[198:201], v[64:67]
	v_lshl_add_u64 v[234:235], s[46:47], 0, v[170:171]
	s_mov_b32 m0, s38
	v_mfma_f32_16x16x32_bf16 v[100:103], v[210:213], v[112:115], v[100:103]
	v_lshl_add_u64 v[226:227], s[46:47], 0, v[174:175]
	v_mfma_f32_16x16x32_bf16 v[108:111], v[218:221], v[112:115], v[108:111]
	v_mfma_f32_16x16x32_bf16 v[112:115], v[206:209], v[160:163], v[124:127]
	v_mfma_f32_16x16x32_bf16 v[116:119], v[218:221], v[164:167], v[116:119]
	v_mfma_f32_16x16x32_bf16 v[68:71], v[210:213], v[202:205], v[68:71]
	v_mfma_f32_16x16x32_bf16 v[64:67], v[218:221], v[202:205], v[64:67]
	v_mfma_f32_16x16x32_bf16 v[112:115], v[210:213], v[164:167], v[112:115]
	s_barrier
	s_setprio 0
	ds_read_b128 v[124:127], v190 offset:16384
	ds_read_b128 v[132:135], v190 offset:17408
	ds_read_b128 v[140:143], v190 offset:18432
	ds_read_b128 v[152:155], v190 offset:19456
	ds_read_b128 v[160:163], v190 offset:20480
	ds_read_b128 v[164:167], v190 offset:21504
	ds_read_b128 v[198:201], v190 offset:22528
	ds_read_b128 v[202:205], v190 offset:23552
	global_load_lds_dwordx4 v[226:227], off
	s_mov_b32 m0, s39
	s_setprio 1
	global_load_lds_dwordx4 v[234:235], off
	s_waitcnt vmcnt(10)
	s_barrier
	s_waitcnt lgkmcnt(7)
	v_mfma_f32_16x16x32_bf16 v[60:63], v[80:83], v[124:127], v[60:63]
	v_mfma_f32_16x16x32_bf16 v[48:51], v[88:91], v[124:127], v[48:51]
	s_waitcnt lgkmcnt(5)
	v_mfma_f32_16x16x32_bf16 v[40:43], v[80:83], v[140:143], v[40:43]
	v_mfma_f32_16x16x32_bf16 v[32:35], v[88:91], v[140:143], v[32:35]
	s_waitcnt lgkmcnt(3)
	v_mfma_f32_16x16x32_bf16 v[24:27], v[80:83], v[160:163], v[24:27]
	v_mfma_f32_16x16x32_bf16 v[16:19], v[88:91], v[160:163], v[16:19]
	s_waitcnt lgkmcnt(1)
	v_mfma_f32_16x16x32_bf16 v[12:15], v[80:83], v[198:201], v[12:15]
	v_mfma_f32_16x16x32_bf16 v[8:11], v[88:91], v[198:201], v[8:11]
	v_mfma_f32_16x16x32_bf16 v[60:63], v[84:87], v[132:135], v[60:63]
	s_add_u32 s68, s24, 0x80000
	s_addc_u32 s69, s25, 0
	v_mfma_f32_16x16x32_bf16 v[48:51], v[92:95], v[132:135], v[48:51]
	s_add_i32 s70, s2, s66
	v_mfma_f32_16x16x32_bf16 v[40:43], v[84:87], v[152:155], v[40:43]
	v_mfma_f32_16x16x32_bf16 v[32:35], v[92:95], v[152:155], v[32:35]
	v_mfma_f32_16x16x32_bf16 v[24:27], v[84:87], v[164:167], v[24:27]
	v_mfma_f32_16x16x32_bf16 v[16:19], v[92:95], v[164:167], v[16:19]
	s_waitcnt lgkmcnt(0)
	v_mfma_f32_16x16x32_bf16 v[12:15], v[84:87], v[202:205], v[12:15]
	v_mfma_f32_16x16x32_bf16 v[8:11], v[92:95], v[202:205], v[8:11]
	s_barrier
	s_setprio 0
	s_mov_b32 m0, s70
	s_nop 0
	global_load_lds_dwordx4 v172, s[68:69]
	s_add_i32 m0, s70, 0x2000
	s_setprio 1
	global_load_lds_dwordx4 v168, s[68:69]
	s_waitcnt vmcnt(6)
	s_barrier
; #define PG8_STAGE(bufoff, gbase, voff) do { _Pragma("unroll") for (int _i = 0; _i < 2; ++_i) \
;         __builtin_amdgcn_global_load_lds((const unsigned*)((const char*)(gbase) + (voff)[_i]), (LAS unsigned*)(lds + (bufoff) + ldsw + _i * 8192), 16, 0, 0); } while (0)
; #define PG8_LDA(dst, b, h) do { _Pragma("unroll") for (int m = 0; m < 4; ++m) _Pragma("unroll") for (int k = 0; k < 2; ++k) dst[m][k] = *(const LAS bf16x8*)(lds + PG8_SA(b, h) + aoff + m * 2048 + k * 1024); } while (0)
; #define PG8_LDB(dst, b, h) do { _Pragma("unroll") for (int n = 0; n < 2; ++n) _Pragma("unroll") for (int k = 0; k < 2; ++k) dst[n][k] = *(const LAS bf16x8*)(lds + PG8_SB(b, h) + boff + n * 2048 + k * 1024); } while (0)
; #define PG8_MMA(ai, bj, At, Bt) do { __builtin_amdgcn_s_setprio(1); _Pragma("unroll") for (int m = 0; m < 4; ++m) _Pragma("unroll") for (int n = 0; n < 2; ++n) _Pragma("unroll") for (int k = 0; k < 2; ++k) \
;         acc[ai][bj][m][n] = __builtin_amdgcn_mfma_f32_16x16x32_bf16(Bt[n][k], At[m][k], acc[ai][bj][m][n], 0, 0, 0); __builtin_amdgcn_s_setprio(0); } while (0)
; #define PG8_WAIT_V(n) asm volatile("s_waitcnt vmcnt(" #n ")" ::: "memory")
; #define PG8_WAIT_L(n) asm volatile("s_waitcnt lgkmcnt(" #n ")" ::: "memory")
; #define PG8_BAR __builtin_amdgcn_s_barrier()
; #define PG8_SCHED __builtin_amdgcn_sched_barrier(0)
; template <class Map, class Epi>
; DI void gemm_phase(LAS unsigned char* lds, const Map& MP, const Epi& E, const int nM, const int nN, const int K, const int lda, const int ldb) {
;     ...
;             PG8_WAIT_V(6); PG8_BAR; PG8_MMA(1, 1, At, B1); PG8_BAR;
;             PG8_LDB(B0, 1, 0); PG8_SCHED; PG8_LDA(At, 1, 0); PG8_STAGE(PG8_SA(0, 1), a2 + hstepA, voffA);
;             PG8_WAIT_L(8); PG8_BAR; PG8_WAIT_L(0); PG8_MMA(0, 0, At, B0); PG8_BAR; PG8_SCHED;
;             PG8_LDB(B1, 1, 1); PG8_STAGE(PG8_SB(1, 0), b3, voffB);
;             PG8_BAR; PG8_WAIT_L(0); PG8_MMA(0, 1, At, B1); PG8_BAR;
;             PG8_LDA(At, 1, 1); PG8_STAGE(PG8_SA(1, 0), a3, voffA);
;             PG8_BAR; PG8_WAIT_L(0); PG8_MMA(1, 0, At, B0); PG8_BAR; PG8_SCHED;
	v_mfma_f32_16x16x32_bf16 v[56:59], v[206:209], v[124:127], v[56:59]
	v_mfma_f32_16x16x32_bf16 v[52:55], v[214:217], v[124:127], v[52:55]
	s_add_i32 s68, 0, 0x18000
	v_add_u32_e32 v92, s68, v188
	ds_read_b128 v[80:83], v92
	v_mfma_f32_16x16x32_bf16 v[44:47], v[206:209], v[140:143], v[44:47]
	v_mfma_f32_16x16x32_bf16 v[36:39], v[214:217], v[140:143], v[36:39]
	ds_read_b128 v[84:87], v92 offset:1024
	v_mfma_f32_16x16x32_bf16 v[28:31], v[206:209], v[160:163], v[28:31]
	v_mfma_f32_16x16x32_bf16 v[20:23], v[214:217], v[160:163], v[20:23]
	ds_read_b128 v[88:91], v92 offset:2048
	v_mfma_f32_16x16x32_bf16 v[4:7], v[206:209], v[198:201], v[4:7]
	v_mfma_f32_16x16x32_bf16 v[0:3], v[214:217], v[198:201], v[0:3]
	ds_read_b128 v[92:95], v92 offset:3072
	v_mfma_f32_16x16x32_bf16 v[56:59], v[210:213], v[132:135], v[56:59]
	s_add_u32 s46, s46, 0x80000
	s_addc_u32 s47, s47, 0
	v_mfma_f32_16x16x32_bf16 v[52:55], v[218:221], v[132:135], v[52:55]
	v_mfma_f32_16x16x32_bf16 v[44:47], v[210:213], v[152:155], v[44:47]
	v_mfma_f32_16x16x32_bf16 v[36:39], v[218:221], v[152:155], v[36:39]
	v_mfma_f32_16x16x32_bf16 v[28:31], v[210:213], v[164:167], v[28:31]
	v_mfma_f32_16x16x32_bf16 v[20:23], v[218:221], v[164:167], v[20:23]
	v_mfma_f32_16x16x32_bf16 v[4:7], v[210:213], v[202:205], v[4:7]
	v_mfma_f32_16x16x32_bf16 v[0:3], v[218:221], v[202:205], v[0:3]
	s_barrier
	s_setprio 0
	s_mov_b32 m0, s56
	ds_read_b128 v[124:127], v190 offset:32768
	ds_read_b128 v[132:135], v190 offset:33792
	ds_read_b128 v[160:163], v190 offset:34816
	ds_read_b128 v[164:167], v190 offset:35840
	ds_read_b128 v[198:201], v190 offset:36864
	ds_read_b128 v[202:205], v190 offset:37888
	ds_read_b128 v[206:209], v190 offset:38912
	ds_read_b128 v[210:213], v190 offset:39936
	global_load_lds_dwordx4 v174, s[46:47]
	s_mov_b32 m0, s57
	s_setprio 1
	global_load_lds_dwordx4 v170, s[46:47]
	s_waitcnt lgkmcnt(8)
	s_barrier
	s_waitcnt lgkmcnt(7)
	v_mfma_f32_16x16x32_bf16 v[140:143], v[80:83], v[124:127], v[148:151]
	s_waitcnt lgkmcnt(6)
	v_mfma_f32_16x16x32_bf16 v[148:151], v[84:87], v[132:135], v[140:143]
	v_mfma_f32_16x16x32_bf16 v[140:143], v[88:91], v[124:127], v[144:147]
	s_waitcnt lgkmcnt(5)
	v_mfma_f32_16x16x32_bf16 v[136:139], v[80:83], v[160:163], v[136:139]
	v_mfma_f32_16x16x32_bf16 v[128:131], v[88:91], v[160:163], v[128:131]
	s_waitcnt lgkmcnt(3)
	v_mfma_f32_16x16x32_bf16 v[120:123], v[80:83], v[198:201], v[120:123]
	v_mfma_f32_16x16x32_bf16 v[104:107], v[88:91], v[198:201], v[104:107]
	s_waitcnt lgkmcnt(1)
	v_mfma_f32_16x16x32_bf16 v[76:79], v[80:83], v[206:209], v[76:79]
	v_mfma_f32_16x16x32_bf16 v[72:75], v[88:91], v[206:209], v[72:75]
	s_add_i32 s46, 0, 0x1c000
	v_mfma_f32_16x16x32_bf16 v[144:147], v[92:95], v[132:135], v[140:143]
	v_add_u32_e32 v140, s46, v188
	v_mfma_f32_16x16x32_bf16 v[136:139], v[84:87], v[164:167], v[136:139]
	s_add_i32 s47, s68, s66
	v_mfma_f32_16x16x32_bf16 v[128:131], v[92:95], v[164:167], v[128:131]
	v_mfma_f32_16x16x32_bf16 v[120:123], v[84:87], v[202:205], v[120:123]
	v_mfma_f32_16x16x32_bf16 v[104:107], v[92:95], v[202:205], v[104:107]
	s_waitcnt lgkmcnt(0)
	v_mfma_f32_16x16x32_bf16 v[76:79], v[84:87], v[210:213], v[76:79]
	v_mfma_f32_16x16x32_bf16 v[72:75], v[92:95], v[210:213], v[72:75]
	s_barrier
	s_setprio 0
	ds_read_b128 v[214:217], v140
	ds_read_b128 v[218:221], v140 offset:1024
	ds_read_b128 v[222:225], v140 offset:2048
	ds_read_b128 v[230:233], v140 offset:3072
	v_lshl_add_u64 v[140:141], v[184:185], 0, s[14:15]
	s_mov_b32 m0, s47
	s_nop 0
	global_load_lds_dwordx4 v[140:141], off
	v_lshl_add_u64 v[140:141], v[194:195], 0, s[14:15]
	s_add_i32 m0, s47, 0x2000
	s_setprio 1
	global_load_lds_dwordx4 v[140:141], off
	s_barrier
	s_waitcnt lgkmcnt(1)
	v_mfma_f32_16x16x32_bf16 v[96:99], v[222:225], v[124:127], v[96:99]
	v_mfma_f32_16x16x32_bf16 v[140:143], v[214:217], v[124:127], v[156:159]
	s_waitcnt lgkmcnt(0)
	v_mfma_f32_16x16x32_bf16 v[152:155], v[230:233], v[132:135], v[96:99]
	v_mfma_f32_16x16x32_bf16 v[96:99], v[214:217], v[160:163], v[100:103]
	v_mfma_f32_16x16x32_bf16 v[156:159], v[218:221], v[132:135], v[140:143]
	v_mfma_f32_16x16x32_bf16 v[140:143], v[218:221], v[164:167], v[96:99]
	v_mfma_f32_16x16x32_bf16 v[96:99], v[222:225], v[160:163], v[108:111]
	v_mfma_f32_16x16x32_bf16 v[132:135], v[230:233], v[164:167], v[96:99]
	v_mfma_f32_16x16x32_bf16 v[96:99], v[214:217], v[198:201], v[112:115]
	s_mov_b32 m0, s63
	v_mfma_f32_16x16x32_bf16 v[124:127], v[218:221], v[202:205], v[96:99]
	v_lshl_add_u64 v[184:185], v[226:227], 0, s[14:15]
	v_mfma_f32_16x16x32_bf16 v[96:99], v[222:225], v[198:201], v[116:119]
	v_mfma_f32_16x16x32_bf16 v[68:71], v[214:217], v[206:209], v[68:71]
	v_mfma_f32_16x16x32_bf16 v[64:67], v[222:225], v[206:209], v[64:67]
	v_mfma_f32_16x16x32_bf16 v[116:119], v[230:233], v[202:205], v[96:99]
	v_mfma_f32_16x16x32_bf16 v[68:71], v[218:221], v[210:213], v[68:71]
	v_mfma_f32_16x16x32_bf16 v[64:67], v[230:233], v[210:213], v[64:67]
	s_barrier
	s_setprio 0
	ds_read_b128 v[96:99], v190 offset:49152
	ds_read_b128 v[100:103], v190 offset:50176
	ds_read_b128 v[108:111], v190 offset:51200
	ds_read_b128 v[112:115], v190 offset:52224
	ds_read_b128 v[160:163], v190 offset:53248
	ds_read_b128 v[164:167], v190 offset:54272
	ds_read_b128 v[198:201], v190 offset:55296
	ds_read_b128 v[202:205], v190 offset:56320
	global_load_lds_dwordx4 v[184:185], off
	v_lshl_add_u64 v[184:185], v[234:235], 0, s[14:15]
	s_mov_b32 m0, s4
	s_setprio 1
	global_load_lds_dwordx4 v[184:185], off
	s_waitcnt vmcnt(10)
	s_barrier
; #define PG8_STAGE(bufoff, gbase, voff) do { _Pragma("unroll") for (int _i = 0; _i < 2; ++_i) \
;         __builtin_amdgcn_global_load_lds((const unsigned*)((const char*)(gbase) + (voff)[_i]), (LAS unsigned*)(lds + (bufoff) + ldsw + _i * 8192), 16, 0, 0); } while (0)
; #define PG8_LDA(dst, b, h) do { _Pragma("unroll") for (int m = 0; m < 4; ++m) _Pragma("unroll") for (int k = 0; k < 2; ++k) dst[m][k] = *(const LAS bf16x8*)(lds + PG8_SA(b, h) + aoff + m * 2048 + k * 1024); } while (0)
; #define PG8_WAIT_V(n) asm volatile("s_waitcnt vmcnt(" #n ")" ::: "memory")
; #define PG8_WAIT_L(n) asm volatile("s_waitcnt lgkmcnt(" #n ")" ::: "memory")
; template <class Map, class Epi>
; DI void gemm_phase(LAS unsigned char* lds, const Map& MP, const Epi& E, const int nM, const int nN, const int K, const int lda, const int ldb) {
;     ...
;             const bool last = (t == nt - 2);
;             const char* a1 = cA + (size_t)(t + 1) * kstep;
;             const char* a2 = last ? nA : cA + (size_t)(t + 2) * kstep; const char* b2 = last ? nB : cB + (size_t)(t + 2) * kstep;
;             const char* a3 = a2 + kstep; const char* b3 = b2 + kstep;
;             PG8_LDB(B0, 0, 0); PG8_SCHED; PG8_LDA(At, 0, 0); PG8_STAGE(PG8_SA(1, 1), a1 + hstepA, voffA);
;             PG8_WAIT_L(8); PG8_BAR; PG8_WAIT_L(0); PG8_MMA(0, 0, At, B0); PG8_BAR; PG8_SCHED;
;             PG8_LDB(B1, 0, 1); PG8_STAGE(PG8_SB(0, 0), b2, voffB);
;             PG8_BAR; PG8_WAIT_L(0); PG8_MMA(0, 1, At, B1); PG8_BAR;
;             PG8_LDA(At, 0, 1); PG8_STAGE(PG8_SA(0, 0), a2, voffA);
;             PG8_BAR; PG8_WAIT_L(0); PG8_MMA(1, 0, At, B0); PG8_BAR; PG8_SCHED;
;             PG8_STAGE(PG8_SB(0, 1), b2 + hstepB, voffB);
;             PG8_WAIT_V(6); PG8_BAR; PG8_MMA(1, 1, At, B1); PG8_BAR;
;             PG8_LDB(B0, 1, 0); PG8_SCHED; PG8_LDA(At, 1, 0); PG8_STAGE(PG8_SA(0, 1), a2 + hstepA, voffA);
;             PG8_WAIT_L(8); PG8_BAR; PG8_WAIT_L(0); PG8_MMA(0, 0, At, B0); PG8_BAR; PG8_SCHED;
;             PG8_LDB(B1, 1, 1); PG8_STAGE(PG8_SB(1, 0), b3, voffB);
;             PG8_BAR; PG8_WAIT_L(0); PG8_MMA(0, 1, At, B1); PG8_BAR;
;             PG8_LDA(At, 1, 1); PG8_STAGE(PG8_SA(1, 0), a3, voffA);
;             PG8_BAR; PG8_WAIT_L(0); PG8_MMA(1, 0, At, B0); PG8_BAR; PG8_SCHED;
;             PG8_STAGE(PG8_SB(1, 1), b3 + hstepB, voffB);
;             PG8_WAIT_V(6); PG8_BAR; PG8_MMA(1, 1, At, B1); PG8_BAR;
	s_waitcnt lgkmcnt(7)
	v_mfma_f32_16x16x32_bf16 v[60:63], v[80:83], v[96:99], v[60:63]
	v_mfma_f32_16x16x32_bf16 v[48:51], v[88:91], v[96:99], v[48:51]
	s_waitcnt lgkmcnt(5)
	v_mfma_f32_16x16x32_bf16 v[40:43], v[80:83], v[108:111], v[40:43]
	v_mfma_f32_16x16x32_bf16 v[32:35], v[88:91], v[108:111], v[32:35]
	s_waitcnt lgkmcnt(3)
	v_mfma_f32_16x16x32_bf16 v[24:27], v[80:83], v[160:163], v[24:27]
	v_mfma_f32_16x16x32_bf16 v[16:19], v[88:91], v[160:163], v[16:19]
	s_waitcnt lgkmcnt(1)
	v_mfma_f32_16x16x32_bf16 v[12:15], v[80:83], v[198:201], v[12:15]
	v_mfma_f32_16x16x32_bf16 v[8:11], v[88:91], v[198:201], v[8:11]
	v_mfma_f32_16x16x32_bf16 v[60:63], v[84:87], v[100:103], v[60:63]
	s_add_u32 s24, s24, 0x80080
	s_addc_u32 s25, s25, 0
	v_mfma_f32_16x16x32_bf16 v[48:51], v[92:95], v[100:103], v[48:51]
	s_add_i32 s46, s46, s66
	v_mfma_f32_16x16x32_bf16 v[40:43], v[84:87], v[112:115], v[40:43]
	v_mfma_f32_16x16x32_bf16 v[32:35], v[92:95], v[112:115], v[32:35]
	v_mfma_f32_16x16x32_bf16 v[24:27], v[84:87], v[164:167], v[24:27]
	v_mfma_f32_16x16x32_bf16 v[16:19], v[92:95], v[164:167], v[16:19]
	s_waitcnt lgkmcnt(0)
	v_mfma_f32_16x16x32_bf16 v[12:15], v[84:87], v[202:205], v[12:15]
	v_mfma_f32_16x16x32_bf16 v[8:11], v[92:95], v[202:205], v[8:11]
	s_barrier
	s_setprio 0
	s_mov_b32 m0, s46
	s_nop 0
	global_load_lds_dwordx4 v172, s[24:25]
	s_add_i32 m0, s46, 0x2000
	s_setprio 1
	global_load_lds_dwordx4 v168, s[24:25]
	s_waitcnt vmcnt(6)
	s_barrier
	v_mfma_f32_16x16x32_bf16 v[56:59], v[214:217], v[96:99], v[56:59]
	v_mfma_f32_16x16x32_bf16 v[52:55], v[222:225], v[96:99], v[52:55]
	ds_read_b128 v[80:83], v189
	v_mfma_f32_16x16x32_bf16 v[44:47], v[214:217], v[108:111], v[44:47]
	v_mfma_f32_16x16x32_bf16 v[36:39], v[222:225], v[108:111], v[36:39]
	ds_read_b128 v[84:87], v189 offset:1024
	v_mfma_f32_16x16x32_bf16 v[28:31], v[214:217], v[160:163], v[28:31]
	v_mfma_f32_16x16x32_bf16 v[20:23], v[222:225], v[160:163], v[20:23]
	ds_read_b128 v[88:91], v189 offset:2048
	v_mfma_f32_16x16x32_bf16 v[4:7], v[214:217], v[198:201], v[4:7]
	v_mfma_f32_16x16x32_bf16 v[0:3], v[222:225], v[198:201], v[0:3]
	ds_read_b128 v[92:95], v189 offset:3072
	v_mfma_f32_16x16x32_bf16 v[56:59], v[218:221], v[100:103], v[56:59]
	s_add_i32 s3, s3, 2
	v_mfma_f32_16x16x32_bf16 v[52:55], v[230:233], v[100:103], v[52:55]
	s_add_u32 vcc_lo, vcc_lo, 0x100
	s_addc_u32 vcc_hi, vcc_hi, 0
	v_mfma_f32_16x16x32_bf16 v[44:47], v[218:221], v[112:115], v[44:47]
	s_add_u32 s42, s42, 0x100
	s_addc_u32 s43, s43, 0
	v_mfma_f32_16x16x32_bf16 v[36:39], v[230:233], v[112:115], v[36:39]
	s_add_u32 s24, s42, 0xfff80080
	s_addc_u32 s25, s43, -1
	s_cmp_eq_u32 s3, 28
	s_cselect_b32 s47, s23, s25
	s_cselect_b32 s46, s58, s24
	s_cselect_b32 s25, s21, vcc_hi
	s_cselect_b32 s24, s59, vcc_lo
	s_cmp_gt_u32 s3, 29
	v_mfma_f32_16x16x32_bf16 v[28:31], v[218:221], v[164:167], v[28:31]
	v_mfma_f32_16x16x32_bf16 v[20:23], v[230:233], v[164:167], v[20:23]
	v_mfma_f32_16x16x32_bf16 v[4:7], v[218:221], v[202:205], v[4:7]
	v_mfma_f32_16x16x32_bf16 v[0:3], v[230:233], v[202:205], v[0:3]
	s_barrier
	s_setprio 0
	s_cbranch_scc0 .LBB1_1069
; DI float silu_mul(float g, float v) { return g * v * __builtin_amdgcn_rcpf(1.0f + __builtin_amdgcn_exp2f(-LOG2E * g)); }
;     DI void operator()(const f32x4 (&acc)[2][2][4][2], const Unit& u, int wr, int wc, int fr, int fq) const {
;         const int row0 = u.pm * BM + wr * 64 + fr, ch0 = u.pn * 128 + wc * 32 + 8 * fq;
;         f32x4 w0[2], w1[2], w2[2], bb[2];
; #pragma unroll
;         for (int n = 0; n < 2; ++n) { w0[n] = *(const f32x4*)(cw + ch0 + 4 * n); w1[n] = *(const f32x4*)(cw + DFF + ch0 + 4 * n); w2[n] = *(const f32x4*)(cw + 2 * DFF + ch0 + 4 * n); bb[n] = *(const f32x4*)(cb + ch0 + 4 * n); }
; #pragma unroll
;         for (int ai = 0; ai < 2; ++ai)
; #pragma unroll
;             for (int m = 0; m < 4; ++m) {
;                 const bool efirst = (m == 0) && (fr == 0), elast = (m == 3) && (fr == 15);
;                 const int row = row0 + ai * HALF + m * 16;
;                 f32x4 gc[2];
; #pragma unroll
;                 for (int n = 0; n < 2; ++n) {
;                     const f32x4 g = acc[ai][0][m][n];
;                     const f32x4 gprev = acc[ai][0][m > 0 ? m - 1 : 0][n], gnext = acc[ai][0][m < 3 ? m + 1 : 3][n];
;                     f32x4 up, dn;
; #pragma unroll
;                     for (int e = 0; e < 4; ++e) {
;                         const float pu = (m > 0 && fr == 15) ? gprev[e] : g[e];
;                         const float pd = (m < 3 && fr == 0) ? gnext[e] : g[e];
;                         up[e] = dpp_ror1(pu); dn[e] = dpp_ror15(pd);
;                     }
;                     if (efirst) up = (f32x4){0.f, 0.f, 0.f, 0.f};
;                     if (elast) dn = (f32x4){0.f, 0.f, 0.f, 0.f};
;                     gc[n] = w0[n] * up + w1[n] * g + w2[n] * dn + bb[n];
;                 }
;                 if (efirst || elast) {
;                     const size_t eo = (size_t)((row >> 6) * 2 + (elast ? 1 : 0)) * DFF + ch0;
; #pragma unroll
;                     for (int n = 0; n < 2; ++n) { *(f32x4*)(EP + eo + 4 * n) = gc[n]; *(f32x4*)(ER + eo + 4 * n) = acc[ai][0][m][n]; *(f32x4*)(EV + eo + 4 * n) = acc[ai][1][m][n]; }
;                 } else {
;                     const f32x4 v0 = acc[ai][1][m][0], v1 = acc[ai][1][m][1];
;                     u32x4 o;
;                     o[0] = pack2(silu_mul(gc[0][0], v0[0]), silu_mul(gc[0][1], v0[1])); o[1] = pack2(silu_mul(gc[0][2], v0[2]), silu_mul(gc[0][3], v0[3]));
	s_waitcnt lgkmcnt(0)
	s_lshl_b32 s21, s45, 7
	v_mov_b32_e32 v194, v186
	v_mov_b32_e32 v80, v187
	s_or_b32 s21, s21, s62
	v_lshl_add_u32 v184, v80, 3, s21
	v_ashrrev_i32_e32 v185, 31, v184
	v_lshlrev_b64 v[80:81], 2, v[184:185]
	v_lshl_add_u64 v[84:85], s[6:7], 0, v[80:81]
	v_lshl_add_u64 v[88:89], s[16:17], 0, v[80:81]
	v_lshl_add_u64 v[92:93], s[18:19], 0, v[80:81]
	v_lshl_add_u64 v[112:113], s[52:53], 0, v[80:81]
	global_load_dwordx4 v[80:83], v[84:85], off offset:16
	global_load_dwordx4 v[96:99], v[84:85], off
	s_nop 0
	global_load_dwordx4 v[84:87], v[88:89], off offset:16
	global_load_dwordx4 v[100:103], v[88:89], off
	s_nop 0
	global_load_dwordx4 v[88:91], v[92:93], off offset:16
	global_load_dwordx4 v[108:111], v[92:93], off
	s_nop 0
	global_load_dwordx4 v[92:95], v[112:113], off offset:16
	s_nop 0
	global_load_dwordx4 v[112:115], v[112:113], off
	v_cmp_eq_u32_e32 vcc, 0, v194
	s_nop 0
	s_nop 0
	v_cndmask_b32_e32 v161, v148, v136, vcc
	v_cndmask_b32_e32 v162, v149, v137, vcc
	v_cndmask_b32_e32 v163, v150, v138, vcc
	v_mov_b32_dpp v160, v161 row_ror:15 row_mask:0xf bank_mask:0xf
	s_nop 0
	s_nop 0
	v_mov_b32_dpp v161, v162 row_ror:15 row_mask:0xf bank_mask:0xf
	v_mov_b32_dpp v164, v150 row_ror:1 row_mask:0xf bank_mask:0xf
	v_cndmask_b32_e32 v165, v151, v139, vcc
	v_mov_b32_dpp v162, v163 row_ror:15 row_mask:0xf bank_mask:0xf
	v_mov_b32_dpp v195, v151 row_ror:1 row_mask:0xf bank_mask:0xf
	v_mov_b32_dpp v166, v148 row_ror:1 row_mask:0xf bank_mask:0xf
	v_mov_b32_dpp v167, v149 row_ror:1 row_mask:0xf bank_mask:0xf
	v_mov_b32_dpp v163, v165 row_ror:15 row_mask:0xf bank_mask:0xf
	v_cndmask_b32_e64 v165, v195, 0, vcc
	v_cndmask_b32_e64 v164, v164, 0, vcc
	v_cndmask_b32_e64 v167, v167, 0, vcc
	v_cndmask_b32_e64 v166, v166, 0, vcc
	s_nop 0
	s_nop 0
	v_mov_b32_dpp v195, v144 row_ror:1 row_mask:0xf bank_mask:0xf
	v_mov_b32_dpp v196, v145 row_ror:1 row_mask:0xf bank_mask:0xf
	v_mov_b32_dpp v198, v146 row_ror:1 row_mask:0xf bank_mask:0xf
	v_cndmask_b32_e32 v199, v147, v131, vcc
	v_mov_b32_dpp v200, v147 row_ror:1 row_mask:0xf bank_mask:0xf
	v_cndmask_b32_e64 v198, v198, 0, vcc
	v_cndmask_b32_e64 v201, v196, 0, vcc
	s_lshl_b32 s3, s44, 8
	s_add_i32 s3, s3, s49
	v_add_u32_e32 v193, s3, v194
	v_cmp_ne_u32_e64 s[46:47], 0, v194
	s_waitcnt vmcnt(0)
	v_pk_mul_f32 v[164:165], v[98:99], v[164:165]
	v_pk_mul_f32 v[166:167], v[96:97], v[166:167]
	v_pk_fma_f32 v[164:165], v[150:151], v[102:103], v[164:165]
	v_pk_fma_f32 v[166:167], v[148:149], v[100:101], v[166:167]
	v_pk_fma_f32 v[162:163], v[110:111], v[162:163], v[164:165]
	v_cndmask_b32_e32 v165, v144, v128, vcc
	v_pk_fma_f32 v[160:161], v[108:109], v[160:161], v[166:167]
	v_cndmask_b32_e32 v166, v145, v129, vcc
	v_mov_b32_dpp v164, v165 row_ror:15 row_mask:0xf bank_mask:0xf
	v_cndmask_b32_e32 v167, v146, v130, vcc
	v_pk_add_f32 v[162:163], v[114:115], v[162:163]
	v_mov_b32_dpp v165, v166 row_ror:15 row_mask:0xf bank_mask:0xf
	v_pk_add_f32 v[160:161], v[112:113], v[160:161]
	s_nop 0
	v_mov_b32_dpp v166, v167 row_ror:15 row_mask:0xf bank_mask:0xf
	s_nop 1
	v_mov_b32_dpp v167, v199 row_ror:15 row_mask:0xf bank_mask:0xf
	v_cndmask_b32_e64 v199, v200, 0, vcc
	v_cndmask_b32_e64 v200, v195, 0, vcc
	v_pk_mul_f32 v[200:201], v[80:81], v[200:201]
	v_pk_mul_f32 v[198:199], v[82:83], v[198:199]
	v_pk_fma_f32 v[200:201], v[144:145], v[84:85], v[200:201]
	v_pk_fma_f32 v[198:199], v[146:147], v[86:87], v[198:199]
	v_pk_fma_f32 v[164:165], v[88:89], v[164:165], v[200:201]
	v_pk_fma_f32 v[166:167], v[90:91], v[166:167], v[198:199]
	v_pk_add_f32 v[164:165], v[92:93], v[164:165]
	v_pk_add_f32 v[166:167], v[94:95], v[166:167]
	s_and_saveexec_b64 s[24:25], s[46:47]
	s_xor_b64 s[24:25], exec, s[24:25]
	s_cbranch_execz .LBB1_1072
	v_mul_f32_e32 v195, 0xbfb8aa3b, v160
	v_exp_f32_e32 v195, v195
	v_mul_f32_e32 v196, 0xbfb8aa3b, v161
	v_exp_f32_e32 v196, v196
	v_pk_mul_f32 v[160:161], v[156:157], v[160:161]
	v_add_f32_e32 v195, 1.0, v195
	v_rcp_f32_e32 v198, v195
	v_add_f32_e32 v196, 1.0, v196
	v_mul_f32_e32 v195, 0xbfb8aa3b, v162
	v_rcp_f32_e32 v199, v196
	v_exp_f32_e32 v195, v195
	v_mul_f32_e32 v196, 0xbfb8aa3b, v163
	v_exp_f32_e32 v196, v196
	v_pk_mul_f32 v[160:161], v[160:161], v[198:199]
	v_add_f32_e32 v195, 1.0, v195
	v_rcp_f32_e32 v200, v195
	v_add_f32_e32 v195, 1.0, v196
	v_rcp_f32_e32 v201, v195
	v_cvt_pk_bf16_f32 v160, v160, v161
	v_mul_f32_e32 v161, 0xbfb8aa3b, v164
	v_exp_f32_e32 v195, v161
	v_mul_f32_e32 v161, 0xbfb8aa3b, v165
	v_exp_f32_e32 v196, v161
	v_pk_mul_f32 v[162:163], v[158:159], v[162:163]
	v_pk_mul_f32 v[164:165], v[152:153], v[164:165]
	v_pk_mul_f32 v[162:163], v[162:163], v[200:201]
	s_nop 0
	v_cvt_pk_bf16_f32 v161, v162, v163
	v_add_f32_e32 v162, 1.0, v195
	v_mul_f32_e32 v195, 0xbfb8aa3b, v166
	v_add_f32_e32 v163, 1.0, v196
	v_exp_f32_e32 v195, v195
	v_mul_f32_e32 v196, 0xbfb8aa3b, v167
	v_exp_f32_e32 v196, v196
	v_rcp_f32_e32 v162, v162
	v_add_f32_e32 v195, 1.0, v195
	v_rcp_f32_e32 v198, v195
	v_add_f32_e32 v195, 1.0, v196
	v_rcp_f32_e32 v163, v163
	v_rcp_f32_e32 v199, v195
	v_pk_mul_f32 v[166:167], v[154:155], v[166:167]
	v_pk_mul_f32 v[162:163], v[164:165], v[162:163]
	v_pk_mul_f32 v[164:165], v[166:167], v[198:199]
	v_cvt_pk_bf16_f32 v162, v162, v163
	v_cvt_pk_bf16_f32 v163, v164, v165
	v_mov_b64_e32 v[164:165], s[54:55]
	v_mad_i64_i32 v[164:165], s[42:43], v193, s60, v[164:165]
	v_lshl_add_u64 v[164:165], v[184:185], 1, v[164:165]
	global_store_dwordx4 v[164:165], v[160:163], off

; #define PG8_STAGE(bufoff, gbase, voff) do { _Pragma("unroll") for (int _i = 0; _i < 2; ++_i) \
;         __builtin_amdgcn_global_load_lds((const unsigned*)((const char*)(gbase) + (voff)[_i]), (LAS unsigned*)(lds + (bufoff) + ldsw + _i * 8192), 16, 0, 0); } while (0)
; #define PG8_LDA(dst, b, h) do { _Pragma("unroll") for (int m = 0; m < 4; ++m) _Pragma("unroll") for (int k = 0; k < 2; ++k) dst[m][k] = *(const LAS bf16x8*)(lds + PG8_SA(b, h) + aoff + m * 2048 + k * 1024); } while (0)
; #define PG8_LDB(dst, b, h) do { _Pragma("unroll") for (int n = 0; n < 2; ++n) _Pragma("unroll") for (int k = 0; k < 2; ++k) dst[n][k] = *(const LAS bf16x8*)(lds + PG8_SB(b, h) + boff + n * 2048 + k * 1024); } while (0)
; #define PG8_MMA(ai, bj, At, Bt) do { __builtin_amdgcn_s_setprio(1); _Pragma("unroll") for (int m = 0; m < 4; ++m) _Pragma("unroll") for (int n = 0; n < 2; ++n) _Pragma("unroll") for (int k = 0; k < 2; ++k) \
;         acc[ai][bj][m][n] = __builtin_amdgcn_mfma_f32_16x16x32_bf16(Bt[n][k], At[m][k], acc[ai][bj][m][n], 0, 0, 0); __builtin_amdgcn_s_setprio(0); } while (0)
; #define PG8_WAIT_V(n) asm volatile("s_waitcnt vmcnt(" #n ")" ::: "memory")
; #define PG8_WAIT_L(n) asm volatile("s_waitcnt lgkmcnt(" #n ")" ::: "memory")
; template <class Map, class Epi>
; DI void gemm_phase(LAS unsigned char* lds, const Map& MP, const Epi& E, const int nM, const int nN, const int K, const int lda, const int ldb) {
;     ...
;         for (int t = 0; t < nt; t += 2) {
;             const bool last = (t == nt - 2);
;             const char* a1 = cA + (size_t)(t + 1) * kstep;
;             const char* a2 = last ? nA : cA + (size_t)(t + 2) * kstep; const char* b2 = last ? nB : cB + (size_t)(t + 2) * kstep;
;             const char* a3 = a2 + kstep; const char* b3 = b2 + kstep;
;             PG8_LDB(B0, 0, 0); PG8_SCHED; PG8_LDA(At, 0, 0); PG8_STAGE(PG8_SA(1, 1), a1 + hstepA, voffA);
;             PG8_WAIT_L(8); PG8_BAR; PG8_WAIT_L(0); PG8_MMA(0, 0, At, B0); PG8_BAR; PG8_SCHED;
;             PG8_LDB(B1, 0, 1); PG8_STAGE(PG8_SB(0, 0), b2, voffB);
;             PG8_BAR; PG8_WAIT_L(0); PG8_MMA(0, 1, At, B1); PG8_BAR;
;             PG8_LDA(At, 0, 1); PG8_STAGE(PG8_SA(0, 0), a2, voffA);
;             PG8_BAR; PG8_WAIT_L(0); PG8_MMA(1, 0, At, B0); PG8_BAR; PG8_SCHED;
;             PG8_STAGE(PG8_SB(0, 1), b2 + hstepB, voffB);
;             PG8_WAIT_V(6); PG8_BAR; PG8_MMA(1, 1, At, B1); PG8_BAR;
.LBB1_1382:
	s_add_i32 m0, s31, 0xc000
	ds_read_b128 v[166:169], v148
	ds_read_b128 v[170:173], v148 offset:1024
	ds_read_b128 v[174:177], v148 offset:2048
	ds_read_b128 v[178:181], v148 offset:3072
	ds_read_b128 v[182:185], v148 offset:4096
	ds_read_b128 v[186:189], v148 offset:5120
	ds_read_b128 v[190:193], v148 offset:6144
	ds_read_b128 v[198:201], v148 offset:7168
	global_load_lds_dwordx4 v138, s[20:21]
	s_add_i32 m0, s31, 0xe000
	s_setprio 1
	global_load_lds_dwordx4 v136, s[20:21]
	s_waitcnt lgkmcnt(8)
	s_barrier
	s_waitcnt lgkmcnt(7)
	v_mfma_f32_16x16x32_bf16 v[124:127], v[150:153], v[166:169], v[124:127]
	v_mfma_f32_16x16x32_bf16 v[120:123], v[158:161], v[166:169], v[120:123]
	s_waitcnt lgkmcnt(5)
	v_mfma_f32_16x16x32_bf16 v[116:119], v[150:153], v[174:177], v[116:119]
	v_mfma_f32_16x16x32_bf16 v[112:115], v[158:161], v[174:177], v[112:115]
	s_waitcnt lgkmcnt(3)
	v_mfma_f32_16x16x32_bf16 v[100:103], v[150:153], v[182:185], v[100:103]
	v_mfma_f32_16x16x32_bf16 v[96:99], v[158:161], v[182:185], v[96:99]
	s_waitcnt lgkmcnt(1)
	v_mfma_f32_16x16x32_bf16 v[84:87], v[150:153], v[190:193], v[84:87]
	v_mfma_f32_16x16x32_bf16 v[80:83], v[158:161], v[190:193], v[80:83]
	v_mfma_f32_16x16x32_bf16 v[124:127], v[154:157], v[170:173], v[124:127]
	s_add_i32 s54, s44, s29
	v_mfma_f32_16x16x32_bf16 v[120:123], v[162:165], v[170:173], v[120:123]
	v_lshl_add_u64 v[194:195], s[22:23], 0, v[132:133]
	v_mfma_f32_16x16x32_bf16 v[116:119], v[154:157], v[178:181], v[116:119]
	v_lshl_add_u64 v[218:219], s[22:23], 0, v[128:129]
	v_mfma_f32_16x16x32_bf16 v[112:115], v[162:165], v[178:181], v[112:115]
	v_mfma_f32_16x16x32_bf16 v[100:103], v[154:157], v[186:189], v[100:103]
	v_mfma_f32_16x16x32_bf16 v[96:99], v[162:165], v[186:189], v[96:99]
	s_waitcnt lgkmcnt(0)
	v_mfma_f32_16x16x32_bf16 v[84:87], v[154:157], v[198:201], v[84:87]
	v_mfma_f32_16x16x32_bf16 v[80:83], v[162:165], v[198:201], v[80:83]
	s_barrier
	s_setprio 0
	s_mov_b32 m0, s54
	ds_read_b128 v[202:205], v149
	ds_read_b128 v[206:209], v149 offset:1024
	ds_read_b128 v[210:213], v149 offset:2048
	ds_read_b128 v[214:217], v149 offset:3072
	global_load_lds_dwordx4 v[194:195], off
	s_add_i32 m0, s54, 0x2000
	s_setprio 1
	global_load_lds_dwordx4 v[218:219], off
	s_barrier
	s_waitcnt lgkmcnt(3)
	v_mfma_f32_16x16x32_bf16 v[108:111], v[202:205], v[166:169], v[108:111]
	s_waitcnt lgkmcnt(1)
	v_mfma_f32_16x16x32_bf16 v[104:107], v[210:213], v[166:169], v[104:107]
	v_mfma_f32_16x16x32_bf16 v[92:95], v[202:205], v[174:177], v[92:95]
	v_mfma_f32_16x16x32_bf16 v[88:91], v[210:213], v[174:177], v[88:91]
	v_mfma_f32_16x16x32_bf16 v[76:79], v[202:205], v[182:185], v[76:79]
	v_mfma_f32_16x16x32_bf16 v[72:75], v[210:213], v[182:185], v[72:75]
	v_mfma_f32_16x16x32_bf16 v[68:71], v[202:205], v[190:193], v[68:71]
	v_mfma_f32_16x16x32_bf16 v[64:67], v[210:213], v[190:193], v[64:67]
	v_mfma_f32_16x16x32_bf16 v[108:111], v[206:209], v[170:173], v[108:111]
	v_lshl_add_u64 v[222:223], s[24:25], 0, v[130:131]
	s_mov_b32 m0, s31
	s_waitcnt lgkmcnt(0)
	v_mfma_f32_16x16x32_bf16 v[104:107], v[214:217], v[170:173], v[104:107]
	v_lshl_add_u64 v[220:221], s[24:25], 0, v[134:135]
	v_mfma_f32_16x16x32_bf16 v[92:95], v[206:209], v[178:181], v[92:95]
	v_mfma_f32_16x16x32_bf16 v[88:91], v[214:217], v[178:181], v[88:91]
	v_mfma_f32_16x16x32_bf16 v[76:79], v[206:209], v[186:189], v[76:79]
	v_mfma_f32_16x16x32_bf16 v[72:75], v[214:217], v[186:189], v[72:75]
	v_mfma_f32_16x16x32_bf16 v[68:71], v[206:209], v[198:201], v[68:71]
	v_mfma_f32_16x16x32_bf16 v[64:67], v[214:217], v[198:201], v[64:67]
	s_barrier
	s_setprio 0
	ds_read_b128 v[166:169], v148 offset:16384
	ds_read_b128 v[170:173], v148 offset:17408
	ds_read_b128 v[174:177], v148 offset:18432
	ds_read_b128 v[178:181], v148 offset:19456
	ds_read_b128 v[182:185], v148 offset:20480
	ds_read_b128 v[186:189], v148 offset:21504
	ds_read_b128 v[190:193], v148 offset:22528
	ds_read_b128 v[198:201], v148 offset:23552
	global_load_lds_dwordx4 v[220:221], off
	s_mov_b32 m0, s11
	s_setprio 1
	global_load_lds_dwordx4 v[222:223], off
	s_waitcnt vmcnt(10)
	s_barrier
	s_waitcnt lgkmcnt(7)
	v_mfma_f32_16x16x32_bf16 v[60:63], v[150:153], v[166:169], v[60:63]
	v_mfma_f32_16x16x32_bf16 v[56:59], v[158:161], v[166:169], v[56:59]
	s_waitcnt lgkmcnt(5)
	v_mfma_f32_16x16x32_bf16 v[52:55], v[150:153], v[174:177], v[52:55]
	v_mfma_f32_16x16x32_bf16 v[48:51], v[158:161], v[174:177], v[48:51]
	s_waitcnt lgkmcnt(3)
	v_mfma_f32_16x16x32_bf16 v[36:39], v[150:153], v[182:185], v[36:39]
	v_mfma_f32_16x16x32_bf16 v[32:35], v[158:161], v[182:185], v[32:35]
	s_waitcnt lgkmcnt(1)
	v_mfma_f32_16x16x32_bf16 v[20:23], v[150:153], v[190:193], v[20:23]
	v_mfma_f32_16x16x32_bf16 v[16:19], v[158:161], v[190:193], v[16:19]
	v_mfma_f32_16x16x32_bf16 v[60:63], v[154:157], v[170:173], v[60:63]
	s_add_u32 s54, s22, 0x80000
	s_addc_u32 s55, s23, 0
	v_mfma_f32_16x16x32_bf16 v[56:59], v[162:165], v[170:173], v[56:59]
	s_add_i32 s56, s45, s29
	v_mfma_f32_16x16x32_bf16 v[52:55], v[154:157], v[178:181], v[52:55]
	v_mfma_f32_16x16x32_bf16 v[48:51], v[162:165], v[178:181], v[48:51]
	v_mfma_f32_16x16x32_bf16 v[36:39], v[154:157], v[186:189], v[36:39]
	v_mfma_f32_16x16x32_bf16 v[32:35], v[162:165], v[186:189], v[32:35]
	s_waitcnt lgkmcnt(0)
	v_mfma_f32_16x16x32_bf16 v[20:23], v[154:157], v[198:201], v[20:23]
	v_mfma_f32_16x16x32_bf16 v[16:19], v[162:165], v[198:201], v[16:19]
	s_barrier
	s_setprio 0
	s_mov_b32 m0, s56
	s_nop 0
	global_load_lds_dwordx4 v132, s[54:55]
	s_add_i32 m0, s56, 0x2000
	s_setprio 1
	global_load_lds_dwordx4 v128, s[54:55]
	s_waitcnt vmcnt(6)
	s_barrier
; #define PG8_STAGE(bufoff, gbase, voff) do { _Pragma("unroll") for (int _i = 0; _i < 2; ++_i) \
;         __builtin_amdgcn_global_load_lds((const unsigned*)((const char*)(gbase) + (voff)[_i]), (LAS unsigned*)(lds + (bufoff) + ldsw + _i * 8192), 16, 0, 0); } while (0)
; #define PG8_LDA(dst, b, h) do { _Pragma("unroll") for (int m = 0; m < 4; ++m) _Pragma("unroll") for (int k = 0; k < 2; ++k) dst[m][k] = *(const LAS bf16x8*)(lds + PG8_SA(b, h) + aoff + m * 2048 + k * 1024); } while (0)
; #define PG8_LDB(dst, b, h) do { _Pragma("unroll") for (int n = 0; n < 2; ++n) _Pragma("unroll") for (int k = 0; k < 2; ++k) dst[n][k] = *(const LAS bf16x8*)(lds + PG8_SB(b, h) + boff + n * 2048 + k * 1024); } while (0)
; #define PG8_MMA(ai, bj, At, Bt) do { __builtin_amdgcn_s_setprio(1); _Pragma("unroll") for (int m = 0; m < 4; ++m) _Pragma("unroll") for (int n = 0; n < 2; ++n) _Pragma("unroll") for (int k = 0; k < 2; ++k) \
;         acc[ai][bj][m][n] = __builtin_amdgcn_mfma_f32_16x16x32_bf16(Bt[n][k], At[m][k], acc[ai][bj][m][n], 0, 0, 0); __builtin_amdgcn_s_setprio(0); } while (0)
; #define PG8_WAIT_V(n) asm volatile("s_waitcnt vmcnt(" #n ")" ::: "memory")
; #define PG8_WAIT_L(n) asm volatile("s_waitcnt lgkmcnt(" #n ")" ::: "memory")
; #define PG8_BAR __builtin_amdgcn_s_barrier()
; #define PG8_SCHED __builtin_amdgcn_sched_barrier(0)
; template <class Map, class Epi>
; DI void gemm_phase(LAS unsigned char* lds, const Map& MP, const Epi& E, const int nM, const int nN, const int K, const int lda, const int ldb) {
;     ...
;             PG8_WAIT_V(6); PG8_BAR; PG8_MMA(1, 1, At, B1); PG8_BAR;
;             PG8_LDB(B0, 1, 0); PG8_SCHED; PG8_LDA(At, 1, 0); PG8_STAGE(PG8_SA(0, 1), a2 + hstepA, voffA);
;             PG8_WAIT_L(8); PG8_BAR; PG8_WAIT_L(0); PG8_MMA(0, 0, At, B0); PG8_BAR; PG8_SCHED;
;             PG8_LDB(B1, 1, 1); PG8_STAGE(PG8_SB(1, 0), b3, voffB);
;             PG8_BAR; PG8_WAIT_L(0); PG8_MMA(0, 1, At, B1); PG8_BAR;
;             PG8_LDA(At, 1, 1); PG8_STAGE(PG8_SA(1, 0), a3, voffA);
;             PG8_BAR; PG8_WAIT_L(0); PG8_MMA(1, 0, At, B0); PG8_BAR; PG8_SCHED;
	v_mfma_f32_16x16x32_bf16 v[44:47], v[202:205], v[166:169], v[44:47]
	v_mfma_f32_16x16x32_bf16 v[40:43], v[210:213], v[166:169], v[40:43]
	s_add_i32 s54, 0, 0x18000
	v_add_u32_e32 v162, s54, v146
	ds_read_b128 v[150:153], v162
	v_mfma_f32_16x16x32_bf16 v[28:31], v[202:205], v[174:177], v[28:31]
	v_mfma_f32_16x16x32_bf16 v[24:27], v[210:213], v[174:177], v[24:27]
	ds_read_b128 v[154:157], v162 offset:1024
	v_mfma_f32_16x16x32_bf16 v[12:15], v[202:205], v[182:185], v[12:15]
	v_mfma_f32_16x16x32_bf16 v[8:11], v[210:213], v[182:185], v[8:11]
	ds_read_b128 v[158:161], v162 offset:2048
	v_mfma_f32_16x16x32_bf16 v[4:7], v[202:205], v[190:193], v[4:7]
	v_mfma_f32_16x16x32_bf16 v[0:3], v[210:213], v[190:193], v[0:3]
	ds_read_b128 v[162:165], v162 offset:3072
	v_mfma_f32_16x16x32_bf16 v[44:47], v[206:209], v[170:173], v[44:47]
	s_add_u32 s24, s24, 0x80000
	s_addc_u32 s25, s25, 0
	v_mfma_f32_16x16x32_bf16 v[40:43], v[214:217], v[170:173], v[40:43]
	v_mfma_f32_16x16x32_bf16 v[28:31], v[206:209], v[178:181], v[28:31]
	v_mfma_f32_16x16x32_bf16 v[24:27], v[214:217], v[178:181], v[24:27]
	v_mfma_f32_16x16x32_bf16 v[12:15], v[206:209], v[186:189], v[12:15]
	v_mfma_f32_16x16x32_bf16 v[8:11], v[214:217], v[186:189], v[8:11]
	v_mfma_f32_16x16x32_bf16 v[4:7], v[206:209], v[198:201], v[4:7]
	v_mfma_f32_16x16x32_bf16 v[0:3], v[214:217], v[198:201], v[0:3]
	s_barrier
	s_setprio 0
	s_mov_b32 m0, s34
	ds_read_b128 v[166:169], v148 offset:32768
	ds_read_b128 v[170:173], v148 offset:33792
	ds_read_b128 v[174:177], v148 offset:34816
	ds_read_b128 v[178:181], v148 offset:35840
	ds_read_b128 v[182:185], v148 offset:36864
	ds_read_b128 v[186:189], v148 offset:37888
	ds_read_b128 v[190:193], v148 offset:38912
	ds_read_b128 v[198:201], v148 offset:39936
	global_load_lds_dwordx4 v134, s[24:25]
	s_mov_b32 m0, s35
	s_setprio 1
	global_load_lds_dwordx4 v130, s[24:25]
	s_waitcnt lgkmcnt(8)
	s_barrier
	s_waitcnt lgkmcnt(7)
	v_mfma_f32_16x16x32_bf16 v[124:127], v[150:153], v[166:169], v[124:127]
	v_mfma_f32_16x16x32_bf16 v[120:123], v[158:161], v[166:169], v[120:123]
	s_waitcnt lgkmcnt(5)
	v_mfma_f32_16x16x32_bf16 v[116:119], v[150:153], v[174:177], v[116:119]
	v_mfma_f32_16x16x32_bf16 v[112:115], v[158:161], v[174:177], v[112:115]
	s_waitcnt lgkmcnt(3)
	v_mfma_f32_16x16x32_bf16 v[100:103], v[150:153], v[182:185], v[100:103]
	v_mfma_f32_16x16x32_bf16 v[96:99], v[158:161], v[182:185], v[96:99]
	s_waitcnt lgkmcnt(1)
	v_mfma_f32_16x16x32_bf16 v[84:87], v[150:153], v[190:193], v[84:87]
	v_mfma_f32_16x16x32_bf16 v[80:83], v[158:161], v[190:193], v[80:83]
	v_mfma_f32_16x16x32_bf16 v[124:127], v[154:157], v[170:173], v[124:127]
	s_add_i32 s24, 0, 0x1c000
	v_mfma_f32_16x16x32_bf16 v[120:123], v[162:165], v[170:173], v[120:123]
	s_add_i32 s25, s54, s29
	v_mfma_f32_16x16x32_bf16 v[116:119], v[154:157], v[178:181], v[116:119]
	v_add_u32_e32 v196, s24, v146
	v_mfma_f32_16x16x32_bf16 v[112:115], v[162:165], v[178:181], v[112:115]
	v_lshl_add_u64 v[194:195], v[194:195], 0, s[8:9]
	v_mfma_f32_16x16x32_bf16 v[100:103], v[154:157], v[186:189], v[100:103]
	v_mfma_f32_16x16x32_bf16 v[96:99], v[162:165], v[186:189], v[96:99]
	s_waitcnt lgkmcnt(0)
	v_mfma_f32_16x16x32_bf16 v[84:87], v[154:157], v[198:201], v[84:87]
	v_mfma_f32_16x16x32_bf16 v[80:83], v[162:165], v[198:201], v[80:83]
	s_barrier
	s_setprio 0
	s_mov_b32 m0, s25
	ds_read_b128 v[202:205], v196
	ds_read_b128 v[206:209], v196 offset:1024
	ds_read_b128 v[210:213], v196 offset:2048
	ds_read_b128 v[214:217], v196 offset:3072
	global_load_lds_dwordx4 v[194:195], off
	v_lshl_add_u64 v[194:195], v[218:219], 0, s[8:9]
	s_add_i32 m0, s25, 0x2000
	s_setprio 1
	global_load_lds_dwordx4 v[194:195], off
	s_barrier
	s_waitcnt lgkmcnt(3)
	v_mfma_f32_16x16x32_bf16 v[108:111], v[202:205], v[166:169], v[108:111]
	s_waitcnt lgkmcnt(1)
	v_mfma_f32_16x16x32_bf16 v[104:107], v[210:213], v[166:169], v[104:107]
	v_mfma_f32_16x16x32_bf16 v[92:95], v[202:205], v[174:177], v[92:95]
	v_mfma_f32_16x16x32_bf16 v[88:91], v[210:213], v[174:177], v[88:91]
	v_mfma_f32_16x16x32_bf16 v[76:79], v[202:205], v[182:185], v[76:79]
	v_mfma_f32_16x16x32_bf16 v[72:75], v[210:213], v[182:185], v[72:75]
	v_mfma_f32_16x16x32_bf16 v[68:71], v[202:205], v[190:193], v[68:71]
	v_mfma_f32_16x16x32_bf16 v[64:67], v[210:213], v[190:193], v[64:67]
	v_mfma_f32_16x16x32_bf16 v[108:111], v[206:209], v[170:173], v[108:111]
	s_mov_b32 m0, s39
	s_waitcnt lgkmcnt(0)
	v_mfma_f32_16x16x32_bf16 v[104:107], v[214:217], v[170:173], v[104:107]
	v_lshl_add_u64 v[194:195], v[220:221], 0, s[8:9]
	v_mfma_f32_16x16x32_bf16 v[92:95], v[206:209], v[178:181], v[92:95]
	v_mfma_f32_16x16x32_bf16 v[88:91], v[214:217], v[178:181], v[88:91]
	v_mfma_f32_16x16x32_bf16 v[76:79], v[206:209], v[186:189], v[76:79]
	v_mfma_f32_16x16x32_bf16 v[72:75], v[214:217], v[186:189], v[72:75]
	v_mfma_f32_16x16x32_bf16 v[68:71], v[206:209], v[198:201], v[68:71]
	v_mfma_f32_16x16x32_bf16 v[64:67], v[214:217], v[198:201], v[64:67]
	s_barrier
	s_setprio 0
	ds_read_b128 v[166:169], v148 offset:49152
	ds_read_b128 v[170:173], v148 offset:50176
	ds_read_b128 v[174:177], v148 offset:51200
	ds_read_b128 v[178:181], v148 offset:52224
	ds_read_b128 v[182:185], v148 offset:53248
	ds_read_b128 v[186:189], v148 offset:54272
	ds_read_b128 v[190:193], v148 offset:55296
	ds_read_b128 v[198:201], v148 offset:56320
	global_load_lds_dwordx4 v[194:195], off
	v_lshl_add_u64 v[194:195], v[222:223], 0, s[8:9]
	s_mov_b32 m0, s42
	s_setprio 1
	global_load_lds_dwordx4 v[194:195], off
	s_waitcnt vmcnt(10)
	s_barrier
; #define PG8_STAGE(bufoff, gbase, voff) do { _Pragma("unroll") for (int _i = 0; _i < 2; ++_i) \
;         __builtin_amdgcn_global_load_lds((const unsigned*)((const char*)(gbase) + (voff)[_i]), (LAS unsigned*)(lds + (bufoff) + ldsw + _i * 8192), 16, 0, 0); } while (0)
; #define PG8_LDA(dst, b, h) do { _Pragma("unroll") for (int m = 0; m < 4; ++m) _Pragma("unroll") for (int k = 0; k < 2; ++k) dst[m][k] = *(const LAS bf16x8*)(lds + PG8_SA(b, h) + aoff + m * 2048 + k * 1024); } while (0)
; #define PG8_WAIT_V(n) asm volatile("s_waitcnt vmcnt(" #n ")" ::: "memory")
; #define PG8_WAIT_L(n) asm volatile("s_waitcnt lgkmcnt(" #n ")" ::: "memory")
; template <class Map, class Epi>
; DI void gemm_phase(LAS unsigned char* lds, const Map& MP, const Epi& E, const int nM, const int nN, const int K, const int lda, const int ldb) {
;     ...
;             const bool last = (t == nt - 2);
;             const char* a1 = cA + (size_t)(t + 1) * kstep;
;             const char* a2 = last ? nA : cA + (size_t)(t + 2) * kstep; const char* b2 = last ? nB : cB + (size_t)(t + 2) * kstep;
;             const char* a3 = a2 + kstep; const char* b3 = b2 + kstep;
;             PG8_LDB(B0, 0, 0); PG8_SCHED; PG8_LDA(At, 0, 0); PG8_STAGE(PG8_SA(1, 1), a1 + hstepA, voffA);
;             PG8_WAIT_L(8); PG8_BAR; PG8_WAIT_L(0); PG8_MMA(0, 0, At, B0); PG8_BAR; PG8_SCHED;
;             PG8_LDB(B1, 0, 1); PG8_STAGE(PG8_SB(0, 0), b2, voffB);
;             PG8_BAR; PG8_WAIT_L(0); PG8_MMA(0, 1, At, B1); PG8_BAR;
;             PG8_LDA(At, 0, 1); PG8_STAGE(PG8_SA(0, 0), a2, voffA);
;             PG8_BAR; PG8_WAIT_L(0); PG8_MMA(1, 0, At, B0); PG8_BAR; PG8_SCHED;
;             PG8_STAGE(PG8_SB(0, 1), b2 + hstepB, voffB);
;             PG8_WAIT_V(6); PG8_BAR; PG8_MMA(1, 1, At, B1); PG8_BAR;
;             PG8_LDB(B0, 1, 0); PG8_SCHED; PG8_LDA(At, 1, 0); PG8_STAGE(PG8_SA(0, 1), a2 + hstepA, voffA);
;             PG8_WAIT_L(8); PG8_BAR; PG8_WAIT_L(0); PG8_MMA(0, 0, At, B0); PG8_BAR; PG8_SCHED;
;             PG8_LDB(B1, 1, 1); PG8_STAGE(PG8_SB(1, 0), b3, voffB);
;             PG8_BAR; PG8_WAIT_L(0); PG8_MMA(0, 1, At, B1); PG8_BAR;
;             PG8_LDA(At, 1, 1); PG8_STAGE(PG8_SA(1, 0), a3, voffA);
;             PG8_BAR; PG8_WAIT_L(0); PG8_MMA(1, 0, At, B0); PG8_BAR; PG8_SCHED;
;             PG8_STAGE(PG8_SB(1, 1), b3 + hstepB, voffB);
;             PG8_WAIT_V(6); PG8_BAR; PG8_MMA(1, 1, At, B1); PG8_BAR;
	s_waitcnt lgkmcnt(7)
	v_mfma_f32_16x16x32_bf16 v[60:63], v[150:153], v[166:169], v[60:63]
	v_mfma_f32_16x16x32_bf16 v[56:59], v[158:161], v[166:169], v[56:59]
	s_waitcnt lgkmcnt(5)
	v_mfma_f32_16x16x32_bf16 v[52:55], v[150:153], v[174:177], v[52:55]
	v_mfma_f32_16x16x32_bf16 v[48:51], v[158:161], v[174:177], v[48:51]
	s_waitcnt lgkmcnt(3)
	v_mfma_f32_16x16x32_bf16 v[36:39], v[150:153], v[182:185], v[36:39]
	v_mfma_f32_16x16x32_bf16 v[32:35], v[158:161], v[182:185], v[32:35]
	s_waitcnt lgkmcnt(1)
	v_mfma_f32_16x16x32_bf16 v[20:23], v[150:153], v[190:193], v[20:23]
	v_mfma_f32_16x16x32_bf16 v[16:19], v[158:161], v[190:193], v[16:19]
	v_mfma_f32_16x16x32_bf16 v[60:63], v[154:157], v[170:173], v[60:63]
	s_add_u32 s22, s22, 0x80080
	s_addc_u32 s23, s23, 0
	v_mfma_f32_16x16x32_bf16 v[56:59], v[162:165], v[170:173], v[56:59]
	s_add_i32 s24, s24, s29
	v_mfma_f32_16x16x32_bf16 v[52:55], v[154:157], v[178:181], v[52:55]
	v_mfma_f32_16x16x32_bf16 v[48:51], v[162:165], v[178:181], v[48:51]
	v_mfma_f32_16x16x32_bf16 v[36:39], v[154:157], v[186:189], v[36:39]
	v_mfma_f32_16x16x32_bf16 v[32:35], v[162:165], v[186:189], v[32:35]
	s_waitcnt lgkmcnt(0)
	v_mfma_f32_16x16x32_bf16 v[20:23], v[154:157], v[198:201], v[20:23]
	v_mfma_f32_16x16x32_bf16 v[16:19], v[162:165], v[198:201], v[16:19]
	s_barrier
	s_setprio 0
	s_mov_b32 m0, s24
	s_nop 0
	global_load_lds_dwordx4 v132, s[22:23]
	s_add_i32 m0, s24, 0x2000
	s_setprio 1
	global_load_lds_dwordx4 v128, s[22:23]
	s_waitcnt vmcnt(6)
	s_barrier
	v_mfma_f32_16x16x32_bf16 v[44:47], v[202:205], v[166:169], v[44:47]
	v_mfma_f32_16x16x32_bf16 v[40:43], v[210:213], v[166:169], v[40:43]
	ds_read_b128 v[150:153], v147
	v_mfma_f32_16x16x32_bf16 v[28:31], v[202:205], v[174:177], v[28:31]
	v_mfma_f32_16x16x32_bf16 v[24:27], v[210:213], v[174:177], v[24:27]
	ds_read_b128 v[154:157], v147 offset:1024
	v_mfma_f32_16x16x32_bf16 v[12:15], v[202:205], v[182:185], v[12:15]
	v_mfma_f32_16x16x32_bf16 v[8:11], v[210:213], v[182:185], v[8:11]
	ds_read_b128 v[158:161], v147 offset:2048
	v_mfma_f32_16x16x32_bf16 v[4:7], v[202:205], v[190:193], v[4:7]
	v_mfma_f32_16x16x32_bf16 v[0:3], v[210:213], v[190:193], v[0:3]
	ds_read_b128 v[162:165], v147 offset:3072
	v_mfma_f32_16x16x32_bf16 v[44:47], v[206:209], v[170:173], v[44:47]
	s_add_i32 s3, s3, 2
	v_mfma_f32_16x16x32_bf16 v[40:43], v[214:217], v[170:173], v[40:43]
	s_add_u32 s52, s52, 0x100
	s_addc_u32 s53, s53, 0
	v_mfma_f32_16x16x32_bf16 v[28:31], v[206:209], v[178:181], v[28:31]
	s_add_u32 s20, s20, 0x100
	s_addc_u32 s21, s21, 0
	v_mfma_f32_16x16x32_bf16 v[24:27], v[214:217], v[178:181], v[24:27]
	s_add_u32 s22, s20, 0xfff80080
	s_addc_u32 s23, s21, -1
	s_cmp_eq_u32 s3, 28
	s_cselect_b32 s25, s15, s23
	s_cselect_b32 s24, s48, s22
	s_cselect_b32 s23, s13, s53
	s_cselect_b32 s22, s49, s52
	s_cmp_gt_u32 s3, 29
	v_mfma_f32_16x16x32_bf16 v[12:15], v[206:209], v[186:189], v[12:15]
	v_mfma_f32_16x16x32_bf16 v[8:11], v[214:217], v[186:189], v[8:11]
	v_mfma_f32_16x16x32_bf16 v[4:7], v[206:209], v[198:201], v[4:7]
	v_mfma_f32_16x16x32_bf16 v[0:3], v[214:217], v[198:201], v[0:3]
	s_barrier
	s_setprio 0
	s_cbranch_scc0 .LBB1_1382
; DI unsigned pack2(float a, float b) { f32x2 v = {a, b}; hwbf16x2 r = __builtin_convertvector(v, hwbf16x2); return __builtin_bit_cast(unsigned, r); }
;     DI const char* a(const Unit& u) const { return (const char*)(A + (size_t)u.pm * BM * lda); }
;     DI const char* a(const Unit& u) const { return (const char*)(A + (size_t)u.pm * BM * 2048 + (u.pn >> 1) * 512); }
;     DI const char* a(const Unit& u) const { return (const char*)((u.pn < 12 ? A1 : A2) + (size_t)u.pm * BM * 512); }
; #define PG8_WAIT_V(n) asm volatile("s_waitcnt vmcnt(" #n ")" ::: "memory")
; #define PG8_BAR __builtin_amdgcn_s_barrier()
;     DI void operator()(const f32x4 (&acc)[2][2][4][2], const Unit& u, int wr, int wc, int fr, int fq) const {
;         bf16_t* O = O1; int ldc = ldc1, pn = u.pn; if (pn >= split) { O = O2; ldc = ldc2; pn -= split; }
;         const int row0 = u.pm * BM + wr * 64 + fr, col0 = pn * BM + wc * 32 + 8 * fq;
; #pragma unroll
;         for (int ai = 0; ai < 2; ++ai)
; #pragma unroll
;             for (int m = 0; m < 4; ++m) { bf16_t* rowp = O + (size_t)(row0 + ai * HALF + m * 16) * ldc + col0;
; #pragma unroll
;                 for (int bj = 0; bj < 2; ++bj) { const f32x4 v0 = acc[ai][bj][m][0], v1 = acc[ai][bj][m][1];
;                     u32x4 o; o[0] = pack2(v0[0], v0[1]); o[1] = pack2(v0[2], v0[3]); o[2] = pack2(v1[0], v1[1]); o[3] = pack2(v1[2], v1[3]);
;                     *(u32x4*)(rowp + bj * HALF) = o; } }
; template <class Map, class Epi>
; DI void gemm_phase(LAS unsigned char* lds, const Map& MP, const Epi& E, const int nM, const int nN, const int K, const int lda, const int ldb) {
;     ...
;         if (!has_next) break;
; #pragma unroll
;         for (int a = 0; a < 2; ++a)
; #pragma unroll
;             for (int b = 0; b < 2; ++b)
; #pragma unroll
;                 for (int m = 0; m < 4; ++m)
; #pragma unroll
;                     for (int n = 0; n < 2; ++n) acc[a][b][m][n] = (f32x4){0.f, 0.f, 0.f, 0.f};
;         cur = nxt; cA = nA; cB = nB; ++ui;
;     }
;     PG8_WAIT_V(0);
;     if (wr == 0) PG8_BAR;
;     PG8_BAR;
	s_waitcnt lgkmcnt(0)
	s_lshl_b32 s3, s10, 8
	v_mov_b32_e32 v150, v144
	v_mov_b32_e32 v151, v145
	s_add_i32 s3, s3, s37
	v_cvt_pk_bf16_f32 v68, v68, v69
	v_add_u32_e32 v154, s3, v150
	s_lshl_b32 s3, s47, 8
	s_or_b32 s3, s3, s38
	v_lshl_add_u32 v150, v151, 3, s3
	v_ashrrev_i32_e32 v151, 31, v150
	v_lshl_add_u64 v[150:151], v[150:151], 1, s[6:7]
	v_cvt_pk_bf16_f32 v69, v70, v71
	v_cvt_pk_bf16_f32 v70, v64, v65
	v_add_u32_e32 v64, 0x80, v154
	v_mad_i64_i32 v[152:153], s[20:21], v154, s46, v[150:151]
	v_cvt_pk_bf16_f32 v108, v108, v109
	v_cvt_pk_bf16_f32 v109, v110, v111
	v_cvt_pk_bf16_f32 v110, v104, v105
	v_cvt_pk_bf16_f32 v111, v106, v107
	v_add_u32_e32 v104, 16, v154
	v_mad_i64_i32 v[64:65], s[20:21], v64, s46, v[150:151]
	v_cvt_pk_bf16_f32 v44, v44, v45
	v_cvt_pk_bf16_f32 v45, v46, v47
	v_cvt_pk_bf16_f32 v46, v40, v41
	v_cvt_pk_bf16_f32 v47, v42, v43
	v_add_u32_e32 v40, 0x90, v154
	global_store_dwordx4 v[152:153], v[108:111], off offset:256
	v_cvt_pk_bf16_f32 v92, v92, v93
	v_cvt_pk_bf16_f32 v93, v94, v95
	v_mad_i64_i32 v[108:109], s[20:21], v104, s46, v[150:151]
	v_cvt_pk_bf16_f32 v94, v88, v89
	v_cvt_pk_bf16_f32 v95, v90, v91
	v_add_u32_e32 v88, 32, v154
	global_store_dwordx4 v[64:65], v[44:47], off offset:256
	v_cvt_pk_bf16_f32 v28, v28, v29
	v_cvt_pk_bf16_f32 v29, v30, v31
	v_mad_i64_i32 v[44:45], s[20:21], v40, s46, v[150:151]
	v_cvt_pk_bf16_f32 v30, v24, v25
	v_cvt_pk_bf16_f32 v31, v26, v27
	v_add_u32_e32 v24, 0xa0, v154
	global_store_dwordx4 v[108:109], v[92:95], off offset:256
	v_cvt_pk_bf16_f32 v76, v76, v77
	v_cvt_pk_bf16_f32 v77, v78, v79
	v_mad_i64_i32 v[92:93], s[20:21], v88, s46, v[150:151]
	v_cvt_pk_bf16_f32 v78, v72, v73
	v_cvt_pk_bf16_f32 v79, v74, v75
	v_add_u32_e32 v72, 48, v154
	global_store_dwordx4 v[44:45], v[28:31], off offset:256
	v_cvt_pk_bf16_f32 v12, v12, v13
	v_cvt_pk_bf16_f32 v13, v14, v15
	v_mad_i64_i32 v[28:29], s[20:21], v24, s46, v[150:151]
	v_cvt_pk_bf16_f32 v14, v8, v9
	v_cvt_pk_bf16_f32 v15, v10, v11
	v_add_u32_e32 v8, 0xb0, v154
	global_store_dwordx4 v[92:93], v[76:79], off offset:256
	global_store_dwordx4 v[28:29], v[12:15], off offset:256
	v_cvt_pk_bf16_f32 v124, v124, v125
	v_mad_i64_i32 v[76:77], s[20:21], v72, s46, v[150:151]
	v_mad_i64_i32 v[12:13], s[20:21], v8, s46, v[150:151]
	v_cvt_pk_bf16_f32 v125, v126, v127
	v_cvt_pk_bf16_f32 v126, v120, v121
	v_cvt_pk_bf16_f32 v127, v122, v123
	v_cvt_pk_bf16_f32 v104, v116, v117
	v_cvt_pk_bf16_f32 v105, v118, v119
	v_cvt_pk_bf16_f32 v106, v112, v113
	v_cvt_pk_bf16_f32 v107, v114, v115
	v_cvt_pk_bf16_f32 v88, v100, v101
	v_cvt_pk_bf16_f32 v89, v102, v103
	v_cvt_pk_bf16_f32 v90, v96, v97
	v_cvt_pk_bf16_f32 v91, v98, v99
	v_cvt_pk_bf16_f32 v72, v84, v85
	v_cvt_pk_bf16_f32 v73, v86, v87
	v_cvt_pk_bf16_f32 v74, v80, v81
	v_cvt_pk_bf16_f32 v75, v82, v83
	v_cvt_pk_bf16_f32 v71, v66, v67
	v_cvt_pk_bf16_f32 v60, v60, v61
	v_cvt_pk_bf16_f32 v61, v62, v63
	v_cvt_pk_bf16_f32 v62, v56, v57
	v_cvt_pk_bf16_f32 v63, v58, v59
	v_cvt_pk_bf16_f32 v40, v52, v53
	v_cvt_pk_bf16_f32 v41, v54, v55
	v_cvt_pk_bf16_f32 v42, v48, v49
	v_cvt_pk_bf16_f32 v43, v50, v51
	v_cvt_pk_bf16_f32 v24, v36, v37
	v_cvt_pk_bf16_f32 v25, v38, v39
	v_cvt_pk_bf16_f32 v26, v32, v33
	v_cvt_pk_bf16_f32 v27, v34, v35
	v_cvt_pk_bf16_f32 v8, v20, v21
	v_cvt_pk_bf16_f32 v9, v22, v23
	v_cvt_pk_bf16_f32 v10, v16, v17
	v_cvt_pk_bf16_f32 v11, v18, v19
	v_cvt_pk_bf16_f32 v4, v4, v5
	v_cvt_pk_bf16_f32 v5, v6, v7
	v_cvt_pk_bf16_f32 v6, v0, v1
	v_cvt_pk_bf16_f32 v7, v2, v3
	s_and_b64 vcc, exec, s[40:41]
	s_mov_b32 s47, s12
	s_mov_b32 s10, s14
	s_mov_b64 s[20:21], s[18:19]
	s_mov_b64 s[22:23], s[16:17]
	global_store_dwordx4 v[152:153], v[124:127], off
	global_store_dwordx4 v[108:109], v[104:107], off
	global_store_dwordx4 v[92:93], v[88:91], off
	global_store_dwordx4 v[76:77], v[72:75], off
	global_store_dwordx4 v[76:77], v[68:71], off offset:256
	global_store_dwordx4 v[64:65], v[60:63], off
	global_store_dwordx4 v[44:45], v[40:43], off
	global_store_dwordx4 v[28:29], v[24:27], off
	global_store_dwordx4 v[12:13], v[8:11], off
	global_store_dwordx4 v[12:13], v[4:7], off offset:256
	s_cbranch_vccz .LBB1_1379
	s_waitcnt vmcnt(0)
	s_cmpk_gt_u32 s4, 0xff
	s_cbranch_scc1 .LBB1_1386
	s_barrier

; #define PG8_STAGE(bufoff, gbase, voff) do { _Pragma("unroll") for (int _i = 0; _i < 2; ++_i) \
;         __builtin_amdgcn_global_load_lds((const unsigned*)((const char*)(gbase) + (voff)[_i]), (LAS unsigned*)(lds + (bufoff) + ldsw + _i * 8192), 16, 0, 0); } while (0)
; #define PG8_LDA(dst, b, h) do { _Pragma("unroll") for (int m = 0; m < 4; ++m) _Pragma("unroll") for (int k = 0; k < 2; ++k) dst[m][k] = *(const LAS bf16x8*)(lds + PG8_SA(b, h) + aoff + m * 2048 + k * 1024); } while (0)
; #define PG8_LDB(dst, b, h) do { _Pragma("unroll") for (int n = 0; n < 2; ++n) _Pragma("unroll") for (int k = 0; k < 2; ++k) dst[n][k] = *(const LAS bf16x8*)(lds + PG8_SB(b, h) + boff + n * 2048 + k * 1024); } while (0)
; #define PG8_MMA(ai, bj, At, Bt) do { __builtin_amdgcn_s_setprio(1); _Pragma("unroll") for (int m = 0; m < 4; ++m) _Pragma("unroll") for (int n = 0; n < 2; ++n) _Pragma("unroll") for (int k = 0; k < 2; ++k) \
;         acc[ai][bj][m][n] = __builtin_amdgcn_mfma_f32_16x16x32_bf16(Bt[n][k], At[m][k], acc[ai][bj][m][n], 0, 0, 0); __builtin_amdgcn_s_setprio(0); } while (0)
; #define PG8_WAIT_V(n) asm volatile("s_waitcnt vmcnt(" #n ")" ::: "memory")
; #define PG8_WAIT_L(n) asm volatile("s_waitcnt lgkmcnt(" #n ")" ::: "memory")
; template <class Map, class Epi>
; DI void gemm_phase(LAS unsigned char* lds, const Map& MP, const Epi& E, const int nM, const int nN, const int K, const int lda, const int ldb) {
;     ...
;         for (int t = 0; t < nt; t += 2) {
;             const bool last = (t == nt - 2);
;             const char* a1 = cA + (size_t)(t + 1) * kstep;
;             const char* a2 = last ? nA : cA + (size_t)(t + 2) * kstep; const char* b2 = last ? nB : cB + (size_t)(t + 2) * kstep;
;             const char* a3 = a2 + kstep; const char* b3 = b2 + kstep;
;             PG8_LDB(B0, 0, 0); PG8_SCHED; PG8_LDA(At, 0, 0); PG8_STAGE(PG8_SA(1, 1), a1 + hstepA, voffA);
;             PG8_WAIT_L(8); PG8_BAR; PG8_WAIT_L(0); PG8_MMA(0, 0, At, B0); PG8_BAR; PG8_SCHED;
;             PG8_LDB(B1, 0, 1); PG8_STAGE(PG8_SB(0, 0), b2, voffB);
;             PG8_BAR; PG8_WAIT_L(0); PG8_MMA(0, 1, At, B1); PG8_BAR;
;             PG8_LDA(At, 0, 1); PG8_STAGE(PG8_SA(0, 0), a2, voffA);
;             PG8_BAR; PG8_WAIT_L(0); PG8_MMA(1, 0, At, B0); PG8_BAR; PG8_SCHED;
;             PG8_STAGE(PG8_SB(0, 1), b2 + hstepB, voffB);
;             PG8_WAIT_V(6); PG8_BAR; PG8_MMA(1, 1, At, B1); PG8_BAR;
.LBB1_1529:
	s_add_i32 m0, s11, 0xc000
	ds_read_b128 v[166:169], v148
	ds_read_b128 v[170:173], v148 offset:1024
	ds_read_b128 v[174:177], v148 offset:2048
	ds_read_b128 v[178:181], v148 offset:3072
	ds_read_b128 v[182:185], v148 offset:4096
	ds_read_b128 v[186:189], v148 offset:5120
	ds_read_b128 v[190:193], v148 offset:6144
	ds_read_b128 v[198:201], v148 offset:7168
	global_load_lds_dwordx4 v138, s[18:19]
	s_add_i32 m0, s11, 0xe000
	s_setprio 1
	global_load_lds_dwordx4 v136, s[18:19]
	s_waitcnt lgkmcnt(8)
	s_barrier
	s_waitcnt lgkmcnt(7)
	v_mfma_f32_16x16x32_bf16 v[124:127], v[150:153], v[166:169], v[124:127]
	v_mfma_f32_16x16x32_bf16 v[120:123], v[158:161], v[166:169], v[120:123]
	s_waitcnt lgkmcnt(5)
	v_mfma_f32_16x16x32_bf16 v[116:119], v[150:153], v[174:177], v[116:119]
	v_mfma_f32_16x16x32_bf16 v[112:115], v[158:161], v[174:177], v[112:115]
	s_waitcnt lgkmcnt(3)
	v_mfma_f32_16x16x32_bf16 v[100:103], v[150:153], v[182:185], v[100:103]
	v_mfma_f32_16x16x32_bf16 v[96:99], v[158:161], v[182:185], v[96:99]
	s_waitcnt lgkmcnt(1)
	v_mfma_f32_16x16x32_bf16 v[84:87], v[150:153], v[190:193], v[84:87]
	v_mfma_f32_16x16x32_bf16 v[80:83], v[158:161], v[190:193], v[80:83]
	v_mfma_f32_16x16x32_bf16 v[124:127], v[154:157], v[170:173], v[124:127]
	s_add_i32 s57, s47, s31
	v_mfma_f32_16x16x32_bf16 v[120:123], v[162:165], v[170:173], v[120:123]
	v_lshl_add_u64 v[194:195], s[20:21], 0, v[132:133]
	v_mfma_f32_16x16x32_bf16 v[116:119], v[154:157], v[178:181], v[116:119]
	v_lshl_add_u64 v[218:219], s[20:21], 0, v[128:129]
	v_mfma_f32_16x16x32_bf16 v[112:115], v[162:165], v[178:181], v[112:115]
	v_mfma_f32_16x16x32_bf16 v[100:103], v[154:157], v[186:189], v[100:103]
	v_mfma_f32_16x16x32_bf16 v[96:99], v[162:165], v[186:189], v[96:99]
	s_waitcnt lgkmcnt(0)
	v_mfma_f32_16x16x32_bf16 v[84:87], v[154:157], v[198:201], v[84:87]
	v_mfma_f32_16x16x32_bf16 v[80:83], v[162:165], v[198:201], v[80:83]
	s_barrier
	s_setprio 0
	s_mov_b32 m0, s57
	ds_read_b128 v[202:205], v149
	ds_read_b128 v[206:209], v149 offset:1024
	ds_read_b128 v[210:213], v149 offset:2048
	ds_read_b128 v[214:217], v149 offset:3072
	global_load_lds_dwordx4 v[194:195], off
	s_add_i32 m0, s57, 0x2000
	s_setprio 1
	global_load_lds_dwordx4 v[218:219], off
	s_barrier
	s_waitcnt lgkmcnt(3)
	v_mfma_f32_16x16x32_bf16 v[108:111], v[202:205], v[166:169], v[108:111]
	s_waitcnt lgkmcnt(1)
	v_mfma_f32_16x16x32_bf16 v[104:107], v[210:213], v[166:169], v[104:107]
	v_mfma_f32_16x16x32_bf16 v[92:95], v[202:205], v[174:177], v[92:95]
	v_mfma_f32_16x16x32_bf16 v[88:91], v[210:213], v[174:177], v[88:91]
	v_mfma_f32_16x16x32_bf16 v[76:79], v[202:205], v[182:185], v[76:79]
	v_mfma_f32_16x16x32_bf16 v[72:75], v[210:213], v[182:185], v[72:75]
	v_mfma_f32_16x16x32_bf16 v[68:71], v[202:205], v[190:193], v[68:71]
	v_mfma_f32_16x16x32_bf16 v[64:67], v[210:213], v[190:193], v[64:67]
	v_mfma_f32_16x16x32_bf16 v[108:111], v[206:209], v[170:173], v[108:111]
	v_lshl_add_u64 v[222:223], s[22:23], 0, v[130:131]
	s_mov_b32 m0, s11
	s_waitcnt lgkmcnt(0)
	v_mfma_f32_16x16x32_bf16 v[104:107], v[214:217], v[170:173], v[104:107]
	v_lshl_add_u64 v[220:221], s[22:23], 0, v[134:135]
	v_mfma_f32_16x16x32_bf16 v[92:95], v[206:209], v[178:181], v[92:95]
	v_mfma_f32_16x16x32_bf16 v[88:91], v[214:217], v[178:181], v[88:91]
	v_mfma_f32_16x16x32_bf16 v[76:79], v[206:209], v[186:189], v[76:79]
	v_mfma_f32_16x16x32_bf16 v[72:75], v[214:217], v[186:189], v[72:75]
	v_mfma_f32_16x16x32_bf16 v[68:71], v[206:209], v[198:201], v[68:71]
	v_mfma_f32_16x16x32_bf16 v[64:67], v[214:217], v[198:201], v[64:67]
	s_barrier
	s_setprio 0
	ds_read_b128 v[166:169], v148 offset:16384
	ds_read_b128 v[170:173], v148 offset:17408
	ds_read_b128 v[174:177], v148 offset:18432
	ds_read_b128 v[178:181], v148 offset:19456
	ds_read_b128 v[182:185], v148 offset:20480
	ds_read_b128 v[186:189], v148 offset:21504
	ds_read_b128 v[190:193], v148 offset:22528
	ds_read_b128 v[198:201], v148 offset:23552
	global_load_lds_dwordx4 v[220:221], off
	s_mov_b32 m0, s35
	s_setprio 1
	global_load_lds_dwordx4 v[222:223], off
	s_waitcnt vmcnt(10)
	s_barrier
	s_waitcnt lgkmcnt(7)
	v_mfma_f32_16x16x32_bf16 v[60:63], v[150:153], v[166:169], v[60:63]
	v_mfma_f32_16x16x32_bf16 v[56:59], v[158:161], v[166:169], v[56:59]
	s_waitcnt lgkmcnt(5)
	v_mfma_f32_16x16x32_bf16 v[52:55], v[150:153], v[174:177], v[52:55]
	v_mfma_f32_16x16x32_bf16 v[48:51], v[158:161], v[174:177], v[48:51]
	s_waitcnt lgkmcnt(3)
	v_mfma_f32_16x16x32_bf16 v[36:39], v[150:153], v[182:185], v[36:39]
	v_mfma_f32_16x16x32_bf16 v[32:35], v[158:161], v[182:185], v[32:35]
	s_waitcnt lgkmcnt(1)
	v_mfma_f32_16x16x32_bf16 v[20:23], v[150:153], v[190:193], v[20:23]
	v_mfma_f32_16x16x32_bf16 v[16:19], v[158:161], v[190:193], v[16:19]
	v_mfma_f32_16x16x32_bf16 v[60:63], v[154:157], v[170:173], v[60:63]
	s_add_u32 s58, s20, 0x20000
	s_addc_u32 s59, s21, 0
	v_mfma_f32_16x16x32_bf16 v[56:59], v[162:165], v[170:173], v[56:59]
	s_add_i32 s57, s48, s31
	v_mfma_f32_16x16x32_bf16 v[52:55], v[154:157], v[178:181], v[52:55]
	v_mfma_f32_16x16x32_bf16 v[48:51], v[162:165], v[178:181], v[48:51]
	v_mfma_f32_16x16x32_bf16 v[36:39], v[154:157], v[186:189], v[36:39]
	v_mfma_f32_16x16x32_bf16 v[32:35], v[162:165], v[186:189], v[32:35]
	s_waitcnt lgkmcnt(0)
	v_mfma_f32_16x16x32_bf16 v[20:23], v[154:157], v[198:201], v[20:23]
	v_mfma_f32_16x16x32_bf16 v[16:19], v[162:165], v[198:201], v[16:19]
	s_barrier
	s_setprio 0
	s_mov_b32 m0, s57
	s_nop 0
	global_load_lds_dwordx4 v132, s[58:59]
	s_add_i32 m0, s57, 0x2000
	s_setprio 1
	global_load_lds_dwordx4 v128, s[58:59]
	s_waitcnt vmcnt(6)
	s_barrier
; #define PG8_STAGE(bufoff, gbase, voff) do { _Pragma("unroll") for (int _i = 0; _i < 2; ++_i) \
;         __builtin_amdgcn_global_load_lds((const unsigned*)((const char*)(gbase) + (voff)[_i]), (LAS unsigned*)(lds + (bufoff) + ldsw + _i * 8192), 16, 0, 0); } while (0)
; #define PG8_LDA(dst, b, h) do { _Pragma("unroll") for (int m = 0; m < 4; ++m) _Pragma("unroll") for (int k = 0; k < 2; ++k) dst[m][k] = *(const LAS bf16x8*)(lds + PG8_SA(b, h) + aoff + m * 2048 + k * 1024); } while (0)
; #define PG8_LDB(dst, b, h) do { _Pragma("unroll") for (int n = 0; n < 2; ++n) _Pragma("unroll") for (int k = 0; k < 2; ++k) dst[n][k] = *(const LAS bf16x8*)(lds + PG8_SB(b, h) + boff + n * 2048 + k * 1024); } while (0)
; #define PG8_MMA(ai, bj, At, Bt) do { __builtin_amdgcn_s_setprio(1); _Pragma("unroll") for (int m = 0; m < 4; ++m) _Pragma("unroll") for (int n = 0; n < 2; ++n) _Pragma("unroll") for (int k = 0; k < 2; ++k) \
;         acc[ai][bj][m][n] = __builtin_amdgcn_mfma_f32_16x16x32_bf16(Bt[n][k], At[m][k], acc[ai][bj][m][n], 0, 0, 0); __builtin_amdgcn_s_setprio(0); } while (0)
; #define PG8_WAIT_V(n) asm volatile("s_waitcnt vmcnt(" #n ")" ::: "memory")
; #define PG8_WAIT_L(n) asm volatile("s_waitcnt lgkmcnt(" #n ")" ::: "memory")
; #define PG8_BAR __builtin_amdgcn_s_barrier()
; #define PG8_SCHED __builtin_amdgcn_sched_barrier(0)
; template <class Map, class Epi>
; DI void gemm_phase(LAS unsigned char* lds, const Map& MP, const Epi& E, const int nM, const int nN, const int K, const int lda, const int ldb) {
;     ...
;             PG8_WAIT_V(6); PG8_BAR; PG8_MMA(1, 1, At, B1); PG8_BAR;
;             PG8_LDB(B0, 1, 0); PG8_SCHED; PG8_LDA(At, 1, 0); PG8_STAGE(PG8_SA(0, 1), a2 + hstepA, voffA);
;             PG8_WAIT_L(8); PG8_BAR; PG8_WAIT_L(0); PG8_MMA(0, 0, At, B0); PG8_BAR; PG8_SCHED;
;             PG8_LDB(B1, 1, 1); PG8_STAGE(PG8_SB(1, 0), b3, voffB);
;             PG8_BAR; PG8_WAIT_L(0); PG8_MMA(0, 1, At, B1); PG8_BAR;
;             PG8_LDA(At, 1, 1); PG8_STAGE(PG8_SA(1, 0), a3, voffA);
;             PG8_BAR; PG8_WAIT_L(0); PG8_MMA(1, 0, At, B0); PG8_BAR; PG8_SCHED;
	v_mfma_f32_16x16x32_bf16 v[44:47], v[202:205], v[166:169], v[44:47]
	v_mfma_f32_16x16x32_bf16 v[40:43], v[210:213], v[166:169], v[40:43]
	s_add_i32 s57, 0, 0x18000
	v_add_u32_e32 v162, s57, v146
	ds_read_b128 v[150:153], v162
	v_mfma_f32_16x16x32_bf16 v[28:31], v[202:205], v[174:177], v[28:31]
	v_mfma_f32_16x16x32_bf16 v[24:27], v[210:213], v[174:177], v[24:27]
	ds_read_b128 v[154:157], v162 offset:1024
	v_mfma_f32_16x16x32_bf16 v[12:15], v[202:205], v[182:185], v[12:15]
	v_mfma_f32_16x16x32_bf16 v[8:11], v[210:213], v[182:185], v[8:11]
	ds_read_b128 v[158:161], v162 offset:2048
	v_mfma_f32_16x16x32_bf16 v[4:7], v[202:205], v[190:193], v[4:7]
	v_mfma_f32_16x16x32_bf16 v[0:3], v[210:213], v[190:193], v[0:3]
	ds_read_b128 v[162:165], v162 offset:3072
	v_mfma_f32_16x16x32_bf16 v[44:47], v[206:209], v[170:173], v[44:47]
	s_add_u32 s22, s22, 0x20000
	s_addc_u32 s23, s23, 0
	v_mfma_f32_16x16x32_bf16 v[40:43], v[214:217], v[170:173], v[40:43]
	v_mfma_f32_16x16x32_bf16 v[28:31], v[206:209], v[178:181], v[28:31]
	v_mfma_f32_16x16x32_bf16 v[24:27], v[214:217], v[178:181], v[24:27]
	v_mfma_f32_16x16x32_bf16 v[12:15], v[206:209], v[186:189], v[12:15]
	v_mfma_f32_16x16x32_bf16 v[8:11], v[214:217], v[186:189], v[8:11]
	v_mfma_f32_16x16x32_bf16 v[4:7], v[206:209], v[198:201], v[4:7]
	v_mfma_f32_16x16x32_bf16 v[0:3], v[214:217], v[198:201], v[0:3]
	s_barrier
	s_setprio 0
	s_mov_b32 m0, s36
	ds_read_b128 v[166:169], v148 offset:32768
	ds_read_b128 v[170:173], v148 offset:33792
	ds_read_b128 v[174:177], v148 offset:34816
	ds_read_b128 v[178:181], v148 offset:35840
	ds_read_b128 v[182:185], v148 offset:36864
	ds_read_b128 v[186:189], v148 offset:37888
	ds_read_b128 v[190:193], v148 offset:38912
	ds_read_b128 v[198:201], v148 offset:39936
	global_load_lds_dwordx4 v134, s[22:23]
	s_mov_b32 m0, s37
	s_setprio 1
	global_load_lds_dwordx4 v130, s[22:23]
	s_waitcnt lgkmcnt(8)
	s_barrier
	s_waitcnt lgkmcnt(7)
	v_mfma_f32_16x16x32_bf16 v[124:127], v[150:153], v[166:169], v[124:127]
	v_mfma_f32_16x16x32_bf16 v[120:123], v[158:161], v[166:169], v[120:123]
	s_waitcnt lgkmcnt(5)
	v_mfma_f32_16x16x32_bf16 v[116:119], v[150:153], v[174:177], v[116:119]
	v_mfma_f32_16x16x32_bf16 v[112:115], v[158:161], v[174:177], v[112:115]
	s_waitcnt lgkmcnt(3)
	v_mfma_f32_16x16x32_bf16 v[100:103], v[150:153], v[182:185], v[100:103]
	v_mfma_f32_16x16x32_bf16 v[96:99], v[158:161], v[182:185], v[96:99]
	s_waitcnt lgkmcnt(1)
	v_mfma_f32_16x16x32_bf16 v[84:87], v[150:153], v[190:193], v[84:87]
	v_mfma_f32_16x16x32_bf16 v[80:83], v[158:161], v[190:193], v[80:83]
	v_mfma_f32_16x16x32_bf16 v[124:127], v[154:157], v[170:173], v[124:127]
	s_add_i32 s22, 0, 0x1c000
	v_mfma_f32_16x16x32_bf16 v[120:123], v[162:165], v[170:173], v[120:123]
	s_add_i32 s23, s57, s31
	v_mfma_f32_16x16x32_bf16 v[116:119], v[154:157], v[178:181], v[116:119]
	v_add_u32_e32 v196, s22, v146
	v_mfma_f32_16x16x32_bf16 v[112:115], v[162:165], v[178:181], v[112:115]
	v_lshl_add_u64 v[194:195], v[194:195], 0, s[8:9]
	v_mfma_f32_16x16x32_bf16 v[100:103], v[154:157], v[186:189], v[100:103]
	v_mfma_f32_16x16x32_bf16 v[96:99], v[162:165], v[186:189], v[96:99]
	s_waitcnt lgkmcnt(0)
	v_mfma_f32_16x16x32_bf16 v[84:87], v[154:157], v[198:201], v[84:87]
	v_mfma_f32_16x16x32_bf16 v[80:83], v[162:165], v[198:201], v[80:83]
	s_barrier
	s_setprio 0
	s_mov_b32 m0, s23
	ds_read_b128 v[202:205], v196
	ds_read_b128 v[206:209], v196 offset:1024
	ds_read_b128 v[210:213], v196 offset:2048
	ds_read_b128 v[214:217], v196 offset:3072
	global_load_lds_dwordx4 v[194:195], off
	v_lshl_add_u64 v[194:195], v[218:219], 0, s[8:9]
	s_add_i32 m0, s23, 0x2000
	s_setprio 1
	global_load_lds_dwordx4 v[194:195], off
	s_barrier
	s_waitcnt lgkmcnt(3)
	v_mfma_f32_16x16x32_bf16 v[108:111], v[202:205], v[166:169], v[108:111]
	s_waitcnt lgkmcnt(1)
	v_mfma_f32_16x16x32_bf16 v[104:107], v[210:213], v[166:169], v[104:107]
	v_mfma_f32_16x16x32_bf16 v[92:95], v[202:205], v[174:177], v[92:95]
	v_mfma_f32_16x16x32_bf16 v[88:91], v[210:213], v[174:177], v[88:91]
	v_mfma_f32_16x16x32_bf16 v[76:79], v[202:205], v[182:185], v[76:79]
	v_mfma_f32_16x16x32_bf16 v[72:75], v[210:213], v[182:185], v[72:75]
	v_mfma_f32_16x16x32_bf16 v[68:71], v[202:205], v[190:193], v[68:71]
	v_mfma_f32_16x16x32_bf16 v[64:67], v[210:213], v[190:193], v[64:67]
	v_mfma_f32_16x16x32_bf16 v[108:111], v[206:209], v[170:173], v[108:111]
	s_mov_b32 m0, s43
	s_waitcnt lgkmcnt(0)
	v_mfma_f32_16x16x32_bf16 v[104:107], v[214:217], v[170:173], v[104:107]
	v_lshl_add_u64 v[194:195], v[220:221], 0, s[8:9]
	v_mfma_f32_16x16x32_bf16 v[92:95], v[206:209], v[178:181], v[92:95]
	v_mfma_f32_16x16x32_bf16 v[88:91], v[214:217], v[178:181], v[88:91]
	v_mfma_f32_16x16x32_bf16 v[76:79], v[206:209], v[186:189], v[76:79]
	v_mfma_f32_16x16x32_bf16 v[72:75], v[214:217], v[186:189], v[72:75]
	v_mfma_f32_16x16x32_bf16 v[68:71], v[206:209], v[198:201], v[68:71]
	v_mfma_f32_16x16x32_bf16 v[64:67], v[214:217], v[198:201], v[64:67]
	s_barrier
	s_setprio 0
	ds_read_b128 v[166:169], v148 offset:49152
	ds_read_b128 v[170:173], v148 offset:50176
	ds_read_b128 v[174:177], v148 offset:51200
	ds_read_b128 v[178:181], v148 offset:52224
	ds_read_b128 v[182:185], v148 offset:53248
	ds_read_b128 v[186:189], v148 offset:54272
	ds_read_b128 v[190:193], v148 offset:55296
	ds_read_b128 v[198:201], v148 offset:56320
	global_load_lds_dwordx4 v[194:195], off
	v_lshl_add_u64 v[194:195], v[222:223], 0, s[8:9]
	s_mov_b32 m0, s44
	s_setprio 1
	global_load_lds_dwordx4 v[194:195], off
	s_waitcnt vmcnt(10)
	s_barrier
; #define PG8_STAGE(bufoff, gbase, voff) do { _Pragma("unroll") for (int _i = 0; _i < 2; ++_i) \
;         __builtin_amdgcn_global_load_lds((const unsigned*)((const char*)(gbase) + (voff)[_i]), (LAS unsigned*)(lds + (bufoff) + ldsw + _i * 8192), 16, 0, 0); } while (0)
; #define PG8_LDA(dst, b, h) do { _Pragma("unroll") for (int m = 0; m < 4; ++m) _Pragma("unroll") for (int k = 0; k < 2; ++k) dst[m][k] = *(const LAS bf16x8*)(lds + PG8_SA(b, h) + aoff + m * 2048 + k * 1024); } while (0)
; #define PG8_WAIT_V(n) asm volatile("s_waitcnt vmcnt(" #n ")" ::: "memory")
; #define PG8_WAIT_L(n) asm volatile("s_waitcnt lgkmcnt(" #n ")" ::: "memory")
; template <class Map, class Epi>
; DI void gemm_phase(LAS unsigned char* lds, const Map& MP, const Epi& E, const int nM, const int nN, const int K, const int lda, const int ldb) {
;     ...
;             const bool last = (t == nt - 2);
;             const char* a1 = cA + (size_t)(t + 1) * kstep;
;             const char* a2 = last ? nA : cA + (size_t)(t + 2) * kstep; const char* b2 = last ? nB : cB + (size_t)(t + 2) * kstep;
;             const char* a3 = a2 + kstep; const char* b3 = b2 + kstep;
;             PG8_LDB(B0, 0, 0); PG8_SCHED; PG8_LDA(At, 0, 0); PG8_STAGE(PG8_SA(1, 1), a1 + hstepA, voffA);
;             PG8_WAIT_L(8); PG8_BAR; PG8_WAIT_L(0); PG8_MMA(0, 0, At, B0); PG8_BAR; PG8_SCHED;
;             PG8_LDB(B1, 0, 1); PG8_STAGE(PG8_SB(0, 0), b2, voffB);
;             PG8_BAR; PG8_WAIT_L(0); PG8_MMA(0, 1, At, B1); PG8_BAR;
;             PG8_LDA(At, 0, 1); PG8_STAGE(PG8_SA(0, 0), a2, voffA);
;             PG8_BAR; PG8_WAIT_L(0); PG8_MMA(1, 0, At, B0); PG8_BAR; PG8_SCHED;
;             PG8_STAGE(PG8_SB(0, 1), b2 + hstepB, voffB);
;             PG8_WAIT_V(6); PG8_BAR; PG8_MMA(1, 1, At, B1); PG8_BAR;
;             PG8_LDB(B0, 1, 0); PG8_SCHED; PG8_LDA(At, 1, 0); PG8_STAGE(PG8_SA(0, 1), a2 + hstepA, voffA);
;             PG8_WAIT_L(8); PG8_BAR; PG8_WAIT_L(0); PG8_MMA(0, 0, At, B0); PG8_BAR; PG8_SCHED;
;             PG8_LDB(B1, 1, 1); PG8_STAGE(PG8_SB(1, 0), b3, voffB);
;             PG8_BAR; PG8_WAIT_L(0); PG8_MMA(0, 1, At, B1); PG8_BAR;
;             PG8_LDA(At, 1, 1); PG8_STAGE(PG8_SA(1, 0), a3, voffA);
;             PG8_BAR; PG8_WAIT_L(0); PG8_MMA(1, 0, At, B0); PG8_BAR; PG8_SCHED;
;             PG8_STAGE(PG8_SB(1, 1), b3 + hstepB, voffB);
;             PG8_WAIT_V(6); PG8_BAR; PG8_MMA(1, 1, At, B1); PG8_BAR;
	s_waitcnt lgkmcnt(7)
	v_mfma_f32_16x16x32_bf16 v[60:63], v[150:153], v[166:169], v[60:63]
	v_mfma_f32_16x16x32_bf16 v[56:59], v[158:161], v[166:169], v[56:59]
	s_waitcnt lgkmcnt(5)
	v_mfma_f32_16x16x32_bf16 v[52:55], v[150:153], v[174:177], v[52:55]
	v_mfma_f32_16x16x32_bf16 v[48:51], v[158:161], v[174:177], v[48:51]
	s_waitcnt lgkmcnt(3)
	v_mfma_f32_16x16x32_bf16 v[36:39], v[150:153], v[182:185], v[36:39]
	v_mfma_f32_16x16x32_bf16 v[32:35], v[158:161], v[182:185], v[32:35]
	s_waitcnt lgkmcnt(1)
	v_mfma_f32_16x16x32_bf16 v[20:23], v[150:153], v[190:193], v[20:23]
	v_mfma_f32_16x16x32_bf16 v[16:19], v[158:161], v[190:193], v[16:19]
	v_mfma_f32_16x16x32_bf16 v[60:63], v[154:157], v[170:173], v[60:63]
	s_add_u32 s20, s20, 0x20080
	s_addc_u32 s21, s21, 0
	v_mfma_f32_16x16x32_bf16 v[56:59], v[162:165], v[170:173], v[56:59]
	s_add_i32 s22, s22, s31
	v_mfma_f32_16x16x32_bf16 v[52:55], v[154:157], v[178:181], v[52:55]
	v_mfma_f32_16x16x32_bf16 v[48:51], v[162:165], v[178:181], v[48:51]
	v_mfma_f32_16x16x32_bf16 v[36:39], v[154:157], v[186:189], v[36:39]
	v_mfma_f32_16x16x32_bf16 v[32:35], v[162:165], v[186:189], v[32:35]
	s_waitcnt lgkmcnt(0)
	v_mfma_f32_16x16x32_bf16 v[20:23], v[154:157], v[198:201], v[20:23]
	v_mfma_f32_16x16x32_bf16 v[16:19], v[162:165], v[198:201], v[16:19]
	s_barrier
	s_setprio 0
	s_mov_b32 m0, s22
	s_nop 0
	global_load_lds_dwordx4 v132, s[20:21]
	s_add_i32 m0, s22, 0x2000
	s_setprio 1
	global_load_lds_dwordx4 v128, s[20:21]
	s_waitcnt vmcnt(6)
	s_barrier
	v_mfma_f32_16x16x32_bf16 v[44:47], v[202:205], v[166:169], v[44:47]
	v_mfma_f32_16x16x32_bf16 v[40:43], v[210:213], v[166:169], v[40:43]
	ds_read_b128 v[150:153], v147
	v_mfma_f32_16x16x32_bf16 v[28:31], v[202:205], v[174:177], v[28:31]
	v_mfma_f32_16x16x32_bf16 v[24:27], v[210:213], v[174:177], v[24:27]
	ds_read_b128 v[154:157], v147 offset:1024
	v_mfma_f32_16x16x32_bf16 v[12:15], v[202:205], v[182:185], v[12:15]
	v_mfma_f32_16x16x32_bf16 v[8:11], v[210:213], v[182:185], v[8:11]
	ds_read_b128 v[158:161], v147 offset:2048
	v_mfma_f32_16x16x32_bf16 v[4:7], v[202:205], v[190:193], v[4:7]
	v_mfma_f32_16x16x32_bf16 v[0:3], v[210:213], v[190:193], v[0:3]
	ds_read_b128 v[162:165], v147 offset:3072
	v_mfma_f32_16x16x32_bf16 v[44:47], v[206:209], v[170:173], v[44:47]
	s_add_i32 s3, s3, 2
	v_mfma_f32_16x16x32_bf16 v[40:43], v[214:217], v[170:173], v[40:43]
	s_add_u32 s55, s55, 0x100
	s_addc_u32 s56, s56, 0
	v_mfma_f32_16x16x32_bf16 v[28:31], v[206:209], v[178:181], v[28:31]
	s_add_u32 s18, s18, 0x100
	s_addc_u32 s19, s19, 0
	v_mfma_f32_16x16x32_bf16 v[24:27], v[214:217], v[178:181], v[24:27]
	s_add_u32 s20, s18, 0xfffe0080
	s_addc_u32 s21, s19, -1
	s_cmp_eq_u32 s3, 4
	s_cselect_b32 s23, s13, s21
	s_cselect_b32 s22, s52, s20
	s_cselect_b32 s21, s53, s56
	s_cselect_b32 s20, s54, s55
	s_cmp_gt_u32 s3, 5
	v_mfma_f32_16x16x32_bf16 v[12:15], v[206:209], v[186:189], v[12:15]
	v_mfma_f32_16x16x32_bf16 v[8:11], v[214:217], v[186:189], v[8:11]
	v_mfma_f32_16x16x32_bf16 v[4:7], v[206:209], v[198:201], v[4:7]
	v_mfma_f32_16x16x32_bf16 v[0:3], v[214:217], v[198:201], v[0:3]
	s_barrier
	s_setprio 0
	s_cbranch_scc0 .LBB1_1529
; DI unsigned pack2(float a, float b) { f32x2 v = {a, b}; hwbf16x2 r = __builtin_convertvector(v, hwbf16x2); return __builtin_bit_cast(unsigned, r); }
;     DI const char* a(const Unit& u) const { return (const char*)(A + (size_t)u.pm * BM * lda); }
;     DI const char* a(const Unit& u) const { return (const char*)(A + (size_t)u.pm * BM * 2048 + (u.pn >> 1) * 512); }
;     DI const char* a(const Unit& u) const { return (const char*)((u.pn < 12 ? A1 : A2) + (size_t)u.pm * BM * 512); }
; #define PG8_WAIT_V(n) asm volatile("s_waitcnt vmcnt(" #n ")" ::: "memory")
; #define PG8_BAR __builtin_amdgcn_s_barrier()
;     DI void operator()(const f32x4 (&acc)[2][2][4][2], const Unit& u, int wr, int wc, int fr, int fq) const {
;         bf16_t* O = O1; int ldc = ldc1, pn = u.pn; if (pn >= split) { O = O2; ldc = ldc2; pn -= split; }
;         const int row0 = u.pm * BM + wr * 64 + fr, col0 = pn * BM + wc * 32 + 8 * fq;
; #pragma unroll
;         for (int ai = 0; ai < 2; ++ai)
; #pragma unroll
;             for (int m = 0; m < 4; ++m) { bf16_t* rowp = O + (size_t)(row0 + ai * HALF + m * 16) * ldc + col0;
; #pragma unroll
;                 for (int bj = 0; bj < 2; ++bj) { const f32x4 v0 = acc[ai][bj][m][0], v1 = acc[ai][bj][m][1];
;                     u32x4 o; o[0] = pack2(v0[0], v0[1]); o[1] = pack2(v0[2], v0[3]); o[2] = pack2(v1[0], v1[1]); o[3] = pack2(v1[2], v1[3]);
;                     *(u32x4*)(rowp + bj * HALF) = o; } }
; template <class Map, class Epi>
; DI void gemm_phase(LAS unsigned char* lds, const Map& MP, const Epi& E, const int nM, const int nN, const int K, const int lda, const int ldb) {
;     ...
;         if (!has_next) break;
; #pragma unroll
;         for (int a = 0; a < 2; ++a)
; #pragma unroll
;             for (int b = 0; b < 2; ++b)
; #pragma unroll
;                 for (int m = 0; m < 4; ++m)
; #pragma unroll
;                     for (int n = 0; n < 2; ++n) acc[a][b][m][n] = (f32x4){0.f, 0.f, 0.f, 0.f};
;         cur = nxt; cA = nA; cB = nB; ++ui;
;     }
;     PG8_WAIT_V(0);
;     if (wr == 0) PG8_BAR;
;     PG8_BAR;
	s_waitcnt lgkmcnt(0)
	s_cmp_lt_i32 s45, 12
	s_cselect_b32 s3, 0, -12
	s_mov_b32 s13, 0x1e510000
	s_movk_i32 s18, 0xc00
	s_cselect_b32 s13, s13, 0x2a510000
	s_cselect_b32 s20, s18, 0x1000
	s_add_i32 s3, s3, s45
	s_add_u32 s18, s6, s13
	v_mov_b32_e32 v150, v144
	v_mov_b32_e32 v151, v145
	s_addc_u32 s19, s7, 0
	s_lshl_b32 s10, s10, 8
	s_lshl_b32 s3, s3, 8
	s_add_i32 s10, s10, s39
	s_or_b32 s3, s3, s42
	v_add_u32_e32 v154, s10, v150
	v_lshl_add_u32 v150, v151, 3, s3
	v_ashrrev_i32_e32 v151, 31, v150
	v_lshl_add_u64 v[150:151], v[150:151], 1, s[18:19]
	v_mad_i64_i32 v[152:153], s[18:19], s20, v154, 0
	v_cvt_pk_bf16_f32 v108, v108, v109
	v_cvt_pk_bf16_f32 v109, v110, v111
	v_cvt_pk_bf16_f32 v110, v104, v105
	v_add_u32_e32 v104, 16, v154
	v_lshl_add_u64 v[152:153], v[152:153], 1, v[150:151]
	v_cvt_pk_bf16_f32 v111, v106, v107
	v_mad_i64_i32 v[104:105], s[18:19], s20, v104, 0
	v_cvt_pk_bf16_f32 v92, v92, v93
	v_cvt_pk_bf16_f32 v93, v94, v95
	v_cvt_pk_bf16_f32 v94, v88, v89
	v_add_u32_e32 v88, 32, v154
	v_cvt_pk_bf16_f32 v124, v124, v125
	v_cvt_pk_bf16_f32 v125, v126, v127
	v_cvt_pk_bf16_f32 v126, v120, v121
	v_cvt_pk_bf16_f32 v127, v122, v123
	global_store_dwordx4 v[152:153], v[108:111], off offset:256
	v_cvt_pk_bf16_f32 v95, v90, v91
	v_mad_i64_i32 v[88:89], s[18:19], s20, v88, 0
	v_lshl_add_u64 v[108:109], v[104:105], 1, v[150:151]
	v_cvt_pk_bf16_f32 v76, v76, v77
	v_cvt_pk_bf16_f32 v77, v78, v79
	v_cvt_pk_bf16_f32 v78, v72, v73
	v_add_u32_e32 v72, 48, v154
	v_cvt_pk_bf16_f32 v68, v68, v69
	v_cvt_pk_bf16_f32 v69, v70, v71
	v_cvt_pk_bf16_f32 v70, v64, v65
	v_add_u32_e32 v64, 0x80, v154
	global_store_dwordx4 v[152:153], v[124:127], off
	v_cvt_pk_bf16_f32 v104, v116, v117
	v_cvt_pk_bf16_f32 v105, v118, v119
	v_cvt_pk_bf16_f32 v106, v112, v113
	v_cvt_pk_bf16_f32 v107, v114, v115
	global_store_dwordx4 v[108:109], v[92:95], off offset:256
	v_cvt_pk_bf16_f32 v79, v74, v75
	v_mad_i64_i32 v[72:73], s[18:19], s20, v72, 0
	v_lshl_add_u64 v[92:93], v[88:89], 1, v[150:151]
	v_mad_i64_i32 v[64:65], s[18:19], s20, v64, 0
	v_cvt_pk_bf16_f32 v44, v44, v45
	v_cvt_pk_bf16_f32 v45, v46, v47
	v_cvt_pk_bf16_f32 v46, v40, v41
	v_add_u32_e32 v40, 0x90, v154
	global_store_dwordx4 v[108:109], v[104:107], off
	v_cvt_pk_bf16_f32 v88, v100, v101
	v_cvt_pk_bf16_f32 v89, v102, v103
	v_cvt_pk_bf16_f32 v90, v96, v97
	v_cvt_pk_bf16_f32 v91, v98, v99
	global_store_dwordx4 v[92:93], v[76:79], off offset:256
	v_cvt_pk_bf16_f32 v74, v80, v81
	v_cvt_pk_bf16_f32 v75, v82, v83
	v_lshl_add_u64 v[76:77], v[72:73], 1, v[150:151]
	v_cvt_pk_bf16_f32 v72, v84, v85
	v_cvt_pk_bf16_f32 v73, v86, v87
	v_cvt_pk_bf16_f32 v71, v66, v67
	v_lshl_add_u64 v[64:65], v[64:65], 1, v[150:151]
	v_cvt_pk_bf16_f32 v47, v42, v43
	v_mad_i64_i32 v[40:41], s[18:19], s20, v40, 0
	v_cvt_pk_bf16_f32 v28, v28, v29
	v_cvt_pk_bf16_f32 v29, v30, v31
	v_cvt_pk_bf16_f32 v30, v24, v25
	v_add_u32_e32 v24, 0xa0, v154
	global_store_dwordx4 v[92:93], v[88:91], off
	global_store_dwordx4 v[76:77], v[72:75], off
	global_store_dwordx4 v[76:77], v[68:71], off offset:256
	v_cvt_pk_bf16_f32 v60, v60, v61
	v_cvt_pk_bf16_f32 v61, v62, v63
	v_cvt_pk_bf16_f32 v62, v56, v57
	v_cvt_pk_bf16_f32 v63, v58, v59
	global_store_dwordx4 v[64:65], v[44:47], off offset:256
	v_cvt_pk_bf16_f32 v31, v26, v27
	v_mad_i64_i32 v[24:25], s[18:19], s20, v24, 0
	v_lshl_add_u64 v[44:45], v[40:41], 1, v[150:151]
	v_cvt_pk_bf16_f32 v12, v12, v13
	v_cvt_pk_bf16_f32 v13, v14, v15
	v_cvt_pk_bf16_f32 v14, v8, v9
	v_add_u32_e32 v8, 0xb0, v154
	global_store_dwordx4 v[64:65], v[60:63], off
	v_cvt_pk_bf16_f32 v40, v52, v53
	v_cvt_pk_bf16_f32 v41, v54, v55
	v_cvt_pk_bf16_f32 v42, v48, v49
	v_cvt_pk_bf16_f32 v43, v50, v51
	global_store_dwordx4 v[44:45], v[28:31], off offset:256
	v_cvt_pk_bf16_f32 v15, v10, v11
	v_mad_i64_i32 v[8:9], s[18:19], s20, v8, 0
	v_lshl_add_u64 v[28:29], v[24:25], 1, v[150:151]
	global_store_dwordx4 v[44:45], v[40:43], off
	v_cvt_pk_bf16_f32 v24, v36, v37
	v_cvt_pk_bf16_f32 v25, v38, v39
	v_cvt_pk_bf16_f32 v26, v32, v33
	v_cvt_pk_bf16_f32 v27, v34, v35
	global_store_dwordx4 v[28:29], v[12:15], off offset:256
	v_cvt_pk_bf16_f32 v10, v16, v17
	v_cvt_pk_bf16_f32 v11, v18, v19
	v_lshl_add_u64 v[12:13], v[8:9], 1, v[150:151]
	v_cvt_pk_bf16_f32 v8, v20, v21
	v_cvt_pk_bf16_f32 v9, v22, v23
	v_cvt_pk_bf16_f32 v4, v4, v5
	v_cvt_pk_bf16_f32 v5, v6, v7
	v_cvt_pk_bf16_f32 v6, v0, v1
	v_cvt_pk_bf16_f32 v7, v2, v3
	s_and_b64 vcc, exec, s[40:41]
	s_mov_b32 s45, s49
	s_mov_b32 s10, s12
	s_mov_b64 s[18:19], s[16:17]
	s_mov_b64 s[20:21], s[14:15]
	global_store_dwordx4 v[28:29], v[24:27], off
	global_store_dwordx4 v[12:13], v[8:11], off
	global_store_dwordx4 v[12:13], v[4:7], off offset:256
	s_cbranch_vccz .LBB1_1526
	s_waitcnt vmcnt(0)
	s_cmpk_gt_u32 s4, 0xff
	s_cbranch_scc1 .LBB1_1533
	s_barrier

; #define PG8_STAGE(bufoff, gbase, voff) do { _Pragma("unroll") for (int _i = 0; _i < 2; ++_i) \
;         __builtin_amdgcn_global_load_lds((const unsigned*)((const char*)(gbase) + (voff)[_i]), (LAS unsigned*)(lds + (bufoff) + ldsw + _i * 8192), 16, 0, 0); } while (0)
; #define PG8_LDA(dst, b, h) do { _Pragma("unroll") for (int m = 0; m < 4; ++m) _Pragma("unroll") for (int k = 0; k < 2; ++k) dst[m][k] = *(const LAS bf16x8*)(lds + PG8_SA(b, h) + aoff + m * 2048 + k * 1024); } while (0)
; #define PG8_LDB(dst, b, h) do { _Pragma("unroll") for (int n = 0; n < 2; ++n) _Pragma("unroll") for (int k = 0; k < 2; ++k) dst[n][k] = *(const LAS bf16x8*)(lds + PG8_SB(b, h) + boff + n * 2048 + k * 1024); } while (0)
; #define PG8_MMA(ai, bj, At, Bt) do { __builtin_amdgcn_s_setprio(1); _Pragma("unroll") for (int m = 0; m < 4; ++m) _Pragma("unroll") for (int n = 0; n < 2; ++n) _Pragma("unroll") for (int k = 0; k < 2; ++k) \
;         acc[ai][bj][m][n] = __builtin_amdgcn_mfma_f32_16x16x32_bf16(Bt[n][k], At[m][k], acc[ai][bj][m][n], 0, 0, 0); __builtin_amdgcn_s_setprio(0); } while (0)
; #define PG8_WAIT_V(n) asm volatile("s_waitcnt vmcnt(" #n ")" ::: "memory")
; #define PG8_WAIT_L(n) asm volatile("s_waitcnt lgkmcnt(" #n ")" ::: "memory")
; template <class Map, class Epi>
; DI void gemm_phase(LAS unsigned char* lds, const Map& MP, const Epi& E, const int nM, const int nN, const int K, const int lda, const int ldb) {
;     ...
;         for (int t = 0; t < nt; t += 2) {
;             const bool last = (t == nt - 2);
;             const char* a1 = cA + (size_t)(t + 1) * kstep;
;             const char* a2 = last ? nA : cA + (size_t)(t + 2) * kstep; const char* b2 = last ? nB : cB + (size_t)(t + 2) * kstep;
;             const char* a3 = a2 + kstep; const char* b3 = b2 + kstep;
;             PG8_LDB(B0, 0, 0); PG8_SCHED; PG8_LDA(At, 0, 0); PG8_STAGE(PG8_SA(1, 1), a1 + hstepA, voffA);
;             PG8_WAIT_L(8); PG8_BAR; PG8_WAIT_L(0); PG8_MMA(0, 0, At, B0); PG8_BAR; PG8_SCHED;
;             PG8_LDB(B1, 0, 1); PG8_STAGE(PG8_SB(0, 0), b2, voffB);
;             PG8_BAR; PG8_WAIT_L(0); PG8_MMA(0, 1, At, B1); PG8_BAR;
;             PG8_LDA(At, 0, 1); PG8_STAGE(PG8_SA(0, 0), a2, voffA);
;             PG8_BAR; PG8_WAIT_L(0); PG8_MMA(1, 0, At, B0); PG8_BAR; PG8_SCHED;
;             PG8_STAGE(PG8_SB(0, 1), b2 + hstepB, voffB);
;             PG8_WAIT_V(6); PG8_BAR; PG8_MMA(1, 1, At, B1); PG8_BAR;
.LBB1_1764:
	s_add_i32 m0, s24, 0xc000
	ds_read_b128 v[168:171], v150
	ds_read_b128 v[172:175], v150 offset:1024
	ds_read_b128 v[176:179], v150 offset:2048
	ds_read_b128 v[180:183], v150 offset:3072
	ds_read_b128 v[184:187], v150 offset:4096
	ds_read_b128 v[188:191], v150 offset:5120
	ds_read_b128 v[192:195], v150 offset:6144
	ds_read_b128 v[198:201], v150 offset:7168
	global_load_lds_dwordx4 v138, s[10:11]
	s_add_i32 m0, s24, 0xe000
	s_setprio 1
	global_load_lds_dwordx4 v136, s[10:11]
	s_waitcnt lgkmcnt(8)
	s_barrier
	s_waitcnt lgkmcnt(7)
	v_mfma_f32_16x16x32_bf16 v[124:127], v[152:155], v[168:171], v[124:127]
	v_mfma_f32_16x16x32_bf16 v[120:123], v[160:163], v[168:171], v[120:123]
	s_waitcnt lgkmcnt(5)
	v_mfma_f32_16x16x32_bf16 v[108:111], v[152:155], v[176:179], v[108:111]
	v_mfma_f32_16x16x32_bf16 v[104:107], v[160:163], v[176:179], v[104:107]
	s_waitcnt lgkmcnt(3)
	v_mfma_f32_16x16x32_bf16 v[92:95], v[152:155], v[184:187], v[92:95]
	v_mfma_f32_16x16x32_bf16 v[88:91], v[160:163], v[184:187], v[88:91]
	s_waitcnt lgkmcnt(1)
	v_mfma_f32_16x16x32_bf16 v[76:79], v[152:155], v[192:195], v[76:79]
	v_mfma_f32_16x16x32_bf16 v[72:75], v[160:163], v[192:195], v[72:75]
	v_mfma_f32_16x16x32_bf16 v[124:127], v[156:159], v[172:175], v[124:127]
	s_add_i32 s49, s35, s22
	v_mfma_f32_16x16x32_bf16 v[120:123], v[164:167], v[172:175], v[120:123]
	v_lshl_add_u64 v[144:145], s[12:13], 0, v[132:133]
	v_mfma_f32_16x16x32_bf16 v[108:111], v[156:159], v[180:183], v[108:111]
	v_lshl_add_u64 v[218:219], s[12:13], 0, v[128:129]
	v_mfma_f32_16x16x32_bf16 v[104:107], v[164:167], v[180:183], v[104:107]
	v_mfma_f32_16x16x32_bf16 v[92:95], v[156:159], v[188:191], v[92:95]
	v_mfma_f32_16x16x32_bf16 v[88:91], v[164:167], v[188:191], v[88:91]
	s_waitcnt lgkmcnt(0)
	v_mfma_f32_16x16x32_bf16 v[76:79], v[156:159], v[198:201], v[76:79]
	v_mfma_f32_16x16x32_bf16 v[72:75], v[164:167], v[198:201], v[72:75]
	s_barrier
	s_setprio 0
	s_mov_b32 m0, s49
	ds_read_b128 v[202:205], v151
	ds_read_b128 v[206:209], v151 offset:1024
	ds_read_b128 v[210:213], v151 offset:2048
	ds_read_b128 v[214:217], v151 offset:3072
	global_load_lds_dwordx4 v[144:145], off
	s_add_i32 m0, s49, 0x2000
	s_setprio 1
	global_load_lds_dwordx4 v[218:219], off
	s_barrier
	s_waitcnt lgkmcnt(3)
	v_mfma_f32_16x16x32_bf16 v[116:119], v[202:205], v[168:171], v[116:119]
	s_waitcnt lgkmcnt(1)
	v_mfma_f32_16x16x32_bf16 v[112:115], v[210:213], v[168:171], v[112:115]
	v_mfma_f32_16x16x32_bf16 v[100:103], v[202:205], v[176:179], v[100:103]
	v_mfma_f32_16x16x32_bf16 v[96:99], v[210:213], v[176:179], v[96:99]
	v_mfma_f32_16x16x32_bf16 v[84:87], v[202:205], v[184:187], v[84:87]
	v_mfma_f32_16x16x32_bf16 v[80:83], v[210:213], v[184:187], v[80:83]
	v_mfma_f32_16x16x32_bf16 v[68:71], v[202:205], v[192:195], v[68:71]
	v_mfma_f32_16x16x32_bf16 v[64:67], v[210:213], v[192:195], v[64:67]
	v_mfma_f32_16x16x32_bf16 v[116:119], v[206:209], v[172:175], v[116:119]
	v_lshl_add_u64 v[222:223], s[14:15], 0, v[130:131]
	s_mov_b32 m0, s24
	s_waitcnt lgkmcnt(0)
	v_mfma_f32_16x16x32_bf16 v[112:115], v[214:217], v[172:175], v[112:115]
	v_lshl_add_u64 v[220:221], s[14:15], 0, v[134:135]
	v_mfma_f32_16x16x32_bf16 v[100:103], v[206:209], v[180:183], v[100:103]
	v_mfma_f32_16x16x32_bf16 v[96:99], v[214:217], v[180:183], v[96:99]
	v_mfma_f32_16x16x32_bf16 v[84:87], v[206:209], v[188:191], v[84:87]
	v_mfma_f32_16x16x32_bf16 v[80:83], v[214:217], v[188:191], v[80:83]
	v_mfma_f32_16x16x32_bf16 v[68:71], v[206:209], v[198:201], v[68:71]
	v_mfma_f32_16x16x32_bf16 v[64:67], v[214:217], v[198:201], v[64:67]
	s_barrier
	s_setprio 0
	ds_read_b128 v[168:171], v150 offset:16384
	ds_read_b128 v[172:175], v150 offset:17408
	ds_read_b128 v[176:179], v150 offset:18432
	ds_read_b128 v[180:183], v150 offset:19456
	ds_read_b128 v[184:187], v150 offset:20480
	ds_read_b128 v[188:191], v150 offset:21504
	ds_read_b128 v[192:195], v150 offset:22528
	ds_read_b128 v[198:201], v150 offset:23552
	global_load_lds_dwordx4 v[220:221], off
	s_mov_b32 m0, s9
	s_setprio 1
	global_load_lds_dwordx4 v[222:223], off
	s_waitcnt vmcnt(10)
	s_barrier
	s_waitcnt lgkmcnt(7)
	v_mfma_f32_16x16x32_bf16 v[60:63], v[152:155], v[168:171], v[60:63]
	v_mfma_f32_16x16x32_bf16 v[56:59], v[160:163], v[168:171], v[56:59]
	s_waitcnt lgkmcnt(5)
	v_mfma_f32_16x16x32_bf16 v[44:47], v[152:155], v[176:179], v[44:47]
	v_mfma_f32_16x16x32_bf16 v[40:43], v[160:163], v[176:179], v[40:43]
	s_waitcnt lgkmcnt(3)
	v_mfma_f32_16x16x32_bf16 v[28:31], v[152:155], v[184:187], v[28:31]
	v_mfma_f32_16x16x32_bf16 v[24:27], v[160:163], v[184:187], v[24:27]
	s_waitcnt lgkmcnt(1)
	v_mfma_f32_16x16x32_bf16 v[12:15], v[152:155], v[192:195], v[12:15]
	v_mfma_f32_16x16x32_bf16 v[8:11], v[160:163], v[192:195], v[8:11]
	v_mfma_f32_16x16x32_bf16 v[60:63], v[156:159], v[172:175], v[60:63]
	s_add_u32 s54, s12, 0x80000
	s_addc_u32 s55, s13, 0
	v_mfma_f32_16x16x32_bf16 v[56:59], v[164:167], v[172:175], v[56:59]
	s_add_i32 s49, s36, s22
	v_mfma_f32_16x16x32_bf16 v[44:47], v[156:159], v[180:183], v[44:47]
	v_mfma_f32_16x16x32_bf16 v[40:43], v[164:167], v[180:183], v[40:43]
	v_mfma_f32_16x16x32_bf16 v[28:31], v[156:159], v[188:191], v[28:31]
	v_mfma_f32_16x16x32_bf16 v[24:27], v[164:167], v[188:191], v[24:27]
	s_waitcnt lgkmcnt(0)
	v_mfma_f32_16x16x32_bf16 v[12:15], v[156:159], v[198:201], v[12:15]
	v_mfma_f32_16x16x32_bf16 v[8:11], v[164:167], v[198:201], v[8:11]
	s_barrier
	s_setprio 0
	s_mov_b32 m0, s49
	s_nop 0
	global_load_lds_dwordx4 v132, s[54:55]
	s_add_i32 m0, s49, 0x2000
	s_setprio 1
	global_load_lds_dwordx4 v128, s[54:55]
	s_waitcnt vmcnt(6)
	s_barrier
; #define PG8_STAGE(bufoff, gbase, voff) do { _Pragma("unroll") for (int _i = 0; _i < 2; ++_i) \
;         __builtin_amdgcn_global_load_lds((const unsigned*)((const char*)(gbase) + (voff)[_i]), (LAS unsigned*)(lds + (bufoff) + ldsw + _i * 8192), 16, 0, 0); } while (0)
; #define PG8_LDA(dst, b, h) do { _Pragma("unroll") for (int m = 0; m < 4; ++m) _Pragma("unroll") for (int k = 0; k < 2; ++k) dst[m][k] = *(const LAS bf16x8*)(lds + PG8_SA(b, h) + aoff + m * 2048 + k * 1024); } while (0)
; #define PG8_LDB(dst, b, h) do { _Pragma("unroll") for (int n = 0; n < 2; ++n) _Pragma("unroll") for (int k = 0; k < 2; ++k) dst[n][k] = *(const LAS bf16x8*)(lds + PG8_SB(b, h) + boff + n * 2048 + k * 1024); } while (0)
; #define PG8_MMA(ai, bj, At, Bt) do { __builtin_amdgcn_s_setprio(1); _Pragma("unroll") for (int m = 0; m < 4; ++m) _Pragma("unroll") for (int n = 0; n < 2; ++n) _Pragma("unroll") for (int k = 0; k < 2; ++k) \
;         acc[ai][bj][m][n] = __builtin_amdgcn_mfma_f32_16x16x32_bf16(Bt[n][k], At[m][k], acc[ai][bj][m][n], 0, 0, 0); __builtin_amdgcn_s_setprio(0); } while (0)
; #define PG8_WAIT_V(n) asm volatile("s_waitcnt vmcnt(" #n ")" ::: "memory")
; #define PG8_WAIT_L(n) asm volatile("s_waitcnt lgkmcnt(" #n ")" ::: "memory")
; #define PG8_BAR __builtin_amdgcn_s_barrier()
; #define PG8_SCHED __builtin_amdgcn_sched_barrier(0)
; template <class Map, class Epi>
; DI void gemm_phase(LAS unsigned char* lds, const Map& MP, const Epi& E, const int nM, const int nN, const int K, const int lda, const int ldb) {
;     ...
;             PG8_WAIT_V(6); PG8_BAR; PG8_MMA(1, 1, At, B1); PG8_BAR;
;             PG8_LDB(B0, 1, 0); PG8_SCHED; PG8_LDA(At, 1, 0); PG8_STAGE(PG8_SA(0, 1), a2 + hstepA, voffA);
;             PG8_WAIT_L(8); PG8_BAR; PG8_WAIT_L(0); PG8_MMA(0, 0, At, B0); PG8_BAR; PG8_SCHED;
;             PG8_LDB(B1, 1, 1); PG8_STAGE(PG8_SB(1, 0), b3, voffB);
;             PG8_BAR; PG8_WAIT_L(0); PG8_MMA(0, 1, At, B1); PG8_BAR;
;             PG8_LDA(At, 1, 1); PG8_STAGE(PG8_SA(1, 0), a3, voffA);
;             PG8_BAR; PG8_WAIT_L(0); PG8_MMA(1, 0, At, B0); PG8_BAR; PG8_SCHED;
	v_mfma_f32_16x16x32_bf16 v[52:55], v[202:205], v[168:171], v[52:55]
	v_mfma_f32_16x16x32_bf16 v[48:51], v[210:213], v[168:171], v[48:51]
	s_add_i32 s49, 0, 0x18000
	v_add_u32_e32 v164, s49, v148
	ds_read_b128 v[152:155], v164
	v_mfma_f32_16x16x32_bf16 v[36:39], v[202:205], v[176:179], v[36:39]
	v_mfma_f32_16x16x32_bf16 v[32:35], v[210:213], v[176:179], v[32:35]
	ds_read_b128 v[156:159], v164 offset:1024
	v_mfma_f32_16x16x32_bf16 v[20:23], v[202:205], v[184:187], v[20:23]
	v_mfma_f32_16x16x32_bf16 v[16:19], v[210:213], v[184:187], v[16:19]
	ds_read_b128 v[160:163], v164 offset:2048
	v_mfma_f32_16x16x32_bf16 v[4:7], v[202:205], v[192:195], v[4:7]
	v_mfma_f32_16x16x32_bf16 v[0:3], v[210:213], v[192:195], v[0:3]
	ds_read_b128 v[164:167], v164 offset:3072
	v_mfma_f32_16x16x32_bf16 v[52:55], v[206:209], v[172:175], v[52:55]
	s_add_u32 s14, s14, 0x80000
	s_addc_u32 s15, s15, 0
	v_mfma_f32_16x16x32_bf16 v[48:51], v[214:217], v[172:175], v[48:51]
	v_mfma_f32_16x16x32_bf16 v[36:39], v[206:209], v[180:183], v[36:39]
	v_mfma_f32_16x16x32_bf16 v[32:35], v[214:217], v[180:183], v[32:35]
	v_mfma_f32_16x16x32_bf16 v[20:23], v[206:209], v[188:191], v[20:23]
	v_mfma_f32_16x16x32_bf16 v[16:19], v[214:217], v[188:191], v[16:19]
	v_mfma_f32_16x16x32_bf16 v[4:7], v[206:209], v[198:201], v[4:7]
	v_mfma_f32_16x16x32_bf16 v[0:3], v[214:217], v[198:201], v[0:3]
	s_barrier
	s_setprio 0
	s_mov_b32 m0, s25
	ds_read_b128 v[168:171], v150 offset:32768
	ds_read_b128 v[172:175], v150 offset:33792
	ds_read_b128 v[176:179], v150 offset:34816
	ds_read_b128 v[180:183], v150 offset:35840
	ds_read_b128 v[184:187], v150 offset:36864
	ds_read_b128 v[188:191], v150 offset:37888
	ds_read_b128 v[192:195], v150 offset:38912
	ds_read_b128 v[198:201], v150 offset:39936
	global_load_lds_dwordx4 v134, s[14:15]
	s_mov_b32 m0, s26
	s_setprio 1
	global_load_lds_dwordx4 v130, s[14:15]
	s_waitcnt lgkmcnt(8)
	s_barrier
	s_waitcnt lgkmcnt(7)
	v_mfma_f32_16x16x32_bf16 v[124:127], v[152:155], v[168:171], v[124:127]
	v_mfma_f32_16x16x32_bf16 v[120:123], v[160:163], v[168:171], v[120:123]
	s_waitcnt lgkmcnt(5)
	v_mfma_f32_16x16x32_bf16 v[108:111], v[152:155], v[176:179], v[108:111]
	v_mfma_f32_16x16x32_bf16 v[104:107], v[160:163], v[176:179], v[104:107]
	s_waitcnt lgkmcnt(3)
	v_mfma_f32_16x16x32_bf16 v[92:95], v[152:155], v[184:187], v[92:95]
	v_mfma_f32_16x16x32_bf16 v[88:91], v[160:163], v[184:187], v[88:91]
	s_waitcnt lgkmcnt(1)
	v_mfma_f32_16x16x32_bf16 v[76:79], v[152:155], v[192:195], v[76:79]
	v_mfma_f32_16x16x32_bf16 v[72:75], v[160:163], v[192:195], v[72:75]
	v_mfma_f32_16x16x32_bf16 v[124:127], v[156:159], v[172:175], v[124:127]
	s_add_i32 s14, 0, 0x1c000
	v_mfma_f32_16x16x32_bf16 v[120:123], v[164:167], v[172:175], v[120:123]
	s_add_i32 s15, s49, s22
	v_mfma_f32_16x16x32_bf16 v[108:111], v[156:159], v[180:183], v[108:111]
	v_add_u32_e32 v196, s14, v148
	v_mfma_f32_16x16x32_bf16 v[104:107], v[164:167], v[180:183], v[104:107]
	v_lshl_add_u64 v[144:145], v[144:145], 0, s[42:43]
	v_mfma_f32_16x16x32_bf16 v[92:95], v[156:159], v[188:191], v[92:95]
	v_mfma_f32_16x16x32_bf16 v[88:91], v[164:167], v[188:191], v[88:91]
	s_waitcnt lgkmcnt(0)
	v_mfma_f32_16x16x32_bf16 v[76:79], v[156:159], v[198:201], v[76:79]
	v_mfma_f32_16x16x32_bf16 v[72:75], v[164:167], v[198:201], v[72:75]
	s_barrier
	s_setprio 0
	s_mov_b32 m0, s15
	ds_read_b128 v[202:205], v196
	ds_read_b128 v[206:209], v196 offset:1024
	ds_read_b128 v[210:213], v196 offset:2048
	ds_read_b128 v[214:217], v196 offset:3072
	global_load_lds_dwordx4 v[144:145], off
	v_lshl_add_u64 v[144:145], v[218:219], 0, s[42:43]
	s_add_i32 m0, s15, 0x2000
	s_setprio 1
	global_load_lds_dwordx4 v[144:145], off
	s_barrier
	s_waitcnt lgkmcnt(3)
	v_mfma_f32_16x16x32_bf16 v[116:119], v[202:205], v[168:171], v[116:119]
	s_waitcnt lgkmcnt(1)
	v_mfma_f32_16x16x32_bf16 v[112:115], v[210:213], v[168:171], v[112:115]
	v_mfma_f32_16x16x32_bf16 v[100:103], v[202:205], v[176:179], v[100:103]
	v_mfma_f32_16x16x32_bf16 v[96:99], v[210:213], v[176:179], v[96:99]
	v_mfma_f32_16x16x32_bf16 v[84:87], v[202:205], v[184:187], v[84:87]
	v_mfma_f32_16x16x32_bf16 v[80:83], v[210:213], v[184:187], v[80:83]
	v_mfma_f32_16x16x32_bf16 v[68:71], v[202:205], v[192:195], v[68:71]
	v_mfma_f32_16x16x32_bf16 v[64:67], v[210:213], v[192:195], v[64:67]
	v_mfma_f32_16x16x32_bf16 v[116:119], v[206:209], v[172:175], v[116:119]
	s_mov_b32 m0, s30
	s_waitcnt lgkmcnt(0)
	v_mfma_f32_16x16x32_bf16 v[112:115], v[214:217], v[172:175], v[112:115]
	v_lshl_add_u64 v[144:145], v[220:221], 0, s[42:43]
	v_mfma_f32_16x16x32_bf16 v[100:103], v[206:209], v[180:183], v[100:103]
	v_mfma_f32_16x16x32_bf16 v[96:99], v[214:217], v[180:183], v[96:99]
	v_mfma_f32_16x16x32_bf16 v[84:87], v[206:209], v[188:191], v[84:87]
	v_mfma_f32_16x16x32_bf16 v[80:83], v[214:217], v[188:191], v[80:83]
	v_mfma_f32_16x16x32_bf16 v[68:71], v[206:209], v[198:201], v[68:71]
	v_mfma_f32_16x16x32_bf16 v[64:67], v[214:217], v[198:201], v[64:67]
	s_barrier
	s_setprio 0
	ds_read_b128 v[168:171], v150 offset:49152
	ds_read_b128 v[172:175], v150 offset:50176
	ds_read_b128 v[176:179], v150 offset:51200
	ds_read_b128 v[180:183], v150 offset:52224
	ds_read_b128 v[184:187], v150 offset:53248
	ds_read_b128 v[188:191], v150 offset:54272
	ds_read_b128 v[192:195], v150 offset:55296
	ds_read_b128 v[198:201], v150 offset:56320
	global_load_lds_dwordx4 v[144:145], off
	v_lshl_add_u64 v[144:145], v[222:223], 0, s[42:43]
	s_mov_b32 m0, s31
	s_setprio 1
	global_load_lds_dwordx4 v[144:145], off
	s_waitcnt vmcnt(10)
	s_barrier
;     DI void operator()(const f32x4 (&acc)[2][2][4][2], const Unit& u, int wr, int wc, int fr, int fq) const {
;     ...
;         for (int ai = 0; ai < 2; ++ai)
; #pragma unroll
;             for (int m = 0; m < 4; ++m) { const size_t ro = (size_t)(row0 + ai * HALF + m * 16) * D + col0;
; #pragma unroll
;                 for (int bj = 0; bj < 2; ++bj) {
;                     f32x4 x0, x1;
;                     if constexpr (IB) { const u32x4 w = *(const u32x4*)((const bf16_t*)Xin + ro + bj * HALF);
;                         x0 = (f32x4){bflo(w[0]), bfhi(w[0]), bflo(w[1]), bfhi(w[1])}; x1 = (f32x4){bflo(w[2]), bfhi(w[2]), bflo(w[3]), bfhi(w[3])}; }
; template <class Map, class Epi>
; DI void gemm_phase(LAS unsigned char* lds, const Map& MP, const Epi& E, const int nM, const int nN, const int K, const int lda, const int ldb) {
;     ...
;             const bool last = (t == nt - 2);
;             const char* a1 = cA + (size_t)(t + 1) * kstep;
;             const char* a2 = last ? nA : cA + (size_t)(t + 2) * kstep; const char* b2 = last ? nB : cB + (size_t)(t + 2) * kstep;
;             const char* a3 = a2 + kstep; const char* b3 = b2 + kstep;
;             PG8_LDB(B0, 0, 0); PG8_SCHED; PG8_LDA(At, 0, 0); PG8_STAGE(PG8_SA(1, 1), a1 + hstepA, voffA);
;             PG8_WAIT_L(8); PG8_BAR; PG8_WAIT_L(0); PG8_MMA(0, 0, At, B0); PG8_BAR; PG8_SCHED;
;             PG8_LDB(B1, 0, 1); PG8_STAGE(PG8_SB(0, 0), b2, voffB);
;             PG8_BAR; PG8_WAIT_L(0); PG8_MMA(0, 1, At, B1); PG8_BAR;
;             PG8_LDA(At, 0, 1); PG8_STAGE(PG8_SA(0, 0), a2, voffA);
;             PG8_BAR; PG8_WAIT_L(0); PG8_MMA(1, 0, At, B0); PG8_BAR; PG8_SCHED;
;             PG8_STAGE(PG8_SB(0, 1), b2 + hstepB, voffB);
;             PG8_WAIT_V(6); PG8_BAR; PG8_MMA(1, 1, At, B1); PG8_BAR;
;             PG8_LDB(B0, 1, 0); PG8_SCHED; PG8_LDA(At, 1, 0); PG8_STAGE(PG8_SA(0, 1), a2 + hstepA, voffA);
;             PG8_WAIT_L(8); PG8_BAR; PG8_WAIT_L(0); PG8_MMA(0, 0, At, B0); PG8_BAR; PG8_SCHED;
;             PG8_LDB(B1, 1, 1); PG8_STAGE(PG8_SB(1, 0), b3, voffB);
;             PG8_BAR; PG8_WAIT_L(0); PG8_MMA(0, 1, At, B1); PG8_BAR;
;             PG8_LDA(At, 1, 1); PG8_STAGE(PG8_SA(1, 0), a3, voffA);
;             PG8_BAR; PG8_WAIT_L(0); PG8_MMA(1, 0, At, B0); PG8_BAR; PG8_SCHED;
;             PG8_STAGE(PG8_SB(1, 1), b3 + hstepB, voffB);
;             PG8_WAIT_V(6); PG8_BAR; PG8_MMA(1, 1, At, B1); PG8_BAR;
	s_waitcnt lgkmcnt(7)
	v_mfma_f32_16x16x32_bf16 v[60:63], v[152:155], v[168:171], v[60:63]
	v_mfma_f32_16x16x32_bf16 v[56:59], v[160:163], v[168:171], v[56:59]
	s_waitcnt lgkmcnt(5)
	v_mfma_f32_16x16x32_bf16 v[44:47], v[152:155], v[176:179], v[44:47]
	v_mfma_f32_16x16x32_bf16 v[40:43], v[160:163], v[176:179], v[40:43]
	s_waitcnt lgkmcnt(3)
	v_mfma_f32_16x16x32_bf16 v[28:31], v[152:155], v[184:187], v[28:31]
	v_mfma_f32_16x16x32_bf16 v[24:27], v[160:163], v[184:187], v[24:27]
	s_waitcnt lgkmcnt(1)
	v_mfma_f32_16x16x32_bf16 v[12:15], v[152:155], v[192:195], v[12:15]
	v_mfma_f32_16x16x32_bf16 v[8:11], v[160:163], v[192:195], v[8:11]
	v_mfma_f32_16x16x32_bf16 v[60:63], v[156:159], v[172:175], v[60:63]
	s_add_u32 s12, s12, 0x80080
	s_addc_u32 s13, s13, 0
	v_mfma_f32_16x16x32_bf16 v[56:59], v[164:167], v[172:175], v[56:59]
	s_add_i32 s14, s14, s22
	v_mfma_f32_16x16x32_bf16 v[44:47], v[156:159], v[180:183], v[44:47]
	v_mfma_f32_16x16x32_bf16 v[40:43], v[164:167], v[180:183], v[40:43]
	v_mfma_f32_16x16x32_bf16 v[28:31], v[156:159], v[188:191], v[28:31]
	v_mfma_f32_16x16x32_bf16 v[24:27], v[164:167], v[188:191], v[24:27]
	s_waitcnt lgkmcnt(0)
	v_mfma_f32_16x16x32_bf16 v[12:15], v[156:159], v[198:201], v[12:15]
	v_mfma_f32_16x16x32_bf16 v[8:11], v[164:167], v[198:201], v[8:11]
	s_barrier
	s_setprio 0
	s_mov_b32 m0, s14
	s_nop 0
	global_load_lds_dwordx4 v132, s[12:13]
	s_add_i32 m0, s14, 0x2000
	s_setprio 1
	global_load_lds_dwordx4 v128, s[12:13]
	s_waitcnt vmcnt(6)
	s_barrier
	v_mfma_f32_16x16x32_bf16 v[52:55], v[202:205], v[168:171], v[52:55]
	v_mfma_f32_16x16x32_bf16 v[48:51], v[210:213], v[168:171], v[48:51]
	ds_read_b128 v[152:155], v149
	v_mfma_f32_16x16x32_bf16 v[36:39], v[202:205], v[176:179], v[36:39]
	v_mfma_f32_16x16x32_bf16 v[32:35], v[210:213], v[176:179], v[32:35]
	ds_read_b128 v[156:159], v149 offset:1024
	v_mfma_f32_16x16x32_bf16 v[20:23], v[202:205], v[184:187], v[20:23]
	v_mfma_f32_16x16x32_bf16 v[16:19], v[210:213], v[184:187], v[16:19]
	ds_read_b128 v[160:163], v149 offset:2048
	v_mfma_f32_16x16x32_bf16 v[4:7], v[202:205], v[192:195], v[4:7]
	v_mfma_f32_16x16x32_bf16 v[0:3], v[210:213], v[192:195], v[0:3]
	ds_read_b128 v[164:167], v149 offset:3072
	v_mfma_f32_16x16x32_bf16 v[52:55], v[206:209], v[172:175], v[52:55]
	s_add_i32 s3, s3, 2
	v_mfma_f32_16x16x32_bf16 v[48:51], v[214:217], v[172:175], v[48:51]
	s_add_u32 s47, s47, 0x100
	s_addc_u32 s48, s48, 0
	v_mfma_f32_16x16x32_bf16 v[36:39], v[206:209], v[180:183], v[36:39]
	s_add_u32 s10, s10, 0x100
	s_addc_u32 s11, s11, 0
	v_mfma_f32_16x16x32_bf16 v[32:35], v[214:217], v[180:183], v[32:35]
	s_add_u32 s12, s10, 0xfff80080
	s_addc_u32 s13, s11, -1
	s_cmp_eq_u32 s3, 28
	s_cselect_b32 s15, s37, s13
	s_cselect_b32 s14, s38, s12
	s_cselect_b32 s13, s39, s48
	s_cselect_b32 s12, s45, s47
	s_cmp_gt_u32 s3, 29
	v_mfma_f32_16x16x32_bf16 v[20:23], v[206:209], v[188:191], v[20:23]
	v_mfma_f32_16x16x32_bf16 v[16:19], v[214:217], v[188:191], v[16:19]
	v_mfma_f32_16x16x32_bf16 v[4:7], v[206:209], v[198:201], v[4:7]
	v_mfma_f32_16x16x32_bf16 v[0:3], v[214:217], v[198:201], v[0:3]
	s_barrier
	s_setprio 0
	s_cbranch_scc0 .LBB1_1764
	s_waitcnt lgkmcnt(0)
	v_mov_b32_e32 v152, v147
	v_mov_b32_e32 v144, v146
	s_lshl_b32 s2, s2, 8
	s_or_b32 s2, s2, s29
	v_lshl_add_u32 v144, v144, 3, s2
	s_lshl_b32 s2, s8, 8
	s_add_i32 s2, s2, s28
	v_add_u32_e32 v152, s2, v152
	v_ashrrev_i32_e32 v153, 31, v152
	v_lshlrev_b64 v[152:153], 12, v[152:153]
	v_ashrrev_i32_e32 v145, 31, v144
	v_lshl_add_u64 v[152:153], s[4:5], 0, v[152:153]
	v_lshl_add_u64 v[144:145], v[144:145], 1, v[152:153]
	global_load_dwordx4 v[160:163], v[144:145], off
	global_load_dwordx4 v[164:167], v[144:145], off offset:256
	s_mov_b64 s[98:99], 0x10000
	v_lshl_add_u64 v[154:155], v[144:145], 0, s[98:99]
	global_load_dwordx4 v[168:171], v[154:155], off
	global_load_dwordx4 v[172:175], v[154:155], off offset:256
	s_mov_b64 s[98:99], 0x20000
	v_lshl_add_u64 v[154:155], v[144:145], 0, s[98:99]
	global_load_dwordx4 v[176:179], v[154:155], off
	global_load_dwordx4 v[180:183], v[154:155], off offset:256
	s_mov_b64 s[98:99], 0x30000
	v_lshl_add_u64 v[154:155], v[144:145], 0, s[98:99]
	global_load_dwordx4 v[184:187], v[154:155], off
	global_load_dwordx4 v[188:191], v[154:155], off offset:256
	s_mov_b64 s[98:99], 0x80000
	v_lshl_add_u64 v[154:155], v[144:145], 0, s[98:99]
	global_load_dwordx4 v[192:195], v[154:155], off
	global_load_dwordx4 v[198:201], v[154:155], off offset:256
	s_mov_b64 s[98:99], 0x90000
	v_lshl_add_u64 v[154:155], v[144:145], 0, s[98:99]
	global_load_dwordx4 v[202:205], v[154:155], off
	global_load_dwordx4 v[206:209], v[154:155], off offset:256
	s_mov_b64 s[98:99], 0xa0000
	v_lshl_add_u64 v[154:155], v[144:145], 0, s[98:99]
	global_load_dwordx4 v[210:213], v[154:155], off
	global_load_dwordx4 v[214:217], v[154:155], off offset:256
	s_mov_b64 s[98:99], 0xb0000
	v_lshl_add_u64 v[154:155], v[144:145], 0, s[98:99]
	global_load_dwordx4 v[248:251], v[154:155], off
	global_load_dwordx4 v[252:255], v[154:155], off offset:256
	s_waitcnt vmcnt(15)
	s_nop 1
	v_mov_b32_e32 v152, v160
	v_mov_b32_e32 v153, v161
	v_mov_b32_e32 v154, v162
	v_mov_b32_e32 v155, v163
	s_mov_b64 s[2:3], 0x10000
	s_mov_b32 s8, s46
	s_mov_b64 s[10:11], s[6:7]
	s_mov_b64 s[12:13], s[52:53]
	s_waitcnt lgkmcnt(0)
	v_lshlrev_b32_e32 v156, 16, v152
	v_and_b32_e32 v157, 0xffff0000, v152
	v_lshlrev_b32_e32 v152, 16, v153
	v_and_b32_e32 v153, 0xffff0000, v153
	v_lshlrev_b32_e32 v158, 16, v154
	v_and_b32_e32 v159, 0xffff0000, v154
	v_lshlrev_b32_e32 v154, 16, v155
	v_and_b32_e32 v155, 0xffff0000, v155
	v_pk_add_f32 v[126:127], v[126:127], v[152:153]
	v_pk_add_f32 v[124:125], v[124:125], v[156:157]
	v_pk_add_f32 v[152:153], v[122:123], v[154:155]
	v_pk_add_f32 v[122:123], v[120:121], v[158:159]
	v_cvt_pk_bf16_f32 v120, v124, v125
	v_cvt_pk_bf16_f32 v121, v126, v127
	v_cvt_pk_bf16_f32 v122, v122, v123
	v_cvt_pk_bf16_f32 v123, v152, v153
	global_store_dwordx4 v[144:145], v[120:123], off
	s_waitcnt vmcnt(15)
; DI unsigned pack2(float a, float b) { f32x2 v = {a, b}; hwbf16x2 r = __builtin_convertvector(v, hwbf16x2); return __builtin_bit_cast(unsigned, r); }
; DI float bflo(unsigned w) { return __uint_as_float(w << 16); }
; DI float bfhi(unsigned w) { return __uint_as_float(w & 0xffff0000u); }
;     DI void operator()(const f32x4 (&acc)[2][2][4][2], const Unit& u, int wr, int wc, int fr, int fq) const {
;     ...
;         for (int ai = 0; ai < 2; ++ai)
; #pragma unroll
;             for (int m = 0; m < 4; ++m) { const size_t ro = (size_t)(row0 + ai * HALF + m * 16) * D + col0;
; #pragma unroll
;                 for (int bj = 0; bj < 2; ++bj) {
;                     f32x4 x0, x1;
;                     if constexpr (IB) { const u32x4 w = *(const u32x4*)((const bf16_t*)Xin + ro + bj * HALF);
;                         x0 = (f32x4){bflo(w[0]), bfhi(w[0]), bflo(w[1]), bfhi(w[1])}; x1 = (f32x4){bflo(w[2]), bfhi(w[2]), bflo(w[3]), bfhi(w[3])}; }
;                     else { x0 = *(const f32x4*)((const float*)Xin + ro + bj * HALF); x1 = *(const f32x4*)((const float*)Xin + ro + bj * HALF + 4); }
;                     x0 += acc[ai][bj][m][0] * sc[bj][0]; x1 += acc[ai][bj][m][1] * sc[bj][1];
;                     if constexpr (OB) { u32x4 o; o[0] = pack2(x0[0], x0[1]); o[1] = pack2(x0[2], x0[3]); o[2] = pack2(x1[0], x1[1]); o[3] = pack2(x1[2], x1[3]);
;                         *(u32x4*)((bf16_t*)Xout + ro + bj * HALF) = o; }
;                     else { *(f32x4*)((float*)Xout + ro + bj * HALF) = x0; *(f32x4*)((float*)Xout + ro + bj * HALF + 4) = x1; } } }
	s_nop 1
	v_mov_b32_e32 v120, v164
	v_mov_b32_e32 v121, v165
	v_mov_b32_e32 v122, v166
	v_mov_b32_e32 v123, v167
	s_waitcnt lgkmcnt(0)
	v_lshlrev_b32_e32 v124, 16, v120
	v_and_b32_e32 v125, 0xffff0000, v120
	v_lshlrev_b32_e32 v120, 16, v121
	v_and_b32_e32 v121, 0xffff0000, v121
	v_lshlrev_b32_e32 v126, 16, v122
	v_and_b32_e32 v127, 0xffff0000, v122
	v_lshlrev_b32_e32 v122, 16, v123
	v_and_b32_e32 v123, 0xffff0000, v123
	v_pk_add_f32 v[116:117], v[116:117], v[124:125]
	v_pk_add_f32 v[118:119], v[118:119], v[120:121]
	v_pk_add_f32 v[120:121], v[114:115], v[122:123]
	v_pk_add_f32 v[114:115], v[112:113], v[126:127]
	v_cvt_pk_bf16_f32 v112, v116, v117
	v_lshl_add_u64 v[116:117], v[144:145], 0, s[2:3]
	s_mov_b32 s2, 0x10000
	v_cvt_pk_bf16_f32 v113, v118, v119
	v_add_co_u32_e32 v118, vcc, s2, v144
	v_cvt_pk_bf16_f32 v114, v114, v115
	v_cvt_pk_bf16_f32 v115, v120, v121
	v_addc_co_u32_e32 v119, vcc, 0, v145, vcc
	global_store_dwordx4 v[144:145], v[112:115], off offset:256
	s_waitcnt vmcnt(15)
	s_nop 1
	v_mov_b32_e32 v112, v168
	v_mov_b32_e32 v113, v169
	v_mov_b32_e32 v114, v170
	v_mov_b32_e32 v115, v171
	s_mov_b64 s[2:3], 0x20000
	s_waitcnt lgkmcnt(0)
	v_lshlrev_b32_e32 v120, 16, v112
	v_and_b32_e32 v121, 0xffff0000, v112
	v_lshlrev_b32_e32 v112, 16, v113
	v_and_b32_e32 v113, 0xffff0000, v113
	v_lshlrev_b32_e32 v122, 16, v114
	v_and_b32_e32 v123, 0xffff0000, v114
	v_lshlrev_b32_e32 v114, 16, v115
	v_and_b32_e32 v115, 0xffff0000, v115
	v_pk_add_f32 v[110:111], v[110:111], v[112:113]
	v_pk_add_f32 v[108:109], v[108:109], v[120:121]
	v_pk_add_f32 v[112:113], v[106:107], v[114:115]
	v_pk_add_f32 v[106:107], v[104:105], v[122:123]
	v_cvt_pk_bf16_f32 v104, v108, v109
	v_cvt_pk_bf16_f32 v105, v110, v111
	v_cvt_pk_bf16_f32 v106, v106, v107
	v_cvt_pk_bf16_f32 v107, v112, v113
	global_store_dwordx4 v[118:119], v[104:107], off
	s_waitcnt vmcnt(15)
	s_nop 1
	v_mov_b32_e32 v104, v172
	v_mov_b32_e32 v105, v173
	v_mov_b32_e32 v106, v174
	v_mov_b32_e32 v107, v175
	s_waitcnt lgkmcnt(0)
	v_lshlrev_b32_e32 v108, 16, v104
	v_and_b32_e32 v109, 0xffff0000, v104
	v_lshlrev_b32_e32 v104, 16, v105
	v_and_b32_e32 v105, 0xffff0000, v105
	v_lshlrev_b32_e32 v110, 16, v106
	v_and_b32_e32 v111, 0xffff0000, v106
	v_lshlrev_b32_e32 v106, 16, v107
	v_and_b32_e32 v107, 0xffff0000, v107
	v_pk_add_f32 v[100:101], v[100:101], v[108:109]
	v_pk_add_f32 v[102:103], v[102:103], v[104:105]
	v_pk_add_f32 v[104:105], v[98:99], v[106:107]
	v_pk_add_f32 v[98:99], v[96:97], v[110:111]
	v_cvt_pk_bf16_f32 v96, v100, v101
	v_lshl_add_u64 v[100:101], v[144:145], 0, s[2:3]
	s_mov_b32 s2, 0x20000
	v_cvt_pk_bf16_f32 v97, v102, v103
	v_add_co_u32_e32 v102, vcc, s2, v144
	v_cvt_pk_bf16_f32 v98, v98, v99
	v_cvt_pk_bf16_f32 v99, v104, v105
	v_addc_co_u32_e32 v103, vcc, 0, v145, vcc
	global_store_dwordx4 v[116:117], v[96:99], off offset:256
	s_waitcnt vmcnt(15)
	s_nop 1
	v_mov_b32_e32 v96, v176
	v_mov_b32_e32 v97, v177
	v_mov_b32_e32 v98, v178
	v_mov_b32_e32 v99, v179
	s_mov_b64 s[2:3], 0x30000
	s_waitcnt lgkmcnt(0)
	v_lshlrev_b32_e32 v104, 16, v96
	v_and_b32_e32 v105, 0xffff0000, v96
	v_lshlrev_b32_e32 v96, 16, v97
	v_and_b32_e32 v97, 0xffff0000, v97
	v_lshlrev_b32_e32 v106, 16, v98
	v_and_b32_e32 v107, 0xffff0000, v98
	v_lshlrev_b32_e32 v98, 16, v99
	v_and_b32_e32 v99, 0xffff0000, v99
	v_pk_add_f32 v[94:95], v[94:95], v[96:97]
	v_pk_add_f32 v[92:93], v[92:93], v[104:105]
	v_pk_add_f32 v[96:97], v[90:91], v[98:99]
	v_pk_add_f32 v[90:91], v[88:89], v[106:107]
	v_cvt_pk_bf16_f32 v88, v92, v93
	v_cvt_pk_bf16_f32 v89, v94, v95
	v_cvt_pk_bf16_f32 v90, v90, v91
	v_cvt_pk_bf16_f32 v91, v96, v97
	global_store_dwordx4 v[102:103], v[88:91], off
	s_waitcnt vmcnt(15)
	s_nop 1
	v_mov_b32_e32 v88, v180
	v_mov_b32_e32 v89, v181
	v_mov_b32_e32 v90, v182
	v_mov_b32_e32 v91, v183
	s_waitcnt lgkmcnt(0)
	v_lshlrev_b32_e32 v92, 16, v88
	v_and_b32_e32 v93, 0xffff0000, v88
	v_lshlrev_b32_e32 v88, 16, v89
	v_and_b32_e32 v89, 0xffff0000, v89
	v_lshlrev_b32_e32 v94, 16, v90
	v_and_b32_e32 v95, 0xffff0000, v90
	v_lshlrev_b32_e32 v90, 16, v91
	v_and_b32_e32 v91, 0xffff0000, v91
	v_pk_add_f32 v[86:87], v[86:87], v[88:89]
	v_pk_add_f32 v[84:85], v[84:85], v[92:93]
	v_pk_add_f32 v[88:89], v[82:83], v[90:91]
	v_pk_add_f32 v[82:83], v[80:81], v[94:95]
	v_cvt_pk_bf16_f32 v80, v84, v85
	v_cvt_pk_bf16_f32 v81, v86, v87
	v_cvt_pk_bf16_f32 v82, v82, v83
	v_cvt_pk_bf16_f32 v83, v88, v89
	global_store_dwordx4 v[100:101], v[80:83], off offset:256
	s_nop 1
	v_lshl_add_u64 v[80:81], v[144:145], 0, s[2:3]
	s_mov_b32 s2, 0x30000
	v_add_co_u32_e32 v86, vcc, s2, v144
	s_mov_b64 s[2:3], 0x80000
	s_nop 0
	v_addc_co_u32_e32 v87, vcc, 0, v145, vcc
	s_waitcnt vmcnt(15)
	s_nop 1
	v_mov_b32_e32 v82, v184
	v_mov_b32_e32 v83, v185
	v_mov_b32_e32 v84, v186
	v_mov_b32_e32 v85, v187
	s_waitcnt lgkmcnt(0)
	v_lshlrev_b32_e32 v88, 16, v82
	v_and_b32_e32 v89, 0xffff0000, v82
	v_lshlrev_b32_e32 v82, 16, v83
	v_and_b32_e32 v83, 0xffff0000, v83
	v_lshlrev_b32_e32 v90, 16, v84
	v_and_b32_e32 v91, 0xffff0000, v84
	v_lshlrev_b32_e32 v84, 16, v85
	v_and_b32_e32 v85, 0xffff0000, v85
	v_pk_add_f32 v[78:79], v[78:79], v[82:83]
	v_pk_add_f32 v[76:77], v[76:77], v[88:89]
	v_pk_add_f32 v[82:83], v[74:75], v[84:85]
	v_pk_add_f32 v[74:75], v[72:73], v[90:91]
	v_cvt_pk_bf16_f32 v72, v76, v77
	v_cvt_pk_bf16_f32 v73, v78, v79
	v_cvt_pk_bf16_f32 v74, v74, v75
	v_cvt_pk_bf16_f32 v75, v82, v83
	global_store_dwordx4 v[86:87], v[72:75], off
	s_waitcnt vmcnt(15)
	s_nop 1
	v_mov_b32_e32 v72, v188
	v_mov_b32_e32 v73, v189
	v_mov_b32_e32 v74, v190
	v_mov_b32_e32 v75, v191
	s_waitcnt lgkmcnt(0)
; DI unsigned pack2(float a, float b) { f32x2 v = {a, b}; hwbf16x2 r = __builtin_convertvector(v, hwbf16x2); return __builtin_bit_cast(unsigned, r); }
; DI float bflo(unsigned w) { return __uint_as_float(w << 16); }
; DI float bfhi(unsigned w) { return __uint_as_float(w & 0xffff0000u); }
;     DI void operator()(const f32x4 (&acc)[2][2][4][2], const Unit& u, int wr, int wc, int fr, int fq) const {
;     ...
;         for (int ai = 0; ai < 2; ++ai)
; #pragma unroll
;             for (int m = 0; m < 4; ++m) { const size_t ro = (size_t)(row0 + ai * HALF + m * 16) * D + col0;
; #pragma unroll
;                 for (int bj = 0; bj < 2; ++bj) {
;                     f32x4 x0, x1;
;                     if constexpr (IB) { const u32x4 w = *(const u32x4*)((const bf16_t*)Xin + ro + bj * HALF);
;                         x0 = (f32x4){bflo(w[0]), bfhi(w[0]), bflo(w[1]), bfhi(w[1])}; x1 = (f32x4){bflo(w[2]), bfhi(w[2]), bflo(w[3]), bfhi(w[3])}; }
;                     else { x0 = *(const f32x4*)((const float*)Xin + ro + bj * HALF); x1 = *(const f32x4*)((const float*)Xin + ro + bj * HALF + 4); }
;                     x0 += acc[ai][bj][m][0] * sc[bj][0]; x1 += acc[ai][bj][m][1] * sc[bj][1];
;                     if constexpr (OB) { u32x4 o; o[0] = pack2(x0[0], x0[1]); o[1] = pack2(x0[2], x0[3]); o[2] = pack2(x1[0], x1[1]); o[3] = pack2(x1[2], x1[3]);
;                         *(u32x4*)((bf16_t*)Xout + ro + bj * HALF) = o; }
;                     else { *(f32x4*)((float*)Xout + ro + bj * HALF) = x0; *(f32x4*)((float*)Xout + ro + bj * HALF + 4) = x1; } } }
	v_lshlrev_b32_e32 v76, 16, v72
	v_and_b32_e32 v77, 0xffff0000, v72
	v_lshlrev_b32_e32 v72, 16, v73
	v_and_b32_e32 v73, 0xffff0000, v73
	v_lshlrev_b32_e32 v78, 16, v74
	v_and_b32_e32 v79, 0xffff0000, v74
	v_lshlrev_b32_e32 v74, 16, v75
	v_and_b32_e32 v75, 0xffff0000, v75
	v_pk_add_f32 v[70:71], v[70:71], v[72:73]
	v_pk_add_f32 v[68:69], v[68:69], v[76:77]
	v_pk_add_f32 v[72:73], v[66:67], v[74:75]
	v_pk_add_f32 v[66:67], v[64:65], v[78:79]
	v_cvt_pk_bf16_f32 v64, v68, v69
	v_cvt_pk_bf16_f32 v65, v70, v71
	v_cvt_pk_bf16_f32 v66, v66, v67
	v_cvt_pk_bf16_f32 v67, v72, v73
	global_store_dwordx4 v[80:81], v[64:67], off offset:256
	s_nop 1
	v_lshl_add_u64 v[64:65], v[144:145], 0, s[2:3]
	s_mov_b32 s2, 0x80000
	v_add_co_u32_e32 v70, vcc, s2, v144
	s_mov_b64 s[2:3], 0x90000
	s_nop 0
	v_addc_co_u32_e32 v71, vcc, 0, v145, vcc
	s_waitcnt vmcnt(15)
	s_nop 1
	v_mov_b32_e32 v66, v192
	v_mov_b32_e32 v67, v193
	v_mov_b32_e32 v68, v194
	v_mov_b32_e32 v69, v195
	s_waitcnt lgkmcnt(0)
	v_lshlrev_b32_e32 v72, 16, v66
	v_and_b32_e32 v73, 0xffff0000, v66
	v_lshlrev_b32_e32 v66, 16, v67
	v_and_b32_e32 v67, 0xffff0000, v67
	v_lshlrev_b32_e32 v74, 16, v68
	v_and_b32_e32 v75, 0xffff0000, v68
	v_lshlrev_b32_e32 v68, 16, v69
	v_and_b32_e32 v69, 0xffff0000, v69
	v_pk_add_f32 v[62:63], v[62:63], v[66:67]
	v_pk_add_f32 v[60:61], v[60:61], v[72:73]
	v_pk_add_f32 v[66:67], v[58:59], v[68:69]
	v_pk_add_f32 v[58:59], v[56:57], v[74:75]
	v_cvt_pk_bf16_f32 v56, v60, v61
	v_cvt_pk_bf16_f32 v57, v62, v63
	v_cvt_pk_bf16_f32 v58, v58, v59
	v_cvt_pk_bf16_f32 v59, v66, v67
	global_store_dwordx4 v[70:71], v[56:59], off
	s_waitcnt vmcnt(15)
	s_nop 1
	v_mov_b32_e32 v56, v198
	v_mov_b32_e32 v57, v199
	v_mov_b32_e32 v58, v200
	v_mov_b32_e32 v59, v201
	s_waitcnt lgkmcnt(0)
	v_lshlrev_b32_e32 v60, 16, v56
	v_and_b32_e32 v61, 0xffff0000, v56
	v_lshlrev_b32_e32 v56, 16, v57
	v_and_b32_e32 v57, 0xffff0000, v57
	v_lshlrev_b32_e32 v62, 16, v58
	v_and_b32_e32 v63, 0xffff0000, v58
	v_lshlrev_b32_e32 v58, 16, v59
	v_and_b32_e32 v59, 0xffff0000, v59
	v_pk_add_f32 v[54:55], v[54:55], v[56:57]
	v_pk_add_f32 v[52:53], v[52:53], v[60:61]
	v_pk_add_f32 v[56:57], v[50:51], v[58:59]
	v_pk_add_f32 v[50:51], v[48:49], v[62:63]
	v_cvt_pk_bf16_f32 v48, v52, v53
	v_cvt_pk_bf16_f32 v49, v54, v55
	v_cvt_pk_bf16_f32 v50, v50, v51
	v_cvt_pk_bf16_f32 v51, v56, v57
	global_store_dwordx4 v[64:65], v[48:51], off offset:256
	s_nop 1
	v_lshl_add_u64 v[48:49], v[144:145], 0, s[2:3]
	s_mov_b32 s2, 0x90000
	v_add_co_u32_e32 v54, vcc, s2, v144
	s_mov_b64 s[2:3], 0xa0000
	s_nop 0
	v_addc_co_u32_e32 v55, vcc, 0, v145, vcc
	s_waitcnt vmcnt(15)
	s_nop 1
	v_mov_b32_e32 v50, v202
	v_mov_b32_e32 v51, v203
	v_mov_b32_e32 v52, v204
	v_mov_b32_e32 v53, v205
	s_waitcnt lgkmcnt(0)
	v_lshlrev_b32_e32 v56, 16, v50
	v_and_b32_e32 v57, 0xffff0000, v50
	v_lshlrev_b32_e32 v50, 16, v51
	v_and_b32_e32 v51, 0xffff0000, v51
	v_lshlrev_b32_e32 v58, 16, v52
	v_and_b32_e32 v59, 0xffff0000, v52
	v_lshlrev_b32_e32 v52, 16, v53
	v_and_b32_e32 v53, 0xffff0000, v53
	v_pk_add_f32 v[46:47], v[46:47], v[50:51]
	v_pk_add_f32 v[44:45], v[44:45], v[56:57]
	v_pk_add_f32 v[50:51], v[42:43], v[52:53]
	v_pk_add_f32 v[42:43], v[40:41], v[58:59]
	v_cvt_pk_bf16_f32 v40, v44, v45
	v_cvt_pk_bf16_f32 v41, v46, v47
	v_cvt_pk_bf16_f32 v42, v42, v43
	v_cvt_pk_bf16_f32 v43, v50, v51
	global_store_dwordx4 v[54:55], v[40:43], off
	s_waitcnt vmcnt(15)
	s_nop 1
	v_mov_b32_e32 v40, v206
	v_mov_b32_e32 v41, v207
	v_mov_b32_e32 v42, v208
	v_mov_b32_e32 v43, v209
	s_waitcnt lgkmcnt(0)
; DI unsigned pack2(float a, float b) { f32x2 v = {a, b}; hwbf16x2 r = __builtin_convertvector(v, hwbf16x2); return __builtin_bit_cast(unsigned, r); }
; DI float bflo(unsigned w) { return __uint_as_float(w << 16); }
; DI float bfhi(unsigned w) { return __uint_as_float(w & 0xffff0000u); }
;     DI const char* a(const Unit& u) const { return (const char*)(A + (size_t)u.pm * BM * lda); }
;     DI const char* a(const Unit& u) const { return (const char*)(A + (size_t)u.pm * BM * 2048 + (u.pn >> 1) * 512); }
;     DI void operator()(const f32x4 (&acc)[2][2][4][2], const Unit& u, int wr, int wc, int fr, int fq) const {
;     ...
;         for (int ai = 0; ai < 2; ++ai)
; #pragma unroll
;             for (int m = 0; m < 4; ++m) { const size_t ro = (size_t)(row0 + ai * HALF + m * 16) * D + col0;
; #pragma unroll
;                 for (int bj = 0; bj < 2; ++bj) {
;                     f32x4 x0, x1;
;                     if constexpr (IB) { const u32x4 w = *(const u32x4*)((const bf16_t*)Xin + ro + bj * HALF);
;                         x0 = (f32x4){bflo(w[0]), bfhi(w[0]), bflo(w[1]), bfhi(w[1])}; x1 = (f32x4){bflo(w[2]), bfhi(w[2]), bflo(w[3]), bfhi(w[3])}; }
;                     else { x0 = *(const f32x4*)((const float*)Xin + ro + bj * HALF); x1 = *(const f32x4*)((const float*)Xin + ro + bj * HALF + 4); }
;                     x0 += acc[ai][bj][m][0] * sc[bj][0]; x1 += acc[ai][bj][m][1] * sc[bj][1];
;                     if constexpr (OB) { u32x4 o; o[0] = pack2(x0[0], x0[1]); o[1] = pack2(x0[2], x0[3]); o[2] = pack2(x1[0], x1[1]); o[3] = pack2(x1[2], x1[3]);
;                         *(u32x4*)((bf16_t*)Xout + ro + bj * HALF) = o; }
;                     else { *(f32x4*)((float*)Xout + ro + bj * HALF) = x0; *(f32x4*)((float*)Xout + ro + bj * HALF + 4) = x1; } } }
; template <class Map, class Epi>
; DI void gemm_phase(LAS unsigned char* lds, const Map& MP, const Epi& E, const int nM, const int nN, const int K, const int lda, const int ldb) {
;     ...
;         if (!has_next) break;
; #pragma unroll
;         for (int a = 0; a < 2; ++a)
; #pragma unroll
;             for (int b = 0; b < 2; ++b)
; #pragma unroll
;                 for (int m = 0; m < 4; ++m)
; #pragma unroll
;                     for (int n = 0; n < 2; ++n) acc[a][b][m][n] = (f32x4){0.f, 0.f, 0.f, 0.f};
;         cur = nxt; cA = nA; cB = nB; ++ui;
;     }
;     PG8_WAIT_V(0);
;     if (wr == 0) PG8_BAR;
;     PG8_BAR;
	v_lshlrev_b32_e32 v44, 16, v40
	v_and_b32_e32 v45, 0xffff0000, v40
	v_lshlrev_b32_e32 v40, 16, v41
	v_and_b32_e32 v41, 0xffff0000, v41
	v_lshlrev_b32_e32 v46, 16, v42
	v_and_b32_e32 v47, 0xffff0000, v42
	v_lshlrev_b32_e32 v42, 16, v43
	v_and_b32_e32 v43, 0xffff0000, v43
	v_pk_add_f32 v[38:39], v[38:39], v[40:41]
	v_pk_add_f32 v[36:37], v[36:37], v[44:45]
	v_pk_add_f32 v[40:41], v[34:35], v[42:43]
	v_pk_add_f32 v[34:35], v[32:33], v[46:47]
	v_cvt_pk_bf16_f32 v32, v36, v37
	v_cvt_pk_bf16_f32 v33, v38, v39
	v_cvt_pk_bf16_f32 v34, v34, v35
	v_cvt_pk_bf16_f32 v35, v40, v41
	global_store_dwordx4 v[48:49], v[32:35], off offset:256
	s_nop 1
	v_lshl_add_u64 v[32:33], v[144:145], 0, s[2:3]
	s_mov_b32 s2, 0xa0000
	v_add_co_u32_e32 v38, vcc, s2, v144
	s_mov_b64 s[2:3], 0xb0000
	s_nop 0
	v_addc_co_u32_e32 v39, vcc, 0, v145, vcc
	s_waitcnt vmcnt(15)
	s_nop 1
	v_mov_b32_e32 v34, v210
	v_mov_b32_e32 v35, v211
	v_mov_b32_e32 v36, v212
	v_mov_b32_e32 v37, v213
	s_waitcnt lgkmcnt(0)
	v_lshlrev_b32_e32 v40, 16, v34
	v_and_b32_e32 v41, 0xffff0000, v34
	v_lshlrev_b32_e32 v34, 16, v35
	v_and_b32_e32 v35, 0xffff0000, v35
	v_lshlrev_b32_e32 v42, 16, v36
	v_and_b32_e32 v43, 0xffff0000, v36
	v_lshlrev_b32_e32 v36, 16, v37
	v_and_b32_e32 v37, 0xffff0000, v37
	v_pk_add_f32 v[30:31], v[30:31], v[34:35]
	v_pk_add_f32 v[28:29], v[28:29], v[40:41]
	v_pk_add_f32 v[34:35], v[26:27], v[36:37]
	v_pk_add_f32 v[26:27], v[24:25], v[42:43]
	v_cvt_pk_bf16_f32 v24, v28, v29
	v_cvt_pk_bf16_f32 v25, v30, v31
	v_cvt_pk_bf16_f32 v26, v26, v27
	v_cvt_pk_bf16_f32 v27, v34, v35
	global_store_dwordx4 v[38:39], v[24:27], off
	s_waitcnt vmcnt(15)
	s_nop 1
	v_mov_b32_e32 v24, v214
	v_mov_b32_e32 v25, v215
	v_mov_b32_e32 v26, v216
	v_mov_b32_e32 v27, v217
	s_waitcnt lgkmcnt(0)
	v_lshlrev_b32_e32 v28, 16, v24
	v_and_b32_e32 v29, 0xffff0000, v24
	v_lshlrev_b32_e32 v24, 16, v25
	v_and_b32_e32 v25, 0xffff0000, v25
	v_lshlrev_b32_e32 v30, 16, v26
	v_and_b32_e32 v31, 0xffff0000, v26
	v_lshlrev_b32_e32 v26, 16, v27
	v_and_b32_e32 v27, 0xffff0000, v27
	v_pk_add_f32 v[22:23], v[22:23], v[24:25]
	v_pk_add_f32 v[20:21], v[20:21], v[28:29]
	v_pk_add_f32 v[24:25], v[18:19], v[26:27]
	v_pk_add_f32 v[18:19], v[16:17], v[30:31]
	v_cvt_pk_bf16_f32 v16, v20, v21
	v_cvt_pk_bf16_f32 v17, v22, v23
	v_cvt_pk_bf16_f32 v18, v18, v19
	v_cvt_pk_bf16_f32 v19, v24, v25
	global_store_dwordx4 v[32:33], v[16:19], off offset:256
	s_nop 1
	v_lshl_add_u64 v[16:17], v[144:145], 0, s[2:3]
	s_mov_b32 s2, 0xb0000
	v_add_co_u32_e32 v22, vcc, s2, v144
	s_mov_b32 s2, s44
	s_nop 0
	v_addc_co_u32_e32 v23, vcc, 0, v145, vcc
	s_waitcnt vmcnt(15)
	s_nop 1
	v_mov_b32_e32 v18, v248
	v_mov_b32_e32 v19, v249
	v_mov_b32_e32 v20, v250
	v_mov_b32_e32 v21, v251
	s_and_b64 vcc, exec, s[40:41]
	s_waitcnt lgkmcnt(0)
	v_lshlrev_b32_e32 v24, 16, v18
	v_and_b32_e32 v25, 0xffff0000, v18
	v_lshlrev_b32_e32 v18, 16, v19
	v_and_b32_e32 v19, 0xffff0000, v19
	v_lshlrev_b32_e32 v26, 16, v20
	v_and_b32_e32 v27, 0xffff0000, v20
	v_lshlrev_b32_e32 v20, 16, v21
	v_and_b32_e32 v21, 0xffff0000, v21
	v_pk_add_f32 v[14:15], v[14:15], v[18:19]
	v_pk_add_f32 v[12:13], v[12:13], v[24:25]
	v_pk_add_f32 v[18:19], v[10:11], v[20:21]
	v_pk_add_f32 v[10:11], v[8:9], v[26:27]
	v_cvt_pk_bf16_f32 v8, v12, v13
	v_cvt_pk_bf16_f32 v9, v14, v15
	v_cvt_pk_bf16_f32 v10, v10, v11
	v_cvt_pk_bf16_f32 v11, v18, v19
	global_store_dwordx4 v[22:23], v[8:11], off
	s_waitcnt vmcnt(15)
	s_nop 1
	v_mov_b32_e32 v8, v252
	v_mov_b32_e32 v9, v253
	v_mov_b32_e32 v10, v254
	v_mov_b32_e32 v11, v255
	s_waitcnt lgkmcnt(0)
	v_lshlrev_b32_e32 v12, 16, v8
	v_and_b32_e32 v13, 0xffff0000, v8
	v_lshlrev_b32_e32 v8, 16, v9
	v_and_b32_e32 v9, 0xffff0000, v9
	v_lshlrev_b32_e32 v14, 16, v10
	v_and_b32_e32 v15, 0xffff0000, v10
	v_lshlrev_b32_e32 v10, 16, v11
	v_and_b32_e32 v11, 0xffff0000, v11
	v_pk_add_f32 v[6:7], v[6:7], v[8:9]
	v_pk_add_f32 v[4:5], v[4:5], v[12:13]
	v_pk_add_f32 v[8:9], v[2:3], v[10:11]
	v_pk_add_f32 v[2:3], v[0:1], v[14:15]
	v_cvt_pk_bf16_f32 v0, v4, v5
	v_cvt_pk_bf16_f32 v1, v6, v7
	v_cvt_pk_bf16_f32 v2, v2, v3
	v_cvt_pk_bf16_f32 v3, v8, v9
	global_store_dwordx4 v[16:17], v[0:3], off offset:256
	s_cbranch_vccz .LBB1_1761
	s_waitcnt vmcnt(0)
	s_cmpk_gt_u32 s17, 0xff
	s_cbranch_scc1 .LBB1_1768
	s_barrier

; #define PG8_STAGE(bufoff, gbase, voff) do { _Pragma("unroll") for (int _i = 0; _i < 2; ++_i) \
;         __builtin_amdgcn_global_load_lds((const unsigned*)((const char*)(gbase) + (voff)[_i]), (LAS unsigned*)(lds + (bufoff) + ldsw + _i * 8192), 16, 0, 0); } while (0)
; #define PG8_LDA(dst, b, h) do { _Pragma("unroll") for (int m = 0; m < 4; ++m) _Pragma("unroll") for (int k = 0; k < 2; ++k) dst[m][k] = *(const LAS bf16x8*)(lds + PG8_SA(b, h) + aoff + m * 2048 + k * 1024); } while (0)
; #define PG8_LDB(dst, b, h) do { _Pragma("unroll") for (int n = 0; n < 2; ++n) _Pragma("unroll") for (int k = 0; k < 2; ++k) dst[n][k] = *(const LAS bf16x8*)(lds + PG8_SB(b, h) + boff + n * 2048 + k * 1024); } while (0)
; #define PG8_MMA(ai, bj, At, Bt) do { __builtin_amdgcn_s_setprio(1); _Pragma("unroll") for (int m = 0; m < 4; ++m) _Pragma("unroll") for (int n = 0; n < 2; ++n) _Pragma("unroll") for (int k = 0; k < 2; ++k) \
;         acc[ai][bj][m][n] = __builtin_amdgcn_mfma_f32_16x16x32_bf16(Bt[n][k], At[m][k], acc[ai][bj][m][n], 0, 0, 0); __builtin_amdgcn_s_setprio(0); } while (0)
; #define PG8_WAIT_V(n) asm volatile("s_waitcnt vmcnt(" #n ")" ::: "memory")
; #define PG8_WAIT_L(n) asm volatile("s_waitcnt lgkmcnt(" #n ")" ::: "memory")
; #define PG8_BAR __builtin_amdgcn_s_barrier()
; #define PG8_SCHED __builtin_amdgcn_sched_barrier(0)
; template <class Map, class Epi>
; DI void gemm_phase(LAS unsigned char* lds, const Map& MP, const Epi& E, const int nM, const int nN, const int K, const int lda, const int ldb) {
;     ...
;             PG8_LDB(B0, 0, 0); PG8_SCHED; PG8_LDA(At, 0, 0); PG8_STAGE(PG8_SA(1, 1), a1 + hstepA, voffA);
;             PG8_WAIT_L(8); PG8_BAR; PG8_WAIT_L(0); PG8_MMA(0, 0, At, B0); PG8_BAR; PG8_SCHED;
;             PG8_LDB(B1, 0, 1); PG8_STAGE(PG8_SB(0, 0), b2, voffB);
;             PG8_BAR; PG8_WAIT_L(0); PG8_MMA(0, 1, At, B1); PG8_BAR;
;             PG8_LDA(At, 0, 1); PG8_STAGE(PG8_SA(0, 0), a2, voffA);
;             PG8_BAR; PG8_WAIT_L(0); PG8_MMA(1, 0, At, B0); PG8_BAR; PG8_SCHED;
;             PG8_STAGE(PG8_SB(0, 1), b2 + hstepB, voffB);
;             PG8_WAIT_V(6); PG8_BAR; PG8_MMA(1, 1, At, B1); PG8_BAR;
.LBB1_1908:
	s_add_i32 m0, s38, 0xc000
	ds_read_b128 v[96:99], v190
	ds_read_b128 v[100:103], v190 offset:1024
	ds_read_b128 v[108:111], v190 offset:2048
	ds_read_b128 v[112:115], v190 offset:3072
	ds_read_b128 v[160:163], v190 offset:4096
	ds_read_b128 v[164:167], v190 offset:5120
	ds_read_b128 v[198:201], v190 offset:6144
	ds_read_b128 v[202:205], v190 offset:7168
	global_load_lds_dwordx4 v178, s[42:43]
	s_add_i32 m0, s38, 0xe000
	s_setprio 1
	global_load_lds_dwordx4 v176, s[42:43]
	s_waitcnt lgkmcnt(8)
	s_barrier
	s_waitcnt lgkmcnt(7)
	v_mfma_f32_16x16x32_bf16 v[148:151], v[80:83], v[96:99], v[148:151]
	v_mfma_f32_16x16x32_bf16 v[144:147], v[88:91], v[96:99], v[144:147]
	s_waitcnt lgkmcnt(5)
	v_mfma_f32_16x16x32_bf16 v[136:139], v[80:83], v[108:111], v[136:139]
	v_mfma_f32_16x16x32_bf16 v[128:131], v[88:91], v[108:111], v[128:131]
	s_waitcnt lgkmcnt(3)
	v_mfma_f32_16x16x32_bf16 v[120:123], v[80:83], v[160:163], v[120:123]
	v_mfma_f32_16x16x32_bf16 v[104:107], v[88:91], v[160:163], v[104:107]
	s_waitcnt lgkmcnt(1)
	v_mfma_f32_16x16x32_bf16 v[76:79], v[80:83], v[198:201], v[76:79]
	v_mfma_f32_16x16x32_bf16 v[72:75], v[88:91], v[198:201], v[72:75]
	v_mfma_f32_16x16x32_bf16 v[148:151], v[84:87], v[100:103], v[148:151]
	s_add_i32 s68, s2, s54
	v_mfma_f32_16x16x32_bf16 v[144:147], v[92:95], v[100:103], v[144:147]
	v_lshl_add_u64 v[184:185], s[28:29], 0, v[172:173]
	v_mfma_f32_16x16x32_bf16 v[136:139], v[84:87], v[112:115], v[136:139]
	v_lshl_add_u64 v[194:195], s[28:29], 0, v[168:169]
	v_mfma_f32_16x16x32_bf16 v[128:131], v[92:95], v[112:115], v[128:131]
	v_mfma_f32_16x16x32_bf16 v[120:123], v[84:87], v[164:167], v[120:123]
	v_mfma_f32_16x16x32_bf16 v[104:107], v[92:95], v[164:167], v[104:107]
	s_waitcnt lgkmcnt(0)
	v_mfma_f32_16x16x32_bf16 v[76:79], v[84:87], v[202:205], v[76:79]
	v_mfma_f32_16x16x32_bf16 v[72:75], v[92:95], v[202:205], v[72:75]
	s_barrier
	s_setprio 0
	s_mov_b32 m0, s68
	ds_read_b128 v[206:209], v191
	ds_read_b128 v[210:213], v191 offset:1024
	ds_read_b128 v[214:217], v191 offset:2048
	ds_read_b128 v[218:221], v191 offset:3072
	global_load_lds_dwordx4 v[184:185], off
	s_add_i32 m0, s68, 0x2000
	s_setprio 1
	global_load_lds_dwordx4 v[194:195], off
	s_barrier
	s_waitcnt lgkmcnt(3)
	v_mfma_f32_16x16x32_bf16 v[156:159], v[206:209], v[96:99], v[156:159]
	s_waitcnt lgkmcnt(1)
	v_mfma_f32_16x16x32_bf16 v[96:99], v[214:217], v[96:99], v[152:155]
	v_mfma_f32_16x16x32_bf16 v[156:159], v[210:213], v[100:103], v[156:159]
	s_waitcnt lgkmcnt(0)
	v_mfma_f32_16x16x32_bf16 v[96:99], v[218:221], v[100:103], v[96:99]
	v_mfma_f32_16x16x32_bf16 v[100:103], v[206:209], v[108:111], v[140:143]
	v_mfma_f32_16x16x32_bf16 v[108:111], v[214:217], v[108:111], v[132:135]
	v_mfma_f32_16x16x32_bf16 v[116:119], v[214:217], v[160:163], v[116:119]
	v_mfma_f32_16x16x32_bf16 v[68:71], v[206:209], v[198:201], v[68:71]
	v_mfma_f32_16x16x32_bf16 v[64:67], v[214:217], v[198:201], v[64:67]
	v_lshl_add_u64 v[234:235], s[46:47], 0, v[170:171]
	s_mov_b32 m0, s38
	v_mfma_f32_16x16x32_bf16 v[100:103], v[210:213], v[112:115], v[100:103]
	v_lshl_add_u64 v[226:227], s[46:47], 0, v[174:175]
	v_mfma_f32_16x16x32_bf16 v[108:111], v[218:221], v[112:115], v[108:111]
	v_mfma_f32_16x16x32_bf16 v[112:115], v[206:209], v[160:163], v[124:127]
	v_mfma_f32_16x16x32_bf16 v[116:119], v[218:221], v[164:167], v[116:119]
	v_mfma_f32_16x16x32_bf16 v[68:71], v[210:213], v[202:205], v[68:71]
	v_mfma_f32_16x16x32_bf16 v[64:67], v[218:221], v[202:205], v[64:67]
	v_mfma_f32_16x16x32_bf16 v[112:115], v[210:213], v[164:167], v[112:115]
	s_barrier
	s_setprio 0
	ds_read_b128 v[124:127], v190 offset:16384
	ds_read_b128 v[132:135], v190 offset:17408
	ds_read_b128 v[140:143], v190 offset:18432
	ds_read_b128 v[152:155], v190 offset:19456
	ds_read_b128 v[160:163], v190 offset:20480
	ds_read_b128 v[164:167], v190 offset:21504
	ds_read_b128 v[198:201], v190 offset:22528
	ds_read_b128 v[202:205], v190 offset:23552
	global_load_lds_dwordx4 v[226:227], off
	s_mov_b32 m0, s39
	s_setprio 1
	global_load_lds_dwordx4 v[234:235], off
	s_waitcnt vmcnt(10)
	s_barrier
	s_waitcnt lgkmcnt(7)
	v_mfma_f32_16x16x32_bf16 v[60:63], v[80:83], v[124:127], v[60:63]
	v_mfma_f32_16x16x32_bf16 v[48:51], v[88:91], v[124:127], v[48:51]
	s_waitcnt lgkmcnt(5)
	v_mfma_f32_16x16x32_bf16 v[40:43], v[80:83], v[140:143], v[40:43]
	v_mfma_f32_16x16x32_bf16 v[32:35], v[88:91], v[140:143], v[32:35]
	s_waitcnt lgkmcnt(3)
	v_mfma_f32_16x16x32_bf16 v[24:27], v[80:83], v[160:163], v[24:27]
	v_mfma_f32_16x16x32_bf16 v[16:19], v[88:91], v[160:163], v[16:19]
	s_waitcnt lgkmcnt(1)
	v_mfma_f32_16x16x32_bf16 v[12:15], v[80:83], v[198:201], v[12:15]
	v_mfma_f32_16x16x32_bf16 v[8:11], v[88:91], v[198:201], v[8:11]
	v_mfma_f32_16x16x32_bf16 v[60:63], v[84:87], v[132:135], v[60:63]
	s_add_u32 s68, s28, 0x80000
	s_addc_u32 s69, s29, 0
	v_mfma_f32_16x16x32_bf16 v[48:51], v[92:95], v[132:135], v[48:51]
	s_add_i32 s70, s31, s54
	v_mfma_f32_16x16x32_bf16 v[40:43], v[84:87], v[152:155], v[40:43]
	v_mfma_f32_16x16x32_bf16 v[32:35], v[92:95], v[152:155], v[32:35]
	v_mfma_f32_16x16x32_bf16 v[24:27], v[84:87], v[164:167], v[24:27]
	v_mfma_f32_16x16x32_bf16 v[16:19], v[92:95], v[164:167], v[16:19]
	s_waitcnt lgkmcnt(0)
	v_mfma_f32_16x16x32_bf16 v[12:15], v[84:87], v[202:205], v[12:15]
	v_mfma_f32_16x16x32_bf16 v[8:11], v[92:95], v[202:205], v[8:11]
	s_barrier
	s_setprio 0
	s_mov_b32 m0, s70
	s_nop 0
	global_load_lds_dwordx4 v172, s[68:69]
	s_add_i32 m0, s70, 0x2000
	s_setprio 1
	global_load_lds_dwordx4 v168, s[68:69]
	s_waitcnt vmcnt(6)
	s_barrier
; #define PG8_STAGE(bufoff, gbase, voff) do { _Pragma("unroll") for (int _i = 0; _i < 2; ++_i) \
;         __builtin_amdgcn_global_load_lds((const unsigned*)((const char*)(gbase) + (voff)[_i]), (LAS unsigned*)(lds + (bufoff) + ldsw + _i * 8192), 16, 0, 0); } while (0)
; #define PG8_LDA(dst, b, h) do { _Pragma("unroll") for (int m = 0; m < 4; ++m) _Pragma("unroll") for (int k = 0; k < 2; ++k) dst[m][k] = *(const LAS bf16x8*)(lds + PG8_SA(b, h) + aoff + m * 2048 + k * 1024); } while (0)
; #define PG8_LDB(dst, b, h) do { _Pragma("unroll") for (int n = 0; n < 2; ++n) _Pragma("unroll") for (int k = 0; k < 2; ++k) dst[n][k] = *(const LAS bf16x8*)(lds + PG8_SB(b, h) + boff + n * 2048 + k * 1024); } while (0)
; #define PG8_MMA(ai, bj, At, Bt) do { __builtin_amdgcn_s_setprio(1); _Pragma("unroll") for (int m = 0; m < 4; ++m) _Pragma("unroll") for (int n = 0; n < 2; ++n) _Pragma("unroll") for (int k = 0; k < 2; ++k) \
;         acc[ai][bj][m][n] = __builtin_amdgcn_mfma_f32_16x16x32_bf16(Bt[n][k], At[m][k], acc[ai][bj][m][n], 0, 0, 0); __builtin_amdgcn_s_setprio(0); } while (0)
; #define PG8_WAIT_V(n) asm volatile("s_waitcnt vmcnt(" #n ")" ::: "memory")
; #define PG8_WAIT_L(n) asm volatile("s_waitcnt lgkmcnt(" #n ")" ::: "memory")
; #define PG8_BAR __builtin_amdgcn_s_barrier()
; #define PG8_SCHED __builtin_amdgcn_sched_barrier(0)
; template <class Map, class Epi>
; DI void gemm_phase(LAS unsigned char* lds, const Map& MP, const Epi& E, const int nM, const int nN, const int K, const int lda, const int ldb) {
;     ...
;             PG8_WAIT_V(6); PG8_BAR; PG8_MMA(1, 1, At, B1); PG8_BAR;
;             PG8_LDB(B0, 1, 0); PG8_SCHED; PG8_LDA(At, 1, 0); PG8_STAGE(PG8_SA(0, 1), a2 + hstepA, voffA);
;             PG8_WAIT_L(8); PG8_BAR; PG8_WAIT_L(0); PG8_MMA(0, 0, At, B0); PG8_BAR; PG8_SCHED;
;             PG8_LDB(B1, 1, 1); PG8_STAGE(PG8_SB(1, 0), b3, voffB);
;             PG8_BAR; PG8_WAIT_L(0); PG8_MMA(0, 1, At, B1); PG8_BAR;
;             PG8_LDA(At, 1, 1); PG8_STAGE(PG8_SA(1, 0), a3, voffA);
;             PG8_BAR; PG8_WAIT_L(0); PG8_MMA(1, 0, At, B0); PG8_BAR; PG8_SCHED;
	v_mfma_f32_16x16x32_bf16 v[56:59], v[206:209], v[124:127], v[56:59]
	v_mfma_f32_16x16x32_bf16 v[52:55], v[214:217], v[124:127], v[52:55]
	s_add_i32 s68, 0, 0x18000
	v_add_u32_e32 v92, s68, v188
	ds_read_b128 v[80:83], v92
	v_mfma_f32_16x16x32_bf16 v[44:47], v[206:209], v[140:143], v[44:47]
	v_mfma_f32_16x16x32_bf16 v[36:39], v[214:217], v[140:143], v[36:39]
	ds_read_b128 v[84:87], v92 offset:1024
	v_mfma_f32_16x16x32_bf16 v[28:31], v[206:209], v[160:163], v[28:31]
	v_mfma_f32_16x16x32_bf16 v[20:23], v[214:217], v[160:163], v[20:23]
	ds_read_b128 v[88:91], v92 offset:2048
	v_mfma_f32_16x16x32_bf16 v[4:7], v[206:209], v[198:201], v[4:7]
	v_mfma_f32_16x16x32_bf16 v[0:3], v[214:217], v[198:201], v[0:3]
	ds_read_b128 v[92:95], v92 offset:3072
	v_mfma_f32_16x16x32_bf16 v[56:59], v[210:213], v[132:135], v[56:59]
	s_add_u32 s46, s46, 0x80000
	s_addc_u32 s47, s47, 0
	v_mfma_f32_16x16x32_bf16 v[52:55], v[218:221], v[132:135], v[52:55]
	v_mfma_f32_16x16x32_bf16 v[44:47], v[210:213], v[152:155], v[44:47]
	v_mfma_f32_16x16x32_bf16 v[36:39], v[218:221], v[152:155], v[36:39]
	v_mfma_f32_16x16x32_bf16 v[28:31], v[210:213], v[164:167], v[28:31]
	v_mfma_f32_16x16x32_bf16 v[20:23], v[218:221], v[164:167], v[20:23]
	v_mfma_f32_16x16x32_bf16 v[4:7], v[210:213], v[202:205], v[4:7]
	v_mfma_f32_16x16x32_bf16 v[0:3], v[218:221], v[202:205], v[0:3]
	s_barrier
	s_setprio 0
	s_mov_b32 m0, s56
	ds_read_b128 v[124:127], v190 offset:32768
	ds_read_b128 v[132:135], v190 offset:33792
	ds_read_b128 v[160:163], v190 offset:34816
	ds_read_b128 v[164:167], v190 offset:35840
	ds_read_b128 v[198:201], v190 offset:36864
	ds_read_b128 v[202:205], v190 offset:37888
	ds_read_b128 v[206:209], v190 offset:38912
	ds_read_b128 v[210:213], v190 offset:39936
	global_load_lds_dwordx4 v174, s[46:47]
	s_mov_b32 m0, s57
	s_setprio 1
	global_load_lds_dwordx4 v170, s[46:47]
	s_waitcnt lgkmcnt(8)
	s_barrier
	s_waitcnt lgkmcnt(7)
	v_mfma_f32_16x16x32_bf16 v[140:143], v[80:83], v[124:127], v[148:151]
	s_waitcnt lgkmcnt(6)
	v_mfma_f32_16x16x32_bf16 v[148:151], v[84:87], v[132:135], v[140:143]
	v_mfma_f32_16x16x32_bf16 v[140:143], v[88:91], v[124:127], v[144:147]
	s_waitcnt lgkmcnt(5)
	v_mfma_f32_16x16x32_bf16 v[136:139], v[80:83], v[160:163], v[136:139]
	v_mfma_f32_16x16x32_bf16 v[128:131], v[88:91], v[160:163], v[128:131]
	s_waitcnt lgkmcnt(3)
	v_mfma_f32_16x16x32_bf16 v[120:123], v[80:83], v[198:201], v[120:123]
	v_mfma_f32_16x16x32_bf16 v[104:107], v[88:91], v[198:201], v[104:107]
	s_waitcnt lgkmcnt(1)
	v_mfma_f32_16x16x32_bf16 v[76:79], v[80:83], v[206:209], v[76:79]
	v_mfma_f32_16x16x32_bf16 v[72:75], v[88:91], v[206:209], v[72:75]
	s_add_i32 s46, 0, 0x1c000
	v_mfma_f32_16x16x32_bf16 v[144:147], v[92:95], v[132:135], v[140:143]
	v_add_u32_e32 v140, s46, v188
	v_mfma_f32_16x16x32_bf16 v[136:139], v[84:87], v[164:167], v[136:139]
	s_add_i32 s47, s68, s54
	v_mfma_f32_16x16x32_bf16 v[128:131], v[92:95], v[164:167], v[128:131]
	v_mfma_f32_16x16x32_bf16 v[120:123], v[84:87], v[202:205], v[120:123]
	v_mfma_f32_16x16x32_bf16 v[104:107], v[92:95], v[202:205], v[104:107]
	s_waitcnt lgkmcnt(0)
	v_mfma_f32_16x16x32_bf16 v[76:79], v[84:87], v[210:213], v[76:79]
	v_mfma_f32_16x16x32_bf16 v[72:75], v[92:95], v[210:213], v[72:75]
	s_barrier
	s_setprio 0
	ds_read_b128 v[214:217], v140
	ds_read_b128 v[218:221], v140 offset:1024
	ds_read_b128 v[222:225], v140 offset:2048
	ds_read_b128 v[230:233], v140 offset:3072
	v_lshl_add_u64 v[140:141], v[184:185], 0, s[14:15]
	s_mov_b32 m0, s47
	s_nop 0
	global_load_lds_dwordx4 v[140:141], off
	v_lshl_add_u64 v[140:141], v[194:195], 0, s[14:15]
	s_add_i32 m0, s47, 0x2000
	s_setprio 1
	global_load_lds_dwordx4 v[140:141], off
	s_barrier
	s_waitcnt lgkmcnt(1)
	v_mfma_f32_16x16x32_bf16 v[96:99], v[222:225], v[124:127], v[96:99]
	v_mfma_f32_16x16x32_bf16 v[140:143], v[214:217], v[124:127], v[156:159]
	s_waitcnt lgkmcnt(0)
	v_mfma_f32_16x16x32_bf16 v[152:155], v[230:233], v[132:135], v[96:99]
	v_mfma_f32_16x16x32_bf16 v[96:99], v[214:217], v[160:163], v[100:103]
	v_mfma_f32_16x16x32_bf16 v[156:159], v[218:221], v[132:135], v[140:143]
	v_mfma_f32_16x16x32_bf16 v[140:143], v[218:221], v[164:167], v[96:99]
	v_mfma_f32_16x16x32_bf16 v[96:99], v[222:225], v[160:163], v[108:111]
	v_mfma_f32_16x16x32_bf16 v[132:135], v[230:233], v[164:167], v[96:99]
	v_mfma_f32_16x16x32_bf16 v[96:99], v[214:217], v[198:201], v[112:115]
	s_mov_b32 m0, s63
	v_mfma_f32_16x16x32_bf16 v[124:127], v[218:221], v[202:205], v[96:99]
	v_lshl_add_u64 v[184:185], v[226:227], 0, s[14:15]
	v_mfma_f32_16x16x32_bf16 v[96:99], v[222:225], v[198:201], v[116:119]
	v_mfma_f32_16x16x32_bf16 v[68:71], v[214:217], v[206:209], v[68:71]
	v_mfma_f32_16x16x32_bf16 v[64:67], v[222:225], v[206:209], v[64:67]
	v_mfma_f32_16x16x32_bf16 v[116:119], v[230:233], v[202:205], v[96:99]
	v_mfma_f32_16x16x32_bf16 v[68:71], v[218:221], v[210:213], v[68:71]
	v_mfma_f32_16x16x32_bf16 v[64:67], v[230:233], v[210:213], v[64:67]
	s_barrier
	s_setprio 0
	ds_read_b128 v[96:99], v190 offset:49152
	ds_read_b128 v[100:103], v190 offset:50176
	ds_read_b128 v[108:111], v190 offset:51200
	ds_read_b128 v[112:115], v190 offset:52224
	ds_read_b128 v[160:163], v190 offset:53248
	ds_read_b128 v[164:167], v190 offset:54272
	ds_read_b128 v[198:201], v190 offset:55296
	ds_read_b128 v[202:205], v190 offset:56320
	global_load_lds_dwordx4 v[184:185], off
	v_lshl_add_u64 v[184:185], v[234:235], 0, s[14:15]
	s_mov_b32 m0, s66
	s_setprio 1
	global_load_lds_dwordx4 v[184:185], off
	s_waitcnt vmcnt(10)
	s_barrier
; #define PG8_STAGE(bufoff, gbase, voff) do { _Pragma("unroll") for (int _i = 0; _i < 2; ++_i) \
;         __builtin_amdgcn_global_load_lds((const unsigned*)((const char*)(gbase) + (voff)[_i]), (LAS unsigned*)(lds + (bufoff) + ldsw + _i * 8192), 16, 0, 0); } while (0)
; #define PG8_MMA(ai, bj, At, Bt) do { __builtin_amdgcn_s_setprio(1); _Pragma("unroll") for (int m = 0; m < 4; ++m) _Pragma("unroll") for (int n = 0; n < 2; ++n) _Pragma("unroll") for (int k = 0; k < 2; ++k) \
;         acc[ai][bj][m][n] = __builtin_amdgcn_mfma_f32_16x16x32_bf16(Bt[n][k], At[m][k], acc[ai][bj][m][n], 0, 0, 0); __builtin_amdgcn_s_setprio(0); } while (0)
; #define PG8_WAIT_V(n) asm volatile("s_waitcnt vmcnt(" #n ")" ::: "memory")
; #define PG8_WAIT_L(n) asm volatile("s_waitcnt lgkmcnt(" #n ")" ::: "memory")
; #define PG8_BAR __builtin_amdgcn_s_barrier()
; #define PG8_SCHED __builtin_amdgcn_sched_barrier(0)
; template <class Map, class Epi>
; DI void gemm_phase(LAS unsigned char* lds, const Map& MP, const Epi& E, const int nM, const int nN, const int K, const int lda, const int ldb) {
;     ...
;             const char* a1 = cA + (size_t)(t + 1) * kstep;
;             const char* a2 = last ? nA : cA + (size_t)(t + 2) * kstep; const char* b2 = last ? nB : cB + (size_t)(t + 2) * kstep;
;             const char* a3 = a2 + kstep; const char* b3 = b2 + kstep;
;     ...
;             PG8_BAR; PG8_WAIT_L(0); PG8_MMA(1, 0, At, B0); PG8_BAR; PG8_SCHED;
;             PG8_STAGE(PG8_SB(1, 1), b3 + hstepB, voffB);
;             PG8_WAIT_V(6); PG8_BAR; PG8_MMA(1, 1, At, B1); PG8_BAR;
	s_waitcnt lgkmcnt(7)
	v_mfma_f32_16x16x32_bf16 v[60:63], v[80:83], v[96:99], v[60:63]
	v_mfma_f32_16x16x32_bf16 v[48:51], v[88:91], v[96:99], v[48:51]
	s_waitcnt lgkmcnt(5)
	v_mfma_f32_16x16x32_bf16 v[40:43], v[80:83], v[108:111], v[40:43]
	v_mfma_f32_16x16x32_bf16 v[32:35], v[88:91], v[108:111], v[32:35]
	s_waitcnt lgkmcnt(3)
	v_mfma_f32_16x16x32_bf16 v[24:27], v[80:83], v[160:163], v[24:27]
	v_mfma_f32_16x16x32_bf16 v[16:19], v[88:91], v[160:163], v[16:19]
	s_waitcnt lgkmcnt(1)
	v_mfma_f32_16x16x32_bf16 v[12:15], v[80:83], v[198:201], v[12:15]
	v_mfma_f32_16x16x32_bf16 v[8:11], v[88:91], v[198:201], v[8:11]
	v_mfma_f32_16x16x32_bf16 v[60:63], v[84:87], v[100:103], v[60:63]
	s_add_u32 s28, s28, 0x80080
	s_addc_u32 s29, s29, 0
	v_mfma_f32_16x16x32_bf16 v[48:51], v[92:95], v[100:103], v[48:51]
	s_add_i32 s46, s46, s54
	v_mfma_f32_16x16x32_bf16 v[40:43], v[84:87], v[112:115], v[40:43]
	v_mfma_f32_16x16x32_bf16 v[32:35], v[92:95], v[112:115], v[32:35]
	v_mfma_f32_16x16x32_bf16 v[24:27], v[84:87], v[164:167], v[24:27]
	v_mfma_f32_16x16x32_bf16 v[16:19], v[92:95], v[164:167], v[16:19]
	s_waitcnt lgkmcnt(0)
	v_mfma_f32_16x16x32_bf16 v[12:15], v[84:87], v[202:205], v[12:15]
	v_mfma_f32_16x16x32_bf16 v[8:11], v[92:95], v[202:205], v[8:11]
	s_barrier
	s_setprio 0
	s_mov_b32 m0, s46
	s_nop 0
	global_load_lds_dwordx4 v172, s[28:29]
	s_add_i32 m0, s46, 0x2000
	s_setprio 1
	global_load_lds_dwordx4 v168, s[28:29]
	s_waitcnt vmcnt(6)
	s_barrier
	v_mfma_f32_16x16x32_bf16 v[56:59], v[214:217], v[96:99], v[56:59]
	v_mfma_f32_16x16x32_bf16 v[52:55], v[222:225], v[96:99], v[52:55]
	ds_read_b128 v[80:83], v189
	v_mfma_f32_16x16x32_bf16 v[44:47], v[214:217], v[108:111], v[44:47]
	v_mfma_f32_16x16x32_bf16 v[36:39], v[222:225], v[108:111], v[36:39]
	ds_read_b128 v[84:87], v189 offset:1024
	v_mfma_f32_16x16x32_bf16 v[28:31], v[214:217], v[160:163], v[28:31]
	v_mfma_f32_16x16x32_bf16 v[20:23], v[222:225], v[160:163], v[20:23]
	ds_read_b128 v[88:91], v189 offset:2048
	v_mfma_f32_16x16x32_bf16 v[4:7], v[214:217], v[198:201], v[4:7]
	v_mfma_f32_16x16x32_bf16 v[0:3], v[222:225], v[198:201], v[0:3]
	ds_read_b128 v[92:95], v189 offset:3072
	v_mfma_f32_16x16x32_bf16 v[56:59], v[218:221], v[100:103], v[56:59]
	s_add_i32 s3, s3, 2
	v_mfma_f32_16x16x32_bf16 v[52:55], v[230:233], v[100:103], v[52:55]
	s_add_u32 vcc_lo, vcc_lo, 0x100
	s_addc_u32 vcc_hi, vcc_hi, 0
	v_mfma_f32_16x16x32_bf16 v[44:47], v[218:221], v[112:115], v[44:47]
	s_add_u32 s42, s42, 0x100
	s_addc_u32 s43, s43, 0
	v_mfma_f32_16x16x32_bf16 v[36:39], v[230:233], v[112:115], v[36:39]
	s_add_u32 s28, s42, 0xfff80080
	s_addc_u32 s29, s43, -1
	s_cmp_eq_u32 s3, 28
	s_cselect_b32 s47, s23, s29
	s_cselect_b32 s46, s58, s28
	s_cselect_b32 s29, s21, vcc_hi
	s_cselect_b32 s28, s59, vcc_lo
	s_cmp_gt_u32 s3, 29
	v_mfma_f32_16x16x32_bf16 v[28:31], v[218:221], v[164:167], v[28:31]
	v_mfma_f32_16x16x32_bf16 v[20:23], v[230:233], v[164:167], v[20:23]
	v_mfma_f32_16x16x32_bf16 v[4:7], v[218:221], v[202:205], v[4:7]
	v_mfma_f32_16x16x32_bf16 v[0:3], v[230:233], v[202:205], v[0:3]
	s_barrier
	s_setprio 0
	s_cbranch_scc0 .LBB1_1908
; DI float silu_mul(float g, float v) { return g * v * __builtin_amdgcn_rcpf(1.0f + __builtin_amdgcn_exp2f(-LOG2E * g)); }
;     DI void operator()(const f32x4 (&acc)[2][2][4][2], const Unit& u, int wr, int wc, int fr, int fq) const {
;         const int row0 = u.pm * BM + wr * 64 + fr, ch0 = u.pn * 128 + wc * 32 + 8 * fq;
;         f32x4 w0[2], w1[2], w2[2], bb[2];
; #pragma unroll
;         for (int n = 0; n < 2; ++n) { w0[n] = *(const f32x4*)(cw + ch0 + 4 * n); w1[n] = *(const f32x4*)(cw + DFF + ch0 + 4 * n); w2[n] = *(const f32x4*)(cw + 2 * DFF + ch0 + 4 * n); bb[n] = *(const f32x4*)(cb + ch0 + 4 * n); }
; #pragma unroll
;         for (int ai = 0; ai < 2; ++ai)
; #pragma unroll
;             for (int m = 0; m < 4; ++m) {
;                 const bool efirst = (m == 0) && (fr == 0), elast = (m == 3) && (fr == 15);
;                 const int row = row0 + ai * HALF + m * 16;
;                 f32x4 gc[2];
; #pragma unroll
;                 for (int n = 0; n < 2; ++n) {
;                     const f32x4 g = acc[ai][0][m][n];
;                     const f32x4 gprev = acc[ai][0][m > 0 ? m - 1 : 0][n], gnext = acc[ai][0][m < 3 ? m + 1 : 3][n];
;                     f32x4 up, dn;
; #pragma unroll
;                     for (int e = 0; e < 4; ++e) {
;                         const float pu = (m > 0 && fr == 15) ? gprev[e] : g[e];
;                         const float pd = (m < 3 && fr == 0) ? gnext[e] : g[e];
;                         up[e] = dpp_ror1(pu); dn[e] = dpp_ror15(pd);
;                     }
;                     if (efirst) up = (f32x4){0.f, 0.f, 0.f, 0.f};
;                     if (elast) dn = (f32x4){0.f, 0.f, 0.f, 0.f};
;                     gc[n] = w0[n] * up + w1[n] * g + w2[n] * dn + bb[n];
;                 }
;                 if (efirst || elast) {
;                     const size_t eo = (size_t)((row >> 6) * 2 + (elast ? 1 : 0)) * DFF + ch0;
; #pragma unroll
;                     for (int n = 0; n < 2; ++n) { *(f32x4*)(EP + eo + 4 * n) = gc[n]; *(f32x4*)(ER + eo + 4 * n) = acc[ai][0][m][n]; *(f32x4*)(EV + eo + 4 * n) = acc[ai][1][m][n]; }
;                 } else {
;                     const f32x4 v0 = acc[ai][1][m][0], v1 = acc[ai][1][m][1];
;                     u32x4 o;
;                     o[0] = pack2(silu_mul(gc[0][0], v0[0]), silu_mul(gc[0][1], v0[1])); o[1] = pack2(silu_mul(gc[0][2], v0[2]), silu_mul(gc[0][3], v0[3]));
	s_waitcnt lgkmcnt(0)
	s_lshl_b32 s21, s45, 7
	v_mov_b32_e32 v194, v186
	v_mov_b32_e32 v80, v187
	s_or_b32 s21, s21, s62
	v_lshl_add_u32 v184, v80, 3, s21
	v_ashrrev_i32_e32 v185, 31, v184
	v_lshlrev_b64 v[80:81], 2, v[184:185]
	v_lshl_add_u64 v[84:85], s[4:5], 0, v[80:81]
	v_lshl_add_u64 v[88:89], s[16:17], 0, v[80:81]
	v_lshl_add_u64 v[92:93], s[18:19], 0, v[80:81]
	v_lshl_add_u64 v[112:113], s[6:7], 0, v[80:81]
	global_load_dwordx4 v[80:83], v[84:85], off offset:16
	global_load_dwordx4 v[96:99], v[84:85], off
	s_nop 0
	global_load_dwordx4 v[84:87], v[88:89], off offset:16
	global_load_dwordx4 v[100:103], v[88:89], off
	s_nop 0
	global_load_dwordx4 v[88:91], v[92:93], off offset:16
	global_load_dwordx4 v[108:111], v[92:93], off
	s_nop 0
	global_load_dwordx4 v[92:95], v[112:113], off offset:16
	s_nop 0
	global_load_dwordx4 v[112:115], v[112:113], off
	v_cmp_eq_u32_e32 vcc, 0, v194
	s_nop 0
	s_nop 0
	v_cndmask_b32_e32 v161, v148, v136, vcc
	v_cndmask_b32_e32 v162, v149, v137, vcc
	v_cndmask_b32_e32 v163, v150, v138, vcc
	v_mov_b32_dpp v160, v161 row_ror:15 row_mask:0xf bank_mask:0xf
	s_nop 0
	s_nop 0
	v_mov_b32_dpp v161, v162 row_ror:15 row_mask:0xf bank_mask:0xf
	v_mov_b32_dpp v164, v150 row_ror:1 row_mask:0xf bank_mask:0xf
	v_cndmask_b32_e32 v165, v151, v139, vcc
	v_mov_b32_dpp v162, v163 row_ror:15 row_mask:0xf bank_mask:0xf
	v_mov_b32_dpp v195, v151 row_ror:1 row_mask:0xf bank_mask:0xf
	v_mov_b32_dpp v166, v148 row_ror:1 row_mask:0xf bank_mask:0xf
	v_mov_b32_dpp v167, v149 row_ror:1 row_mask:0xf bank_mask:0xf
	v_mov_b32_dpp v163, v165 row_ror:15 row_mask:0xf bank_mask:0xf
	v_cndmask_b32_e64 v165, v195, 0, vcc
	v_cndmask_b32_e64 v164, v164, 0, vcc
	v_cndmask_b32_e64 v167, v167, 0, vcc
	v_cndmask_b32_e64 v166, v166, 0, vcc
	s_nop 0
	s_nop 0
	v_mov_b32_dpp v195, v144 row_ror:1 row_mask:0xf bank_mask:0xf
	v_mov_b32_dpp v196, v145 row_ror:1 row_mask:0xf bank_mask:0xf
	v_mov_b32_dpp v198, v146 row_ror:1 row_mask:0xf bank_mask:0xf
	v_cndmask_b32_e32 v199, v147, v131, vcc
	v_mov_b32_dpp v200, v147 row_ror:1 row_mask:0xf bank_mask:0xf
	v_cndmask_b32_e64 v198, v198, 0, vcc
	v_cndmask_b32_e64 v201, v196, 0, vcc
	s_lshl_b32 s3, s44, 8
	s_add_i32 s3, s3, s49
	v_add_u32_e32 v193, s3, v194
	v_cmp_ne_u32_e64 s[46:47], 0, v194
	s_waitcnt vmcnt(0)
	v_pk_mul_f32 v[164:165], v[98:99], v[164:165]
	v_pk_mul_f32 v[166:167], v[96:97], v[166:167]
	v_pk_fma_f32 v[164:165], v[150:151], v[102:103], v[164:165]
	v_pk_fma_f32 v[166:167], v[148:149], v[100:101], v[166:167]
	v_pk_fma_f32 v[162:163], v[110:111], v[162:163], v[164:165]
	v_cndmask_b32_e32 v165, v144, v128, vcc
	v_pk_fma_f32 v[160:161], v[108:109], v[160:161], v[166:167]
	v_cndmask_b32_e32 v166, v145, v129, vcc
	v_mov_b32_dpp v164, v165 row_ror:15 row_mask:0xf bank_mask:0xf
	v_cndmask_b32_e32 v167, v146, v130, vcc
	v_pk_add_f32 v[162:163], v[114:115], v[162:163]
	v_mov_b32_dpp v165, v166 row_ror:15 row_mask:0xf bank_mask:0xf
	v_pk_add_f32 v[160:161], v[112:113], v[160:161]
	s_nop 0
	v_mov_b32_dpp v166, v167 row_ror:15 row_mask:0xf bank_mask:0xf
	s_nop 1
	v_mov_b32_dpp v167, v199 row_ror:15 row_mask:0xf bank_mask:0xf
	v_cndmask_b32_e64 v199, v200, 0, vcc
	v_cndmask_b32_e64 v200, v195, 0, vcc
	v_pk_mul_f32 v[200:201], v[80:81], v[200:201]
	v_pk_mul_f32 v[198:199], v[82:83], v[198:199]
	v_pk_fma_f32 v[200:201], v[144:145], v[84:85], v[200:201]
	v_pk_fma_f32 v[198:199], v[146:147], v[86:87], v[198:199]
	v_pk_fma_f32 v[164:165], v[88:89], v[164:165], v[200:201]
	v_pk_fma_f32 v[166:167], v[90:91], v[166:167], v[198:199]
	v_pk_add_f32 v[164:165], v[92:93], v[164:165]
	v_pk_add_f32 v[166:167], v[94:95], v[166:167]
	s_and_saveexec_b64 s[28:29], s[46:47]
	s_xor_b64 s[28:29], exec, s[28:29]
	s_cbranch_execz .LBB1_1911
	v_mul_f32_e32 v195, 0xbfb8aa3b, v160
	v_exp_f32_e32 v195, v195
	v_mul_f32_e32 v196, 0xbfb8aa3b, v161
	v_exp_f32_e32 v196, v196
	v_pk_mul_f32 v[160:161], v[156:157], v[160:161]
	v_add_f32_e32 v195, 1.0, v195
	v_rcp_f32_e32 v198, v195
	v_add_f32_e32 v196, 1.0, v196
	v_mul_f32_e32 v195, 0xbfb8aa3b, v162
	v_rcp_f32_e32 v199, v196
	v_exp_f32_e32 v195, v195
	v_mul_f32_e32 v196, 0xbfb8aa3b, v163
	v_exp_f32_e32 v196, v196
	v_pk_mul_f32 v[160:161], v[160:161], v[198:199]
	v_add_f32_e32 v195, 1.0, v195
	v_rcp_f32_e32 v200, v195
	v_add_f32_e32 v195, 1.0, v196
	v_rcp_f32_e32 v201, v195
	v_cvt_pk_bf16_f32 v160, v160, v161
	v_mul_f32_e32 v161, 0xbfb8aa3b, v164
	v_exp_f32_e32 v195, v161
	v_mul_f32_e32 v161, 0xbfb8aa3b, v165
	v_exp_f32_e32 v196, v161
	v_pk_mul_f32 v[162:163], v[158:159], v[162:163]
	v_pk_mul_f32 v[164:165], v[152:153], v[164:165]
	v_pk_mul_f32 v[162:163], v[162:163], v[200:201]
	s_nop 0
	v_cvt_pk_bf16_f32 v161, v162, v163
	v_add_f32_e32 v162, 1.0, v195
	v_mul_f32_e32 v195, 0xbfb8aa3b, v166
	v_add_f32_e32 v163, 1.0, v196
	v_exp_f32_e32 v195, v195
	v_mul_f32_e32 v196, 0xbfb8aa3b, v167
	v_exp_f32_e32 v196, v196
	v_rcp_f32_e32 v162, v162
	v_add_f32_e32 v195, 1.0, v195
	v_rcp_f32_e32 v198, v195
	v_add_f32_e32 v195, 1.0, v196
	v_rcp_f32_e32 v163, v163
	v_rcp_f32_e32 v199, v195
	v_pk_mul_f32 v[166:167], v[154:155], v[166:167]
	v_pk_mul_f32 v[162:163], v[164:165], v[162:163]
	v_pk_mul_f32 v[164:165], v[166:167], v[198:199]
	v_cvt_pk_bf16_f32 v162, v162, v163
	v_cvt_pk_bf16_f32 v163, v164, v165
	v_mov_b64_e32 v[164:165], s[52:53]
	v_mad_i64_i32 v[164:165], s[42:43], v193, s60, v[164:165]
	v_lshl_add_u64 v[164:165], v[184:185], 1, v[164:165]
	global_store_dwordx4 v[164:165], v[160:163], off

; #define PG8_STAGE(bufoff, gbase, voff) do { _Pragma("unroll") for (int _i = 0; _i < 2; ++_i) \
;         __builtin_amdgcn_global_load_lds((const unsigned*)((const char*)(gbase) + (voff)[_i]), (LAS unsigned*)(lds + (bufoff) + ldsw + _i * 8192), 16, 0, 0); } while (0)
; #define PG8_LDA(dst, b, h) do { _Pragma("unroll") for (int m = 0; m < 4; ++m) _Pragma("unroll") for (int k = 0; k < 2; ++k) dst[m][k] = *(const LAS bf16x8*)(lds + PG8_SA(b, h) + aoff + m * 2048 + k * 1024); } while (0)
; #define PG8_LDB(dst, b, h) do { _Pragma("unroll") for (int n = 0; n < 2; ++n) _Pragma("unroll") for (int k = 0; k < 2; ++k) dst[n][k] = *(const LAS bf16x8*)(lds + PG8_SB(b, h) + boff + n * 2048 + k * 1024); } while (0)
; #define PG8_MMA(ai, bj, At, Bt) do { __builtin_amdgcn_s_setprio(1); _Pragma("unroll") for (int m = 0; m < 4; ++m) _Pragma("unroll") for (int n = 0; n < 2; ++n) _Pragma("unroll") for (int k = 0; k < 2; ++k) \
;         acc[ai][bj][m][n] = __builtin_amdgcn_mfma_f32_16x16x32_bf16(Bt[n][k], At[m][k], acc[ai][bj][m][n], 0, 0, 0); __builtin_amdgcn_s_setprio(0); } while (0)
; #define PG8_WAIT_V(n) asm volatile("s_waitcnt vmcnt(" #n ")" ::: "memory")
; #define PG8_WAIT_L(n) asm volatile("s_waitcnt lgkmcnt(" #n ")" ::: "memory")
; #define PG8_BAR __builtin_amdgcn_s_barrier()
; #define PG8_SCHED __builtin_amdgcn_sched_barrier(0)
; template <class Map, class Epi>
; DI void gemm_phase(LAS unsigned char* lds, const Map& MP, const Epi& E, const int nM, const int nN, const int K, const int lda, const int ldb) {
;     ...
;             PG8_LDB(B0, 0, 0); PG8_SCHED; PG8_LDA(At, 0, 0); PG8_STAGE(PG8_SA(1, 1), a1 + hstepA, voffA);
;             PG8_WAIT_L(8); PG8_BAR; PG8_WAIT_L(0); PG8_MMA(0, 0, At, B0); PG8_BAR; PG8_SCHED;
;             PG8_LDB(B1, 0, 1); PG8_STAGE(PG8_SB(0, 0), b2, voffB);
;             PG8_BAR; PG8_WAIT_L(0); PG8_MMA(0, 1, At, B1); PG8_BAR;
;             PG8_LDA(At, 0, 1); PG8_STAGE(PG8_SA(0, 0), a2, voffA);
;             PG8_BAR; PG8_WAIT_L(0); PG8_MMA(1, 0, At, B0); PG8_BAR; PG8_SCHED;
;             PG8_STAGE(PG8_SB(0, 1), b2 + hstepB, voffB);
;             PG8_WAIT_V(6); PG8_BAR; PG8_MMA(1, 1, At, B1); PG8_BAR;
.LBB1_2339:
	s_add_i32 m0, s9, 0xc000
	ds_read_b128 v[168:171], v166
	ds_read_b128 v[172:175], v166 offset:1024
	ds_read_b128 v[176:179], v166 offset:2048
	ds_read_b128 v[180:183], v166 offset:3072
	ds_read_b128 v[184:187], v166 offset:4096
	ds_read_b128 v[188:191], v166 offset:5120
	ds_read_b128 v[192:195], v166 offset:6144
	ds_read_b128 v[198:201], v166 offset:7168
	global_load_lds_dwordx4 v154, s[10:11]
	s_add_i32 m0, s9, 0xe000
	s_setprio 1
	global_load_lds_dwordx4 v152, s[10:11]
	s_waitcnt lgkmcnt(8)
	s_barrier
	s_waitcnt lgkmcnt(7)
	v_mfma_f32_16x16x32_bf16 v[140:143], v[40:43], v[168:171], v[140:143]
	v_mfma_f32_16x16x32_bf16 v[136:139], v[56:59], v[168:171], v[136:139]
	s_waitcnt lgkmcnt(5)
	v_mfma_f32_16x16x32_bf16 v[124:127], v[40:43], v[176:179], v[124:127]
	v_mfma_f32_16x16x32_bf16 v[120:123], v[56:59], v[176:179], v[120:123]
	s_waitcnt lgkmcnt(3)
	v_mfma_f32_16x16x32_bf16 v[108:111], v[40:43], v[184:187], v[108:111]
	v_mfma_f32_16x16x32_bf16 v[104:107], v[56:59], v[184:187], v[104:107]
	s_waitcnt lgkmcnt(1)
	v_mfma_f32_16x16x32_bf16 v[92:95], v[40:43], v[192:195], v[92:95]
	v_mfma_f32_16x16x32_bf16 v[88:91], v[56:59], v[192:195], v[88:91]
	v_mfma_f32_16x16x32_bf16 v[140:143], v[44:47], v[172:175], v[140:143]
	s_add_i32 s57, s35, s22
	v_mfma_f32_16x16x32_bf16 v[136:139], v[60:63], v[172:175], v[136:139]
	v_lshl_add_u64 v[160:161], s[12:13], 0, v[148:149]
	v_mfma_f32_16x16x32_bf16 v[124:127], v[44:47], v[180:183], v[124:127]
	v_lshl_add_u64 v[218:219], s[12:13], 0, v[144:145]
	v_mfma_f32_16x16x32_bf16 v[120:123], v[60:63], v[180:183], v[120:123]
	v_mfma_f32_16x16x32_bf16 v[108:111], v[44:47], v[188:191], v[108:111]
	v_mfma_f32_16x16x32_bf16 v[104:107], v[60:63], v[188:191], v[104:107]
	s_waitcnt lgkmcnt(0)
	v_mfma_f32_16x16x32_bf16 v[92:95], v[44:47], v[198:201], v[92:95]
	v_mfma_f32_16x16x32_bf16 v[88:91], v[60:63], v[198:201], v[88:91]
	s_barrier
	s_setprio 0
	s_mov_b32 m0, s57
	ds_read_b128 v[202:205], v167
	ds_read_b128 v[206:209], v167 offset:1024
	ds_read_b128 v[210:213], v167 offset:2048
	ds_read_b128 v[214:217], v167 offset:3072
	global_load_lds_dwordx4 v[160:161], off
	s_add_i32 m0, s57, 0x2000
	s_setprio 1
	global_load_lds_dwordx4 v[218:219], off
	s_barrier
	s_waitcnt lgkmcnt(3)
	v_mfma_f32_16x16x32_bf16 v[132:135], v[202:205], v[168:171], v[132:135]
	s_waitcnt lgkmcnt(1)
	v_mfma_f32_16x16x32_bf16 v[128:131], v[210:213], v[168:171], v[128:131]
	v_mfma_f32_16x16x32_bf16 v[116:119], v[202:205], v[176:179], v[116:119]
	v_mfma_f32_16x16x32_bf16 v[112:115], v[210:213], v[176:179], v[112:115]
	v_mfma_f32_16x16x32_bf16 v[100:103], v[202:205], v[184:187], v[100:103]
	v_mfma_f32_16x16x32_bf16 v[96:99], v[210:213], v[184:187], v[96:99]
	v_mfma_f32_16x16x32_bf16 v[84:87], v[202:205], v[192:195], v[84:87]
	v_mfma_f32_16x16x32_bf16 v[80:83], v[210:213], v[192:195], v[80:83]
	v_mfma_f32_16x16x32_bf16 v[132:135], v[206:209], v[172:175], v[132:135]
	v_lshl_add_u64 v[222:223], s[14:15], 0, v[146:147]
	s_mov_b32 m0, s9
	s_waitcnt lgkmcnt(0)
	v_mfma_f32_16x16x32_bf16 v[128:131], v[214:217], v[172:175], v[128:131]
	v_lshl_add_u64 v[220:221], s[14:15], 0, v[150:151]
	v_mfma_f32_16x16x32_bf16 v[116:119], v[206:209], v[180:183], v[116:119]
	v_mfma_f32_16x16x32_bf16 v[112:115], v[214:217], v[180:183], v[112:115]
	v_mfma_f32_16x16x32_bf16 v[100:103], v[206:209], v[188:191], v[100:103]
	v_mfma_f32_16x16x32_bf16 v[96:99], v[214:217], v[188:191], v[96:99]
	v_mfma_f32_16x16x32_bf16 v[84:87], v[206:209], v[198:201], v[84:87]
	v_mfma_f32_16x16x32_bf16 v[80:83], v[214:217], v[198:201], v[80:83]
	s_barrier
	s_setprio 0
	ds_read_b128 v[168:171], v166 offset:16384
	ds_read_b128 v[172:175], v166 offset:17408
	ds_read_b128 v[176:179], v166 offset:18432
	ds_read_b128 v[180:183], v166 offset:19456
	ds_read_b128 v[184:187], v166 offset:20480
	ds_read_b128 v[188:191], v166 offset:21504
	ds_read_b128 v[192:195], v166 offset:22528
	ds_read_b128 v[198:201], v166 offset:23552
	global_load_lds_dwordx4 v[220:221], off
	s_mov_b32 m0, s24
	s_setprio 1
	global_load_lds_dwordx4 v[222:223], off
	s_waitcnt vmcnt(10)
	s_barrier
	s_waitcnt lgkmcnt(7)
	v_mfma_f32_16x16x32_bf16 v[76:79], v[40:43], v[168:171], v[76:79]
	v_mfma_f32_16x16x32_bf16 v[72:75], v[56:59], v[168:171], v[72:75]
	s_waitcnt lgkmcnt(5)
	v_mfma_f32_16x16x32_bf16 v[52:55], v[40:43], v[176:179], v[52:55]
	v_mfma_f32_16x16x32_bf16 v[48:51], v[56:59], v[176:179], v[48:51]
	s_waitcnt lgkmcnt(3)
	v_mfma_f32_16x16x32_bf16 v[28:31], v[40:43], v[184:187], v[28:31]
	v_mfma_f32_16x16x32_bf16 v[24:27], v[56:59], v[184:187], v[24:27]
	s_waitcnt lgkmcnt(1)
	v_mfma_f32_16x16x32_bf16 v[12:15], v[40:43], v[192:195], v[12:15]
	v_mfma_f32_16x16x32_bf16 v[8:11], v[56:59], v[192:195], v[8:11]
	v_mfma_f32_16x16x32_bf16 v[76:79], v[44:47], v[172:175], v[76:79]
	s_add_u32 s58, s12, 0x20000
	s_addc_u32 s59, s13, 0
	v_mfma_f32_16x16x32_bf16 v[72:75], v[60:63], v[172:175], v[72:75]
	s_add_i32 s57, s36, s22
	v_mfma_f32_16x16x32_bf16 v[52:55], v[44:47], v[180:183], v[52:55]
	v_mfma_f32_16x16x32_bf16 v[48:51], v[60:63], v[180:183], v[48:51]
	v_mfma_f32_16x16x32_bf16 v[28:31], v[44:47], v[188:191], v[28:31]
	v_mfma_f32_16x16x32_bf16 v[24:27], v[60:63], v[188:191], v[24:27]
	s_waitcnt lgkmcnt(0)
	v_mfma_f32_16x16x32_bf16 v[12:15], v[44:47], v[198:201], v[12:15]
	v_mfma_f32_16x16x32_bf16 v[8:11], v[60:63], v[198:201], v[8:11]
	s_barrier
	s_setprio 0
	s_mov_b32 m0, s57
	s_nop 0
	global_load_lds_dwordx4 v148, s[58:59]
	s_add_i32 m0, s57, 0x2000
	s_setprio 1
	global_load_lds_dwordx4 v144, s[58:59]
	s_waitcnt vmcnt(6)
	s_barrier
; #define PG8_STAGE(bufoff, gbase, voff) do { _Pragma("unroll") for (int _i = 0; _i < 2; ++_i) \
;         __builtin_amdgcn_global_load_lds((const unsigned*)((const char*)(gbase) + (voff)[_i]), (LAS unsigned*)(lds + (bufoff) + ldsw + _i * 8192), 16, 0, 0); } while (0)
; #define PG8_LDA(dst, b, h) do { _Pragma("unroll") for (int m = 0; m < 4; ++m) _Pragma("unroll") for (int k = 0; k < 2; ++k) dst[m][k] = *(const LAS bf16x8*)(lds + PG8_SA(b, h) + aoff + m * 2048 + k * 1024); } while (0)
; #define PG8_LDB(dst, b, h) do { _Pragma("unroll") for (int n = 0; n < 2; ++n) _Pragma("unroll") for (int k = 0; k < 2; ++k) dst[n][k] = *(const LAS bf16x8*)(lds + PG8_SB(b, h) + boff + n * 2048 + k * 1024); } while (0)
; #define PG8_MMA(ai, bj, At, Bt) do { __builtin_amdgcn_s_setprio(1); _Pragma("unroll") for (int m = 0; m < 4; ++m) _Pragma("unroll") for (int n = 0; n < 2; ++n) _Pragma("unroll") for (int k = 0; k < 2; ++k) \
;         acc[ai][bj][m][n] = __builtin_amdgcn_mfma_f32_16x16x32_bf16(Bt[n][k], At[m][k], acc[ai][bj][m][n], 0, 0, 0); __builtin_amdgcn_s_setprio(0); } while (0)
; #define PG8_WAIT_V(n) asm volatile("s_waitcnt vmcnt(" #n ")" ::: "memory")
; #define PG8_WAIT_L(n) asm volatile("s_waitcnt lgkmcnt(" #n ")" ::: "memory")
; #define PG8_BAR __builtin_amdgcn_s_barrier()
; #define PG8_SCHED __builtin_amdgcn_sched_barrier(0)
; template <class Map, class Epi>
; DI void gemm_phase(LAS unsigned char* lds, const Map& MP, const Epi& E, const int nM, const int nN, const int K, const int lda, const int ldb) {
;     ...
;             PG8_WAIT_V(6); PG8_BAR; PG8_MMA(1, 1, At, B1); PG8_BAR;
;             PG8_LDB(B0, 1, 0); PG8_SCHED; PG8_LDA(At, 1, 0); PG8_STAGE(PG8_SA(0, 1), a2 + hstepA, voffA);
;             PG8_WAIT_L(8); PG8_BAR; PG8_WAIT_L(0); PG8_MMA(0, 0, At, B0); PG8_BAR; PG8_SCHED;
;             PG8_LDB(B1, 1, 1); PG8_STAGE(PG8_SB(1, 0), b3, voffB);
;             PG8_BAR; PG8_WAIT_L(0); PG8_MMA(0, 1, At, B1); PG8_BAR;
;             PG8_LDA(At, 1, 1); PG8_STAGE(PG8_SA(1, 0), a3, voffA);
;             PG8_BAR; PG8_WAIT_L(0); PG8_MMA(1, 0, At, B0); PG8_BAR; PG8_SCHED;
	v_mfma_f32_16x16x32_bf16 v[36:39], v[202:205], v[176:179], v[36:39]
	v_mfma_f32_16x16x32_bf16 v[32:35], v[210:213], v[176:179], v[32:35]
	v_mfma_f32_16x16x32_bf16 v[20:23], v[202:205], v[184:187], v[20:23]
	v_mfma_f32_16x16x32_bf16 v[16:19], v[210:213], v[184:187], v[16:19]
	v_mfma_f32_16x16x32_bf16 v[4:7], v[202:205], v[192:195], v[4:7]
	v_mfma_f32_16x16x32_bf16 v[0:3], v[210:213], v[192:195], v[0:3]
	v_mfma_f32_16x16x32_bf16 v[40:43], v[202:205], v[168:171], v[68:71]
	s_add_i32 s57, 0, 0x18000
	v_add_u32_e32 v68, s57, v164
	ds_read_b128 v[56:59], v68
	ds_read_b128 v[60:63], v68 offset:1024
	v_mfma_f32_16x16x32_bf16 v[44:47], v[210:213], v[168:171], v[64:67]
	ds_read_b128 v[64:67], v68 offset:2048
	ds_read_b128 v[68:71], v68 offset:3072
	v_mfma_f32_16x16x32_bf16 v[36:39], v[206:209], v[180:183], v[36:39]
	s_add_u32 s14, s14, 0x80000
	s_addc_u32 s15, s15, 0
	v_mfma_f32_16x16x32_bf16 v[32:35], v[214:217], v[180:183], v[32:35]
	v_mfma_f32_16x16x32_bf16 v[20:23], v[206:209], v[188:191], v[20:23]
	v_mfma_f32_16x16x32_bf16 v[16:19], v[214:217], v[188:191], v[16:19]
	v_mfma_f32_16x16x32_bf16 v[4:7], v[206:209], v[198:201], v[4:7]
	v_mfma_f32_16x16x32_bf16 v[0:3], v[214:217], v[198:201], v[0:3]
	v_mfma_f32_16x16x32_bf16 v[40:43], v[206:209], v[172:175], v[40:43]
	v_mfma_f32_16x16x32_bf16 v[44:47], v[214:217], v[172:175], v[44:47]
	s_barrier
	s_setprio 0
	s_mov_b32 m0, s25
	ds_read_b128 v[168:171], v166 offset:32768
	ds_read_b128 v[172:175], v166 offset:33792
	ds_read_b128 v[176:179], v166 offset:34816
	ds_read_b128 v[180:183], v166 offset:35840
	ds_read_b128 v[184:187], v166 offset:36864
	ds_read_b128 v[188:191], v166 offset:37888
	ds_read_b128 v[192:195], v166 offset:38912
	ds_read_b128 v[198:201], v166 offset:39936
	global_load_lds_dwordx4 v150, s[14:15]
	s_mov_b32 m0, s26
	s_setprio 1
	global_load_lds_dwordx4 v146, s[14:15]
	s_waitcnt lgkmcnt(8)
	s_barrier
	s_waitcnt lgkmcnt(7)
	v_mfma_f32_16x16x32_bf16 v[140:143], v[56:59], v[168:171], v[140:143]
	v_mfma_f32_16x16x32_bf16 v[136:139], v[64:67], v[168:171], v[136:139]
	s_waitcnt lgkmcnt(5)
	v_mfma_f32_16x16x32_bf16 v[124:127], v[56:59], v[176:179], v[124:127]
	v_mfma_f32_16x16x32_bf16 v[120:123], v[64:67], v[176:179], v[120:123]
	s_waitcnt lgkmcnt(3)
	v_mfma_f32_16x16x32_bf16 v[108:111], v[56:59], v[184:187], v[108:111]
	v_mfma_f32_16x16x32_bf16 v[104:107], v[64:67], v[184:187], v[104:107]
	s_waitcnt lgkmcnt(1)
	v_mfma_f32_16x16x32_bf16 v[92:95], v[56:59], v[192:195], v[92:95]
	v_mfma_f32_16x16x32_bf16 v[88:91], v[64:67], v[192:195], v[88:91]
	v_mfma_f32_16x16x32_bf16 v[140:143], v[60:63], v[172:175], v[140:143]
	s_add_i32 s14, 0, 0x1c000
	v_mfma_f32_16x16x32_bf16 v[136:139], v[68:71], v[172:175], v[136:139]
	s_add_i32 s15, s57, s22
	v_mfma_f32_16x16x32_bf16 v[124:127], v[60:63], v[180:183], v[124:127]
	v_add_u32_e32 v196, s14, v164
	v_mfma_f32_16x16x32_bf16 v[120:123], v[68:71], v[180:183], v[120:123]
	v_lshl_add_u64 v[160:161], v[160:161], 0, s[46:47]
	v_mfma_f32_16x16x32_bf16 v[108:111], v[60:63], v[188:191], v[108:111]
	v_mfma_f32_16x16x32_bf16 v[104:107], v[68:71], v[188:191], v[104:107]
	s_waitcnt lgkmcnt(0)
	v_mfma_f32_16x16x32_bf16 v[92:95], v[60:63], v[198:201], v[92:95]
	v_mfma_f32_16x16x32_bf16 v[88:91], v[68:71], v[198:201], v[88:91]
	s_barrier
	s_setprio 0
	s_mov_b32 m0, s15
	ds_read_b128 v[202:205], v196
	ds_read_b128 v[206:209], v196 offset:1024
	ds_read_b128 v[210:213], v196 offset:2048
	ds_read_b128 v[214:217], v196 offset:3072
	global_load_lds_dwordx4 v[160:161], off
	v_lshl_add_u64 v[160:161], v[218:219], 0, s[46:47]
	s_add_i32 m0, s15, 0x2000
	s_setprio 1
	global_load_lds_dwordx4 v[160:161], off
	s_barrier
	s_waitcnt lgkmcnt(3)
	v_mfma_f32_16x16x32_bf16 v[132:135], v[202:205], v[168:171], v[132:135]
	s_waitcnt lgkmcnt(1)
	v_mfma_f32_16x16x32_bf16 v[128:131], v[210:213], v[168:171], v[128:131]
	v_mfma_f32_16x16x32_bf16 v[116:119], v[202:205], v[176:179], v[116:119]
	v_mfma_f32_16x16x32_bf16 v[112:115], v[210:213], v[176:179], v[112:115]
	v_mfma_f32_16x16x32_bf16 v[100:103], v[202:205], v[184:187], v[100:103]
	v_mfma_f32_16x16x32_bf16 v[96:99], v[210:213], v[184:187], v[96:99]
	v_mfma_f32_16x16x32_bf16 v[84:87], v[202:205], v[192:195], v[84:87]
	v_mfma_f32_16x16x32_bf16 v[80:83], v[210:213], v[192:195], v[80:83]
	v_mfma_f32_16x16x32_bf16 v[132:135], v[206:209], v[172:175], v[132:135]
	s_mov_b32 m0, s30
	s_waitcnt lgkmcnt(0)
	v_mfma_f32_16x16x32_bf16 v[128:131], v[214:217], v[172:175], v[128:131]
	v_lshl_add_u64 v[160:161], v[220:221], 0, s[46:47]
	v_mfma_f32_16x16x32_bf16 v[116:119], v[206:209], v[180:183], v[116:119]
	v_mfma_f32_16x16x32_bf16 v[112:115], v[214:217], v[180:183], v[112:115]
	v_mfma_f32_16x16x32_bf16 v[100:103], v[206:209], v[188:191], v[100:103]
	v_mfma_f32_16x16x32_bf16 v[96:99], v[214:217], v[188:191], v[96:99]
	v_mfma_f32_16x16x32_bf16 v[84:87], v[206:209], v[198:201], v[84:87]
	v_mfma_f32_16x16x32_bf16 v[80:83], v[214:217], v[198:201], v[80:83]
	s_barrier
	s_setprio 0
	ds_read_b128 v[168:171], v166 offset:49152
	ds_read_b128 v[172:175], v166 offset:50176
	ds_read_b128 v[176:179], v166 offset:51200
	ds_read_b128 v[180:183], v166 offset:52224
	ds_read_b128 v[184:187], v166 offset:53248
	ds_read_b128 v[188:191], v166 offset:54272
	ds_read_b128 v[192:195], v166 offset:55296
	ds_read_b128 v[198:201], v166 offset:56320
	global_load_lds_dwordx4 v[160:161], off
	v_lshl_add_u64 v[160:161], v[222:223], 0, s[46:47]
	s_mov_b32 m0, s31
	s_setprio 1
	global_load_lds_dwordx4 v[160:161], off
	s_waitcnt vmcnt(10)
	s_barrier
; DI unsigned pack2(float a, float b) { f32x2 v = {a, b}; hwbf16x2 r = __builtin_convertvector(v, hwbf16x2); return __builtin_bit_cast(unsigned, r); }
; DI float bflo(unsigned w) { return __uint_as_float(w << 16); }
; DI float bfhi(unsigned w) { return __uint_as_float(w & 0xffff0000u); }
; #define PG8_WAIT_V(n) asm volatile("s_waitcnt vmcnt(" #n ")" ::: "memory")
;     DI void operator()(const f32x4 (&acc)[2][2][4][2], const Unit& u, int wr, int wc, int fr, int fq) const {
;         const int row0 = u.pm * BM + wr * 64 + fr, col0 = u.pn * BM + wc * 32 + 8 * fq;
;         f32x4 sc[2][2];
; #pragma unroll
;         for (int bj = 0; bj < 2; ++bj)
; #pragma unroll
;             for (int n = 0; n < 2; ++n) sc[bj][n] = scale ? *(const f32x4*)(scale + col0 + bj * HALF + 4 * n) : (f32x4){1.f, 1.f, 1.f, 1.f};
; #pragma unroll
;         for (int ai = 0; ai < 2; ++ai)
; #pragma unroll
;             for (int m = 0; m < 4; ++m) { const size_t ro = (size_t)(row0 + ai * HALF + m * 16) * D + col0;
; #pragma unroll
;                 for (int bj = 0; bj < 2; ++bj) {
;                     f32x4 x0, x1;
;                     if constexpr (IB) { const u32x4 w = *(const u32x4*)((const bf16_t*)Xin + ro + bj * HALF);
;                         x0 = (f32x4){bflo(w[0]), bfhi(w[0]), bflo(w[1]), bfhi(w[1])}; x1 = (f32x4){bflo(w[2]), bfhi(w[2]), bflo(w[3]), bfhi(w[3])}; }
;                     else { x0 = *(const f32x4*)((const float*)Xin + ro + bj * HALF); x1 = *(const f32x4*)((const float*)Xin + ro + bj * HALF + 4); }
;                     x0 += acc[ai][bj][m][0] * sc[bj][0]; x1 += acc[ai][bj][m][1] * sc[bj][1];
;                     if constexpr (OB) { u32x4 o; o[0] = pack2(x0[0], x0[1]); o[1] = pack2(x0[2], x0[3]); o[2] = pack2(x1[0], x1[1]); o[3] = pack2(x1[2], x1[3]);
;                         *(u32x4*)((bf16_t*)Xout + ro + bj * HALF) = o; }
;                     else { *(f32x4*)((float*)Xout + ro + bj * HALF) = x0; *(f32x4*)((float*)Xout + ro + bj * HALF + 4) = x1; } } }
; template <class Map, class Epi>
; DI void gemm_phase(LAS unsigned char* lds, const Map& MP, const Epi& E, const int nM, const int nN, const int K, const int lda, const int ldb) {
;     ...
;             PG8_BAR; PG8_WAIT_L(0); PG8_MMA(1, 0, At, B0); PG8_BAR; PG8_SCHED;
;             PG8_STAGE(PG8_SB(1, 1), b3 + hstepB, voffB);
;             PG8_WAIT_V(6); PG8_BAR; PG8_MMA(1, 1, At, B1); PG8_BAR;
	s_waitcnt lgkmcnt(7)
	v_mfma_f32_16x16x32_bf16 v[76:79], v[56:59], v[168:171], v[76:79]
	v_mfma_f32_16x16x32_bf16 v[72:75], v[64:67], v[168:171], v[72:75]
	s_waitcnt lgkmcnt(5)
	v_mfma_f32_16x16x32_bf16 v[52:55], v[56:59], v[176:179], v[52:55]
	v_mfma_f32_16x16x32_bf16 v[48:51], v[64:67], v[176:179], v[48:51]
	s_waitcnt lgkmcnt(3)
	v_mfma_f32_16x16x32_bf16 v[28:31], v[56:59], v[184:187], v[28:31]
	v_mfma_f32_16x16x32_bf16 v[24:27], v[64:67], v[184:187], v[24:27]
	s_waitcnt lgkmcnt(1)
	v_mfma_f32_16x16x32_bf16 v[12:15], v[56:59], v[192:195], v[12:15]
	v_mfma_f32_16x16x32_bf16 v[8:11], v[64:67], v[192:195], v[8:11]
	v_mfma_f32_16x16x32_bf16 v[76:79], v[60:63], v[172:175], v[76:79]
	s_add_u32 s12, s12, 0x20080
	s_addc_u32 s13, s13, 0
	v_mfma_f32_16x16x32_bf16 v[72:75], v[68:71], v[172:175], v[72:75]
	s_add_i32 s14, s14, s22
	v_mfma_f32_16x16x32_bf16 v[52:55], v[60:63], v[180:183], v[52:55]
	v_mfma_f32_16x16x32_bf16 v[48:51], v[68:71], v[180:183], v[48:51]
	v_mfma_f32_16x16x32_bf16 v[28:31], v[60:63], v[188:191], v[28:31]
	v_mfma_f32_16x16x32_bf16 v[24:27], v[68:71], v[188:191], v[24:27]
	s_waitcnt lgkmcnt(0)
	v_mfma_f32_16x16x32_bf16 v[12:15], v[60:63], v[198:201], v[12:15]
	v_mfma_f32_16x16x32_bf16 v[8:11], v[68:71], v[198:201], v[8:11]
	s_barrier
	s_setprio 0
	s_mov_b32 m0, s14
	s_nop 0
	global_load_lds_dwordx4 v148, s[12:13]
	s_add_i32 m0, s14, 0x2000
	s_setprio 1
	global_load_lds_dwordx4 v144, s[12:13]
	s_waitcnt vmcnt(6)
	s_barrier
	v_mfma_f32_16x16x32_bf16 v[40:43], v[202:205], v[168:171], v[40:43]
	v_mfma_f32_16x16x32_bf16 v[68:71], v[206:209], v[172:175], v[40:43]
	v_mfma_f32_16x16x32_bf16 v[40:43], v[210:213], v[168:171], v[44:47]
	v_mfma_f32_16x16x32_bf16 v[36:39], v[202:205], v[176:179], v[36:39]
	v_mfma_f32_16x16x32_bf16 v[32:35], v[210:213], v[176:179], v[32:35]
	v_mfma_f32_16x16x32_bf16 v[20:23], v[202:205], v[184:187], v[20:23]
	v_mfma_f32_16x16x32_bf16 v[16:19], v[210:213], v[184:187], v[16:19]
	v_mfma_f32_16x16x32_bf16 v[4:7], v[202:205], v[192:195], v[4:7]
	v_mfma_f32_16x16x32_bf16 v[0:3], v[210:213], v[192:195], v[0:3]
	s_add_i32 s3, s3, 2
	v_mfma_f32_16x16x32_bf16 v[64:67], v[214:217], v[172:175], v[40:43]
	s_add_u32 s53, s53, 0x100
	s_addc_u32 s56, s56, 0
	ds_read_b128 v[40:43], v165
	ds_read_b128 v[44:47], v165 offset:1024
	ds_read_b128 v[56:59], v165 offset:2048
	ds_read_b128 v[60:63], v165 offset:3072
	v_mfma_f32_16x16x32_bf16 v[36:39], v[206:209], v[180:183], v[36:39]
	s_add_u32 s10, s10, 0x100
	s_addc_u32 s11, s11, 0
	v_mfma_f32_16x16x32_bf16 v[32:35], v[214:217], v[180:183], v[32:35]
	s_add_u32 s12, s10, 0xfff80080
	s_addc_u32 s13, s11, -1
	s_cmp_eq_u32 s3, 4
	s_cselect_b32 s15, s38, s13
	s_cselect_b32 s14, s39, s12
	s_cselect_b32 s13, s48, s56
	s_cselect_b32 s12, s49, s53
	s_cmp_gt_u32 s3, 5
	v_mfma_f32_16x16x32_bf16 v[20:23], v[206:209], v[188:191], v[20:23]
	v_mfma_f32_16x16x32_bf16 v[16:19], v[214:217], v[188:191], v[16:19]
	v_mfma_f32_16x16x32_bf16 v[4:7], v[206:209], v[198:201], v[4:7]
	v_mfma_f32_16x16x32_bf16 v[0:3], v[214:217], v[198:201], v[0:3]
	s_barrier
	s_setprio 0
	s_cbranch_scc0 .LBB1_2339
	s_waitcnt lgkmcnt(0)
	s_lshl_b32 s2, s2, 8
	v_mov_b32_e32 v40, v163
	v_mov_b32_e32 v168, v162
	s_or_b32 s2, s2, s29
	s_and_b64 vcc, exec, s[40:41]
	v_lshl_add_u32 v160, v40, 3, s2
	s_lshl_b32 s2, s8, 8
	s_add_i32 s2, s2, s28
	v_add_u32_e32 v168, s2, v168
	v_ashrrev_i32_e32 v169, 31, v168
	v_ashrrev_i32_e32 v161, 31, v160
	v_lshlrev_b64 v[168:169], 11, v[168:169]
	v_lshl_add_u64 v[44:45], v[160:161], 2, s[44:45]
	v_lshl_add_u64 v[160:161], v[168:169], 0, v[160:161]
	v_lshlrev_b64 v[160:161], 1, v[160:161]
	v_lshl_add_u64 v[172:173], s[4:5], 0, v[160:161]
	global_load_dwordx4 v[56:59], v[44:45], off offset:16
	global_load_dwordx4 v[60:63], v[44:45], off
	global_load_dwordx4 v[40:43], v[44:45], off offset:528
	s_nop 0
	global_load_dwordx4 v[44:47], v[44:45], off offset:512
	s_mov_b64 s[2:3], 0x10000
	global_load_dwordx4 v[178:181], v[172:173], off
	global_load_dwordx4 v[182:185], v[172:173], off offset:256
	s_mov_b64 s[98:99], 0x10000
	v_lshl_add_u64 v[170:171], v[172:173], 0, s[98:99]
	global_load_dwordx4 v[186:189], v[170:171], off
	global_load_dwordx4 v[190:193], v[170:171], off offset:256
	s_mov_b64 s[98:99], 0x20000
	v_lshl_add_u64 v[170:171], v[172:173], 0, s[98:99]
	global_load_dwordx4 v[198:201], v[170:171], off
	global_load_dwordx4 v[202:205], v[170:171], off offset:256
	s_mov_b64 s[98:99], 0x30000
	v_lshl_add_u64 v[170:171], v[172:173], 0, s[98:99]
	global_load_dwordx4 v[206:209], v[170:171], off
	global_load_dwordx4 v[210:213], v[170:171], off offset:256
	s_mov_b64 s[98:99], 0x80000
	v_lshl_add_u64 v[170:171], v[172:173], 0, s[98:99]
	global_load_dwordx4 v[214:217], v[170:171], off
	global_load_dwordx4 v[248:251], v[170:171], off offset:256
	s_mov_b64 s[98:99], 0x90000
	v_lshl_add_u64 v[170:171], v[172:173], 0, s[98:99]
	global_load_dwordx4 v[252:255], v[170:171], off
	s_waitcnt vmcnt(10)
	s_nop 1
	v_mov_b32_e32 v168, v178
	v_mov_b32_e32 v169, v179
	v_mov_b32_e32 v170, v180
	v_mov_b32_e32 v171, v181
	s_mov_b32 s8, s52
	s_mov_b64 s[10:11], s[54:55]
	s_mov_b64 s[12:13], s[6:7]
	s_waitcnt lgkmcnt(0)
	v_lshlrev_b32_e32 v174, 16, v168
	v_and_b32_e32 v175, 0xffff0000, v168
	v_lshlrev_b32_e32 v168, 16, v169
	v_and_b32_e32 v169, 0xffff0000, v169
	v_lshlrev_b32_e32 v176, 16, v170
	v_and_b32_e32 v177, 0xffff0000, v170
	v_lshlrev_b32_e32 v170, 16, v171
	v_and_b32_e32 v171, 0xffff0000, v171
	v_pk_fma_f32 v[142:143], v[142:143], v[62:63], v[168:169]
	v_pk_fma_f32 v[140:141], v[140:141], v[60:61], v[174:175]
	v_pk_fma_f32 v[168:169], v[138:139], v[58:59], v[170:171]
	v_pk_fma_f32 v[138:139], v[136:137], v[56:57], v[176:177]
	v_cvt_pk_bf16_f32 v136, v140, v141
	v_cvt_pk_bf16_f32 v137, v142, v143
	v_cvt_pk_bf16_f32 v138, v138, v139
	v_cvt_pk_bf16_f32 v139, v168, v169
	v_lshl_add_u64 v[140:141], s[42:43], 0, v[160:161]
	global_store_dwordx4 v[140:141], v[136:139], off
	s_waitcnt vmcnt(10)
; DI unsigned pack2(float a, float b) { f32x2 v = {a, b}; hwbf16x2 r = __builtin_convertvector(v, hwbf16x2); return __builtin_bit_cast(unsigned, r); }
; DI float bflo(unsigned w) { return __uint_as_float(w << 16); }
; DI float bfhi(unsigned w) { return __uint_as_float(w & 0xffff0000u); }
;     DI void operator()(const f32x4 (&acc)[2][2][4][2], const Unit& u, int wr, int wc, int fr, int fq) const {
;     ...
;         for (int ai = 0; ai < 2; ++ai)
; #pragma unroll
;             for (int m = 0; m < 4; ++m) { const size_t ro = (size_t)(row0 + ai * HALF + m * 16) * D + col0;
; #pragma unroll
;                 for (int bj = 0; bj < 2; ++bj) {
;                     f32x4 x0, x1;
;                     if constexpr (IB) { const u32x4 w = *(const u32x4*)((const bf16_t*)Xin + ro + bj * HALF);
;                         x0 = (f32x4){bflo(w[0]), bfhi(w[0]), bflo(w[1]), bfhi(w[1])}; x1 = (f32x4){bflo(w[2]), bfhi(w[2]), bflo(w[3]), bfhi(w[3])}; }
;                     else { x0 = *(const f32x4*)((const float*)Xin + ro + bj * HALF); x1 = *(const f32x4*)((const float*)Xin + ro + bj * HALF + 4); }
;                     x0 += acc[ai][bj][m][0] * sc[bj][0]; x1 += acc[ai][bj][m][1] * sc[bj][1];
;                     if constexpr (OB) { u32x4 o; o[0] = pack2(x0[0], x0[1]); o[1] = pack2(x0[2], x0[3]); o[2] = pack2(x1[0], x1[1]); o[3] = pack2(x1[2], x1[3]);
;                         *(u32x4*)((bf16_t*)Xout + ro + bj * HALF) = o; }
;                     else { *(f32x4*)((float*)Xout + ro + bj * HALF) = x0; *(f32x4*)((float*)Xout + ro + bj * HALF + 4) = x1; } } }
	s_nop 1
	v_mov_b32_e32 v136, v182
	v_mov_b32_e32 v137, v183
	v_mov_b32_e32 v138, v184
	v_mov_b32_e32 v139, v185
	s_waitcnt lgkmcnt(0)
	v_lshlrev_b32_e32 v142, 16, v136
	v_and_b32_e32 v143, 0xffff0000, v136
	v_lshlrev_b32_e32 v136, 16, v137
	v_and_b32_e32 v137, 0xffff0000, v137
	v_lshlrev_b32_e32 v168, 16, v138
	v_and_b32_e32 v169, 0xffff0000, v138
	v_lshlrev_b32_e32 v138, 16, v139
	v_and_b32_e32 v139, 0xffff0000, v139
	v_pk_fma_f32 v[134:135], v[134:135], v[46:47], v[136:137]
	v_pk_fma_f32 v[132:133], v[132:133], v[44:45], v[142:143]
	v_pk_fma_f32 v[136:137], v[130:131], v[42:43], v[138:139]
	v_pk_fma_f32 v[130:131], v[128:129], v[40:41], v[168:169]
	v_cvt_pk_bf16_f32 v128, v132, v133
	v_cvt_pk_bf16_f32 v129, v134, v135
	v_cvt_pk_bf16_f32 v130, v130, v131
	v_cvt_pk_bf16_f32 v131, v136, v137
	v_lshl_add_u64 v[132:133], v[160:161], 0, s[2:3]
	global_store_dwordx4 v[140:141], v[128:131], off offset:256
	v_lshl_add_u64 v[134:135], s[4:5], 0, v[132:133]
	s_waitcnt vmcnt(10)
	s_nop 1
	v_mov_b32_e32 v128, v186
	v_mov_b32_e32 v129, v187
	v_mov_b32_e32 v130, v188
	v_mov_b32_e32 v131, v189
	s_mov_b64 s[2:3], 0x20000
	s_waitcnt lgkmcnt(0)
	v_lshlrev_b32_e32 v136, 16, v128
	v_and_b32_e32 v137, 0xffff0000, v128
	v_lshlrev_b32_e32 v128, 16, v129
	v_and_b32_e32 v129, 0xffff0000, v129
	v_lshlrev_b32_e32 v138, 16, v130
	v_and_b32_e32 v139, 0xffff0000, v130
	v_lshlrev_b32_e32 v130, 16, v131
	v_and_b32_e32 v131, 0xffff0000, v131
	v_pk_fma_f32 v[126:127], v[126:127], v[62:63], v[128:129]
	v_pk_fma_f32 v[124:125], v[124:125], v[60:61], v[136:137]
	v_pk_fma_f32 v[128:129], v[122:123], v[58:59], v[130:131]
	v_pk_fma_f32 v[122:123], v[120:121], v[56:57], v[138:139]
	v_cvt_pk_bf16_f32 v120, v124, v125
	v_cvt_pk_bf16_f32 v121, v126, v127
	v_cvt_pk_bf16_f32 v122, v122, v123
	v_cvt_pk_bf16_f32 v123, v128, v129
	v_lshl_add_u64 v[124:125], s[42:43], 0, v[132:133]
	global_store_dwordx4 v[124:125], v[120:123], off
	s_waitcnt vmcnt(10)
	s_nop 1
	v_mov_b32_e32 v120, v190
	v_mov_b32_e32 v121, v191
	v_mov_b32_e32 v122, v192
	v_mov_b32_e32 v123, v193
	s_waitcnt lgkmcnt(0)
	v_lshlrev_b32_e32 v126, 16, v120
	v_and_b32_e32 v127, 0xffff0000, v120
	v_lshlrev_b32_e32 v120, 16, v121
	v_and_b32_e32 v121, 0xffff0000, v121
	v_lshlrev_b32_e32 v128, 16, v122
	v_and_b32_e32 v129, 0xffff0000, v122
	v_lshlrev_b32_e32 v122, 16, v123
	v_and_b32_e32 v123, 0xffff0000, v123
	v_pk_fma_f32 v[118:119], v[118:119], v[46:47], v[120:121]
	v_pk_fma_f32 v[116:117], v[116:117], v[44:45], v[126:127]
	v_pk_fma_f32 v[120:121], v[114:115], v[42:43], v[122:123]
	v_pk_fma_f32 v[114:115], v[112:113], v[40:41], v[128:129]
	v_cvt_pk_bf16_f32 v112, v116, v117
	v_cvt_pk_bf16_f32 v113, v118, v119
	v_cvt_pk_bf16_f32 v114, v114, v115
	v_cvt_pk_bf16_f32 v115, v120, v121
	v_lshl_add_u64 v[116:117], v[160:161], 0, s[2:3]
	global_store_dwordx4 v[124:125], v[112:115], off offset:256
	v_lshl_add_u64 v[118:119], s[4:5], 0, v[116:117]
	s_waitcnt vmcnt(10)
	s_nop 1
	v_mov_b32_e32 v112, v198
	v_mov_b32_e32 v113, v199
	v_mov_b32_e32 v114, v200
	v_mov_b32_e32 v115, v201
	s_mov_b64 s[2:3], 0x30000
	s_waitcnt lgkmcnt(0)
	v_lshlrev_b32_e32 v120, 16, v112
	v_and_b32_e32 v121, 0xffff0000, v112
	v_lshlrev_b32_e32 v112, 16, v113
	v_and_b32_e32 v113, 0xffff0000, v113
	v_lshlrev_b32_e32 v122, 16, v114
	v_and_b32_e32 v123, 0xffff0000, v114
	v_lshlrev_b32_e32 v114, 16, v115
	v_and_b32_e32 v115, 0xffff0000, v115
	v_pk_fma_f32 v[110:111], v[110:111], v[62:63], v[112:113]
	v_pk_fma_f32 v[108:109], v[108:109], v[60:61], v[120:121]
	v_pk_fma_f32 v[112:113], v[106:107], v[58:59], v[114:115]
	v_pk_fma_f32 v[106:107], v[104:105], v[56:57], v[122:123]
	v_cvt_pk_bf16_f32 v104, v108, v109
	v_cvt_pk_bf16_f32 v105, v110, v111
	v_cvt_pk_bf16_f32 v106, v106, v107
	v_cvt_pk_bf16_f32 v107, v112, v113
	v_lshl_add_u64 v[108:109], s[42:43], 0, v[116:117]
	global_store_dwordx4 v[108:109], v[104:107], off
	s_waitcnt vmcnt(10)
	s_nop 1
	v_mov_b32_e32 v104, v202
	v_mov_b32_e32 v105, v203
	v_mov_b32_e32 v106, v204
	v_mov_b32_e32 v107, v205
	s_waitcnt lgkmcnt(0)
	v_lshlrev_b32_e32 v110, 16, v104
	v_and_b32_e32 v111, 0xffff0000, v104
	v_lshlrev_b32_e32 v104, 16, v105
	v_and_b32_e32 v105, 0xffff0000, v105
	v_lshlrev_b32_e32 v112, 16, v106
	v_and_b32_e32 v113, 0xffff0000, v106
	v_lshlrev_b32_e32 v106, 16, v107
	v_and_b32_e32 v107, 0xffff0000, v107
	v_pk_fma_f32 v[102:103], v[102:103], v[46:47], v[104:105]
	v_pk_fma_f32 v[100:101], v[100:101], v[44:45], v[110:111]
	v_pk_fma_f32 v[104:105], v[98:99], v[42:43], v[106:107]
	v_pk_fma_f32 v[98:99], v[96:97], v[40:41], v[112:113]
	v_cvt_pk_bf16_f32 v96, v100, v101
	v_cvt_pk_bf16_f32 v97, v102, v103
	v_cvt_pk_bf16_f32 v98, v98, v99
	v_cvt_pk_bf16_f32 v99, v104, v105
	v_lshl_add_u64 v[100:101], v[160:161], 0, s[2:3]
	global_store_dwordx4 v[108:109], v[96:99], off offset:256
	v_lshl_add_u64 v[102:103], s[4:5], 0, v[100:101]
	s_waitcnt vmcnt(10)
	s_nop 1
	v_mov_b32_e32 v96, v206
	v_mov_b32_e32 v97, v207
	v_mov_b32_e32 v98, v208
	v_mov_b32_e32 v99, v209
	s_mov_b64 s[2:3], 0x80000
	s_waitcnt lgkmcnt(0)
	v_lshlrev_b32_e32 v104, 16, v96
	v_and_b32_e32 v105, 0xffff0000, v96
	v_lshlrev_b32_e32 v96, 16, v97
	v_and_b32_e32 v97, 0xffff0000, v97
	v_lshlrev_b32_e32 v106, 16, v98
	v_and_b32_e32 v107, 0xffff0000, v98
	v_lshlrev_b32_e32 v98, 16, v99
	v_and_b32_e32 v99, 0xffff0000, v99
	v_pk_fma_f32 v[94:95], v[94:95], v[62:63], v[96:97]
	v_pk_fma_f32 v[92:93], v[92:93], v[60:61], v[104:105]
	v_pk_fma_f32 v[96:97], v[90:91], v[58:59], v[98:99]
	v_pk_fma_f32 v[90:91], v[88:89], v[56:57], v[106:107]
	v_cvt_pk_bf16_f32 v88, v92, v93
	v_cvt_pk_bf16_f32 v89, v94, v95
	v_cvt_pk_bf16_f32 v90, v90, v91
	v_cvt_pk_bf16_f32 v91, v96, v97
	v_lshl_add_u64 v[92:93], s[42:43], 0, v[100:101]
	global_store_dwordx4 v[92:93], v[88:91], off
	s_waitcnt vmcnt(10)
; DI unsigned pack2(float a, float b) { f32x2 v = {a, b}; hwbf16x2 r = __builtin_convertvector(v, hwbf16x2); return __builtin_bit_cast(unsigned, r); }
; DI float bflo(unsigned w) { return __uint_as_float(w << 16); }
; DI float bfhi(unsigned w) { return __uint_as_float(w & 0xffff0000u); }
;     DI void operator()(const f32x4 (&acc)[2][2][4][2], const Unit& u, int wr, int wc, int fr, int fq) const {
;     ...
;         for (int ai = 0; ai < 2; ++ai)
; #pragma unroll
;             for (int m = 0; m < 4; ++m) { const size_t ro = (size_t)(row0 + ai * HALF + m * 16) * D + col0;
; #pragma unroll
;                 for (int bj = 0; bj < 2; ++bj) {
;                     f32x4 x0, x1;
;                     if constexpr (IB) { const u32x4 w = *(const u32x4*)((const bf16_t*)Xin + ro + bj * HALF);
;                         x0 = (f32x4){bflo(w[0]), bfhi(w[0]), bflo(w[1]), bfhi(w[1])}; x1 = (f32x4){bflo(w[2]), bfhi(w[2]), bflo(w[3]), bfhi(w[3])}; }
;                     else { x0 = *(const f32x4*)((const float*)Xin + ro + bj * HALF); x1 = *(const f32x4*)((const float*)Xin + ro + bj * HALF + 4); }
;                     x0 += acc[ai][bj][m][0] * sc[bj][0]; x1 += acc[ai][bj][m][1] * sc[bj][1];
;                     if constexpr (OB) { u32x4 o; o[0] = pack2(x0[0], x0[1]); o[1] = pack2(x0[2], x0[3]); o[2] = pack2(x1[0], x1[1]); o[3] = pack2(x1[2], x1[3]);
;                         *(u32x4*)((bf16_t*)Xout + ro + bj * HALF) = o; }
;                     else { *(f32x4*)((float*)Xout + ro + bj * HALF) = x0; *(f32x4*)((float*)Xout + ro + bj * HALF + 4) = x1; } } }
	s_nop 1
	v_mov_b32_e32 v88, v210
	v_mov_b32_e32 v89, v211
	v_mov_b32_e32 v90, v212
	v_mov_b32_e32 v91, v213
	s_waitcnt lgkmcnt(0)
	v_lshlrev_b32_e32 v94, 16, v88
	v_and_b32_e32 v95, 0xffff0000, v88
	v_lshlrev_b32_e32 v88, 16, v89
	v_and_b32_e32 v89, 0xffff0000, v89
	v_lshlrev_b32_e32 v96, 16, v90
	v_and_b32_e32 v97, 0xffff0000, v90
	v_lshlrev_b32_e32 v90, 16, v91
	v_and_b32_e32 v91, 0xffff0000, v91
	v_pk_fma_f32 v[86:87], v[86:87], v[46:47], v[88:89]
	v_pk_fma_f32 v[84:85], v[84:85], v[44:45], v[94:95]
	v_pk_fma_f32 v[88:89], v[82:83], v[42:43], v[90:91]
	v_pk_fma_f32 v[82:83], v[80:81], v[40:41], v[96:97]
	v_cvt_pk_bf16_f32 v80, v84, v85
	v_cvt_pk_bf16_f32 v81, v86, v87
	v_cvt_pk_bf16_f32 v82, v82, v83
	v_cvt_pk_bf16_f32 v83, v88, v89
	v_lshl_add_u64 v[84:85], v[160:161], 0, s[2:3]
	global_store_dwordx4 v[92:93], v[80:83], off offset:256
	v_lshl_add_u64 v[86:87], s[4:5], 0, v[84:85]
	s_waitcnt vmcnt(10)
	s_nop 1
	v_mov_b32_e32 v80, v214
	v_mov_b32_e32 v81, v215
	v_mov_b32_e32 v82, v216
	v_mov_b32_e32 v83, v217
	s_mov_b64 s[2:3], 0x90000
	s_waitcnt lgkmcnt(0)
	v_lshlrev_b32_e32 v88, 16, v80
	v_and_b32_e32 v89, 0xffff0000, v80
	v_lshlrev_b32_e32 v80, 16, v81
	v_and_b32_e32 v81, 0xffff0000, v81
	v_lshlrev_b32_e32 v90, 16, v82
	v_and_b32_e32 v91, 0xffff0000, v82
	v_lshlrev_b32_e32 v82, 16, v83
	v_and_b32_e32 v83, 0xffff0000, v83
	v_pk_fma_f32 v[78:79], v[78:79], v[62:63], v[80:81]
	v_pk_fma_f32 v[76:77], v[76:77], v[60:61], v[88:89]
	v_pk_fma_f32 v[80:81], v[74:75], v[58:59], v[82:83]
	v_pk_fma_f32 v[74:75], v[72:73], v[56:57], v[90:91]
	v_cvt_pk_bf16_f32 v72, v76, v77
	v_cvt_pk_bf16_f32 v73, v78, v79
	v_cvt_pk_bf16_f32 v74, v74, v75
	v_cvt_pk_bf16_f32 v75, v80, v81
	v_lshl_add_u64 v[76:77], s[42:43], 0, v[84:85]
	global_store_dwordx4 v[76:77], v[72:75], off
	s_waitcnt vmcnt(10)
	s_nop 1
	v_mov_b32_e32 v72, v248
	v_mov_b32_e32 v73, v249
	v_mov_b32_e32 v74, v250
	v_mov_b32_e32 v75, v251
	s_waitcnt lgkmcnt(0)
	v_lshlrev_b32_e32 v78, 16, v72
	v_and_b32_e32 v79, 0xffff0000, v72
	v_lshlrev_b32_e32 v72, 16, v73
	v_and_b32_e32 v73, 0xffff0000, v73
	v_lshlrev_b32_e32 v80, 16, v74
	v_and_b32_e32 v81, 0xffff0000, v74
	v_lshlrev_b32_e32 v74, 16, v75
	v_and_b32_e32 v75, 0xffff0000, v75
	v_pk_fma_f32 v[70:71], v[70:71], v[46:47], v[72:73]
	v_pk_fma_f32 v[68:69], v[68:69], v[44:45], v[78:79]
	v_pk_fma_f32 v[72:73], v[66:67], v[42:43], v[74:75]
	v_pk_fma_f32 v[66:67], v[64:65], v[40:41], v[80:81]
	v_cvt_pk_bf16_f32 v64, v68, v69
	v_cvt_pk_bf16_f32 v65, v70, v71
	v_cvt_pk_bf16_f32 v66, v66, v67
	v_cvt_pk_bf16_f32 v67, v72, v73
	v_lshl_add_u64 v[68:69], v[160:161], 0, s[2:3]
	global_store_dwordx4 v[76:77], v[64:67], off offset:256
	v_lshl_add_u64 v[70:71], s[4:5], 0, v[68:69]
	s_waitcnt vmcnt(10)
	s_nop 1
	v_mov_b32_e32 v64, v252
	v_mov_b32_e32 v65, v253
	v_mov_b32_e32 v66, v254
	v_mov_b32_e32 v67, v255
	s_mov_b64 s[2:3], 0xa0000
	s_waitcnt lgkmcnt(0)
	v_lshlrev_b32_e32 v72, 16, v64
	v_and_b32_e32 v73, 0xffff0000, v64
	v_lshlrev_b32_e32 v64, 16, v65
	v_and_b32_e32 v65, 0xffff0000, v65
	v_lshlrev_b32_e32 v74, 16, v66
	v_and_b32_e32 v75, 0xffff0000, v66
	v_lshlrev_b32_e32 v66, 16, v67
	v_and_b32_e32 v67, 0xffff0000, v67
	v_pk_fma_f32 v[54:55], v[54:55], v[62:63], v[64:65]
	v_pk_fma_f32 v[52:53], v[52:53], v[60:61], v[72:73]
	v_pk_fma_f32 v[64:65], v[50:51], v[58:59], v[66:67]
	v_pk_fma_f32 v[50:51], v[48:49], v[56:57], v[74:75]
	v_cvt_pk_bf16_f32 v48, v52, v53
	v_cvt_pk_bf16_f32 v49, v54, v55
	v_cvt_pk_bf16_f32 v50, v50, v51
	v_cvt_pk_bf16_f32 v51, v64, v65
	v_lshl_add_u64 v[52:53], s[42:43], 0, v[68:69]
	global_store_dwordx4 v[52:53], v[48:51], off
	global_load_dwordx4 v[48:51], v[70:71], off offset:256
	s_waitcnt vmcnt(0) lgkmcnt(0)
; DI unsigned pack2(float a, float b) { f32x2 v = {a, b}; hwbf16x2 r = __builtin_convertvector(v, hwbf16x2); return __builtin_bit_cast(unsigned, r); }
; DI float bflo(unsigned w) { return __uint_as_float(w << 16); }
; DI float bfhi(unsigned w) { return __uint_as_float(w & 0xffff0000u); }
;     DI const char* a(const Unit& u) const { return (const char*)(A + (size_t)u.pm * BM * lda); }
;     DI const char* a(const Unit& u) const { return (const char*)(A + (size_t)u.pm * BM * 2048 + (u.pn >> 1) * 512); }
;     DI void operator()(const f32x4 (&acc)[2][2][4][2], const Unit& u, int wr, int wc, int fr, int fq) const {
;     ...
;         for (int ai = 0; ai < 2; ++ai)
; #pragma unroll
;             for (int m = 0; m < 4; ++m) { const size_t ro = (size_t)(row0 + ai * HALF + m * 16) * D + col0;
; #pragma unroll
;                 for (int bj = 0; bj < 2; ++bj) {
;                     f32x4 x0, x1;
;                     if constexpr (IB) { const u32x4 w = *(const u32x4*)((const bf16_t*)Xin + ro + bj * HALF);
;                         x0 = (f32x4){bflo(w[0]), bfhi(w[0]), bflo(w[1]), bfhi(w[1])}; x1 = (f32x4){bflo(w[2]), bfhi(w[2]), bflo(w[3]), bfhi(w[3])}; }
;                     else { x0 = *(const f32x4*)((const float*)Xin + ro + bj * HALF); x1 = *(const f32x4*)((const float*)Xin + ro + bj * HALF + 4); }
;                     x0 += acc[ai][bj][m][0] * sc[bj][0]; x1 += acc[ai][bj][m][1] * sc[bj][1];
;                     if constexpr (OB) { u32x4 o; o[0] = pack2(x0[0], x0[1]); o[1] = pack2(x0[2], x0[3]); o[2] = pack2(x1[0], x1[1]); o[3] = pack2(x1[2], x1[3]);
;                         *(u32x4*)((bf16_t*)Xout + ro + bj * HALF) = o; }
;                     else { *(f32x4*)((float*)Xout + ro + bj * HALF) = x0; *(f32x4*)((float*)Xout + ro + bj * HALF + 4) = x1; } } }
; template <class Map, class Epi>
; DI void gemm_phase(LAS unsigned char* lds, const Map& MP, const Epi& E, const int nM, const int nN, const int K, const int lda, const int ldb) {
;     ...
;         if (!has_next) break;
; #pragma unroll
;         for (int a = 0; a < 2; ++a)
; #pragma unroll
;             for (int b = 0; b < 2; ++b)
; #pragma unroll
;                 for (int m = 0; m < 4; ++m)
; #pragma unroll
;                     for (int n = 0; n < 2; ++n) acc[a][b][m][n] = (f32x4){0.f, 0.f, 0.f, 0.f};
;         cur = nxt; cA = nA; cB = nB; ++ui;
;     }
;     PG8_WAIT_V(0);
;     if (wr == 0) PG8_BAR;
;     PG8_BAR;
	v_lshlrev_b32_e32 v54, 16, v48
	v_and_b32_e32 v55, 0xffff0000, v48
	v_lshlrev_b32_e32 v48, 16, v49
	v_and_b32_e32 v49, 0xffff0000, v49
	v_lshlrev_b32_e32 v64, 16, v50
	v_and_b32_e32 v65, 0xffff0000, v50
	v_lshlrev_b32_e32 v50, 16, v51
	v_and_b32_e32 v51, 0xffff0000, v51
	v_pk_fma_f32 v[38:39], v[38:39], v[46:47], v[48:49]
	v_pk_fma_f32 v[36:37], v[36:37], v[44:45], v[54:55]
	v_pk_fma_f32 v[48:49], v[34:35], v[42:43], v[50:51]
	v_pk_fma_f32 v[34:35], v[32:33], v[40:41], v[64:65]
	v_cvt_pk_bf16_f32 v32, v36, v37
	v_cvt_pk_bf16_f32 v33, v38, v39
	v_cvt_pk_bf16_f32 v34, v34, v35
	v_cvt_pk_bf16_f32 v35, v48, v49
	v_lshl_add_u64 v[36:37], v[160:161], 0, s[2:3]
	global_store_dwordx4 v[52:53], v[32:35], off offset:256
	v_lshl_add_u64 v[38:39], s[4:5], 0, v[36:37]
	global_load_dwordx4 v[32:35], v[38:39], off
	s_mov_b64 s[2:3], 0xb0000
	s_waitcnt vmcnt(0) lgkmcnt(0)
	v_lshlrev_b32_e32 v48, 16, v32
	v_and_b32_e32 v49, 0xffff0000, v32
	v_lshlrev_b32_e32 v32, 16, v33
	v_and_b32_e32 v33, 0xffff0000, v33
	v_lshlrev_b32_e32 v50, 16, v34
	v_and_b32_e32 v51, 0xffff0000, v34
	v_lshlrev_b32_e32 v34, 16, v35
	v_and_b32_e32 v35, 0xffff0000, v35
	v_pk_fma_f32 v[30:31], v[30:31], v[62:63], v[32:33]
	v_pk_fma_f32 v[28:29], v[28:29], v[60:61], v[48:49]
	v_pk_fma_f32 v[32:33], v[26:27], v[58:59], v[34:35]
	v_pk_fma_f32 v[26:27], v[24:25], v[56:57], v[50:51]
	v_cvt_pk_bf16_f32 v24, v28, v29
	v_cvt_pk_bf16_f32 v25, v30, v31
	v_cvt_pk_bf16_f32 v26, v26, v27
	v_cvt_pk_bf16_f32 v27, v32, v33
	v_lshl_add_u64 v[28:29], s[42:43], 0, v[36:37]
	global_store_dwordx4 v[28:29], v[24:27], off
	global_load_dwordx4 v[24:27], v[38:39], off offset:256
	s_waitcnt vmcnt(0) lgkmcnt(0)
	v_lshlrev_b32_e32 v30, 16, v24
	v_and_b32_e32 v31, 0xffff0000, v24
	v_lshlrev_b32_e32 v24, 16, v25
	v_and_b32_e32 v25, 0xffff0000, v25
	v_lshlrev_b32_e32 v32, 16, v26
	v_and_b32_e32 v33, 0xffff0000, v26
	v_lshlrev_b32_e32 v26, 16, v27
	v_and_b32_e32 v27, 0xffff0000, v27
	v_pk_fma_f32 v[22:23], v[22:23], v[46:47], v[24:25]
	v_pk_fma_f32 v[20:21], v[20:21], v[44:45], v[30:31]
	v_pk_fma_f32 v[24:25], v[18:19], v[42:43], v[26:27]
	v_pk_fma_f32 v[18:19], v[16:17], v[40:41], v[32:33]
	v_cvt_pk_bf16_f32 v16, v20, v21
	v_cvt_pk_bf16_f32 v17, v22, v23
	v_cvt_pk_bf16_f32 v18, v18, v19
	v_cvt_pk_bf16_f32 v19, v24, v25
	v_lshl_add_u64 v[20:21], v[160:161], 0, s[2:3]
	global_store_dwordx4 v[28:29], v[16:19], off offset:256
	v_lshl_add_u64 v[22:23], s[4:5], 0, v[20:21]
	global_load_dwordx4 v[16:19], v[22:23], off
	s_mov_b32 s2, s37
	s_waitcnt vmcnt(0) lgkmcnt(0)
	v_lshlrev_b32_e32 v24, 16, v16
	v_and_b32_e32 v25, 0xffff0000, v16
	v_lshlrev_b32_e32 v16, 16, v17
	v_and_b32_e32 v17, 0xffff0000, v17
	v_lshlrev_b32_e32 v26, 16, v18
	v_and_b32_e32 v27, 0xffff0000, v18
	v_lshlrev_b32_e32 v18, 16, v19
	v_and_b32_e32 v19, 0xffff0000, v19
	v_pk_fma_f32 v[14:15], v[14:15], v[62:63], v[16:17]
	v_pk_fma_f32 v[12:13], v[12:13], v[60:61], v[24:25]
	v_pk_fma_f32 v[16:17], v[10:11], v[58:59], v[18:19]
	v_pk_fma_f32 v[10:11], v[8:9], v[56:57], v[26:27]
	v_cvt_pk_bf16_f32 v8, v12, v13
	v_cvt_pk_bf16_f32 v9, v14, v15
	v_cvt_pk_bf16_f32 v10, v10, v11
	v_cvt_pk_bf16_f32 v11, v16, v17
	v_lshl_add_u64 v[12:13], s[42:43], 0, v[20:21]
	global_store_dwordx4 v[12:13], v[8:11], off
	global_load_dwordx4 v[8:11], v[22:23], off offset:256
	s_waitcnt vmcnt(0) lgkmcnt(0)
	v_lshlrev_b32_e32 v14, 16, v8
	v_and_b32_e32 v15, 0xffff0000, v8
	v_lshlrev_b32_e32 v8, 16, v9
	v_and_b32_e32 v9, 0xffff0000, v9
	v_lshlrev_b32_e32 v16, 16, v10
	v_and_b32_e32 v17, 0xffff0000, v10
	v_lshlrev_b32_e32 v10, 16, v11
	v_and_b32_e32 v11, 0xffff0000, v11
	v_pk_fma_f32 v[6:7], v[6:7], v[46:47], v[8:9]
	v_pk_fma_f32 v[4:5], v[4:5], v[44:45], v[14:15]
	v_pk_fma_f32 v[8:9], v[2:3], v[42:43], v[10:11]
	v_pk_fma_f32 v[2:3], v[0:1], v[40:41], v[16:17]
	v_cvt_pk_bf16_f32 v0, v4, v5
	v_cvt_pk_bf16_f32 v1, v6, v7
	v_cvt_pk_bf16_f32 v2, v2, v3
	v_cvt_pk_bf16_f32 v3, v8, v9
	global_store_dwordx4 v[12:13], v[0:3], off offset:256
	s_cbranch_vccz .LBB1_2336
	s_waitcnt vmcnt(0)
	s_cmpk_gt_u32 s17, 0xff
	s_cbranch_scc1 .LBB1_2343
	s_barrier

; #define PG8_STAGE(bufoff, gbase, voff) do { _Pragma("unroll") for (int _i = 0; _i < 2; ++_i) \
;         __builtin_amdgcn_global_load_lds((const unsigned*)((const char*)(gbase) + (voff)[_i]), (LAS unsigned*)(lds + (bufoff) + ldsw + _i * 8192), 16, 0, 0); } while (0)
; #define PG8_LDA(dst, b, h) do { _Pragma("unroll") for (int m = 0; m < 4; ++m) _Pragma("unroll") for (int k = 0; k < 2; ++k) dst[m][k] = *(const LAS bf16x8*)(lds + PG8_SA(b, h) + aoff + m * 2048 + k * 1024); } while (0)
; #define PG8_LDB(dst, b, h) do { _Pragma("unroll") for (int n = 0; n < 2; ++n) _Pragma("unroll") for (int k = 0; k < 2; ++k) dst[n][k] = *(const LAS bf16x8*)(lds + PG8_SB(b, h) + boff + n * 2048 + k * 1024); } while (0)
; #define PG8_MMA(ai, bj, At, Bt) do { __builtin_amdgcn_s_setprio(1); _Pragma("unroll") for (int m = 0; m < 4; ++m) _Pragma("unroll") for (int n = 0; n < 2; ++n) _Pragma("unroll") for (int k = 0; k < 2; ++k) \
;         acc[ai][bj][m][n] = __builtin_amdgcn_mfma_f32_16x16x32_bf16(Bt[n][k], At[m][k], acc[ai][bj][m][n], 0, 0, 0); __builtin_amdgcn_s_setprio(0); } while (0)
; #define PG8_WAIT_V(n) asm volatile("s_waitcnt vmcnt(" #n ")" ::: "memory")
; #define PG8_WAIT_L(n) asm volatile("s_waitcnt lgkmcnt(" #n ")" ::: "memory")
; #define PG8_BAR __builtin_amdgcn_s_barrier()
; #define PG8_SCHED __builtin_amdgcn_sched_barrier(0)
; template <class Map, class Epi>
; DI void gemm_phase(LAS unsigned char* lds, const Map& MP, const Epi& E, const int nM, const int nN, const int K, const int lda, const int ldb) {
;     ...
;             PG8_LDB(B0, 0, 0); PG8_SCHED; PG8_LDA(At, 0, 0); PG8_STAGE(PG8_SA(1, 1), a1 + hstepA, voffA);
;             PG8_WAIT_L(8); PG8_BAR; PG8_WAIT_L(0); PG8_MMA(0, 0, At, B0); PG8_BAR; PG8_SCHED;
;             PG8_LDB(B1, 0, 1); PG8_STAGE(PG8_SB(0, 0), b2, voffB);
;             PG8_BAR; PG8_WAIT_L(0); PG8_MMA(0, 1, At, B1); PG8_BAR;
;             PG8_LDA(At, 0, 1); PG8_STAGE(PG8_SA(0, 0), a2, voffA);
;             PG8_BAR; PG8_WAIT_L(0); PG8_MMA(1, 0, At, B0); PG8_BAR; PG8_SCHED;
;             PG8_STAGE(PG8_SB(0, 1), b2 + hstepB, voffB);
;             PG8_WAIT_V(6); PG8_BAR; PG8_MMA(1, 1, At, B1); PG8_BAR;
.LBB1_2483:
	s_add_i32 m0, s38, 0xc000
	ds_read_b128 v[96:99], v190
	ds_read_b128 v[100:103], v190 offset:1024
	ds_read_b128 v[108:111], v190 offset:2048
	ds_read_b128 v[112:115], v190 offset:3072
	ds_read_b128 v[160:163], v190 offset:4096
	ds_read_b128 v[164:167], v190 offset:5120
	ds_read_b128 v[198:201], v190 offset:6144
	ds_read_b128 v[202:205], v190 offset:7168
	global_load_lds_dwordx4 v178, s[42:43]
	s_add_i32 m0, s38, 0xe000
	s_setprio 1
	global_load_lds_dwordx4 v176, s[42:43]
	s_waitcnt lgkmcnt(8)
	s_barrier
	s_waitcnt lgkmcnt(7)
	v_mfma_f32_16x16x32_bf16 v[148:151], v[80:83], v[96:99], v[148:151]
	v_mfma_f32_16x16x32_bf16 v[144:147], v[88:91], v[96:99], v[144:147]
	s_waitcnt lgkmcnt(5)
	v_mfma_f32_16x16x32_bf16 v[136:139], v[80:83], v[108:111], v[136:139]
	v_mfma_f32_16x16x32_bf16 v[128:131], v[88:91], v[108:111], v[128:131]
	s_waitcnt lgkmcnt(3)
	v_mfma_f32_16x16x32_bf16 v[120:123], v[80:83], v[160:163], v[120:123]
	v_mfma_f32_16x16x32_bf16 v[104:107], v[88:91], v[160:163], v[104:107]
	s_waitcnt lgkmcnt(1)
	v_mfma_f32_16x16x32_bf16 v[76:79], v[80:83], v[198:201], v[76:79]
	v_mfma_f32_16x16x32_bf16 v[72:75], v[88:91], v[198:201], v[72:75]
	v_mfma_f32_16x16x32_bf16 v[148:151], v[84:87], v[100:103], v[148:151]
	s_add_i32 s68, s2, s37
	v_mfma_f32_16x16x32_bf16 v[144:147], v[92:95], v[100:103], v[144:147]
	v_lshl_add_u64 v[184:185], s[28:29], 0, v[172:173]
	v_mfma_f32_16x16x32_bf16 v[136:139], v[84:87], v[112:115], v[136:139]
	v_lshl_add_u64 v[194:195], s[28:29], 0, v[168:169]
	v_mfma_f32_16x16x32_bf16 v[128:131], v[92:95], v[112:115], v[128:131]
	v_mfma_f32_16x16x32_bf16 v[120:123], v[84:87], v[164:167], v[120:123]
	v_mfma_f32_16x16x32_bf16 v[104:107], v[92:95], v[164:167], v[104:107]
	s_waitcnt lgkmcnt(0)
	v_mfma_f32_16x16x32_bf16 v[76:79], v[84:87], v[202:205], v[76:79]
	v_mfma_f32_16x16x32_bf16 v[72:75], v[92:95], v[202:205], v[72:75]
	s_barrier
	s_setprio 0
	s_mov_b32 m0, s68
	ds_read_b128 v[206:209], v191
	ds_read_b128 v[210:213], v191 offset:1024
	ds_read_b128 v[214:217], v191 offset:2048
	ds_read_b128 v[218:221], v191 offset:3072
	global_load_lds_dwordx4 v[184:185], off
	s_add_i32 m0, s68, 0x2000
	s_setprio 1
	global_load_lds_dwordx4 v[194:195], off
	s_barrier
	s_waitcnt lgkmcnt(3)
	v_mfma_f32_16x16x32_bf16 v[156:159], v[206:209], v[96:99], v[156:159]
	s_waitcnt lgkmcnt(1)
	v_mfma_f32_16x16x32_bf16 v[96:99], v[214:217], v[96:99], v[152:155]
	v_mfma_f32_16x16x32_bf16 v[156:159], v[210:213], v[100:103], v[156:159]
	s_waitcnt lgkmcnt(0)
	v_mfma_f32_16x16x32_bf16 v[96:99], v[218:221], v[100:103], v[96:99]
	v_mfma_f32_16x16x32_bf16 v[100:103], v[206:209], v[108:111], v[140:143]
	v_mfma_f32_16x16x32_bf16 v[108:111], v[214:217], v[108:111], v[132:135]
	v_mfma_f32_16x16x32_bf16 v[116:119], v[214:217], v[160:163], v[116:119]
	v_mfma_f32_16x16x32_bf16 v[68:71], v[206:209], v[198:201], v[68:71]
	v_mfma_f32_16x16x32_bf16 v[64:67], v[214:217], v[198:201], v[64:67]
	v_lshl_add_u64 v[232:233], s[46:47], 0, v[170:171]
	s_mov_b32 m0, s38
	v_mfma_f32_16x16x32_bf16 v[100:103], v[210:213], v[112:115], v[100:103]
	v_lshl_add_u64 v[230:231], s[46:47], 0, v[174:175]
	v_mfma_f32_16x16x32_bf16 v[108:111], v[218:221], v[112:115], v[108:111]
	v_mfma_f32_16x16x32_bf16 v[112:115], v[206:209], v[160:163], v[124:127]
	v_mfma_f32_16x16x32_bf16 v[116:119], v[218:221], v[164:167], v[116:119]
	v_mfma_f32_16x16x32_bf16 v[68:71], v[210:213], v[202:205], v[68:71]
	v_mfma_f32_16x16x32_bf16 v[64:67], v[218:221], v[202:205], v[64:67]
	v_mfma_f32_16x16x32_bf16 v[112:115], v[210:213], v[164:167], v[112:115]
	s_barrier
	s_setprio 0
	ds_read_b128 v[124:127], v190 offset:16384
	ds_read_b128 v[132:135], v190 offset:17408
	ds_read_b128 v[140:143], v190 offset:18432
	ds_read_b128 v[152:155], v190 offset:19456
	ds_read_b128 v[160:163], v190 offset:20480
	ds_read_b128 v[164:167], v190 offset:21504
	ds_read_b128 v[198:201], v190 offset:22528
	ds_read_b128 v[202:205], v190 offset:23552
	global_load_lds_dwordx4 v[230:231], off
	s_mov_b32 m0, s39
	s_setprio 1
	global_load_lds_dwordx4 v[232:233], off
	s_waitcnt vmcnt(10)
	s_barrier
	s_waitcnt lgkmcnt(7)
	v_mfma_f32_16x16x32_bf16 v[60:63], v[80:83], v[124:127], v[60:63]
	v_mfma_f32_16x16x32_bf16 v[48:51], v[88:91], v[124:127], v[48:51]
	s_waitcnt lgkmcnt(5)
	v_mfma_f32_16x16x32_bf16 v[40:43], v[80:83], v[140:143], v[40:43]
	v_mfma_f32_16x16x32_bf16 v[32:35], v[88:91], v[140:143], v[32:35]
	s_waitcnt lgkmcnt(3)
	v_mfma_f32_16x16x32_bf16 v[24:27], v[80:83], v[160:163], v[24:27]
	v_mfma_f32_16x16x32_bf16 v[16:19], v[88:91], v[160:163], v[16:19]
	s_waitcnt lgkmcnt(1)
	v_mfma_f32_16x16x32_bf16 v[12:15], v[80:83], v[198:201], v[12:15]
	v_mfma_f32_16x16x32_bf16 v[8:11], v[88:91], v[198:201], v[8:11]
	v_mfma_f32_16x16x32_bf16 v[60:63], v[84:87], v[132:135], v[60:63]
	s_add_u32 s68, s28, 0x80000
	s_addc_u32 s69, s29, 0
	v_mfma_f32_16x16x32_bf16 v[48:51], v[92:95], v[132:135], v[48:51]
	s_add_i32 s70, s67, s37
	v_mfma_f32_16x16x32_bf16 v[40:43], v[84:87], v[152:155], v[40:43]
	v_mfma_f32_16x16x32_bf16 v[32:35], v[92:95], v[152:155], v[32:35]
	v_mfma_f32_16x16x32_bf16 v[24:27], v[84:87], v[164:167], v[24:27]
	v_mfma_f32_16x16x32_bf16 v[16:19], v[92:95], v[164:167], v[16:19]
	s_waitcnt lgkmcnt(0)
	v_mfma_f32_16x16x32_bf16 v[12:15], v[84:87], v[202:205], v[12:15]
	v_mfma_f32_16x16x32_bf16 v[8:11], v[92:95], v[202:205], v[8:11]
	s_barrier
	s_setprio 0
	s_mov_b32 m0, s70
	s_nop 0
	global_load_lds_dwordx4 v172, s[68:69]
	s_add_i32 m0, s70, 0x2000
	s_setprio 1
	global_load_lds_dwordx4 v168, s[68:69]
	s_waitcnt vmcnt(6)
	s_barrier
; #define PG8_STAGE(bufoff, gbase, voff) do { _Pragma("unroll") for (int _i = 0; _i < 2; ++_i) \
;         __builtin_amdgcn_global_load_lds((const unsigned*)((const char*)(gbase) + (voff)[_i]), (LAS unsigned*)(lds + (bufoff) + ldsw + _i * 8192), 16, 0, 0); } while (0)
; #define PG8_LDA(dst, b, h) do { _Pragma("unroll") for (int m = 0; m < 4; ++m) _Pragma("unroll") for (int k = 0; k < 2; ++k) dst[m][k] = *(const LAS bf16x8*)(lds + PG8_SA(b, h) + aoff + m * 2048 + k * 1024); } while (0)
; #define PG8_LDB(dst, b, h) do { _Pragma("unroll") for (int n = 0; n < 2; ++n) _Pragma("unroll") for (int k = 0; k < 2; ++k) dst[n][k] = *(const LAS bf16x8*)(lds + PG8_SB(b, h) + boff + n * 2048 + k * 1024); } while (0)
; #define PG8_MMA(ai, bj, At, Bt) do { __builtin_amdgcn_s_setprio(1); _Pragma("unroll") for (int m = 0; m < 4; ++m) _Pragma("unroll") for (int n = 0; n < 2; ++n) _Pragma("unroll") for (int k = 0; k < 2; ++k) \
;         acc[ai][bj][m][n] = __builtin_amdgcn_mfma_f32_16x16x32_bf16(Bt[n][k], At[m][k], acc[ai][bj][m][n], 0, 0, 0); __builtin_amdgcn_s_setprio(0); } while (0)
; #define PG8_WAIT_V(n) asm volatile("s_waitcnt vmcnt(" #n ")" ::: "memory")
; #define PG8_WAIT_L(n) asm volatile("s_waitcnt lgkmcnt(" #n ")" ::: "memory")
; #define PG8_BAR __builtin_amdgcn_s_barrier()
; #define PG8_SCHED __builtin_amdgcn_sched_barrier(0)
; template <class Map, class Epi>
; DI void gemm_phase(LAS unsigned char* lds, const Map& MP, const Epi& E, const int nM, const int nN, const int K, const int lda, const int ldb) {
;     ...
;             PG8_WAIT_V(6); PG8_BAR; PG8_MMA(1, 1, At, B1); PG8_BAR;
;             PG8_LDB(B0, 1, 0); PG8_SCHED; PG8_LDA(At, 1, 0); PG8_STAGE(PG8_SA(0, 1), a2 + hstepA, voffA);
;             PG8_WAIT_L(8); PG8_BAR; PG8_WAIT_L(0); PG8_MMA(0, 0, At, B0); PG8_BAR; PG8_SCHED;
;             PG8_LDB(B1, 1, 1); PG8_STAGE(PG8_SB(1, 0), b3, voffB);
;             PG8_BAR; PG8_WAIT_L(0); PG8_MMA(0, 1, At, B1); PG8_BAR;
;             PG8_LDA(At, 1, 1); PG8_STAGE(PG8_SA(1, 0), a3, voffA);
;             PG8_BAR; PG8_WAIT_L(0); PG8_MMA(1, 0, At, B0); PG8_BAR; PG8_SCHED;
	v_mfma_f32_16x16x32_bf16 v[56:59], v[206:209], v[124:127], v[56:59]
	v_mfma_f32_16x16x32_bf16 v[52:55], v[214:217], v[124:127], v[52:55]
	s_add_i32 s68, 0, 0x18000
	v_add_u32_e32 v92, s68, v188
	ds_read_b128 v[80:83], v92
	v_mfma_f32_16x16x32_bf16 v[44:47], v[206:209], v[140:143], v[44:47]
	v_mfma_f32_16x16x32_bf16 v[36:39], v[214:217], v[140:143], v[36:39]
	ds_read_b128 v[84:87], v92 offset:1024
	v_mfma_f32_16x16x32_bf16 v[28:31], v[206:209], v[160:163], v[28:31]
	v_mfma_f32_16x16x32_bf16 v[20:23], v[214:217], v[160:163], v[20:23]
	ds_read_b128 v[88:91], v92 offset:2048
	v_mfma_f32_16x16x32_bf16 v[4:7], v[206:209], v[198:201], v[4:7]
	v_mfma_f32_16x16x32_bf16 v[0:3], v[214:217], v[198:201], v[0:3]
	ds_read_b128 v[92:95], v92 offset:3072
	v_mfma_f32_16x16x32_bf16 v[56:59], v[210:213], v[132:135], v[56:59]
	s_add_u32 s46, s46, 0x80000
	s_addc_u32 s47, s47, 0
	v_mfma_f32_16x16x32_bf16 v[52:55], v[218:221], v[132:135], v[52:55]
	v_mfma_f32_16x16x32_bf16 v[44:47], v[210:213], v[152:155], v[44:47]
	v_mfma_f32_16x16x32_bf16 v[36:39], v[218:221], v[152:155], v[36:39]
	v_mfma_f32_16x16x32_bf16 v[28:31], v[210:213], v[164:167], v[28:31]
	v_mfma_f32_16x16x32_bf16 v[20:23], v[218:221], v[164:167], v[20:23]
	v_mfma_f32_16x16x32_bf16 v[4:7], v[210:213], v[202:205], v[4:7]
	v_mfma_f32_16x16x32_bf16 v[0:3], v[218:221], v[202:205], v[0:3]
	s_barrier
	s_setprio 0
	s_mov_b32 m0, s55
	ds_read_b128 v[124:127], v190 offset:32768
	ds_read_b128 v[132:135], v190 offset:33792
	ds_read_b128 v[160:163], v190 offset:34816
	ds_read_b128 v[164:167], v190 offset:35840
	ds_read_b128 v[198:201], v190 offset:36864
	ds_read_b128 v[202:205], v190 offset:37888
	ds_read_b128 v[206:209], v190 offset:38912
	ds_read_b128 v[210:213], v190 offset:39936
	global_load_lds_dwordx4 v174, s[46:47]
	s_mov_b32 m0, s56
	s_setprio 1
	global_load_lds_dwordx4 v170, s[46:47]
	s_waitcnt lgkmcnt(8)
	s_barrier
	s_waitcnt lgkmcnt(7)
	v_mfma_f32_16x16x32_bf16 v[140:143], v[80:83], v[124:127], v[148:151]
	s_waitcnt lgkmcnt(6)
	v_mfma_f32_16x16x32_bf16 v[148:151], v[84:87], v[132:135], v[140:143]
	v_mfma_f32_16x16x32_bf16 v[140:143], v[88:91], v[124:127], v[144:147]
	s_waitcnt lgkmcnt(5)
	v_mfma_f32_16x16x32_bf16 v[136:139], v[80:83], v[160:163], v[136:139]
	v_mfma_f32_16x16x32_bf16 v[128:131], v[88:91], v[160:163], v[128:131]
	s_waitcnt lgkmcnt(3)
	v_mfma_f32_16x16x32_bf16 v[120:123], v[80:83], v[198:201], v[120:123]
	v_mfma_f32_16x16x32_bf16 v[104:107], v[88:91], v[198:201], v[104:107]
	s_waitcnt lgkmcnt(1)
	v_mfma_f32_16x16x32_bf16 v[76:79], v[80:83], v[206:209], v[76:79]
	v_mfma_f32_16x16x32_bf16 v[72:75], v[88:91], v[206:209], v[72:75]
	s_add_i32 s46, 0, 0x1c000
	v_mfma_f32_16x16x32_bf16 v[144:147], v[92:95], v[132:135], v[140:143]
	v_add_u32_e32 v140, s46, v188
	v_mfma_f32_16x16x32_bf16 v[136:139], v[84:87], v[164:167], v[136:139]
	s_add_i32 s47, s68, s37
	v_mfma_f32_16x16x32_bf16 v[128:131], v[92:95], v[164:167], v[128:131]
	v_mfma_f32_16x16x32_bf16 v[120:123], v[84:87], v[202:205], v[120:123]
	v_mfma_f32_16x16x32_bf16 v[104:107], v[92:95], v[202:205], v[104:107]
	s_waitcnt lgkmcnt(0)
	v_mfma_f32_16x16x32_bf16 v[76:79], v[84:87], v[210:213], v[76:79]
	v_mfma_f32_16x16x32_bf16 v[72:75], v[92:95], v[210:213], v[72:75]
	s_barrier
	s_setprio 0
	ds_read_b128 v[214:217], v140
	ds_read_b128 v[218:221], v140 offset:1024
	ds_read_b128 v[222:225], v140 offset:2048
	ds_read_b128 v[226:229], v140 offset:3072
	v_lshl_add_u64 v[140:141], v[184:185], 0, s[14:15]
	s_mov_b32 m0, s47
	s_nop 0
	global_load_lds_dwordx4 v[140:141], off
	v_lshl_add_u64 v[140:141], v[194:195], 0, s[14:15]
	s_add_i32 m0, s47, 0x2000
	s_setprio 1
	global_load_lds_dwordx4 v[140:141], off
	s_barrier
	s_waitcnt lgkmcnt(1)
	v_mfma_f32_16x16x32_bf16 v[96:99], v[222:225], v[124:127], v[96:99]
	v_mfma_f32_16x16x32_bf16 v[140:143], v[214:217], v[124:127], v[156:159]
	s_waitcnt lgkmcnt(0)
	v_mfma_f32_16x16x32_bf16 v[152:155], v[226:229], v[132:135], v[96:99]
	v_mfma_f32_16x16x32_bf16 v[96:99], v[214:217], v[160:163], v[100:103]
	v_mfma_f32_16x16x32_bf16 v[156:159], v[218:221], v[132:135], v[140:143]
	v_mfma_f32_16x16x32_bf16 v[140:143], v[218:221], v[164:167], v[96:99]
	v_mfma_f32_16x16x32_bf16 v[96:99], v[222:225], v[160:163], v[108:111]
	v_mfma_f32_16x16x32_bf16 v[132:135], v[226:229], v[164:167], v[96:99]
	v_mfma_f32_16x16x32_bf16 v[96:99], v[214:217], v[198:201], v[112:115]
	s_mov_b32 m0, s62
	v_mfma_f32_16x16x32_bf16 v[124:127], v[218:221], v[202:205], v[96:99]
	v_lshl_add_u64 v[184:185], v[230:231], 0, s[14:15]
	v_mfma_f32_16x16x32_bf16 v[96:99], v[222:225], v[198:201], v[116:119]
	v_mfma_f32_16x16x32_bf16 v[68:71], v[214:217], v[206:209], v[68:71]
	v_mfma_f32_16x16x32_bf16 v[64:67], v[222:225], v[206:209], v[64:67]
	v_mfma_f32_16x16x32_bf16 v[116:119], v[226:229], v[202:205], v[96:99]
	v_mfma_f32_16x16x32_bf16 v[68:71], v[218:221], v[210:213], v[68:71]
	v_mfma_f32_16x16x32_bf16 v[64:67], v[226:229], v[210:213], v[64:67]
	s_barrier
	s_setprio 0
	ds_read_b128 v[96:99], v190 offset:49152
	ds_read_b128 v[100:103], v190 offset:50176
	ds_read_b128 v[108:111], v190 offset:51200
	ds_read_b128 v[112:115], v190 offset:52224
	ds_read_b128 v[160:163], v190 offset:53248
	ds_read_b128 v[164:167], v190 offset:54272
	ds_read_b128 v[198:201], v190 offset:55296
	ds_read_b128 v[202:205], v190 offset:56320
	global_load_lds_dwordx4 v[184:185], off
	v_lshl_add_u64 v[184:185], v[232:233], 0, s[14:15]
	s_mov_b32 m0, s63
	s_setprio 1
	global_load_lds_dwordx4 v[184:185], off
	s_waitcnt vmcnt(10)
	s_barrier
; #define PG8_STAGE(bufoff, gbase, voff) do { _Pragma("unroll") for (int _i = 0; _i < 2; ++_i) \
;         __builtin_amdgcn_global_load_lds((const unsigned*)((const char*)(gbase) + (voff)[_i]), (LAS unsigned*)(lds + (bufoff) + ldsw + _i * 8192), 16, 0, 0); } while (0)
; #define PG8_MMA(ai, bj, At, Bt) do { __builtin_amdgcn_s_setprio(1); _Pragma("unroll") for (int m = 0; m < 4; ++m) _Pragma("unroll") for (int n = 0; n < 2; ++n) _Pragma("unroll") for (int k = 0; k < 2; ++k) \
;         acc[ai][bj][m][n] = __builtin_amdgcn_mfma_f32_16x16x32_bf16(Bt[n][k], At[m][k], acc[ai][bj][m][n], 0, 0, 0); __builtin_amdgcn_s_setprio(0); } while (0)
; #define PG8_WAIT_V(n) asm volatile("s_waitcnt vmcnt(" #n ")" ::: "memory")
; #define PG8_WAIT_L(n) asm volatile("s_waitcnt lgkmcnt(" #n ")" ::: "memory")
; #define PG8_BAR __builtin_amdgcn_s_barrier()
; #define PG8_SCHED __builtin_amdgcn_sched_barrier(0)
; template <class Map, class Epi>
; DI void gemm_phase(LAS unsigned char* lds, const Map& MP, const Epi& E, const int nM, const int nN, const int K, const int lda, const int ldb) {
;     ...
;             const char* a1 = cA + (size_t)(t + 1) * kstep;
;             const char* a2 = last ? nA : cA + (size_t)(t + 2) * kstep; const char* b2 = last ? nB : cB + (size_t)(t + 2) * kstep;
;             const char* a3 = a2 + kstep; const char* b3 = b2 + kstep;
;     ...
;             PG8_BAR; PG8_WAIT_L(0); PG8_MMA(1, 0, At, B0); PG8_BAR; PG8_SCHED;
;             PG8_STAGE(PG8_SB(1, 1), b3 + hstepB, voffB);
;             PG8_WAIT_V(6); PG8_BAR; PG8_MMA(1, 1, At, B1); PG8_BAR;
	s_waitcnt lgkmcnt(7)
	v_mfma_f32_16x16x32_bf16 v[60:63], v[80:83], v[96:99], v[60:63]
	v_mfma_f32_16x16x32_bf16 v[48:51], v[88:91], v[96:99], v[48:51]
	s_waitcnt lgkmcnt(5)
	v_mfma_f32_16x16x32_bf16 v[40:43], v[80:83], v[108:111], v[40:43]
	v_mfma_f32_16x16x32_bf16 v[32:35], v[88:91], v[108:111], v[32:35]
	s_waitcnt lgkmcnt(3)
	v_mfma_f32_16x16x32_bf16 v[24:27], v[80:83], v[160:163], v[24:27]
	v_mfma_f32_16x16x32_bf16 v[16:19], v[88:91], v[160:163], v[16:19]
	s_waitcnt lgkmcnt(1)
	v_mfma_f32_16x16x32_bf16 v[12:15], v[80:83], v[198:201], v[12:15]
	v_mfma_f32_16x16x32_bf16 v[8:11], v[88:91], v[198:201], v[8:11]
	v_mfma_f32_16x16x32_bf16 v[60:63], v[84:87], v[100:103], v[60:63]
	s_add_u32 s28, s28, 0x80080
	s_addc_u32 s29, s29, 0
	v_mfma_f32_16x16x32_bf16 v[48:51], v[92:95], v[100:103], v[48:51]
	s_add_i32 s46, s46, s37
	v_mfma_f32_16x16x32_bf16 v[40:43], v[84:87], v[112:115], v[40:43]
	v_mfma_f32_16x16x32_bf16 v[32:35], v[92:95], v[112:115], v[32:35]
	v_mfma_f32_16x16x32_bf16 v[24:27], v[84:87], v[164:167], v[24:27]
	v_mfma_f32_16x16x32_bf16 v[16:19], v[92:95], v[164:167], v[16:19]
	s_waitcnt lgkmcnt(0)
	v_mfma_f32_16x16x32_bf16 v[12:15], v[84:87], v[202:205], v[12:15]
	v_mfma_f32_16x16x32_bf16 v[8:11], v[92:95], v[202:205], v[8:11]
	s_barrier
	s_setprio 0
	s_mov_b32 m0, s46
	s_nop 0
	global_load_lds_dwordx4 v172, s[28:29]
	s_add_i32 m0, s46, 0x2000
	s_setprio 1
	global_load_lds_dwordx4 v168, s[28:29]
	s_waitcnt vmcnt(6)
	s_barrier
	v_mfma_f32_16x16x32_bf16 v[56:59], v[214:217], v[96:99], v[56:59]
	v_mfma_f32_16x16x32_bf16 v[52:55], v[222:225], v[96:99], v[52:55]
	ds_read_b128 v[80:83], v189
	v_mfma_f32_16x16x32_bf16 v[44:47], v[214:217], v[108:111], v[44:47]
	v_mfma_f32_16x16x32_bf16 v[36:39], v[222:225], v[108:111], v[36:39]
	ds_read_b128 v[84:87], v189 offset:1024
	v_mfma_f32_16x16x32_bf16 v[28:31], v[214:217], v[160:163], v[28:31]
	v_mfma_f32_16x16x32_bf16 v[20:23], v[222:225], v[160:163], v[20:23]
	ds_read_b128 v[88:91], v189 offset:2048
	v_mfma_f32_16x16x32_bf16 v[4:7], v[214:217], v[198:201], v[4:7]
	v_mfma_f32_16x16x32_bf16 v[0:3], v[222:225], v[198:201], v[0:3]
	ds_read_b128 v[92:95], v189 offset:3072
	v_mfma_f32_16x16x32_bf16 v[56:59], v[218:221], v[100:103], v[56:59]
	s_add_i32 s3, s3, 2
	v_mfma_f32_16x16x32_bf16 v[52:55], v[226:229], v[100:103], v[52:55]
	s_add_u32 vcc_lo, vcc_lo, 0x100
	s_addc_u32 vcc_hi, vcc_hi, 0
	v_mfma_f32_16x16x32_bf16 v[44:47], v[218:221], v[112:115], v[44:47]
	s_add_u32 s42, s42, 0x100
	s_addc_u32 s43, s43, 0
	v_mfma_f32_16x16x32_bf16 v[36:39], v[226:229], v[112:115], v[36:39]
	s_add_u32 s28, s42, 0xfff80080
	s_addc_u32 s29, s43, -1
	s_cmp_eq_u32 s3, 28
	s_cselect_b32 s47, s23, s29
	s_cselect_b32 s46, s58, s28
	s_cselect_b32 s29, s21, vcc_hi
	s_cselect_b32 s28, s59, vcc_lo
	s_cmp_gt_u32 s3, 29
	v_mfma_f32_16x16x32_bf16 v[28:31], v[218:221], v[164:167], v[28:31]
	v_mfma_f32_16x16x32_bf16 v[20:23], v[226:229], v[164:167], v[20:23]
	v_mfma_f32_16x16x32_bf16 v[4:7], v[218:221], v[202:205], v[4:7]
	v_mfma_f32_16x16x32_bf16 v[0:3], v[226:229], v[202:205], v[0:3]
	s_barrier
	s_setprio 0
	s_cbranch_scc0 .LBB1_2483
; DI float silu_mul(float g, float v) { return g * v * __builtin_amdgcn_rcpf(1.0f + __builtin_amdgcn_exp2f(-LOG2E * g)); }
;     DI void operator()(const f32x4 (&acc)[2][2][4][2], const Unit& u, int wr, int wc, int fr, int fq) const {
;         const int row0 = u.pm * BM + wr * 64 + fr, ch0 = u.pn * 128 + wc * 32 + 8 * fq;
;         f32x4 w0[2], w1[2], w2[2], bb[2];
; #pragma unroll
;         for (int n = 0; n < 2; ++n) { w0[n] = *(const f32x4*)(cw + ch0 + 4 * n); w1[n] = *(const f32x4*)(cw + DFF + ch0 + 4 * n); w2[n] = *(const f32x4*)(cw + 2 * DFF + ch0 + 4 * n); bb[n] = *(const f32x4*)(cb + ch0 + 4 * n); }
; #pragma unroll
;         for (int ai = 0; ai < 2; ++ai)
; #pragma unroll
;             for (int m = 0; m < 4; ++m) {
;                 const bool efirst = (m == 0) && (fr == 0), elast = (m == 3) && (fr == 15);
;                 const int row = row0 + ai * HALF + m * 16;
;                 f32x4 gc[2];
; #pragma unroll
;                 for (int n = 0; n < 2; ++n) {
;                     const f32x4 g = acc[ai][0][m][n];
;                     const f32x4 gprev = acc[ai][0][m > 0 ? m - 1 : 0][n], gnext = acc[ai][0][m < 3 ? m + 1 : 3][n];
;                     f32x4 up, dn;
; #pragma unroll
;                     for (int e = 0; e < 4; ++e) {
;                         const float pu = (m > 0 && fr == 15) ? gprev[e] : g[e];
;                         const float pd = (m < 3 && fr == 0) ? gnext[e] : g[e];
;                         up[e] = dpp_ror1(pu); dn[e] = dpp_ror15(pd);
;                     }
;                     if (efirst) up = (f32x4){0.f, 0.f, 0.f, 0.f};
;                     if (elast) dn = (f32x4){0.f, 0.f, 0.f, 0.f};
;                     gc[n] = w0[n] * up + w1[n] * g + w2[n] * dn + bb[n];
;                 }
;                 if (efirst || elast) {
;                     const size_t eo = (size_t)((row >> 6) * 2 + (elast ? 1 : 0)) * DFF + ch0;
; #pragma unroll
;                     for (int n = 0; n < 2; ++n) { *(f32x4*)(EP + eo + 4 * n) = gc[n]; *(f32x4*)(ER + eo + 4 * n) = acc[ai][0][m][n]; *(f32x4*)(EV + eo + 4 * n) = acc[ai][1][m][n]; }
;                 } else {
;                     const f32x4 v0 = acc[ai][1][m][0], v1 = acc[ai][1][m][1];
;                     u32x4 o;
;                     o[0] = pack2(silu_mul(gc[0][0], v0[0]), silu_mul(gc[0][1], v0[1])); o[1] = pack2(silu_mul(gc[0][2], v0[2]), silu_mul(gc[0][3], v0[3]));
	s_waitcnt lgkmcnt(0)
	s_lshl_b32 s21, s45, 7
	v_mov_b32_e32 v80, v187
	v_mov_b32_e32 v194, v186
	s_or_b32 s21, s21, s57
	v_lshl_add_u32 v184, v80, 3, s21
	v_ashrrev_i32_e32 v185, 31, v184
	v_lshlrev_b64 v[80:81], 2, v[184:185]
	v_lshl_add_u64 v[84:85], s[4:5], 0, v[80:81]
	v_lshl_add_u64 v[88:89], s[16:17], 0, v[80:81]
	v_lshl_add_u64 v[92:93], s[18:19], 0, v[80:81]
	v_lshl_add_u64 v[112:113], s[6:7], 0, v[80:81]
	global_load_dwordx4 v[80:83], v[84:85], off offset:16
	global_load_dwordx4 v[96:99], v[84:85], off
	s_nop 0
	global_load_dwordx4 v[84:87], v[88:89], off offset:16
	global_load_dwordx4 v[100:103], v[88:89], off
	s_nop 0
	global_load_dwordx4 v[88:91], v[92:93], off offset:16
	global_load_dwordx4 v[108:111], v[92:93], off
	s_nop 0
	global_load_dwordx4 v[92:95], v[112:113], off offset:16
	s_nop 0
	global_load_dwordx4 v[112:115], v[112:113], off
	v_cmp_eq_u32_e32 vcc, 0, v194
	s_nop 0
	s_nop 0
	v_cndmask_b32_e32 v161, v148, v136, vcc
	v_cndmask_b32_e32 v162, v149, v137, vcc
	v_cndmask_b32_e32 v163, v150, v138, vcc
	v_mov_b32_dpp v160, v161 row_ror:15 row_mask:0xf bank_mask:0xf
	s_nop 0
	s_nop 0
	v_mov_b32_dpp v161, v162 row_ror:15 row_mask:0xf bank_mask:0xf
	v_mov_b32_dpp v164, v150 row_ror:1 row_mask:0xf bank_mask:0xf
	v_cndmask_b32_e32 v165, v151, v139, vcc
	v_mov_b32_dpp v162, v163 row_ror:15 row_mask:0xf bank_mask:0xf
	v_mov_b32_dpp v195, v151 row_ror:1 row_mask:0xf bank_mask:0xf
	v_mov_b32_dpp v166, v148 row_ror:1 row_mask:0xf bank_mask:0xf
	v_mov_b32_dpp v167, v149 row_ror:1 row_mask:0xf bank_mask:0xf
	v_mov_b32_dpp v163, v165 row_ror:15 row_mask:0xf bank_mask:0xf
	v_cndmask_b32_e64 v165, v195, 0, vcc
	v_cndmask_b32_e64 v164, v164, 0, vcc
	v_cndmask_b32_e64 v167, v167, 0, vcc
	v_cndmask_b32_e64 v166, v166, 0, vcc
	s_nop 0
	s_nop 0
	v_mov_b32_dpp v195, v144 row_ror:1 row_mask:0xf bank_mask:0xf
	v_mov_b32_dpp v196, v145 row_ror:1 row_mask:0xf bank_mask:0xf
	v_mov_b32_dpp v198, v146 row_ror:1 row_mask:0xf bank_mask:0xf
	v_cndmask_b32_e32 v199, v147, v131, vcc
	v_mov_b32_dpp v200, v147 row_ror:1 row_mask:0xf bank_mask:0xf
	v_cndmask_b32_e64 v198, v198, 0, vcc
	v_cndmask_b32_e64 v201, v196, 0, vcc
	s_lshl_b32 s3, s44, 8
	s_add_i32 s3, s3, s49
	v_add_u32_e32 v193, s3, v194
	v_cmp_ne_u32_e64 s[46:47], 0, v194
	s_waitcnt vmcnt(0)
	v_pk_mul_f32 v[164:165], v[98:99], v[164:165]
	v_pk_mul_f32 v[166:167], v[96:97], v[166:167]
	v_pk_fma_f32 v[164:165], v[150:151], v[102:103], v[164:165]
	v_pk_fma_f32 v[166:167], v[148:149], v[100:101], v[166:167]
	v_pk_fma_f32 v[162:163], v[110:111], v[162:163], v[164:165]
	v_cndmask_b32_e32 v165, v144, v128, vcc
	v_pk_fma_f32 v[160:161], v[108:109], v[160:161], v[166:167]
	v_cndmask_b32_e32 v166, v145, v129, vcc
	v_mov_b32_dpp v164, v165 row_ror:15 row_mask:0xf bank_mask:0xf
	v_cndmask_b32_e32 v167, v146, v130, vcc
	v_pk_add_f32 v[162:163], v[114:115], v[162:163]
	v_mov_b32_dpp v165, v166 row_ror:15 row_mask:0xf bank_mask:0xf
	v_pk_add_f32 v[160:161], v[112:113], v[160:161]
	s_nop 0
	v_mov_b32_dpp v166, v167 row_ror:15 row_mask:0xf bank_mask:0xf
	s_nop 1
	v_mov_b32_dpp v167, v199 row_ror:15 row_mask:0xf bank_mask:0xf
	v_cndmask_b32_e64 v199, v200, 0, vcc
	v_cndmask_b32_e64 v200, v195, 0, vcc
	v_pk_mul_f32 v[200:201], v[80:81], v[200:201]
	v_pk_mul_f32 v[198:199], v[82:83], v[198:199]
	v_pk_fma_f32 v[200:201], v[144:145], v[84:85], v[200:201]
	v_pk_fma_f32 v[198:199], v[146:147], v[86:87], v[198:199]
	v_pk_fma_f32 v[164:165], v[88:89], v[164:165], v[200:201]
	v_pk_fma_f32 v[166:167], v[90:91], v[166:167], v[198:199]
	v_pk_add_f32 v[164:165], v[92:93], v[164:165]
	v_pk_add_f32 v[166:167], v[94:95], v[166:167]
	s_and_saveexec_b64 s[28:29], s[46:47]
	s_xor_b64 s[28:29], exec, s[28:29]
	s_cbranch_execz .LBB1_2486
	v_mul_f32_e32 v195, 0xbfb8aa3b, v160
	v_exp_f32_e32 v195, v195
	v_mul_f32_e32 v196, 0xbfb8aa3b, v161
	v_exp_f32_e32 v196, v196
	v_pk_mul_f32 v[160:161], v[156:157], v[160:161]
	v_add_f32_e32 v195, 1.0, v195
	v_rcp_f32_e32 v198, v195
	v_add_f32_e32 v196, 1.0, v196
	v_mul_f32_e32 v195, 0xbfb8aa3b, v162
	v_rcp_f32_e32 v199, v196
	v_exp_f32_e32 v195, v195
	v_mul_f32_e32 v196, 0xbfb8aa3b, v163
	v_exp_f32_e32 v196, v196
	v_pk_mul_f32 v[160:161], v[160:161], v[198:199]
	v_add_f32_e32 v195, 1.0, v195
	v_rcp_f32_e32 v200, v195
	v_add_f32_e32 v195, 1.0, v196
	v_rcp_f32_e32 v201, v195
	v_cvt_pk_bf16_f32 v160, v160, v161
	v_mul_f32_e32 v161, 0xbfb8aa3b, v164
	v_exp_f32_e32 v195, v161
	v_mul_f32_e32 v161, 0xbfb8aa3b, v165
	v_exp_f32_e32 v196, v161
	v_pk_mul_f32 v[162:163], v[158:159], v[162:163]
	v_pk_mul_f32 v[164:165], v[152:153], v[164:165]
	v_pk_mul_f32 v[162:163], v[162:163], v[200:201]
	s_nop 0
	v_cvt_pk_bf16_f32 v161, v162, v163
	v_add_f32_e32 v162, 1.0, v195
	v_mul_f32_e32 v195, 0xbfb8aa3b, v166
	v_add_f32_e32 v163, 1.0, v196
	v_exp_f32_e32 v195, v195
	v_mul_f32_e32 v196, 0xbfb8aa3b, v167
	v_exp_f32_e32 v196, v196
	v_rcp_f32_e32 v162, v162
	v_add_f32_e32 v195, 1.0, v195
	v_rcp_f32_e32 v198, v195
	v_add_f32_e32 v195, 1.0, v196
	v_rcp_f32_e32 v163, v163
	v_rcp_f32_e32 v199, v195
	v_pk_mul_f32 v[166:167], v[154:155], v[166:167]
	v_pk_mul_f32 v[162:163], v[164:165], v[162:163]
	v_pk_mul_f32 v[164:165], v[166:167], v[198:199]
	v_cvt_pk_bf16_f32 v162, v162, v163
	v_cvt_pk_bf16_f32 v163, v164, v165
	v_mov_b64_e32 v[164:165], s[52:53]
	v_mad_i64_i32 v[164:165], s[42:43], v193, s60, v[164:165]
	v_lshl_add_u64 v[164:165], v[184:185], 1, v[164:165]
	global_store_dwordx4 v[164:165], v[160:163], off
